# GEMM loops: remaining p7 DMAs via freed SGPR pair, ds_read base-address adds hoisted out of the K loop, duplicate lgkmcnt(0) dropped
# speedup vs baseline: 1.0326x; 1.0082x over previous
.LBB0_86:
	v_mov_b64_e32 v[0:1], 0x800
	s_ashr_i32 s7, s6, 31
	v_cmp_lt_i64_e32 vcc, s[8:9], v[0:1]
	s_lshl_b64 s[8:9], s[6:7], 20
	s_add_u32 s8, s23, s8
	s_addc_u32 s9, s24, s9
	s_and_b64 s[10:11], vcc, exec
	s_cselect_b32 s7, s9, s15
	s_cselect_b32 s38, s8, s14
	s_ashr_i32 s5, s4, 31
	s_lshl_b64 s[10:11], s[4:5], 20
	s_add_u32 s10, s25, s10
	s_addc_u32 s11, s26, s11
	s_and_b64 s[18:19], vcc, exec
	s_cselect_b32 s5, s11, s17
	s_cselect_b32 s39, s10, s16
	s_add_u32 s14, s14, 0x80080
	s_addc_u32 s15, s15, 0
	s_add_u32 s40, s16, 0x100
	v_mov_b32_e32 v0, 0
	s_addc_u32 s41, s17, 0
	s_mov_b32 s42, -2
	v_mov_b32_e32 v1, v0
	v_mov_b32_e32 v2, v0
	v_mov_b32_e32 v3, v0
	v_mov_b32_e32 v4, v0
	v_mov_b32_e32 v5, v0
	v_mov_b32_e32 v6, v0
	v_mov_b32_e32 v7, v0
	v_mov_b32_e32 v16, v0
	v_mov_b32_e32 v17, v0
	v_mov_b32_e32 v18, v0
	v_mov_b32_e32 v19, v0
	v_mov_b32_e32 v20, v0
	v_mov_b32_e32 v21, v0
	v_mov_b32_e32 v22, v0
	v_mov_b32_e32 v23, v0
	v_mov_b32_e32 v32, v0
	v_mov_b32_e32 v33, v0
	v_mov_b32_e32 v34, v0
	v_mov_b32_e32 v35, v0
	v_mov_b32_e32 v36, v0
	v_mov_b32_e32 v37, v0
	v_mov_b32_e32 v38, v0
	v_mov_b32_e32 v39, v0
	v_mov_b32_e32 v48, v0
	v_mov_b32_e32 v49, v0
	v_mov_b32_e32 v50, v0
	v_mov_b32_e32 v51, v0
	v_mov_b32_e32 v52, v0
	v_mov_b32_e32 v53, v0
	v_mov_b32_e32 v54, v0
	v_mov_b32_e32 v55, v0
	v_mov_b32_e32 v8, v0
	v_mov_b32_e32 v9, v0
	v_mov_b32_e32 v10, v0
	v_mov_b32_e32 v11, v0
	v_mov_b32_e32 v12, v0
	v_mov_b32_e32 v13, v0
	v_mov_b32_e32 v14, v0
	v_mov_b32_e32 v15, v0
	v_mov_b32_e32 v24, v0
	v_mov_b32_e32 v25, v0
	v_mov_b32_e32 v26, v0
	v_mov_b32_e32 v27, v0
	v_mov_b32_e32 v28, v0
	v_mov_b32_e32 v29, v0
	v_mov_b32_e32 v30, v0
	v_mov_b32_e32 v31, v0
	v_mov_b32_e32 v40, v0
	v_mov_b32_e32 v41, v0
	v_mov_b32_e32 v42, v0
	v_mov_b32_e32 v43, v0
	v_mov_b32_e32 v44, v0
	v_mov_b32_e32 v45, v0
	v_mov_b32_e32 v46, v0
	v_mov_b32_e32 v47, v0
	v_mov_b32_e32 v56, v0
	v_mov_b32_e32 v57, v0
	v_mov_b32_e32 v58, v0
	v_mov_b32_e32 v59, v0
	v_mov_b32_e32 v60, v0
	v_mov_b32_e32 v61, v0
	v_mov_b32_e32 v62, v0
	v_mov_b32_e32 v63, v0
	v_mov_b32_e32 v64, v0
	v_mov_b32_e32 v65, v0
	v_mov_b32_e32 v66, v0
	v_mov_b32_e32 v67, v0
	v_mov_b32_e32 v68, v0
	v_mov_b32_e32 v69, v0
	v_mov_b32_e32 v70, v0
	v_mov_b32_e32 v71, v0
	v_mov_b32_e32 v80, v0
	v_mov_b32_e32 v81, v0
	v_mov_b32_e32 v82, v0
	v_mov_b32_e32 v83, v0
	v_mov_b32_e32 v84, v0
	v_mov_b32_e32 v85, v0
	v_mov_b32_e32 v86, v0
	v_mov_b32_e32 v87, v0
	v_mov_b32_e32 v96, v0
	v_mov_b32_e32 v97, v0
	v_mov_b32_e32 v98, v0
	v_mov_b32_e32 v99, v0
	v_mov_b32_e32 v100, v0
	v_mov_b32_e32 v101, v0
	v_mov_b32_e32 v102, v0
	v_mov_b32_e32 v103, v0
	v_mov_b32_e32 v112, v0
	v_mov_b32_e32 v113, v0
	v_mov_b32_e32 v114, v0
	v_mov_b32_e32 v115, v0
	v_mov_b32_e32 v116, v0
	v_mov_b32_e32 v117, v0
	v_mov_b32_e32 v118, v0
	v_mov_b32_e32 v119, v0
	v_mov_b32_e32 v72, v0
	v_mov_b32_e32 v73, v0
	v_mov_b32_e32 v74, v0
	v_mov_b32_e32 v75, v0
	v_mov_b32_e32 v76, v0
	v_mov_b32_e32 v77, v0
	v_mov_b32_e32 v78, v0
	v_mov_b32_e32 v79, v0
	v_mov_b32_e32 v88, v0
	v_mov_b32_e32 v89, v0
	v_mov_b32_e32 v90, v0
	v_mov_b32_e32 v91, v0
	v_mov_b32_e32 v92, v0
	v_mov_b32_e32 v93, v0
	v_mov_b32_e32 v94, v0
	v_mov_b32_e32 v95, v0
	v_mov_b32_e32 v104, v0
	v_mov_b32_e32 v105, v0
	v_mov_b32_e32 v106, v0
	v_mov_b32_e32 v107, v0
	v_mov_b32_e32 v108, v0
	v_mov_b32_e32 v109, v0
	v_mov_b32_e32 v110, v0
	v_mov_b32_e32 v111, v0
	v_mov_b32_e32 v120, v0
	v_mov_b32_e32 v121, v0
	v_mov_b32_e32 v122, v0
	v_mov_b32_e32 v123, v0
	v_mov_b32_e32 v124, v0
	v_mov_b32_e32 v125, v0
	v_mov_b32_e32 v126, v0
	v_mov_b32_e32 v127, v0
	s_mov_b64 s[48:49], 0x80
	v_add_u32_e32 v220, 0x10000, v183
.LBB0_87:
	s_add_u32 s16, s14, 0xfff80080
	s_addc_u32 s17, s15, -1
	s_add_i32 s43, 0, 0x10000
	ds_read_b128 v[128:131], v220 offset:0
	ds_read_b128 v[132:135], v220 offset:1024
	ds_read_b128 v[136:139], v220 offset:2048
	ds_read_b128 v[140:143], v220 offset:3072
	s_cmp_eq_u32 s42, 28
	s_cselect_b32 s19, s7, s17
	s_cselect_b32 s18, s38, s16
	s_cselect_b32 s17, s5, s41
	s_cselect_b32 s16, s39, s40
	s_add_i32 m0, s28, 0xc000
	ds_read_b128 v[144:147], v185
	ds_read_b128 v[148:151], v185 offset:1024
	ds_read_b128 v[152:155], v185 offset:2048
	ds_read_b128 v[156:159], v185 offset:3072
	ds_read_b128 v[170:173], v185 offset:4096
	ds_read_b128 v[174:177], v185 offset:5120
	ds_read_b128 v[178:181], v185 offset:6144
	ds_read_b128 v[186:189], v185 offset:7168
	global_load_lds_dwordx4 v166, s[14:15]
	s_add_i32 m0, s28, 0xe000
	s_nop 0
	global_load_lds_dwordx4 v168, s[14:15]
	s_waitcnt lgkmcnt(8)
	s_barrier
	s_waitcnt lgkmcnt(0)
	v_mfma_f32_16x16x32_bf16 v[124:127], v[128:131], v[144:147], v[124:127]
	v_mfma_f32_16x16x32_bf16 v[120:123], v[136:139], v[144:147], v[120:123]
	v_mfma_f32_16x16x32_bf16 v[108:111], v[128:131], v[152:155], v[108:111]
	v_mfma_f32_16x16x32_bf16 v[104:107], v[136:139], v[152:155], v[104:107]
	v_mfma_f32_16x16x32_bf16 v[92:95], v[128:131], v[170:173], v[92:95]
	v_mfma_f32_16x16x32_bf16 v[88:91], v[136:139], v[170:173], v[88:91]
	v_mfma_f32_16x16x32_bf16 v[76:79], v[128:131], v[178:181], v[76:79]
	v_mfma_f32_16x16x32_bf16 v[72:75], v[136:139], v[178:181], v[72:75]
	v_mfma_f32_16x16x32_bf16 v[124:127], v[132:135], v[148:151], v[124:127]
	v_mfma_f32_16x16x32_bf16 v[120:123], v[140:143], v[148:151], v[120:123]
	v_mfma_f32_16x16x32_bf16 v[108:111], v[132:135], v[156:159], v[108:111]
	v_mfma_f32_16x16x32_bf16 v[104:107], v[140:143], v[156:159], v[104:107]
	v_mfma_f32_16x16x32_bf16 v[92:95], v[132:135], v[174:177], v[92:95]
	v_mfma_f32_16x16x32_bf16 v[88:91], v[140:143], v[174:177], v[88:91]
	v_mfma_f32_16x16x32_bf16 v[76:79], v[132:135], v[186:189], v[76:79]
	v_mfma_f32_16x16x32_bf16 v[72:75], v[140:143], v[186:189], v[72:75]
	s_barrier
	s_add_i32 s46, 0, 0x14000
	s_add_i32 s43, s43, s27
	ds_read_b128 v[196:199], v220 offset:16384
	ds_read_b128 v[204:207], v220 offset:17408
	ds_read_b128 v[208:211], v220 offset:18432
	ds_read_b128 v[214:217], v220 offset:19456
	s_mov_b32 m0, s43
	s_nop 0
	global_load_lds_dwordx4 v192, s[16:17]
	s_add_i32 m0, s43, 0x2000
	s_nop 0
	global_load_lds_dwordx4 v164, s[16:17]
	s_barrier
	s_waitcnt lgkmcnt(0)
	v_mfma_f32_16x16x32_bf16 v[116:119], v[196:199], v[144:147], v[116:119]
	v_mfma_f32_16x16x32_bf16 v[112:115], v[208:211], v[144:147], v[112:115]
	v_mfma_f32_16x16x32_bf16 v[100:103], v[196:199], v[152:155], v[100:103]
	v_mfma_f32_16x16x32_bf16 v[96:99], v[208:211], v[152:155], v[96:99]
	v_mfma_f32_16x16x32_bf16 v[84:87], v[196:199], v[170:173], v[84:87]
	v_mfma_f32_16x16x32_bf16 v[80:83], v[208:211], v[170:173], v[80:83]
	v_mfma_f32_16x16x32_bf16 v[68:71], v[196:199], v[178:181], v[68:71]
	v_mfma_f32_16x16x32_bf16 v[64:67], v[208:211], v[178:181], v[64:67]
	v_mfma_f32_16x16x32_bf16 v[116:119], v[204:207], v[148:151], v[116:119]
	v_mfma_f32_16x16x32_bf16 v[112:115], v[214:217], v[148:151], v[112:115]
	v_mfma_f32_16x16x32_bf16 v[100:103], v[204:207], v[156:159], v[100:103]
	v_mfma_f32_16x16x32_bf16 v[96:99], v[214:217], v[156:159], v[96:99]
	v_mfma_f32_16x16x32_bf16 v[84:87], v[204:207], v[174:177], v[84:87]
	v_mfma_f32_16x16x32_bf16 v[80:83], v[214:217], v[174:177], v[80:83]
	v_mfma_f32_16x16x32_bf16 v[68:71], v[204:207], v[186:189], v[68:71]
	v_mfma_f32_16x16x32_bf16 v[64:67], v[214:217], v[186:189], v[64:67]
	s_mov_b32 m0, s28
	s_add_u32 s48, s18, 0x80
	s_addc_u32 s49, s19, 0
	s_barrier
	ds_read_b128 v[144:147], v185 offset:16384
	ds_read_b128 v[148:151], v185 offset:17408
	ds_read_b128 v[152:155], v185 offset:18432
	ds_read_b128 v[156:159], v185 offset:19456
	ds_read_b128 v[170:173], v185 offset:20480
	ds_read_b128 v[174:177], v185 offset:21504
	ds_read_b128 v[178:181], v185 offset:22528
	ds_read_b128 v[186:189], v185 offset:23552
	global_load_lds_dwordx4 v160, s[18:19]
	s_mov_b32 m0, s29
	s_nop 0
	global_load_lds_dwordx4 v162, s[18:19]
	s_barrier
	s_waitcnt lgkmcnt(0)
	v_mfma_f32_16x16x32_bf16 v[60:63], v[128:131], v[144:147], v[60:63]
	v_mfma_f32_16x16x32_bf16 v[56:59], v[136:139], v[144:147], v[56:59]
	v_mfma_f32_16x16x32_bf16 v[44:47], v[128:131], v[152:155], v[44:47]
	v_mfma_f32_16x16x32_bf16 v[40:43], v[136:139], v[152:155], v[40:43]
	v_mfma_f32_16x16x32_bf16 v[28:31], v[128:131], v[170:173], v[28:31]
	v_mfma_f32_16x16x32_bf16 v[24:27], v[136:139], v[170:173], v[24:27]
	v_mfma_f32_16x16x32_bf16 v[12:15], v[128:131], v[178:181], v[12:15]
	v_mfma_f32_16x16x32_bf16 v[8:11], v[136:139], v[178:181], v[8:11]
	v_mfma_f32_16x16x32_bf16 v[60:63], v[132:135], v[148:151], v[60:63]
	v_mfma_f32_16x16x32_bf16 v[56:59], v[140:143], v[148:151], v[56:59]
	v_mfma_f32_16x16x32_bf16 v[44:47], v[132:135], v[156:159], v[44:47]
	v_mfma_f32_16x16x32_bf16 v[40:43], v[140:143], v[156:159], v[40:43]
	v_mfma_f32_16x16x32_bf16 v[28:31], v[132:135], v[174:177], v[28:31]
	v_mfma_f32_16x16x32_bf16 v[24:27], v[140:143], v[174:177], v[24:27]
	v_mfma_f32_16x16x32_bf16 v[12:15], v[132:135], v[186:189], v[12:15]
	v_mfma_f32_16x16x32_bf16 v[8:11], v[140:143], v[186:189], v[8:11]
	s_barrier
	s_add_u32 s44, s16, 0x80000
	s_addc_u32 s45, s17, 0
	s_add_i32 s43, s46, s27
	s_mov_b32 m0, s43
	s_nop 0
	global_load_lds_dwordx4 v192, s[44:45]
	s_add_i32 m0, s43, 0x2000
	s_nop 0
	global_load_lds_dwordx4 v164, s[44:45]
	s_waitcnt vmcnt(6)
	s_barrier
	v_mfma_f32_16x16x32_bf16 v[52:55], v[196:199], v[144:147], v[52:55]
	v_mfma_f32_16x16x32_bf16 v[48:51], v[208:211], v[144:147], v[48:51]
	v_mfma_f32_16x16x32_bf16 v[36:39], v[196:199], v[152:155], v[36:39]
	v_mfma_f32_16x16x32_bf16 v[32:35], v[208:211], v[152:155], v[32:35]
	v_mfma_f32_16x16x32_bf16 v[20:23], v[196:199], v[170:173], v[20:23]
	v_mfma_f32_16x16x32_bf16 v[16:19], v[208:211], v[170:173], v[16:19]
	v_mfma_f32_16x16x32_bf16 v[4:7], v[196:199], v[178:181], v[4:7]
	v_mfma_f32_16x16x32_bf16 v[0:3], v[208:211], v[178:181], v[0:3]
	v_mfma_f32_16x16x32_bf16 v[52:55], v[204:207], v[148:151], v[52:55]
	v_mfma_f32_16x16x32_bf16 v[48:51], v[214:217], v[148:151], v[48:51]
	v_mfma_f32_16x16x32_bf16 v[36:39], v[204:207], v[156:159], v[36:39]
	v_mfma_f32_16x16x32_bf16 v[32:35], v[214:217], v[156:159], v[32:35]
	v_mfma_f32_16x16x32_bf16 v[20:23], v[204:207], v[174:177], v[20:23]
	v_mfma_f32_16x16x32_bf16 v[16:19], v[214:217], v[174:177], v[16:19]
	v_mfma_f32_16x16x32_bf16 v[4:7], v[204:207], v[186:189], v[4:7]
	v_mfma_f32_16x16x32_bf16 v[0:3], v[214:217], v[186:189], v[0:3]
	s_add_i32 s43, 0, 0x18000
	s_barrier
	ds_read_b128 v[128:131], v220 offset:32768
	ds_read_b128 v[132:135], v220 offset:33792
	ds_read_b128 v[136:139], v220 offset:34816
	ds_read_b128 v[140:143], v220 offset:35840
	s_add_u32 s18, s18, 0x80000
	s_addc_u32 s19, s19, 0
	s_mov_b32 m0, s30
	ds_read_b128 v[144:147], v185 offset:32768
	ds_read_b128 v[148:151], v185 offset:33792
	ds_read_b128 v[152:155], v185 offset:34816
	ds_read_b128 v[156:159], v185 offset:35840
	ds_read_b128 v[170:173], v185 offset:36864
	ds_read_b128 v[174:177], v185 offset:37888
	ds_read_b128 v[178:181], v185 offset:38912
	ds_read_b128 v[186:189], v185 offset:39936
	global_load_lds_dwordx4 v160, s[18:19]
	s_mov_b32 m0, s31
	s_nop 0
	global_load_lds_dwordx4 v162, s[18:19]
	s_waitcnt lgkmcnt(8)
	s_barrier
	s_waitcnt lgkmcnt(0)
	v_mfma_f32_16x16x32_bf16 v[124:127], v[128:131], v[144:147], v[124:127]
	v_mfma_f32_16x16x32_bf16 v[120:123], v[136:139], v[144:147], v[120:123]
	v_mfma_f32_16x16x32_bf16 v[108:111], v[128:131], v[152:155], v[108:111]
	v_mfma_f32_16x16x32_bf16 v[104:107], v[136:139], v[152:155], v[104:107]
	v_mfma_f32_16x16x32_bf16 v[92:95], v[128:131], v[170:173], v[92:95]
	v_mfma_f32_16x16x32_bf16 v[88:91], v[136:139], v[170:173], v[88:91]
	v_mfma_f32_16x16x32_bf16 v[76:79], v[128:131], v[178:181], v[76:79]
	v_mfma_f32_16x16x32_bf16 v[72:75], v[136:139], v[178:181], v[72:75]
	v_mfma_f32_16x16x32_bf16 v[124:127], v[132:135], v[148:151], v[124:127]
	v_mfma_f32_16x16x32_bf16 v[120:123], v[140:143], v[148:151], v[120:123]
	v_mfma_f32_16x16x32_bf16 v[108:111], v[132:135], v[156:159], v[108:111]
	v_mfma_f32_16x16x32_bf16 v[104:107], v[140:143], v[156:159], v[104:107]
	v_mfma_f32_16x16x32_bf16 v[92:95], v[132:135], v[174:177], v[92:95]
	v_mfma_f32_16x16x32_bf16 v[88:91], v[140:143], v[174:177], v[88:91]
	v_mfma_f32_16x16x32_bf16 v[76:79], v[132:135], v[186:189], v[76:79]
	v_mfma_f32_16x16x32_bf16 v[72:75], v[140:143], v[186:189], v[72:75]
	s_barrier
	s_add_i32 s18, 0, 0x1c000
	s_add_i32 s19, s43, s27
	s_add_i32 m0, s19, 0xffffff80
	ds_read_b128 v[196:199], v220 offset:49152
	ds_read_b128 v[204:207], v220 offset:50176
	ds_read_b128 v[208:211], v220 offset:51200
	ds_read_b128 v[214:217], v220 offset:52224
	global_load_lds_dwordx4 v192, s[16:17] offset:128
	s_add_i32 m0, s19, 0x1f80
	s_nop 0
	global_load_lds_dwordx4 v164, s[16:17] offset:128
	s_barrier
	s_waitcnt lgkmcnt(0)
	v_mfma_f32_16x16x32_bf16 v[116:119], v[196:199], v[144:147], v[116:119]
	v_mfma_f32_16x16x32_bf16 v[112:115], v[208:211], v[144:147], v[112:115]
	v_mfma_f32_16x16x32_bf16 v[100:103], v[196:199], v[152:155], v[100:103]
	v_mfma_f32_16x16x32_bf16 v[96:99], v[208:211], v[152:155], v[96:99]
	v_mfma_f32_16x16x32_bf16 v[84:87], v[196:199], v[170:173], v[84:87]
	v_mfma_f32_16x16x32_bf16 v[80:83], v[208:211], v[170:173], v[80:83]
	v_mfma_f32_16x16x32_bf16 v[68:71], v[196:199], v[178:181], v[68:71]
	v_mfma_f32_16x16x32_bf16 v[64:67], v[208:211], v[178:181], v[64:67]
	v_mfma_f32_16x16x32_bf16 v[116:119], v[204:207], v[148:151], v[116:119]
	v_mfma_f32_16x16x32_bf16 v[112:115], v[214:217], v[148:151], v[112:115]
	v_mfma_f32_16x16x32_bf16 v[100:103], v[204:207], v[156:159], v[100:103]
	v_mfma_f32_16x16x32_bf16 v[96:99], v[214:217], v[156:159], v[96:99]
	v_mfma_f32_16x16x32_bf16 v[84:87], v[204:207], v[174:177], v[84:87]
	v_mfma_f32_16x16x32_bf16 v[80:83], v[214:217], v[174:177], v[80:83]
	v_mfma_f32_16x16x32_bf16 v[68:71], v[204:207], v[186:189], v[68:71]
	v_mfma_f32_16x16x32_bf16 v[64:67], v[214:217], v[186:189], v[64:67]
	s_mov_b32 m0, s35
	s_barrier
	ds_read_b128 v[144:147], v185 offset:49152
	ds_read_b128 v[148:151], v185 offset:50176
	ds_read_b128 v[152:155], v185 offset:51200
	ds_read_b128 v[156:159], v185 offset:52224
	ds_read_b128 v[170:173], v185 offset:53248
	ds_read_b128 v[174:177], v185 offset:54272
	ds_read_b128 v[178:181], v185 offset:55296
	ds_read_b128 v[186:189], v185 offset:56320
	global_load_lds_dwordx4 v160, s[48:49]
	s_mov_b32 m0, s36
	s_nop 0
	global_load_lds_dwordx4 v162, s[48:49]
	s_barrier
	s_waitcnt lgkmcnt(0)
	v_mfma_f32_16x16x32_bf16 v[60:63], v[128:131], v[144:147], v[60:63]
	v_mfma_f32_16x16x32_bf16 v[56:59], v[136:139], v[144:147], v[56:59]
	v_mfma_f32_16x16x32_bf16 v[44:47], v[128:131], v[152:155], v[44:47]
	v_mfma_f32_16x16x32_bf16 v[40:43], v[136:139], v[152:155], v[40:43]
	v_mfma_f32_16x16x32_bf16 v[28:31], v[128:131], v[170:173], v[28:31]
	v_mfma_f32_16x16x32_bf16 v[24:27], v[136:139], v[170:173], v[24:27]
	v_mfma_f32_16x16x32_bf16 v[12:15], v[128:131], v[178:181], v[12:15]
	v_mfma_f32_16x16x32_bf16 v[8:11], v[136:139], v[178:181], v[8:11]
	v_mfma_f32_16x16x32_bf16 v[60:63], v[132:135], v[148:151], v[60:63]
	v_mfma_f32_16x16x32_bf16 v[56:59], v[140:143], v[148:151], v[56:59]
	v_mfma_f32_16x16x32_bf16 v[44:47], v[132:135], v[156:159], v[44:47]
	v_mfma_f32_16x16x32_bf16 v[40:43], v[140:143], v[156:159], v[40:43]
	v_mfma_f32_16x16x32_bf16 v[28:31], v[132:135], v[174:177], v[28:31]
	v_mfma_f32_16x16x32_bf16 v[24:27], v[140:143], v[174:177], v[24:27]
	v_mfma_f32_16x16x32_bf16 v[12:15], v[132:135], v[186:189], v[12:15]
	v_mfma_f32_16x16x32_bf16 v[8:11], v[140:143], v[186:189], v[8:11]
	s_barrier
	s_add_u32 s16, s16, 0x80080
	s_addc_u32 s17, s17, 0
	s_add_i32 s18, s18, s27
	s_mov_b32 m0, s18
	s_nop 0
	global_load_lds_dwordx4 v192, s[16:17]
	s_add_i32 m0, s18, 0x2000
	s_nop 0
	global_load_lds_dwordx4 v164, s[16:17]
	s_waitcnt vmcnt(6)
	s_barrier
	v_mfma_f32_16x16x32_bf16 v[52:55], v[196:199], v[144:147], v[52:55]
	v_mfma_f32_16x16x32_bf16 v[48:51], v[208:211], v[144:147], v[48:51]
	v_mfma_f32_16x16x32_bf16 v[36:39], v[196:199], v[152:155], v[36:39]
	v_mfma_f32_16x16x32_bf16 v[32:35], v[208:211], v[152:155], v[32:35]
	v_mfma_f32_16x16x32_bf16 v[20:23], v[196:199], v[170:173], v[20:23]
	v_mfma_f32_16x16x32_bf16 v[16:19], v[208:211], v[170:173], v[16:19]
	v_mfma_f32_16x16x32_bf16 v[4:7], v[196:199], v[178:181], v[4:7]
	v_mfma_f32_16x16x32_bf16 v[0:3], v[208:211], v[178:181], v[0:3]
	v_mfma_f32_16x16x32_bf16 v[52:55], v[204:207], v[148:151], v[52:55]
	v_mfma_f32_16x16x32_bf16 v[48:51], v[214:217], v[148:151], v[48:51]
	v_mfma_f32_16x16x32_bf16 v[36:39], v[204:207], v[156:159], v[36:39]
	v_mfma_f32_16x16x32_bf16 v[32:35], v[214:217], v[156:159], v[32:35]
	v_mfma_f32_16x16x32_bf16 v[20:23], v[204:207], v[174:177], v[20:23]
	v_mfma_f32_16x16x32_bf16 v[16:19], v[214:217], v[174:177], v[16:19]
	v_mfma_f32_16x16x32_bf16 v[4:7], v[204:207], v[186:189], v[4:7]
	v_mfma_f32_16x16x32_bf16 v[0:3], v[214:217], v[186:189], v[0:3]
	s_add_i32 s42, s42, 2
	s_add_u32 s14, s14, 0x100
	s_addc_u32 s15, s15, 0
	s_add_u32 s40, s40, 0x100
	s_addc_u32 s41, s41, 0
	s_cmp_gt_u32 s42, 29
	s_barrier
	s_cbranch_scc0 .LBB0_87
	v_lshl_or_b32 v128, s13, 8, v184
	v_lshl_add_u32 v172, s12, 8, v182
	v_ashrrev_i32_e32 v129, 31, v128
	v_lshlrev_b64 v[170:171], 1, v[128:129]
	v_ashrrev_i32_e32 v173, 31, v172
	v_lshl_add_u64 v[174:175], s[2:3], 0, v[170:171]
	v_lshlrev_b64 v[128:129], 13, v[172:173]
	v_lshl_add_u64 v[130:131], v[174:175], 0, v[128:129]
	global_load_dwordx4 v[186:189], v[130:131], off
	global_load_dwordx4 v[196:199], v[130:131], off offset:256
	s_lshl_b32 s5, s13, 1
	v_mul_f32_e32 v133, 0xbfb8aa3b, v124
	v_mul_f32_e32 v135, 0xbfb8aa3b, v125
	v_mul_f32_e32 v137, 0xbfb8aa3b, v126
	v_mul_f32_e32 v138, 0xbfb8aa3b, v127
	v_mul_f32_e32 v139, 0xbfb8aa3b, v120
	v_mul_f32_e32 v140, 0xbfb8aa3b, v121
	s_and_b32 s12, s5, -4
	v_or_b32_e32 v132, 16, v172
	v_or_b32_e32 v136, 48, v172
	v_exp_f32_e32 v148, v133
	v_exp_f32_e32 v149, v135
	v_exp_f32_e32 v150, v137
	v_exp_f32_e32 v151, v138
	v_exp_f32_e32 v204, v139
	v_exp_f32_e32 v205, v140
	s_ashr_i32 s13, s12, 31
	v_or_b32_e32 v134, 32, v172
	v_ashrrev_i32_e32 v133, 31, v132
	v_ashrrev_i32_e32 v137, 31, v136
	s_lshl_b64 s[12:13], s[12:13], 2
	v_mul_f32_e32 v141, 0xbfb8aa3b, v122
	v_ashrrev_i32_e32 v135, 31, v134
	v_lshlrev_b64 v[180:181], 13, v[132:133]
	v_lshlrev_b64 v[176:177], 13, v[136:137]
	s_add_u32 s12, s33, s12
	v_exp_f32_e32 v212, v141
	v_lshlrev_b64 v[138:139], 7, v[172:173]
	v_lshlrev_b64 v[140:141], 7, v[132:133]
	v_lshlrev_b64 v[142:143], 7, v[134:135]
	v_lshlrev_b64 v[178:179], 13, v[134:135]
	v_lshlrev_b64 v[144:145], 7, v[136:137]
	v_lshl_add_u64 v[128:129], s[2:3], 0, v[128:129]
	v_lshl_add_u64 v[130:131], v[174:175], 0, v[180:181]
	v_lshl_add_u64 v[136:137], v[174:175], 0, v[176:177]
	s_addc_u32 s13, s34, s13
	v_lshl_add_u64 v[146:147], v[174:175], 0, v[178:179]
	v_lshl_add_u64 v[190:191], v[128:129], 0, v[170:171]
	global_load_dwordx4 v[156:159], v[130:131], off
	global_load_dwordx4 v[152:155], v[130:131], off offset:256
	global_load_dwordx4 v[132:135], v[136:137], off
	s_nop 0
	global_load_dwordx4 v[128:131], v[136:137], off offset:256
	v_add_f32_e32 v148, 1.0, v148
	v_add_f32_e32 v149, 1.0, v149
	v_add_f32_e32 v150, 1.0, v150
	v_add_f32_e32 v151, 1.0, v151
	v_add_f32_e32 v173, 1.0, v204
	v_add_f32_e32 v204, 1.0, v205
	v_lshl_add_u64 v[136:137], s[12:13], 0, v[138:139]
	v_lshl_add_u64 v[138:139], s[12:13], 0, v[140:141]
	v_lshl_add_u64 v[140:141], s[12:13], 0, v[142:143]
	v_lshl_add_u64 v[144:145], s[12:13], 0, v[144:145]
	v_rcp_f32_e32 v214, v148
	v_rcp_f32_e32 v215, v149
	v_rcp_f32_e32 v216, v150
	v_rcp_f32_e32 v217, v151
	v_rcp_f32_e32 v218, v204
	global_load_dwordx4 v[204:207], v[136:137], off
	global_load_dwordx4 v[208:211], v[138:139], off
	s_nop 0
	global_load_dwordx4 v[136:139], v[140:141], off
	global_load_dwordx4 v[148:151], v[146:147], off
	s_nop 0
	global_load_dwordx4 v[140:143], v[146:147], off offset:256
	s_nop 0
	global_load_dwordx4 v[144:147], v[144:145], off
	v_rcp_f32_e32 v173, v173
	v_mul_f32_e32 v124, v124, v214
	v_mul_f32_e32 v125, v125, v215
	v_mul_f32_e32 v127, v127, v217
	v_mul_f32_e32 v120, v120, v173
	v_mul_f32_e32 v121, v121, v218
	s_mov_b32 s14, 0x358637bd
	s_mov_b32 s5, 0x800000
	v_mul_f32_e32 v126, v126, v216
	s_mov_b64 s[16:17], s[10:11]
	s_mov_b32 s11, 0xc000
	s_waitcnt vmcnt(0)
	v_lshlrev_b32_e32 v173, 16, v186
	v_and_b32_e32 v186, 0xffff0000, v186
	v_lshlrev_b32_e32 v214, 16, v187
	v_and_b32_e32 v187, 0xffff0000, v187
	v_mul_f32_e32 v125, v125, v186
	v_mul_f32_e32 v127, v127, v187
	v_add_f32_e32 v186, 1.0, v212
	v_mul_f32_e32 v187, 0xbfb8aa3b, v123
	v_rcp_f32_e32 v186, v186
	v_exp_f32_e32 v187, v187
	v_mul_f32_e32 v124, v124, v173
	v_and_b32_e32 v173, 0xffff0000, v188
	v_mul_f32_e32 v122, v122, v186
	v_add_f32_e32 v186, 1.0, v187
	v_mul_f32_e32 v187, 0xbfb8aa3b, v116
	v_rcp_f32_e32 v186, v186
	v_exp_f32_e32 v187, v187
	v_mul_f32_e32 v121, v121, v173
	v_lshlrev_b32_e32 v173, 16, v189
	v_mul_f32_e32 v123, v123, v186
	v_add_f32_e32 v186, 1.0, v187
	v_mul_f32_e32 v187, 0xbfb8aa3b, v117
	v_rcp_f32_e32 v186, v186
	v_exp_f32_e32 v187, v187
	v_mul_f32_e32 v122, v122, v173
	v_and_b32_e32 v173, 0xffff0000, v189
	v_mul_f32_e32 v116, v116, v186
	v_add_f32_e32 v186, 1.0, v187
	v_mul_f32_e32 v187, 0xbfb8aa3b, v118
	v_rcp_f32_e32 v186, v186
	v_exp_f32_e32 v187, v187
	v_mul_f32_e32 v123, v123, v173
	v_lshlrev_b32_e32 v173, 16, v196
	v_mul_f32_e32 v173, v116, v173
	v_mul_f32_e32 v116, v117, v186
	v_add_f32_e32 v186, 1.0, v187
	v_mul_f32_e32 v187, 0xbfb8aa3b, v119
	v_rcp_f32_e32 v186, v186
	v_exp_f32_e32 v187, v187
	v_and_b32_e32 v117, 0xffff0000, v196
	v_lshlrev_b32_e32 v215, 16, v188
	v_mul_f32_e32 v188, v116, v117
	v_mul_f32_e32 v116, v118, v186
	v_add_f32_e32 v118, 1.0, v187
	v_rcp_f32_e32 v118, v118
	v_mul_f32_e32 v186, 0xbfb8aa3b, v112
	v_exp_f32_e32 v186, v186
	v_lshlrev_b32_e32 v117, 16, v197
	v_mul_f32_e32 v187, v116, v117
	v_mul_f32_e32 v116, v119, v118
	v_mul_f32_e32 v119, 0xbfb8aa3b, v113
	v_add_f32_e32 v118, 1.0, v186
	v_exp_f32_e32 v119, v119
	v_rcp_f32_e32 v118, v118
	v_and_b32_e32 v117, 0xffff0000, v197
	v_mul_f32_e32 v186, v116, v117
	v_add_f32_e32 v117, 1.0, v119
	v_mul_f32_e32 v112, v112, v118
	v_rcp_f32_e32 v117, v117
	v_mul_f32_e32 v118, 0xbfb8aa3b, v114
	v_exp_f32_e32 v118, v118
	v_lshlrev_b32_e32 v116, 16, v198
	v_mul_f32_e32 v189, v112, v116
	v_mul_f32_e32 v112, v113, v117
	v_and_b32_e32 v113, 0xffff0000, v198
	v_add_f32_e32 v116, 1.0, v118
	v_mul_f32_e32 v196, v112, v113
	v_mul_f32_e32 v112, 0xbfb8aa3b, v115
	v_rcp_f32_e32 v116, v116
	v_exp_f32_e32 v112, v112
	v_mov_b32_e32 v117, v206
	v_mov_b32_e32 v206, v211
	v_mul_f32_e32 v113, v114, v116
	v_lshlrev_b32_e32 v114, 16, v199
	v_add_f32_e32 v112, 1.0, v112
	v_mul_f32_e32 v197, v113, v114
	v_rcp_f32_e32 v114, v112
	v_mov_b32_e32 v112, v208
	v_mov_b32_e32 v113, v204
	v_mov_b32_e32 v204, v209
	v_pk_add_f32 v[112:113], v[112:113], v[204:205]
	v_mov_b32_e32 v116, v210
	v_pk_add_f32 v[112:113], v[116:117], v[112:113]
	v_mul_f32_e32 v114, v115, v114
	v_pk_add_f32 v[116:117], v[206:207], v[112:113]
	v_mov_b64_e32 v[112:113], s[14:15]
	s_mov_b32 s14, 0x3b000000
	v_pk_fma_f32 v[118:119], v[116:117], s[14:15], v[112:113] op_sel_hi:[1,0,0]
	v_and_b32_e32 v115, 0xffff0000, v199
	v_mul_f32_e32 v116, 0x4b800000, v119
	v_cmp_gt_f32_e32 vcc, s5, v119
	v_mul_f32_e32 v126, v126, v214
	v_mul_f32_e32 v120, v120, v215
	v_cndmask_b32_e32 v116, v119, v116, vcc
	v_rsq_f32_e32 v116, v116
	v_mul_f32_e32 v119, v114, v115
	v_mul_f32_e32 v114, 0x45800000, v116
	v_cndmask_b32_e32 v198, v116, v114, vcc
	v_mul_f32_e32 v114, v124, v198
	v_mul_f32_e32 v115, v125, v198
	v_cvt_pk_bf16_f32 v114, v114, v115
	v_mul_f32_e32 v115, v126, v198
	v_mul_f32_e32 v116, v127, v198
	v_cvt_pk_bf16_f32 v115, v115, v116
	v_mul_f32_e32 v116, v120, v198
	v_mul_f32_e32 v117, v121, v198
	v_cvt_pk_bf16_f32 v116, v116, v117
	v_mul_f32_e32 v117, v122, v198
	v_mul_f32_e32 v120, v123, v198
	v_cvt_pk_bf16_f32 v117, v117, v120
	global_store_dwordx4 v[190:191], v[114:117], off
	v_mul_f32_e32 v119, v119, v198
	v_cmp_gt_f32_e32 vcc, s5, v118
	v_mul_f32_e32 v114, v173, v198
	v_mul_f32_e32 v115, v188, v198
	v_cvt_pk_bf16_f32 v114, v114, v115
	v_mul_f32_e32 v115, v187, v198
	v_mul_f32_e32 v116, v186, v198
	v_cvt_pk_bf16_f32 v115, v115, v116
	v_mul_f32_e32 v116, v189, v198
	v_mul_f32_e32 v117, v196, v198
	v_cvt_pk_bf16_f32 v116, v116, v117
	v_mul_f32_e32 v117, v197, v198
	v_cvt_pk_bf16_f32 v117, v117, v119
	v_mul_f32_e32 v119, 0x4b800000, v118
	v_cndmask_b32_e32 v118, v118, v119, vcc
	global_store_dwordx4 v[190:191], v[114:117], off offset:256
	v_rsq_f32_e32 v118, v118
	v_mul_f32_e32 v123, 0xbfb8aa3b, v61
	v_mul_f32_e32 v114, 0xbfb8aa3b, v108
	v_exp_f32_e32 v116, v114
	v_mul_f32_e32 v114, 0x45800000, v118
	v_cndmask_b32_e32 v117, v118, v114, vcc
	v_mul_f32_e32 v118, 0xbfb8aa3b, v109
	v_add_f32_e32 v116, 1.0, v116
	v_rcp_f32_e32 v116, v116
	v_exp_f32_e32 v118, v118
	v_lshl_add_u64 v[114:115], s[2:3], 0, v[180:181]
	v_lshl_add_u64 v[114:115], v[114:115], 0, v[170:171]
	v_mul_f32_e32 v108, v108, v116
	v_lshlrev_b32_e32 v116, 16, v156
	v_mul_f32_e32 v108, v108, v116
	v_add_f32_e32 v116, 1.0, v118
	v_rcp_f32_e32 v116, v116
	v_mul_f32_e32 v118, 0xbfb8aa3b, v110
	v_exp_f32_e32 v118, v118
	v_mul_f32_e32 v108, v108, v117
	v_mul_f32_e32 v109, v109, v116
	v_and_b32_e32 v116, 0xffff0000, v156
	v_mul_f32_e32 v109, v109, v116
	v_add_f32_e32 v116, 1.0, v118
	v_mul_f32_e32 v118, 0xbfb8aa3b, v111
	v_rcp_f32_e32 v116, v116
	v_exp_f32_e32 v118, v118
	v_mul_f32_e32 v109, v109, v117
	v_cvt_pk_bf16_f32 v108, v108, v109
	v_mul_f32_e32 v109, v110, v116
	v_add_f32_e32 v110, 1.0, v118
	v_rcp_f32_e32 v110, v110
	v_lshlrev_b32_e32 v116, 16, v157
	v_mul_f32_e32 v109, v109, v116
	v_and_b32_e32 v116, 0xffff0000, v157
	v_mul_f32_e32 v110, v111, v110
	v_mul_f32_e32 v111, 0xbfb8aa3b, v104
	v_exp_f32_e32 v111, v111
	v_mul_f32_e32 v110, v110, v116
	v_mul_f32_e32 v109, v109, v117
	v_mul_f32_e32 v110, v110, v117
	v_add_f32_e32 v111, 1.0, v111
	v_cvt_pk_bf16_f32 v109, v109, v110
	v_mul_f32_e32 v110, 0xbfb8aa3b, v105
	v_rcp_f32_e32 v111, v111
	v_exp_f32_e32 v110, v110
	v_exp_f32_e32 v123, v123
	v_mul_f32_e32 v124, 0xbfb8aa3b, v62
	v_mul_f32_e32 v104, v104, v111
	v_lshlrev_b32_e32 v111, 16, v158
	v_add_f32_e32 v110, 1.0, v110
	v_mul_f32_e32 v104, v104, v111
	v_rcp_f32_e32 v110, v110
	v_mul_f32_e32 v111, 0xbfb8aa3b, v106
	v_exp_f32_e32 v111, v111
	v_mul_f32_e32 v104, v104, v117
	v_mul_f32_e32 v105, v105, v110
	v_and_b32_e32 v110, 0xffff0000, v158
	v_mul_f32_e32 v105, v105, v110
	v_add_f32_e32 v110, 1.0, v111
	v_rcp_f32_e32 v111, v110
	v_mul_f32_e32 v110, 0xbfb8aa3b, v107
	v_exp_f32_e32 v116, v110
	v_mul_f32_e32 v105, v105, v117
	v_cvt_pk_bf16_f32 v110, v104, v105
	v_mul_f32_e32 v104, v106, v111
	v_add_f32_e32 v105, 1.0, v116
	v_rcp_f32_e32 v105, v105
	v_lshlrev_b32_e32 v106, 16, v159
	v_mul_f32_e32 v104, v104, v106
	v_and_b32_e32 v106, 0xffff0000, v159
	v_mul_f32_e32 v105, v107, v105
	v_mul_f32_e32 v107, 0xbfb8aa3b, v100
	v_exp_f32_e32 v107, v107
	v_mul_f32_e32 v104, v104, v117
	v_mul_f32_e32 v105, v105, v106
	v_mul_f32_e32 v105, v105, v117
	v_cvt_pk_bf16_f32 v111, v104, v105
	v_add_f32_e32 v104, 1.0, v107
	v_rcp_f32_e32 v104, v104
	v_mul_f32_e32 v105, 0xbfb8aa3b, v101
	v_exp_f32_e32 v105, v105
	global_store_dwordx4 v[114:115], v[108:111], off
	v_mul_f32_e32 v100, v100, v104
	v_lshlrev_b32_e32 v104, 16, v152
	v_mul_f32_e32 v100, v100, v104
	v_add_f32_e32 v104, 1.0, v105
	v_rcp_f32_e32 v104, v104
	v_mul_f32_e32 v105, 0xbfb8aa3b, v102
	v_exp_f32_e32 v105, v105
	v_mul_f32_e32 v100, v100, v117
	v_mul_f32_e32 v101, v101, v104
	v_and_b32_e32 v104, 0xffff0000, v152
	v_mul_f32_e32 v101, v101, v104
	v_add_f32_e32 v104, 1.0, v105
	v_mul_f32_e32 v105, 0xbfb8aa3b, v103
	v_rcp_f32_e32 v104, v104
	v_exp_f32_e32 v105, v105
	v_mul_f32_e32 v101, v101, v117
	v_cvt_pk_bf16_f32 v100, v100, v101
	v_mul_f32_e32 v101, v102, v104
	v_add_f32_e32 v102, 1.0, v105
	v_rcp_f32_e32 v102, v102
	v_lshlrev_b32_e32 v104, 16, v153
	v_mul_f32_e32 v101, v101, v104
	v_and_b32_e32 v104, 0xffff0000, v153
	v_mul_f32_e32 v102, v103, v102
	v_mul_f32_e32 v103, 0xbfb8aa3b, v96
	v_exp_f32_e32 v103, v103
	v_mul_f32_e32 v102, v102, v104
	v_mul_f32_e32 v101, v101, v117
	v_mul_f32_e32 v102, v102, v117
	v_add_f32_e32 v103, 1.0, v103
	v_cvt_pk_bf16_f32 v101, v101, v102
	v_mul_f32_e32 v102, 0xbfb8aa3b, v97
	v_rcp_f32_e32 v103, v103
	v_exp_f32_e32 v102, v102
	v_add_f32_e32 v123, 1.0, v123
	v_rcp_f32_e32 v123, v123
	v_mul_f32_e32 v96, v96, v103
	v_lshlrev_b32_e32 v103, 16, v154
	v_add_f32_e32 v102, 1.0, v102
	v_mul_f32_e32 v96, v96, v103
	v_rcp_f32_e32 v102, v102
	v_mul_f32_e32 v103, 0xbfb8aa3b, v98
	v_exp_f32_e32 v103, v103
	v_mul_f32_e32 v96, v96, v117
	v_mul_f32_e32 v97, v97, v102
	v_and_b32_e32 v102, 0xffff0000, v154
	v_mul_f32_e32 v97, v97, v102
	v_add_f32_e32 v102, 1.0, v103
	v_rcp_f32_e32 v103, v102
	v_mul_f32_e32 v102, 0xbfb8aa3b, v99
	v_exp_f32_e32 v104, v102
	v_mul_f32_e32 v97, v97, v117
	v_cvt_pk_bf16_f32 v102, v96, v97
	v_mul_f32_e32 v96, v98, v103
	v_add_f32_e32 v97, 1.0, v104
	v_rcp_f32_e32 v97, v97
	v_lshlrev_b32_e32 v98, 16, v155
	v_mul_f32_e32 v96, v96, v98
	v_and_b32_e32 v98, 0xffff0000, v155
	v_mul_f32_e32 v97, v99, v97
	v_mul_f32_e32 v99, 0xbfb8aa3b, v93
	v_exp_f32_e32 v99, v99
	v_mul_f32_e32 v97, v97, v98
	v_mul_f32_e32 v96, v96, v117
	v_mul_f32_e32 v97, v97, v117
	v_cvt_pk_bf16_f32 v103, v96, v97
	global_store_dwordx4 v[114:115], v[100:103], off offset:256
	v_add_f32_e32 v99, 1.0, v99
	v_rcp_f32_e32 v99, v99
	v_mul_f32_e32 v100, 0xbfb8aa3b, v94
	v_exp_f32_e32 v100, v100
	v_mul_f32_e32 v98, 0xbfb8aa3b, v92
	v_mul_f32_e32 v93, v93, v99
	v_exp_f32_e32 v98, v98
	v_add_f32_e32 v99, 1.0, v100
	v_mul_f32_e32 v100, 0xbfb8aa3b, v95
	v_rcp_f32_e32 v99, v99
	v_exp_f32_e32 v100, v100
	v_add_f32_e32 v98, 1.0, v98
	v_rcp_f32_e32 v98, v98
	v_mul_f32_e32 v94, v94, v99
	v_add_f32_e32 v99, 1.0, v100
	v_mul_f32_e32 v100, 0xbfb8aa3b, v88
	v_rcp_f32_e32 v99, v99
	v_exp_f32_e32 v100, v100
	v_mul_f32_e32 v92, v92, v98
	v_lshlrev_b32_e32 v98, 16, v148
	v_mul_f32_e32 v95, v95, v99
	v_add_f32_e32 v99, 1.0, v100
	v_mul_f32_e32 v100, 0xbfb8aa3b, v89
	v_rcp_f32_e32 v99, v99
	v_exp_f32_e32 v100, v100
	v_mul_f32_e32 v92, v92, v98
	v_and_b32_e32 v98, 0xffff0000, v148
	v_mul_f32_e32 v88, v88, v99
	v_add_f32_e32 v99, 1.0, v100
	v_mul_f32_e32 v100, 0xbfb8aa3b, v90
	v_rcp_f32_e32 v99, v99
	v_exp_f32_e32 v100, v100
	v_mul_f32_e32 v93, v93, v98
	v_lshlrev_b32_e32 v98, 16, v149
	v_mul_f32_e32 v89, v89, v99
	v_add_f32_e32 v99, 1.0, v100
	v_mul_f32_e32 v100, 0xbfb8aa3b, v91
	v_rcp_f32_e32 v99, v99
	v_exp_f32_e32 v100, v100
	v_mul_f32_e32 v94, v94, v98
	v_and_b32_e32 v98, 0xffff0000, v149
	v_mul_f32_e32 v90, v90, v99
	v_add_f32_e32 v99, 1.0, v100
	v_mul_f32_e32 v100, 0xbfb8aa3b, v84
	v_rcp_f32_e32 v99, v99
	v_exp_f32_e32 v100, v100
	v_mul_f32_e32 v95, v95, v98
	v_lshlrev_b32_e32 v98, 16, v150
	v_mul_f32_e32 v91, v91, v99
	v_add_f32_e32 v99, 1.0, v100
	v_mul_f32_e32 v100, 0xbfb8aa3b, v85
	v_rcp_f32_e32 v99, v99
	v_exp_f32_e32 v100, v100
	v_mul_f32_e32 v88, v88, v98
	v_and_b32_e32 v98, 0xffff0000, v150
	v_mul_f32_e32 v84, v84, v99
	v_add_f32_e32 v99, 1.0, v100
	v_mul_f32_e32 v100, 0xbfb8aa3b, v86
	v_rcp_f32_e32 v99, v99
	v_exp_f32_e32 v100, v100
	v_mul_f32_e32 v89, v89, v98
	v_lshlrev_b32_e32 v98, 16, v151
	v_mul_f32_e32 v90, v90, v98
	v_and_b32_e32 v98, 0xffff0000, v151
	v_mul_f32_e32 v91, v91, v98
	v_lshlrev_b32_e32 v98, 16, v140
	v_mul_f32_e32 v98, v84, v98
	v_mul_f32_e32 v84, v85, v99
	v_add_f32_e32 v99, 1.0, v100
	v_mul_f32_e32 v100, 0xbfb8aa3b, v87
	v_rcp_f32_e32 v99, v99
	v_exp_f32_e32 v100, v100
	v_and_b32_e32 v85, 0xffff0000, v140
	v_mul_f32_e32 v101, v84, v85
	v_mul_f32_e32 v84, v86, v99
	v_add_f32_e32 v86, 1.0, v100
	v_rcp_f32_e32 v86, v86
	v_mul_f32_e32 v99, 0xbfb8aa3b, v80
	v_exp_f32_e32 v99, v99
	v_lshlrev_b32_e32 v85, 16, v141
	v_mul_f32_e32 v100, v84, v85
	v_mul_f32_e32 v84, v87, v86
	v_mul_f32_e32 v87, 0xbfb8aa3b, v81
	v_add_f32_e32 v86, 1.0, v99
	v_exp_f32_e32 v87, v87
	v_rcp_f32_e32 v86, v86
	v_and_b32_e32 v85, 0xffff0000, v141
	v_mul_f32_e32 v99, v84, v85
	v_add_f32_e32 v85, 1.0, v87
	v_mul_f32_e32 v80, v80, v86
	v_rcp_f32_e32 v85, v85
	v_mul_f32_e32 v86, 0xbfb8aa3b, v82
	v_exp_f32_e32 v86, v86
	v_lshlrev_b32_e32 v84, 16, v142
	v_mul_f32_e32 v87, v80, v84
	v_mul_f32_e32 v80, v81, v85
	v_and_b32_e32 v81, 0xffff0000, v142
	v_add_f32_e32 v84, 1.0, v86
	v_mul_f32_e32 v86, v80, v81
	v_mul_f32_e32 v80, 0xbfb8aa3b, v83
	v_rcp_f32_e32 v84, v84
	v_exp_f32_e32 v80, v80
	v_mov_b32_e32 v85, v138
	v_mov_b32_e32 v138, v147
	v_mul_f32_e32 v81, v82, v84
	v_lshlrev_b32_e32 v82, 16, v143
	v_add_f32_e32 v80, 1.0, v80
	v_mul_f32_e32 v102, v81, v82
	v_rcp_f32_e32 v82, v80
	v_mov_b32_e32 v80, v144
	v_mov_b32_e32 v81, v136
	v_mov_b32_e32 v136, v145
	v_pk_add_f32 v[80:81], v[80:81], v[136:137]
	v_mov_b32_e32 v84, v146
	v_pk_add_f32 v[80:81], v[84:85], v[80:81]
	v_lshl_add_u64 v[96:97], s[2:3], 0, v[178:179]
	v_pk_add_f32 v[80:81], v[138:139], v[80:81]
	v_lshl_add_u64 v[96:97], v[96:97], 0, v[170:171]
	v_pk_fma_f32 v[84:85], v[80:81], s[14:15], v[112:113] op_sel_hi:[1,0,0]
	v_mul_f32_e32 v81, v83, v82
	v_mul_f32_e32 v80, 0x4b800000, v85
	v_cmp_gt_f32_e32 vcc, s5, v85
	v_and_b32_e32 v82, 0xffff0000, v143
	v_exp_f32_e32 v124, v124
	v_cndmask_b32_e32 v80, v85, v80, vcc
	v_rsq_f32_e32 v80, v80
	v_mul_f32_e32 v85, v81, v82
	v_mul_f32_e32 v61, v61, v123
	v_mul_f32_e32 v123, 0xbfb8aa3b, v63
	v_mul_f32_e32 v81, 0x45800000, v80
	v_cndmask_b32_e32 v103, v80, v81, vcc
	v_mul_f32_e32 v80, v92, v103
	v_mul_f32_e32 v81, v93, v103
	v_cvt_pk_bf16_f32 v80, v80, v81
	v_mul_f32_e32 v81, v94, v103
	v_mul_f32_e32 v82, v95, v103
	v_cvt_pk_bf16_f32 v81, v81, v82
	v_mul_f32_e32 v82, v88, v103
	v_mul_f32_e32 v83, v89, v103
	v_cvt_pk_bf16_f32 v82, v82, v83
	v_mul_f32_e32 v83, v90, v103
	v_mul_f32_e32 v88, v91, v103
	v_cvt_pk_bf16_f32 v83, v83, v88
	global_store_dwordx4 v[96:97], v[80:83], off
	v_mul_f32_e32 v85, v85, v103
	v_cmp_gt_f32_e32 vcc, s5, v84
	v_mul_f32_e32 v80, v98, v103
	v_mul_f32_e32 v81, v101, v103
	v_cvt_pk_bf16_f32 v80, v80, v81
	v_mul_f32_e32 v81, v100, v103
	v_mul_f32_e32 v82, v99, v103
	v_cvt_pk_bf16_f32 v81, v81, v82
	v_mul_f32_e32 v82, v87, v103
	v_mul_f32_e32 v83, v86, v103
	v_cvt_pk_bf16_f32 v82, v82, v83
	v_mul_f32_e32 v83, v102, v103
	v_cvt_pk_bf16_f32 v83, v83, v85
	v_mul_f32_e32 v85, 0x4b800000, v84
	v_cndmask_b32_e32 v84, v84, v85, vcc
	global_store_dwordx4 v[96:97], v[80:83], off offset:256
	v_rsq_f32_e32 v84, v84
	v_exp_f32_e32 v123, v123
	v_mul_f32_e32 v80, 0xbfb8aa3b, v76
	v_exp_f32_e32 v82, v80
	v_mul_f32_e32 v80, 0x45800000, v84
	v_cndmask_b32_e32 v83, v84, v80, vcc
	v_mul_f32_e32 v84, 0xbfb8aa3b, v77
	v_add_f32_e32 v82, 1.0, v82
	v_rcp_f32_e32 v82, v82
	v_exp_f32_e32 v84, v84
	v_lshl_add_u64 v[80:81], s[2:3], 0, v[176:177]
	v_lshl_add_u64 v[80:81], v[80:81], 0, v[170:171]
	v_mul_f32_e32 v76, v76, v82
	v_lshlrev_b32_e32 v82, 16, v132
	v_mul_f32_e32 v76, v76, v82
	v_add_f32_e32 v82, 1.0, v84
	v_rcp_f32_e32 v82, v82
	v_mul_f32_e32 v84, 0xbfb8aa3b, v78
	v_exp_f32_e32 v84, v84
	v_mul_f32_e32 v76, v76, v83
	v_mul_f32_e32 v77, v77, v82
	v_and_b32_e32 v82, 0xffff0000, v132
	v_mul_f32_e32 v77, v77, v82
	v_add_f32_e32 v82, 1.0, v84
	v_mul_f32_e32 v84, 0xbfb8aa3b, v79
	v_rcp_f32_e32 v82, v82
	v_exp_f32_e32 v84, v84
	v_mul_f32_e32 v77, v77, v83
	v_cvt_pk_bf16_f32 v76, v76, v77
	v_mul_f32_e32 v77, v78, v82
	v_add_f32_e32 v78, 1.0, v84
	v_rcp_f32_e32 v78, v78
	v_lshlrev_b32_e32 v82, 16, v133
	v_mul_f32_e32 v77, v77, v82
	v_and_b32_e32 v82, 0xffff0000, v133
	v_mul_f32_e32 v78, v79, v78
	v_mul_f32_e32 v79, 0xbfb8aa3b, v72
	v_exp_f32_e32 v79, v79
	v_mul_f32_e32 v78, v78, v82
	v_mul_f32_e32 v77, v77, v83
	v_mul_f32_e32 v78, v78, v83
	v_add_f32_e32 v79, 1.0, v79
	v_cvt_pk_bf16_f32 v77, v77, v78
	v_mul_f32_e32 v78, 0xbfb8aa3b, v73
	v_rcp_f32_e32 v79, v79
	v_exp_f32_e32 v78, v78
	v_mul_f32_e32 v72, v72, v79
	v_lshlrev_b32_e32 v79, 16, v134
	v_add_f32_e32 v78, 1.0, v78
	v_mul_f32_e32 v72, v72, v79
	v_rcp_f32_e32 v78, v78
	v_mul_f32_e32 v79, 0xbfb8aa3b, v74
	v_exp_f32_e32 v79, v79
	v_mul_f32_e32 v72, v72, v83
	v_mul_f32_e32 v73, v73, v78
	v_and_b32_e32 v78, 0xffff0000, v134
	v_mul_f32_e32 v73, v73, v78
	v_add_f32_e32 v78, 1.0, v79
	v_rcp_f32_e32 v79, v78
	v_mul_f32_e32 v78, 0xbfb8aa3b, v75
	v_exp_f32_e32 v82, v78
	v_mul_f32_e32 v73, v73, v83
	v_cvt_pk_bf16_f32 v78, v72, v73
	v_mul_f32_e32 v72, v74, v79
	v_add_f32_e32 v73, 1.0, v82
	v_rcp_f32_e32 v73, v73
	v_lshlrev_b32_e32 v74, 16, v135
	v_mul_f32_e32 v72, v72, v74
	v_and_b32_e32 v74, 0xffff0000, v135
	v_mul_f32_e32 v73, v75, v73
	v_mul_f32_e32 v75, 0xbfb8aa3b, v68
	v_exp_f32_e32 v75, v75
	v_mul_f32_e32 v72, v72, v83
	v_mul_f32_e32 v73, v73, v74
	v_mul_f32_e32 v73, v73, v83
	v_cvt_pk_bf16_f32 v79, v72, v73
	v_add_f32_e32 v72, 1.0, v75
	v_rcp_f32_e32 v72, v72
	v_mul_f32_e32 v73, 0xbfb8aa3b, v69
	v_exp_f32_e32 v73, v73
	global_store_dwordx4 v[80:81], v[76:79], off
	v_mul_f32_e32 v68, v68, v72
	v_lshlrev_b32_e32 v72, 16, v128
	v_mul_f32_e32 v68, v68, v72
	v_add_f32_e32 v72, 1.0, v73
	v_rcp_f32_e32 v72, v72
	v_mul_f32_e32 v73, 0xbfb8aa3b, v70
	v_exp_f32_e32 v73, v73
	v_mul_f32_e32 v68, v68, v83
	v_mul_f32_e32 v69, v69, v72
	v_and_b32_e32 v72, 0xffff0000, v128
	v_mul_f32_e32 v69, v69, v72
	v_add_f32_e32 v72, 1.0, v73
	v_mul_f32_e32 v73, 0xbfb8aa3b, v71
	v_rcp_f32_e32 v72, v72
	v_exp_f32_e32 v73, v73
	v_mul_f32_e32 v69, v69, v83
	v_cvt_pk_bf16_f32 v68, v68, v69
	v_mul_f32_e32 v69, v70, v72
	v_add_f32_e32 v70, 1.0, v73
	v_rcp_f32_e32 v70, v70
	v_lshlrev_b32_e32 v72, 16, v129
	v_mul_f32_e32 v69, v69, v72
	v_and_b32_e32 v72, 0xffff0000, v129
	v_mul_f32_e32 v70, v71, v70
	v_mul_f32_e32 v71, 0xbfb8aa3b, v64
	v_exp_f32_e32 v71, v71
	v_mul_f32_e32 v70, v70, v72
	v_mul_f32_e32 v69, v69, v83
	v_mul_f32_e32 v70, v70, v83
	v_add_f32_e32 v71, 1.0, v71
	v_cvt_pk_bf16_f32 v69, v69, v70
	v_mul_f32_e32 v70, 0xbfb8aa3b, v65
	v_rcp_f32_e32 v71, v71
	v_exp_f32_e32 v70, v70
	v_mul_f32_e32 v64, v64, v71
	v_lshlrev_b32_e32 v71, 16, v130
	v_add_f32_e32 v70, 1.0, v70
	v_mul_f32_e32 v64, v64, v71
	v_rcp_f32_e32 v70, v70
	v_mul_f32_e32 v71, 0xbfb8aa3b, v66
	v_exp_f32_e32 v71, v71
	v_mul_f32_e32 v64, v64, v83
	v_mul_f32_e32 v65, v65, v70
	v_and_b32_e32 v70, 0xffff0000, v130
	v_mul_f32_e32 v65, v65, v70
	v_add_f32_e32 v70, 1.0, v71
	v_rcp_f32_e32 v71, v70
	v_mul_f32_e32 v70, 0xbfb8aa3b, v67
	v_exp_f32_e32 v72, v70
	v_mul_f32_e32 v65, v65, v83
	v_cvt_pk_bf16_f32 v70, v64, v65
	v_mul_f32_e32 v64, v66, v71
	v_add_f32_e32 v65, 1.0, v72
	v_rcp_f32_e32 v65, v65
	v_lshlrev_b32_e32 v66, 16, v131
	v_mul_f32_e32 v64, v64, v66
	v_and_b32_e32 v66, 0xffff0000, v131
	v_mul_f32_e32 v65, v67, v65
	v_mul_f32_e32 v64, v64, v83
	v_mul_f32_e32 v65, v65, v66
	v_mul_f32_e32 v65, v65, v83
	v_cvt_pk_bf16_f32 v71, v64, v65
	v_add_u32_e32 v64, 0x80, v172
	v_ashrrev_i32_e32 v65, 31, v64
	v_lshlrev_b64 v[110:111], 13, v[64:65]
	v_lshl_add_u64 v[66:67], v[174:175], 0, v[110:111]
	global_load_dwordx4 v[102:105], v[66:67], off
	v_lshlrev_b64 v[64:65], 7, v[64:65]
	global_store_dwordx4 v[80:81], v[68:71], off offset:256
	v_lshl_add_u64 v[64:65], s[12:13], 0, v[64:65]
	global_load_dwordx4 v[106:109], v[64:65], off
	v_add_u32_e32 v64, 0x90, v172
	v_ashrrev_i32_e32 v65, 31, v64
	v_lshlrev_b64 v[68:69], 7, v[64:65]
	v_lshl_add_u64 v[68:69], s[12:13], 0, v[68:69]
	global_load_dwordx4 v[114:117], v[66:67], off offset:256
	global_load_dwordx4 v[118:121], v[68:69], off
	v_lshlrev_b64 v[100:101], 13, v[64:65]
	v_lshl_add_u64 v[64:65], v[174:175], 0, v[100:101]
	global_load_dwordx4 v[92:95], v[64:65], off
	global_load_dwordx4 v[88:91], v[64:65], off offset:256
	v_add_u32_e32 v64, 0xa0, v172
	v_ashrrev_i32_e32 v65, 31, v64
	v_lshlrev_b64 v[66:67], 7, v[64:65]
	v_lshl_add_u64 v[66:67], s[12:13], 0, v[66:67]
	v_lshlrev_b64 v[98:99], 13, v[64:65]
	v_lshl_add_u64 v[64:65], v[174:175], 0, v[98:99]
	global_load_dwordx4 v[72:75], v[66:67], off
	global_load_dwordx4 v[84:87], v[64:65], off
	v_add_u32_e32 v66, 0xb0, v172
	v_ashrrev_i32_e32 v67, 31, v66
	v_lshlrev_b64 v[68:69], 7, v[66:67]
	v_lshlrev_b64 v[96:97], 13, v[66:67]
	v_mul_f32_e32 v66, 0xbfb8aa3b, v60
	v_exp_f32_e32 v122, v66
	v_lshl_add_u64 v[68:69], s[12:13], 0, v[68:69]
	global_load_dwordx4 v[76:79], v[64:65], off offset:256
	global_load_dwordx4 v[80:83], v[68:69], off
	v_lshl_add_u64 v[64:65], v[174:175], 0, v[96:97]
	v_add_f32_e32 v122, 1.0, v122
	v_rcp_f32_e32 v122, v122
	global_load_dwordx4 v[68:71], v[64:65], off
	s_nop 0
	global_load_dwordx4 v[64:67], v[64:65], off offset:256
	v_lshl_add_u64 v[110:111], s[2:3], 0, v[110:111]
	v_lshl_add_u64 v[110:111], v[110:111], 0, v[170:171]
	v_mul_f32_e32 v60, v60, v122
	s_mov_b32 s13, s4
	s_mov_b32 s12, s6
	s_waitcnt vmcnt(0)
	v_lshlrev_b32_e32 v122, 16, v102
	v_mul_f32_e32 v60, v60, v122
	v_add_f32_e32 v122, 1.0, v124
	v_rcp_f32_e32 v122, v122
	v_and_b32_e32 v102, 0xffff0000, v102
	v_mul_f32_e32 v61, v61, v102
	v_lshlrev_b32_e32 v102, 16, v103
	v_mul_f32_e32 v62, v62, v122
	v_add_f32_e32 v122, 1.0, v123
	v_mul_f32_e32 v123, 0xbfb8aa3b, v56
	v_rcp_f32_e32 v122, v122
	v_exp_f32_e32 v123, v123
	v_mul_f32_e32 v62, v62, v102
	v_and_b32_e32 v102, 0xffff0000, v103
	v_mul_f32_e32 v63, v63, v122
	v_add_f32_e32 v103, 1.0, v123
	v_mul_f32_e32 v122, 0xbfb8aa3b, v57
	v_rcp_f32_e32 v103, v103
	v_exp_f32_e32 v122, v122
	v_mul_f32_e32 v63, v63, v102
	v_lshlrev_b32_e32 v102, 16, v104
	v_mul_f32_e32 v56, v56, v103
	v_add_f32_e32 v103, 1.0, v122
	v_mul_f32_e32 v122, 0xbfb8aa3b, v58
	v_rcp_f32_e32 v103, v103
	v_exp_f32_e32 v122, v122
	v_mul_f32_e32 v56, v56, v102
	v_and_b32_e32 v102, 0xffff0000, v104
	v_mul_f32_e32 v57, v57, v103
	v_add_f32_e32 v103, 1.0, v122
	v_mul_f32_e32 v104, 0xbfb8aa3b, v59
	v_rcp_f32_e32 v103, v103
	v_exp_f32_e32 v104, v104
	v_mul_f32_e32 v57, v57, v102
	v_lshlrev_b32_e32 v102, 16, v105
	v_mul_f32_e32 v58, v58, v103
	v_add_f32_e32 v103, 1.0, v104
	v_mul_f32_e32 v104, 0xbfb8aa3b, v52
	v_rcp_f32_e32 v103, v103
	v_exp_f32_e32 v104, v104
	v_mul_f32_e32 v58, v58, v102
	v_and_b32_e32 v102, 0xffff0000, v105
	v_mul_f32_e32 v59, v59, v103
	v_add_f32_e32 v103, 1.0, v104
	v_mul_f32_e32 v104, 0xbfb8aa3b, v53
	v_rcp_f32_e32 v103, v103
	v_exp_f32_e32 v104, v104
	v_mul_f32_e32 v59, v59, v102
	v_lshlrev_b32_e32 v102, 16, v114
	v_mul_f32_e32 v52, v52, v103
	v_add_f32_e32 v103, 1.0, v104
	v_mul_f32_e32 v104, 0xbfb8aa3b, v54
	v_rcp_f32_e32 v103, v103
	v_exp_f32_e32 v104, v104
	v_mul_f32_e32 v102, v52, v102
	v_mul_f32_e32 v52, v53, v103
	v_add_f32_e32 v103, 1.0, v104
	v_mul_f32_e32 v104, 0xbfb8aa3b, v55
	v_rcp_f32_e32 v103, v103
	v_exp_f32_e32 v104, v104
	v_and_b32_e32 v53, 0xffff0000, v114
	v_mul_f32_e32 v105, v52, v53
	v_mul_f32_e32 v52, v54, v103
	v_add_f32_e32 v54, 1.0, v104
	v_rcp_f32_e32 v54, v54
	v_mul_f32_e32 v103, 0xbfb8aa3b, v48
	v_exp_f32_e32 v103, v103
	v_lshlrev_b32_e32 v53, 16, v115
	v_mul_f32_e32 v104, v52, v53
	v_mul_f32_e32 v52, v55, v54
	v_mul_f32_e32 v55, 0xbfb8aa3b, v49
	v_add_f32_e32 v54, 1.0, v103
	v_exp_f32_e32 v55, v55
	v_rcp_f32_e32 v54, v54
	v_and_b32_e32 v53, 0xffff0000, v115
	v_mul_f32_e32 v103, v52, v53
	v_add_f32_e32 v53, 1.0, v55
	v_mul_f32_e32 v48, v48, v54
	v_rcp_f32_e32 v53, v53
	v_mul_f32_e32 v54, 0xbfb8aa3b, v50
	v_exp_f32_e32 v54, v54
	v_lshlrev_b32_e32 v52, 16, v116
	v_mul_f32_e32 v55, v48, v52
	v_mul_f32_e32 v48, v49, v53
	v_and_b32_e32 v49, 0xffff0000, v116
	v_add_f32_e32 v52, 1.0, v54
	v_mul_f32_e32 v54, v48, v49
	v_mul_f32_e32 v48, 0xbfb8aa3b, v51
	v_rcp_f32_e32 v52, v52
	v_exp_f32_e32 v48, v48
	v_mov_b32_e32 v53, v108
	v_mov_b32_e32 v108, v121
	v_mul_f32_e32 v49, v50, v52
	v_lshlrev_b32_e32 v50, 16, v117
	v_add_f32_e32 v48, 1.0, v48
	v_mul_f32_e32 v114, v49, v50
	v_rcp_f32_e32 v50, v48
	v_mov_b32_e32 v48, v118
	v_mov_b32_e32 v49, v106
	v_mov_b32_e32 v106, v119
	v_pk_add_f32 v[48:49], v[48:49], v[106:107]
	v_mov_b32_e32 v52, v120
	v_pk_add_f32 v[48:49], v[52:53], v[48:49]
	s_nop 0
	v_pk_add_f32 v[48:49], v[108:109], v[48:49]
	s_nop 0
	v_pk_fma_f32 v[52:53], v[48:49], s[14:15], v[112:113] op_sel_hi:[1,0,0]
	v_mul_f32_e32 v49, v51, v50
	v_mul_f32_e32 v48, 0x4b800000, v53
	v_cmp_gt_f32_e32 vcc, s5, v53
	v_and_b32_e32 v50, 0xffff0000, v117
	s_nop 0
	v_cndmask_b32_e32 v48, v53, v48, vcc
	v_rsq_f32_e32 v48, v48
	v_mul_f32_e32 v53, v49, v50
	v_mul_f32_e32 v49, 0x45800000, v48
	v_cndmask_b32_e32 v106, v48, v49, vcc
	v_mul_f32_e32 v48, v60, v106
	v_mul_f32_e32 v49, v61, v106
	v_cvt_pk_bf16_f32 v48, v48, v49
	v_mul_f32_e32 v49, v62, v106
	v_mul_f32_e32 v50, v63, v106
	v_cvt_pk_bf16_f32 v49, v49, v50
	v_mul_f32_e32 v50, v56, v106
	v_mul_f32_e32 v51, v57, v106
	v_cvt_pk_bf16_f32 v50, v50, v51
	v_mul_f32_e32 v51, v58, v106
	v_mul_f32_e32 v56, v59, v106
	v_cvt_pk_bf16_f32 v51, v51, v56
	global_store_dwordx4 v[110:111], v[48:51], off
	v_mul_f32_e32 v53, v53, v106
	v_cmp_gt_f32_e32 vcc, s5, v52
	v_mul_f32_e32 v48, v102, v106
	v_mul_f32_e32 v49, v105, v106
	v_cvt_pk_bf16_f32 v48, v48, v49
	v_mul_f32_e32 v49, v104, v106
	v_mul_f32_e32 v50, v103, v106
	v_cvt_pk_bf16_f32 v49, v49, v50
	v_mul_f32_e32 v50, v55, v106
	v_mul_f32_e32 v51, v54, v106
	v_cvt_pk_bf16_f32 v50, v50, v51
	v_mul_f32_e32 v51, v114, v106
	v_cvt_pk_bf16_f32 v51, v51, v53
	v_mul_f32_e32 v53, 0x4b800000, v52
	v_cndmask_b32_e32 v52, v52, v53, vcc
	global_store_dwordx4 v[110:111], v[48:51], off offset:256
	v_rsq_f32_e32 v52, v52
	s_nop 0
	v_mul_f32_e32 v48, 0xbfb8aa3b, v44
	v_exp_f32_e32 v50, v48
	v_mul_f32_e32 v48, 0x45800000, v52
	v_cndmask_b32_e32 v51, v52, v48, vcc
	v_mul_f32_e32 v52, 0xbfb8aa3b, v45
	v_add_f32_e32 v50, 1.0, v50
	v_rcp_f32_e32 v50, v50
	v_exp_f32_e32 v52, v52
	v_lshl_add_u64 v[48:49], s[2:3], 0, v[100:101]
	v_lshl_add_u64 v[48:49], v[48:49], 0, v[170:171]
	v_mul_f32_e32 v44, v44, v50
	v_lshlrev_b32_e32 v50, 16, v92
	v_mul_f32_e32 v44, v44, v50
	v_add_f32_e32 v50, 1.0, v52
	v_rcp_f32_e32 v50, v50
	v_mul_f32_e32 v52, 0xbfb8aa3b, v46
	v_exp_f32_e32 v52, v52
	v_mul_f32_e32 v44, v44, v51
	v_mul_f32_e32 v45, v45, v50
	v_and_b32_e32 v50, 0xffff0000, v92
	v_mul_f32_e32 v45, v45, v50
	v_add_f32_e32 v50, 1.0, v52
	v_mul_f32_e32 v52, 0xbfb8aa3b, v47
	v_rcp_f32_e32 v50, v50
	v_exp_f32_e32 v52, v52
	v_mul_f32_e32 v45, v45, v51
	v_cvt_pk_bf16_f32 v44, v44, v45
	v_mul_f32_e32 v45, v46, v50
	v_add_f32_e32 v46, 1.0, v52
	v_rcp_f32_e32 v46, v46
	v_lshlrev_b32_e32 v50, 16, v93
	v_mul_f32_e32 v45, v45, v50
	v_and_b32_e32 v50, 0xffff0000, v93
	v_mul_f32_e32 v46, v47, v46
	v_mul_f32_e32 v47, 0xbfb8aa3b, v40
	v_exp_f32_e32 v47, v47
	v_mul_f32_e32 v46, v46, v50
	v_mul_f32_e32 v45, v45, v51
	v_mul_f32_e32 v46, v46, v51
	v_add_f32_e32 v47, 1.0, v47
	v_cvt_pk_bf16_f32 v45, v45, v46
	v_mul_f32_e32 v46, 0xbfb8aa3b, v41
	v_rcp_f32_e32 v47, v47
	v_exp_f32_e32 v46, v46
	v_mul_f32_e32 v40, v40, v47
	v_lshlrev_b32_e32 v47, 16, v94
	v_add_f32_e32 v46, 1.0, v46
	v_mul_f32_e32 v40, v40, v47
	v_rcp_f32_e32 v46, v46
	v_mul_f32_e32 v47, 0xbfb8aa3b, v42
	v_exp_f32_e32 v47, v47
	v_mul_f32_e32 v40, v40, v51
	v_mul_f32_e32 v41, v41, v46
	v_and_b32_e32 v46, 0xffff0000, v94
	v_mul_f32_e32 v41, v41, v46
	v_add_f32_e32 v46, 1.0, v47
	v_rcp_f32_e32 v47, v46
	v_mul_f32_e32 v46, 0xbfb8aa3b, v43
	v_exp_f32_e32 v50, v46
	v_mul_f32_e32 v41, v41, v51
	v_cvt_pk_bf16_f32 v46, v40, v41
	v_mul_f32_e32 v40, v42, v47
	v_add_f32_e32 v41, 1.0, v50
	v_rcp_f32_e32 v41, v41
	v_lshlrev_b32_e32 v42, 16, v95
	v_mul_f32_e32 v40, v40, v42
	v_and_b32_e32 v42, 0xffff0000, v95
	v_mul_f32_e32 v41, v43, v41
	v_mul_f32_e32 v43, 0xbfb8aa3b, v36
	v_exp_f32_e32 v43, v43
	v_mul_f32_e32 v40, v40, v51
	v_mul_f32_e32 v41, v41, v42
	v_mul_f32_e32 v41, v41, v51
	v_cvt_pk_bf16_f32 v47, v40, v41
	v_add_f32_e32 v40, 1.0, v43
	v_rcp_f32_e32 v40, v40
	v_mul_f32_e32 v41, 0xbfb8aa3b, v37
	v_exp_f32_e32 v41, v41
	global_store_dwordx4 v[48:49], v[44:47], off
	v_mul_f32_e32 v36, v36, v40
	v_lshlrev_b32_e32 v40, 16, v88
	v_mul_f32_e32 v36, v36, v40
	v_add_f32_e32 v40, 1.0, v41
	v_rcp_f32_e32 v40, v40
	v_mul_f32_e32 v41, 0xbfb8aa3b, v38
	v_exp_f32_e32 v41, v41
	v_mul_f32_e32 v36, v36, v51
	v_mul_f32_e32 v37, v37, v40
	v_and_b32_e32 v40, 0xffff0000, v88
	v_mul_f32_e32 v37, v37, v40
	v_add_f32_e32 v40, 1.0, v41
	v_mul_f32_e32 v41, 0xbfb8aa3b, v39
	v_rcp_f32_e32 v40, v40
	v_exp_f32_e32 v41, v41
	v_mul_f32_e32 v37, v37, v51
	v_cvt_pk_bf16_f32 v36, v36, v37
	v_mul_f32_e32 v37, v38, v40
	v_add_f32_e32 v38, 1.0, v41
	v_rcp_f32_e32 v38, v38
	v_lshlrev_b32_e32 v40, 16, v89
	v_mul_f32_e32 v37, v37, v40
	v_and_b32_e32 v40, 0xffff0000, v89
	v_mul_f32_e32 v38, v39, v38
	v_mul_f32_e32 v39, 0xbfb8aa3b, v32
	v_exp_f32_e32 v39, v39
	v_mul_f32_e32 v38, v38, v40
	v_mul_f32_e32 v37, v37, v51
	v_mul_f32_e32 v38, v38, v51
	v_add_f32_e32 v39, 1.0, v39
	v_cvt_pk_bf16_f32 v37, v37, v38
	v_mul_f32_e32 v38, 0xbfb8aa3b, v33
	v_rcp_f32_e32 v39, v39
	v_exp_f32_e32 v38, v38
	v_mul_f32_e32 v32, v32, v39
	v_lshlrev_b32_e32 v39, 16, v90
	v_add_f32_e32 v38, 1.0, v38
	v_mul_f32_e32 v32, v32, v39
	v_rcp_f32_e32 v38, v38
	v_mul_f32_e32 v39, 0xbfb8aa3b, v34
	v_exp_f32_e32 v39, v39
	v_mul_f32_e32 v32, v32, v51
	v_mul_f32_e32 v33, v33, v38
	v_and_b32_e32 v38, 0xffff0000, v90
	v_mul_f32_e32 v33, v33, v38
	v_add_f32_e32 v38, 1.0, v39
	v_rcp_f32_e32 v39, v38
	v_mul_f32_e32 v38, 0xbfb8aa3b, v35
	v_exp_f32_e32 v40, v38
	v_mul_f32_e32 v33, v33, v51
	v_cvt_pk_bf16_f32 v38, v32, v33
	v_mul_f32_e32 v32, v34, v39
	v_add_f32_e32 v33, 1.0, v40
	v_rcp_f32_e32 v33, v33
	v_lshlrev_b32_e32 v34, 16, v91
	v_mul_f32_e32 v32, v32, v34
	v_and_b32_e32 v34, 0xffff0000, v91
	v_mul_f32_e32 v33, v35, v33
	v_mul_f32_e32 v35, 0xbfb8aa3b, v29
	v_exp_f32_e32 v35, v35
	v_mul_f32_e32 v33, v33, v34
	v_mul_f32_e32 v32, v32, v51
	v_mul_f32_e32 v33, v33, v51
	v_cvt_pk_bf16_f32 v39, v32, v33
	global_store_dwordx4 v[48:49], v[36:39], off offset:256
	v_add_f32_e32 v35, 1.0, v35
	v_rcp_f32_e32 v35, v35
	v_mul_f32_e32 v36, 0xbfb8aa3b, v30
	v_exp_f32_e32 v36, v36
	v_mul_f32_e32 v34, 0xbfb8aa3b, v28
	v_mul_f32_e32 v29, v29, v35
	v_exp_f32_e32 v34, v34
	v_add_f32_e32 v35, 1.0, v36
	v_mul_f32_e32 v36, 0xbfb8aa3b, v31
	v_rcp_f32_e32 v35, v35
	v_exp_f32_e32 v36, v36
	v_add_f32_e32 v34, 1.0, v34
	v_rcp_f32_e32 v34, v34
	v_mul_f32_e32 v30, v30, v35
	v_add_f32_e32 v35, 1.0, v36
	v_mul_f32_e32 v36, 0xbfb8aa3b, v24
	v_rcp_f32_e32 v35, v35
	v_exp_f32_e32 v36, v36
	v_mul_f32_e32 v28, v28, v34
	v_lshlrev_b32_e32 v34, 16, v84
	v_mul_f32_e32 v31, v31, v35
	v_add_f32_e32 v35, 1.0, v36
	v_mul_f32_e32 v36, 0xbfb8aa3b, v25
	v_rcp_f32_e32 v35, v35
	v_exp_f32_e32 v36, v36
	v_mul_f32_e32 v28, v28, v34
	v_and_b32_e32 v34, 0xffff0000, v84
	v_mul_f32_e32 v24, v24, v35
	v_add_f32_e32 v35, 1.0, v36
	v_mul_f32_e32 v36, 0xbfb8aa3b, v26
	v_rcp_f32_e32 v35, v35
	v_exp_f32_e32 v36, v36
	v_mul_f32_e32 v29, v29, v34
	v_lshlrev_b32_e32 v34, 16, v85
	v_mul_f32_e32 v25, v25, v35
	v_add_f32_e32 v35, 1.0, v36
	v_mul_f32_e32 v36, 0xbfb8aa3b, v27
	v_rcp_f32_e32 v35, v35
	v_exp_f32_e32 v36, v36
	v_mul_f32_e32 v30, v30, v34
	v_and_b32_e32 v34, 0xffff0000, v85
	v_mul_f32_e32 v26, v26, v35
	v_add_f32_e32 v35, 1.0, v36
	v_mul_f32_e32 v36, 0xbfb8aa3b, v20
	v_rcp_f32_e32 v35, v35
	v_exp_f32_e32 v36, v36
	v_mul_f32_e32 v31, v31, v34
	v_lshlrev_b32_e32 v34, 16, v86
	v_mul_f32_e32 v27, v27, v35
	v_add_f32_e32 v35, 1.0, v36
	v_mul_f32_e32 v36, 0xbfb8aa3b, v21
	v_rcp_f32_e32 v35, v35
	v_exp_f32_e32 v36, v36
	v_mul_f32_e32 v24, v24, v34
	v_and_b32_e32 v34, 0xffff0000, v86
	v_mul_f32_e32 v20, v20, v35
	v_add_f32_e32 v35, 1.0, v36
	v_mul_f32_e32 v36, 0xbfb8aa3b, v22
	v_rcp_f32_e32 v35, v35
	v_exp_f32_e32 v36, v36
	v_mul_f32_e32 v25, v25, v34
	v_lshlrev_b32_e32 v34, 16, v87
	v_mul_f32_e32 v26, v26, v34
	v_and_b32_e32 v34, 0xffff0000, v87
	v_mul_f32_e32 v27, v27, v34
	v_lshlrev_b32_e32 v34, 16, v76
	v_mul_f32_e32 v34, v20, v34
	v_mul_f32_e32 v20, v21, v35
	v_add_f32_e32 v35, 1.0, v36
	v_mul_f32_e32 v36, 0xbfb8aa3b, v23
	v_rcp_f32_e32 v35, v35
	v_exp_f32_e32 v36, v36
	v_and_b32_e32 v21, 0xffff0000, v76
	v_mul_f32_e32 v37, v20, v21
	v_mul_f32_e32 v20, v22, v35
	v_add_f32_e32 v22, 1.0, v36
	v_rcp_f32_e32 v22, v22
	v_mul_f32_e32 v35, 0xbfb8aa3b, v16
	v_exp_f32_e32 v35, v35
	v_lshlrev_b32_e32 v21, 16, v77
	v_mul_f32_e32 v36, v20, v21
	v_mul_f32_e32 v20, v23, v22
	v_mul_f32_e32 v23, 0xbfb8aa3b, v17
	v_add_f32_e32 v22, 1.0, v35
	v_exp_f32_e32 v23, v23
	v_rcp_f32_e32 v22, v22
	v_and_b32_e32 v21, 0xffff0000, v77
	v_mul_f32_e32 v35, v20, v21
	v_add_f32_e32 v21, 1.0, v23
	v_mul_f32_e32 v16, v16, v22
	v_rcp_f32_e32 v21, v21
	v_mul_f32_e32 v22, 0xbfb8aa3b, v18
	v_exp_f32_e32 v22, v22
	v_lshlrev_b32_e32 v20, 16, v78
	v_mul_f32_e32 v23, v16, v20
	v_mul_f32_e32 v16, v17, v21
	v_and_b32_e32 v17, 0xffff0000, v78
	v_add_f32_e32 v20, 1.0, v22
	v_mul_f32_e32 v22, v16, v17
	v_mul_f32_e32 v16, 0xbfb8aa3b, v19
	v_rcp_f32_e32 v20, v20
	v_exp_f32_e32 v16, v16
	v_mov_b32_e32 v21, v74
	v_mov_b32_e32 v74, v83
	v_mul_f32_e32 v17, v18, v20
	v_lshlrev_b32_e32 v18, 16, v79
	v_add_f32_e32 v16, 1.0, v16
	v_mul_f32_e32 v38, v17, v18
	v_rcp_f32_e32 v18, v16
	v_mov_b32_e32 v16, v80
	v_mov_b32_e32 v17, v72
	v_mov_b32_e32 v72, v81
	v_pk_add_f32 v[16:17], v[16:17], v[72:73]
	v_mov_b32_e32 v20, v82
	v_pk_add_f32 v[16:17], v[20:21], v[16:17]
	v_lshl_add_u64 v[32:33], s[2:3], 0, v[98:99]
	v_pk_add_f32 v[16:17], v[74:75], v[16:17]
	v_lshl_add_u64 v[32:33], v[32:33], 0, v[170:171]
	v_pk_fma_f32 v[20:21], v[16:17], s[14:15], v[112:113] op_sel_hi:[1,0,0]
	v_mul_f32_e32 v17, v19, v18
	v_mul_f32_e32 v16, 0x4b800000, v21
	v_cmp_gt_f32_e32 vcc, s5, v21
	v_and_b32_e32 v18, 0xffff0000, v79
	s_mov_b64 s[14:15], s[8:9]
	v_cndmask_b32_e32 v16, v21, v16, vcc
	v_rsq_f32_e32 v16, v16
	v_mul_f32_e32 v21, v17, v18
	v_mul_f32_e32 v17, 0x45800000, v16
	v_cndmask_b32_e32 v39, v16, v17, vcc
	v_mul_f32_e32 v16, v28, v39
	v_mul_f32_e32 v17, v29, v39
	v_cvt_pk_bf16_f32 v16, v16, v17
	v_mul_f32_e32 v17, v30, v39
	v_mul_f32_e32 v18, v31, v39
	v_cvt_pk_bf16_f32 v17, v17, v18
	v_mul_f32_e32 v18, v24, v39
	v_mul_f32_e32 v19, v25, v39
	v_cvt_pk_bf16_f32 v18, v18, v19
	v_mul_f32_e32 v19, v26, v39
	v_mul_f32_e32 v24, v27, v39
	v_cvt_pk_bf16_f32 v19, v19, v24
	global_store_dwordx4 v[32:33], v[16:19], off
	v_mul_f32_e32 v21, v21, v39
	v_cmp_gt_f32_e32 vcc, s5, v20
	v_mul_f32_e32 v16, v34, v39
	v_mul_f32_e32 v17, v37, v39
	v_cvt_pk_bf16_f32 v16, v16, v17
	v_mul_f32_e32 v17, v36, v39
	v_mul_f32_e32 v18, v35, v39
	v_cvt_pk_bf16_f32 v17, v17, v18
	v_mul_f32_e32 v18, v23, v39
	v_mul_f32_e32 v19, v22, v39
	v_cvt_pk_bf16_f32 v18, v18, v19
	v_mul_f32_e32 v19, v38, v39
	v_cvt_pk_bf16_f32 v19, v19, v21
	v_mul_f32_e32 v21, 0x4b800000, v20
	v_cndmask_b32_e32 v20, v20, v21, vcc
	global_store_dwordx4 v[32:33], v[16:19], off offset:256
	v_rsq_f32_e32 v20, v20
	s_nop 0
	v_mul_f32_e32 v16, 0xbfb8aa3b, v12
	v_exp_f32_e32 v18, v16
	v_mul_f32_e32 v16, 0x45800000, v20
	v_cndmask_b32_e32 v19, v20, v16, vcc
	v_mul_f32_e32 v20, 0xbfb8aa3b, v13
	v_add_f32_e32 v18, 1.0, v18
	v_rcp_f32_e32 v18, v18
	v_exp_f32_e32 v20, v20
	v_lshl_add_u64 v[16:17], s[2:3], 0, v[96:97]
	v_lshl_add_u64 v[16:17], v[16:17], 0, v[170:171]
	v_mul_f32_e32 v12, v12, v18
	v_lshlrev_b32_e32 v18, 16, v68
	v_mul_f32_e32 v12, v12, v18
	v_add_f32_e32 v18, 1.0, v20
	v_rcp_f32_e32 v18, v18
	v_mul_f32_e32 v20, 0xbfb8aa3b, v14
	v_exp_f32_e32 v20, v20
	v_mul_f32_e32 v12, v12, v19
	v_mul_f32_e32 v13, v13, v18
	v_and_b32_e32 v18, 0xffff0000, v68
	v_mul_f32_e32 v13, v13, v18
	v_add_f32_e32 v18, 1.0, v20
	v_mul_f32_e32 v20, 0xbfb8aa3b, v15
	v_rcp_f32_e32 v18, v18
	v_exp_f32_e32 v20, v20
	v_mul_f32_e32 v13, v13, v19
	v_cvt_pk_bf16_f32 v12, v12, v13
	v_mul_f32_e32 v13, v14, v18
	v_add_f32_e32 v14, 1.0, v20
	v_rcp_f32_e32 v14, v14
	v_lshlrev_b32_e32 v18, 16, v69
	v_mul_f32_e32 v13, v13, v18
	v_and_b32_e32 v18, 0xffff0000, v69
	v_mul_f32_e32 v14, v15, v14
	v_mul_f32_e32 v15, 0xbfb8aa3b, v8
	v_exp_f32_e32 v15, v15
	v_mul_f32_e32 v14, v14, v18
	v_mul_f32_e32 v13, v13, v19
	v_mul_f32_e32 v14, v14, v19
	v_add_f32_e32 v15, 1.0, v15
	v_cvt_pk_bf16_f32 v13, v13, v14
	v_mul_f32_e32 v14, 0xbfb8aa3b, v9
	v_rcp_f32_e32 v15, v15
	v_exp_f32_e32 v14, v14
	s_and_b64 vcc, exec, s[0:1]
	v_mul_f32_e32 v8, v8, v15
	v_lshlrev_b32_e32 v15, 16, v70
	v_add_f32_e32 v14, 1.0, v14
	v_mul_f32_e32 v8, v8, v15
	v_rcp_f32_e32 v14, v14
	v_mul_f32_e32 v15, 0xbfb8aa3b, v10
	v_exp_f32_e32 v15, v15
	v_mul_f32_e32 v8, v8, v19
	v_mul_f32_e32 v9, v9, v14
	v_and_b32_e32 v14, 0xffff0000, v70
	v_mul_f32_e32 v9, v9, v14
	v_add_f32_e32 v14, 1.0, v15
	v_rcp_f32_e32 v15, v14
	v_mul_f32_e32 v14, 0xbfb8aa3b, v11
	v_exp_f32_e32 v18, v14
	v_mul_f32_e32 v9, v9, v19
	v_cvt_pk_bf16_f32 v14, v8, v9
	v_mul_f32_e32 v8, v10, v15
	v_add_f32_e32 v9, 1.0, v18
	v_rcp_f32_e32 v9, v9
	v_lshlrev_b32_e32 v10, 16, v71
	v_mul_f32_e32 v8, v8, v10
	v_and_b32_e32 v10, 0xffff0000, v71
	v_mul_f32_e32 v9, v11, v9
	v_mul_f32_e32 v11, 0xbfb8aa3b, v4
	v_exp_f32_e32 v11, v11
	v_mul_f32_e32 v8, v8, v19
	v_mul_f32_e32 v9, v9, v10
	v_mul_f32_e32 v9, v9, v19
	v_cvt_pk_bf16_f32 v15, v8, v9
	v_add_f32_e32 v8, 1.0, v11
	v_rcp_f32_e32 v8, v8
	v_mul_f32_e32 v9, 0xbfb8aa3b, v5
	v_exp_f32_e32 v9, v9
	global_store_dwordx4 v[16:17], v[12:15], off
	v_mul_f32_e32 v4, v4, v8
	v_lshlrev_b32_e32 v8, 16, v64
	v_mul_f32_e32 v4, v4, v8
	v_add_f32_e32 v8, 1.0, v9
	v_rcp_f32_e32 v8, v8
	v_mul_f32_e32 v9, 0xbfb8aa3b, v6
	v_exp_f32_e32 v9, v9
	v_mul_f32_e32 v4, v4, v19
	v_mul_f32_e32 v5, v5, v8
	v_and_b32_e32 v8, 0xffff0000, v64
	v_mul_f32_e32 v5, v5, v8
	v_add_f32_e32 v8, 1.0, v9
	v_mul_f32_e32 v9, 0xbfb8aa3b, v7
	v_rcp_f32_e32 v8, v8
	v_exp_f32_e32 v9, v9
	v_mul_f32_e32 v5, v5, v19
	v_cvt_pk_bf16_f32 v4, v4, v5
	v_mul_f32_e32 v5, v6, v8
	v_add_f32_e32 v6, 1.0, v9
	v_rcp_f32_e32 v6, v6
	v_lshlrev_b32_e32 v8, 16, v65
	v_mul_f32_e32 v5, v5, v8
	v_and_b32_e32 v8, 0xffff0000, v65
	v_mul_f32_e32 v6, v7, v6
	v_mul_f32_e32 v7, 0xbfb8aa3b, v0
	v_exp_f32_e32 v7, v7
	v_mul_f32_e32 v6, v6, v8
	v_mul_f32_e32 v5, v5, v19
	v_mul_f32_e32 v6, v6, v19
	v_add_f32_e32 v7, 1.0, v7
	v_cvt_pk_bf16_f32 v5, v5, v6
	v_mul_f32_e32 v6, 0xbfb8aa3b, v1
	v_rcp_f32_e32 v7, v7
	v_exp_f32_e32 v6, v6
	v_mul_f32_e32 v0, v0, v7
	v_lshlrev_b32_e32 v7, 16, v66
	v_add_f32_e32 v6, 1.0, v6
	v_mul_f32_e32 v0, v0, v7
	v_rcp_f32_e32 v6, v6
	v_mul_f32_e32 v7, 0xbfb8aa3b, v2
	v_exp_f32_e32 v7, v7
	v_mul_f32_e32 v0, v0, v19
	v_mul_f32_e32 v1, v1, v6
	v_and_b32_e32 v6, 0xffff0000, v66
	v_mul_f32_e32 v1, v1, v6
	v_add_f32_e32 v6, 1.0, v7
	v_rcp_f32_e32 v7, v6
	v_mul_f32_e32 v6, 0xbfb8aa3b, v3
	v_exp_f32_e32 v8, v6
	v_mul_f32_e32 v1, v1, v19
	v_cvt_pk_bf16_f32 v6, v0, v1
	v_mul_f32_e32 v0, v2, v7
	v_add_f32_e32 v1, 1.0, v8
	v_rcp_f32_e32 v1, v1
	v_lshlrev_b32_e32 v2, 16, v67
	v_mul_f32_e32 v0, v0, v2
	v_and_b32_e32 v2, 0xffff0000, v67
	v_mul_f32_e32 v1, v3, v1
	v_mul_f32_e32 v1, v1, v2
	v_mul_f32_e32 v0, v0, v19
	v_mul_f32_e32 v1, v1, v19
	v_cvt_pk_bf16_f32 v7, v0, v1
	global_store_dwordx4 v[16:17], v[4:7], off offset:256
	s_cbranch_vccz .LBB0_80
	s_waitcnt vmcnt(0)
	s_cmpk_gt_u32 s21, 0xff
	s_cbranch_scc1 .LBB0_91
	s_barrier

.LBB0_199:
	v_mov_b64_e32 v[0:1], 0x1000
	s_ashr_i32 s9, s8, 31
	v_cmp_lt_i64_e32 vcc, s[10:11], v[0:1]
	s_lshl_b64 s[10:11], s[8:9], 20
	s_add_u32 s10, s23, s10
	s_addc_u32 s11, s24, s11
	s_and_b64 s[12:13], vcc, exec
	s_cselect_b32 s5, s11, s15
	s_cselect_b32 s9, s10, s14
	s_ashr_i32 s7, s6, 31
	s_lshl_b64 s[12:13], s[6:7], 20
	s_add_u32 s12, s25, s12
	s_addc_u32 s13, s26, s13
	s_and_b64 s[18:19], vcc, exec
	s_cselect_b32 s7, s13, s17
	s_cselect_b32 s37, s12, s16
	s_add_u32 s14, s14, 0x80080
	s_addc_u32 s15, s15, 0
	s_add_u32 s38, s16, 0x100
	v_mov_b32_e32 v0, 0
	s_addc_u32 s39, s17, 0
	s_mov_b32 s40, -2
	v_mov_b32_e32 v1, v0
	v_mov_b32_e32 v2, v0
	v_mov_b32_e32 v3, v0
	v_mov_b32_e32 v4, v0
	v_mov_b32_e32 v5, v0
	v_mov_b32_e32 v6, v0
	v_mov_b32_e32 v7, v0
	v_mov_b32_e32 v8, v0
	v_mov_b32_e32 v9, v0
	v_mov_b32_e32 v10, v0
	v_mov_b32_e32 v11, v0
	v_mov_b32_e32 v16, v0
	v_mov_b32_e32 v17, v0
	v_mov_b32_e32 v18, v0
	v_mov_b32_e32 v19, v0
	v_mov_b32_e32 v24, v0
	v_mov_b32_e32 v25, v0
	v_mov_b32_e32 v26, v0
	v_mov_b32_e32 v27, v0
	v_mov_b32_e32 v32, v0
	v_mov_b32_e32 v33, v0
	v_mov_b32_e32 v34, v0
	v_mov_b32_e32 v35, v0
	v_mov_b32_e32 v40, v0
	v_mov_b32_e32 v41, v0
	v_mov_b32_e32 v42, v0
	v_mov_b32_e32 v43, v0
	v_mov_b32_e32 v48, v0
	v_mov_b32_e32 v49, v0
	v_mov_b32_e32 v50, v0
	v_mov_b32_e32 v51, v0
	v_mov_b32_e32 v12, v0
	v_mov_b32_e32 v13, v0
	v_mov_b32_e32 v14, v0
	v_mov_b32_e32 v15, v0
	v_mov_b32_e32 v20, v0
	v_mov_b32_e32 v21, v0
	v_mov_b32_e32 v22, v0
	v_mov_b32_e32 v23, v0
	v_mov_b32_e32 v28, v0
	v_mov_b32_e32 v29, v0
	v_mov_b32_e32 v30, v0
	v_mov_b32_e32 v31, v0
	v_mov_b32_e32 v36, v0
	v_mov_b32_e32 v37, v0
	v_mov_b32_e32 v38, v0
	v_mov_b32_e32 v39, v0
	v_mov_b32_e32 v44, v0
	v_mov_b32_e32 v45, v0
	v_mov_b32_e32 v46, v0
	v_mov_b32_e32 v47, v0
	v_mov_b32_e32 v52, v0
	v_mov_b32_e32 v53, v0
	v_mov_b32_e32 v54, v0
	v_mov_b32_e32 v55, v0
	v_mov_b32_e32 v56, v0
	v_mov_b32_e32 v57, v0
	v_mov_b32_e32 v58, v0
	v_mov_b32_e32 v59, v0
	v_mov_b32_e32 v60, v0
	v_mov_b32_e32 v61, v0
	v_mov_b32_e32 v62, v0
	v_mov_b32_e32 v63, v0
	v_mov_b32_e32 v64, v0
	v_mov_b32_e32 v65, v0
	v_mov_b32_e32 v66, v0
	v_mov_b32_e32 v67, v0
	v_mov_b32_e32 v68, v0
	v_mov_b32_e32 v69, v0
	v_mov_b32_e32 v70, v0
	v_mov_b32_e32 v71, v0
	v_mov_b32_e32 v72, v0
	v_mov_b32_e32 v73, v0
	v_mov_b32_e32 v74, v0
	v_mov_b32_e32 v75, v0
	v_mov_b32_e32 v80, v0
	v_mov_b32_e32 v81, v0
	v_mov_b32_e32 v82, v0
	v_mov_b32_e32 v83, v0
	v_mov_b32_e32 v88, v0
	v_mov_b32_e32 v89, v0
	v_mov_b32_e32 v90, v0
	v_mov_b32_e32 v91, v0
	v_mov_b32_e32 v96, v0
	v_mov_b32_e32 v97, v0
	v_mov_b32_e32 v98, v0
	v_mov_b32_e32 v99, v0
	v_mov_b32_e32 v104, v0
	v_mov_b32_e32 v105, v0
	v_mov_b32_e32 v106, v0
	v_mov_b32_e32 v107, v0
	v_mov_b32_e32 v112, v0
	v_mov_b32_e32 v113, v0
	v_mov_b32_e32 v114, v0
	v_mov_b32_e32 v115, v0
	v_mov_b32_e32 v76, v0
	v_mov_b32_e32 v77, v0
	v_mov_b32_e32 v78, v0
	v_mov_b32_e32 v79, v0
	v_mov_b32_e32 v84, v0
	v_mov_b32_e32 v85, v0
	v_mov_b32_e32 v86, v0
	v_mov_b32_e32 v87, v0
	v_mov_b32_e32 v92, v0
	v_mov_b32_e32 v93, v0
	v_mov_b32_e32 v94, v0
	v_mov_b32_e32 v95, v0
	v_mov_b32_e32 v100, v0
	v_mov_b32_e32 v101, v0
	v_mov_b32_e32 v102, v0
	v_mov_b32_e32 v103, v0
	v_mov_b32_e32 v108, v0
	v_mov_b32_e32 v109, v0
	v_mov_b32_e32 v110, v0
	v_mov_b32_e32 v111, v0
	v_mov_b32_e32 v116, v0
	v_mov_b32_e32 v117, v0
	v_mov_b32_e32 v118, v0
	v_mov_b32_e32 v119, v0
	v_mov_b32_e32 v120, v0
	v_mov_b32_e32 v121, v0
	v_mov_b32_e32 v122, v0
	v_mov_b32_e32 v123, v0
	v_mov_b32_e32 v124, v0
	v_mov_b32_e32 v125, v0
	v_mov_b32_e32 v126, v0
	v_mov_b32_e32 v127, v0
	s_mov_b64 s[48:49], 0x80
	v_add_u32_e32 v222, 0x10000, v238
.LBB0_200:
	s_add_u32 s16, s14, 0xfff80080
	s_addc_u32 s17, s15, -1
	s_add_i32 s41, 0, 0x10000
	ds_read_b128 v[128:131], v222 offset:0
	ds_read_b128 v[132:135], v222 offset:1024
	ds_read_b128 v[136:139], v222 offset:2048
	ds_read_b128 v[140:143], v222 offset:3072
	s_cmp_eq_u32 s40, 28
	s_cselect_b32 s19, s5, s17
	s_cselect_b32 s18, s9, s16
	s_cselect_b32 s17, s7, s39
	s_cselect_b32 s16, s37, s38
	s_add_i32 m0, s28, 0xc000
	ds_read_b128 v[144:147], v240
	ds_read_b128 v[148:151], v240 offset:1024
	ds_read_b128 v[152:155], v240 offset:2048
	ds_read_b128 v[156:159], v240 offset:3072
	ds_read_b128 v[160:163], v240 offset:4096
	ds_read_b128 v[164:167], v240 offset:5120
	ds_read_b128 v[168:171], v240 offset:6144
	ds_read_b128 v[172:175], v240 offset:7168
	global_load_lds_dwordx4 v218, s[14:15]
	s_add_i32 m0, s28, 0xe000
	s_nop 0
	global_load_lds_dwordx4 v220, s[14:15]
	s_waitcnt lgkmcnt(8)
	s_barrier
	s_waitcnt lgkmcnt(0)
	v_mfma_f32_16x16x32_bf16 v[124:127], v[128:131], v[144:147], v[124:127]
	v_mfma_f32_16x16x32_bf16 v[120:123], v[136:139], v[144:147], v[120:123]
	v_mfma_f32_16x16x32_bf16 v[116:119], v[128:131], v[152:155], v[116:119]
	v_mfma_f32_16x16x32_bf16 v[108:111], v[136:139], v[152:155], v[108:111]
	v_mfma_f32_16x16x32_bf16 v[100:103], v[128:131], v[160:163], v[100:103]
	v_mfma_f32_16x16x32_bf16 v[92:95], v[136:139], v[160:163], v[92:95]
	v_mfma_f32_16x16x32_bf16 v[84:87], v[128:131], v[168:171], v[84:87]
	v_mfma_f32_16x16x32_bf16 v[76:79], v[136:139], v[168:171], v[76:79]
	v_mfma_f32_16x16x32_bf16 v[124:127], v[132:135], v[148:151], v[124:127]
	v_mfma_f32_16x16x32_bf16 v[120:123], v[140:143], v[148:151], v[120:123]
	v_mfma_f32_16x16x32_bf16 v[116:119], v[132:135], v[156:159], v[116:119]
	v_mfma_f32_16x16x32_bf16 v[108:111], v[140:143], v[156:159], v[108:111]
	v_mfma_f32_16x16x32_bf16 v[100:103], v[132:135], v[164:167], v[100:103]
	v_mfma_f32_16x16x32_bf16 v[92:95], v[140:143], v[164:167], v[92:95]
	v_mfma_f32_16x16x32_bf16 v[84:87], v[132:135], v[172:175], v[84:87]
	v_mfma_f32_16x16x32_bf16 v[76:79], v[140:143], v[172:175], v[76:79]
	s_barrier
	s_add_i32 s44, 0, 0x14000
	s_add_i32 s41, s41, s27
	s_mov_b32 m0, s41
	ds_read_b128 v[176:179], v222 offset:16384
	ds_read_b128 v[180:183], v222 offset:17408
	ds_read_b128 v[184:187], v222 offset:18432
	ds_read_b128 v[188:191], v222 offset:19456
	global_load_lds_dwordx4 v206, s[16:17]
	s_add_i32 m0, s41, 0x2000
	s_nop 0
	global_load_lds_dwordx4 v210, s[16:17]
	s_barrier
	s_waitcnt lgkmcnt(0)
	v_mfma_f32_16x16x32_bf16 v[112:115], v[176:179], v[144:147], v[112:115]
	v_mfma_f32_16x16x32_bf16 v[104:107], v[184:187], v[144:147], v[104:107]
	v_mfma_f32_16x16x32_bf16 v[96:99], v[176:179], v[152:155], v[96:99]
	v_mfma_f32_16x16x32_bf16 v[88:91], v[184:187], v[152:155], v[88:91]
	v_mfma_f32_16x16x32_bf16 v[80:83], v[176:179], v[160:163], v[80:83]
	v_mfma_f32_16x16x32_bf16 v[72:75], v[184:187], v[160:163], v[72:75]
	v_mfma_f32_16x16x32_bf16 v[68:71], v[176:179], v[168:171], v[68:71]
	v_mfma_f32_16x16x32_bf16 v[64:67], v[184:187], v[168:171], v[64:67]
	v_mfma_f32_16x16x32_bf16 v[112:115], v[180:183], v[148:151], v[112:115]
	v_mfma_f32_16x16x32_bf16 v[104:107], v[188:191], v[148:151], v[104:107]
	v_mfma_f32_16x16x32_bf16 v[96:99], v[180:183], v[156:159], v[96:99]
	v_mfma_f32_16x16x32_bf16 v[88:91], v[188:191], v[156:159], v[88:91]
	v_mfma_f32_16x16x32_bf16 v[80:83], v[180:183], v[164:167], v[80:83]
	v_mfma_f32_16x16x32_bf16 v[72:75], v[188:191], v[164:167], v[72:75]
	v_mfma_f32_16x16x32_bf16 v[68:71], v[180:183], v[172:175], v[68:71]
	v_mfma_f32_16x16x32_bf16 v[64:67], v[188:191], v[172:175], v[64:67]
	s_mov_b32 m0, s28
	s_add_u32 s48, s18, 0x80
	s_addc_u32 s49, s19, 0
	s_barrier
	ds_read_b128 v[144:147], v240 offset:16384
	ds_read_b128 v[148:151], v240 offset:17408
	ds_read_b128 v[152:155], v240 offset:18432
	ds_read_b128 v[156:159], v240 offset:19456
	ds_read_b128 v[160:163], v240 offset:20480
	ds_read_b128 v[164:167], v240 offset:21504
	ds_read_b128 v[168:171], v240 offset:22528
	ds_read_b128 v[172:175], v240 offset:23552
	global_load_lds_dwordx4 v204, s[18:19]
	s_mov_b32 m0, s29
	s_nop 0
	global_load_lds_dwordx4 v208, s[18:19]
	s_barrier
	s_waitcnt lgkmcnt(0)
	v_mfma_f32_16x16x32_bf16 v[60:63], v[128:131], v[144:147], v[60:63]
	v_mfma_f32_16x16x32_bf16 v[56:59], v[136:139], v[144:147], v[56:59]
	v_mfma_f32_16x16x32_bf16 v[52:55], v[128:131], v[152:155], v[52:55]
	v_mfma_f32_16x16x32_bf16 v[44:47], v[136:139], v[152:155], v[44:47]
	v_mfma_f32_16x16x32_bf16 v[36:39], v[128:131], v[160:163], v[36:39]
	v_mfma_f32_16x16x32_bf16 v[28:31], v[136:139], v[160:163], v[28:31]
	v_mfma_f32_16x16x32_bf16 v[20:23], v[128:131], v[168:171], v[20:23]
	v_mfma_f32_16x16x32_bf16 v[12:15], v[136:139], v[168:171], v[12:15]
	v_mfma_f32_16x16x32_bf16 v[60:63], v[132:135], v[148:151], v[60:63]
	v_mfma_f32_16x16x32_bf16 v[56:59], v[140:143], v[148:151], v[56:59]
	v_mfma_f32_16x16x32_bf16 v[52:55], v[132:135], v[156:159], v[52:55]
	v_mfma_f32_16x16x32_bf16 v[44:47], v[140:143], v[156:159], v[44:47]
	v_mfma_f32_16x16x32_bf16 v[36:39], v[132:135], v[164:167], v[36:39]
	v_mfma_f32_16x16x32_bf16 v[28:31], v[140:143], v[164:167], v[28:31]
	v_mfma_f32_16x16x32_bf16 v[20:23], v[132:135], v[172:175], v[20:23]
	v_mfma_f32_16x16x32_bf16 v[12:15], v[140:143], v[172:175], v[12:15]
	s_barrier
	s_add_u32 s42, s16, 0x80000
	s_addc_u32 s43, s17, 0
	s_add_i32 s41, s44, s27
	s_mov_b32 m0, s41
	s_nop 0
	global_load_lds_dwordx4 v206, s[42:43]
	s_add_i32 m0, s41, 0x2000
	s_nop 0
	global_load_lds_dwordx4 v210, s[42:43]
	s_waitcnt vmcnt(6)
	s_barrier
	v_mfma_f32_16x16x32_bf16 v[48:51], v[176:179], v[144:147], v[48:51]
	v_mfma_f32_16x16x32_bf16 v[40:43], v[184:187], v[144:147], v[40:43]
	v_mfma_f32_16x16x32_bf16 v[32:35], v[176:179], v[152:155], v[32:35]
	v_mfma_f32_16x16x32_bf16 v[24:27], v[184:187], v[152:155], v[24:27]
	v_mfma_f32_16x16x32_bf16 v[16:19], v[176:179], v[160:163], v[16:19]
	v_mfma_f32_16x16x32_bf16 v[8:11], v[184:187], v[160:163], v[8:11]
	v_mfma_f32_16x16x32_bf16 v[4:7], v[176:179], v[168:171], v[4:7]
	v_mfma_f32_16x16x32_bf16 v[0:3], v[184:187], v[168:171], v[0:3]
	v_mfma_f32_16x16x32_bf16 v[48:51], v[180:183], v[148:151], v[48:51]
	v_mfma_f32_16x16x32_bf16 v[40:43], v[188:191], v[148:151], v[40:43]
	v_mfma_f32_16x16x32_bf16 v[32:35], v[180:183], v[156:159], v[32:35]
	v_mfma_f32_16x16x32_bf16 v[24:27], v[188:191], v[156:159], v[24:27]
	v_mfma_f32_16x16x32_bf16 v[16:19], v[180:183], v[164:167], v[16:19]
	v_mfma_f32_16x16x32_bf16 v[8:11], v[188:191], v[164:167], v[8:11]
	v_mfma_f32_16x16x32_bf16 v[4:7], v[180:183], v[172:175], v[4:7]
	v_mfma_f32_16x16x32_bf16 v[0:3], v[188:191], v[172:175], v[0:3]
	s_add_i32 s41, 0, 0x18000
	s_barrier
	ds_read_b128 v[128:131], v222 offset:32768
	ds_read_b128 v[132:135], v222 offset:33792
	ds_read_b128 v[136:139], v222 offset:34816
	ds_read_b128 v[140:143], v222 offset:35840
	s_add_u32 s18, s18, 0x80000
	s_addc_u32 s19, s19, 0
	s_mov_b32 m0, s30
	ds_read_b128 v[144:147], v240 offset:32768
	ds_read_b128 v[148:151], v240 offset:33792
	ds_read_b128 v[152:155], v240 offset:34816
	ds_read_b128 v[156:159], v240 offset:35840
	ds_read_b128 v[160:163], v240 offset:36864
	ds_read_b128 v[164:167], v240 offset:37888
	ds_read_b128 v[168:171], v240 offset:38912
	ds_read_b128 v[172:175], v240 offset:39936
	global_load_lds_dwordx4 v204, s[18:19]
	s_mov_b32 m0, s31
	s_nop 0
	global_load_lds_dwordx4 v208, s[18:19]
	s_waitcnt lgkmcnt(8)
	s_barrier
	s_waitcnt lgkmcnt(0)
	v_mfma_f32_16x16x32_bf16 v[124:127], v[128:131], v[144:147], v[124:127]
	v_mfma_f32_16x16x32_bf16 v[120:123], v[136:139], v[144:147], v[120:123]
	v_mfma_f32_16x16x32_bf16 v[116:119], v[128:131], v[152:155], v[116:119]
	v_mfma_f32_16x16x32_bf16 v[108:111], v[136:139], v[152:155], v[108:111]
	v_mfma_f32_16x16x32_bf16 v[100:103], v[128:131], v[160:163], v[100:103]
	v_mfma_f32_16x16x32_bf16 v[92:95], v[136:139], v[160:163], v[92:95]
	v_mfma_f32_16x16x32_bf16 v[84:87], v[128:131], v[168:171], v[84:87]
	v_mfma_f32_16x16x32_bf16 v[76:79], v[136:139], v[168:171], v[76:79]
	v_mfma_f32_16x16x32_bf16 v[124:127], v[132:135], v[148:151], v[124:127]
	v_mfma_f32_16x16x32_bf16 v[120:123], v[140:143], v[148:151], v[120:123]
	v_mfma_f32_16x16x32_bf16 v[116:119], v[132:135], v[156:159], v[116:119]
	v_mfma_f32_16x16x32_bf16 v[108:111], v[140:143], v[156:159], v[108:111]
	v_mfma_f32_16x16x32_bf16 v[100:103], v[132:135], v[164:167], v[100:103]
	v_mfma_f32_16x16x32_bf16 v[92:95], v[140:143], v[164:167], v[92:95]
	v_mfma_f32_16x16x32_bf16 v[84:87], v[132:135], v[172:175], v[84:87]
	v_mfma_f32_16x16x32_bf16 v[76:79], v[140:143], v[172:175], v[76:79]
	s_barrier
	s_add_i32 s18, 0, 0x1c000
	s_add_i32 s19, s41, s27
	s_add_i32 m0, s19, 0xffffff80
	ds_read_b128 v[176:179], v222 offset:49152
	ds_read_b128 v[180:183], v222 offset:50176
	ds_read_b128 v[184:187], v222 offset:51200
	ds_read_b128 v[188:191], v222 offset:52224
	global_load_lds_dwordx4 v206, s[16:17] offset:128
	s_add_i32 m0, s19, 0x1f80
	s_nop 0
	global_load_lds_dwordx4 v210, s[16:17] offset:128
	s_barrier
	s_waitcnt lgkmcnt(0)
	v_mfma_f32_16x16x32_bf16 v[112:115], v[176:179], v[144:147], v[112:115]
	v_mfma_f32_16x16x32_bf16 v[104:107], v[184:187], v[144:147], v[104:107]
	v_mfma_f32_16x16x32_bf16 v[96:99], v[176:179], v[152:155], v[96:99]
	v_mfma_f32_16x16x32_bf16 v[88:91], v[184:187], v[152:155], v[88:91]
	v_mfma_f32_16x16x32_bf16 v[80:83], v[176:179], v[160:163], v[80:83]
	v_mfma_f32_16x16x32_bf16 v[72:75], v[184:187], v[160:163], v[72:75]
	v_mfma_f32_16x16x32_bf16 v[68:71], v[176:179], v[168:171], v[68:71]
	v_mfma_f32_16x16x32_bf16 v[64:67], v[184:187], v[168:171], v[64:67]
	v_mfma_f32_16x16x32_bf16 v[112:115], v[180:183], v[148:151], v[112:115]
	v_mfma_f32_16x16x32_bf16 v[104:107], v[188:191], v[148:151], v[104:107]
	v_mfma_f32_16x16x32_bf16 v[96:99], v[180:183], v[156:159], v[96:99]
	v_mfma_f32_16x16x32_bf16 v[88:91], v[188:191], v[156:159], v[88:91]
	v_mfma_f32_16x16x32_bf16 v[80:83], v[180:183], v[164:167], v[80:83]
	v_mfma_f32_16x16x32_bf16 v[72:75], v[188:191], v[164:167], v[72:75]
	v_mfma_f32_16x16x32_bf16 v[68:71], v[180:183], v[172:175], v[68:71]
	v_mfma_f32_16x16x32_bf16 v[64:67], v[188:191], v[172:175], v[64:67]
	s_mov_b32 m0, s33
	s_barrier
	ds_read_b128 v[144:147], v240 offset:49152
	ds_read_b128 v[148:151], v240 offset:50176
	ds_read_b128 v[152:155], v240 offset:51200
	ds_read_b128 v[156:159], v240 offset:52224
	ds_read_b128 v[160:163], v240 offset:53248
	ds_read_b128 v[164:167], v240 offset:54272
	ds_read_b128 v[168:171], v240 offset:55296
	ds_read_b128 v[172:175], v240 offset:56320
	global_load_lds_dwordx4 v204, s[48:49]
	s_mov_b32 m0, s34
	s_nop 0
	global_load_lds_dwordx4 v208, s[48:49]
	s_barrier
	s_waitcnt lgkmcnt(0)
	v_mfma_f32_16x16x32_bf16 v[60:63], v[128:131], v[144:147], v[60:63]
	v_mfma_f32_16x16x32_bf16 v[56:59], v[136:139], v[144:147], v[56:59]
	v_mfma_f32_16x16x32_bf16 v[52:55], v[128:131], v[152:155], v[52:55]
	v_mfma_f32_16x16x32_bf16 v[44:47], v[136:139], v[152:155], v[44:47]
	v_mfma_f32_16x16x32_bf16 v[36:39], v[128:131], v[160:163], v[36:39]
	v_mfma_f32_16x16x32_bf16 v[28:31], v[136:139], v[160:163], v[28:31]
	v_mfma_f32_16x16x32_bf16 v[20:23], v[128:131], v[168:171], v[20:23]
	v_mfma_f32_16x16x32_bf16 v[12:15], v[136:139], v[168:171], v[12:15]
	v_mfma_f32_16x16x32_bf16 v[60:63], v[132:135], v[148:151], v[60:63]
	v_mfma_f32_16x16x32_bf16 v[56:59], v[140:143], v[148:151], v[56:59]
	v_mfma_f32_16x16x32_bf16 v[52:55], v[132:135], v[156:159], v[52:55]
	v_mfma_f32_16x16x32_bf16 v[44:47], v[140:143], v[156:159], v[44:47]
	v_mfma_f32_16x16x32_bf16 v[36:39], v[132:135], v[164:167], v[36:39]
	v_mfma_f32_16x16x32_bf16 v[28:31], v[140:143], v[164:167], v[28:31]
	v_mfma_f32_16x16x32_bf16 v[20:23], v[132:135], v[172:175], v[20:23]
	v_mfma_f32_16x16x32_bf16 v[12:15], v[140:143], v[172:175], v[12:15]
	s_barrier
	s_add_u32 s16, s16, 0x80080
	s_addc_u32 s17, s17, 0
	s_add_i32 s18, s18, s27
	s_mov_b32 m0, s18
	s_nop 0
	global_load_lds_dwordx4 v206, s[16:17]
	s_add_i32 m0, s18, 0x2000
	s_nop 0
	global_load_lds_dwordx4 v210, s[16:17]
	s_waitcnt vmcnt(6)
	s_barrier
	v_mfma_f32_16x16x32_bf16 v[48:51], v[176:179], v[144:147], v[48:51]
	v_mfma_f32_16x16x32_bf16 v[40:43], v[184:187], v[144:147], v[40:43]
	v_mfma_f32_16x16x32_bf16 v[32:35], v[176:179], v[152:155], v[32:35]
	v_mfma_f32_16x16x32_bf16 v[24:27], v[184:187], v[152:155], v[24:27]
	v_mfma_f32_16x16x32_bf16 v[16:19], v[176:179], v[160:163], v[16:19]
	v_mfma_f32_16x16x32_bf16 v[8:11], v[184:187], v[160:163], v[8:11]
	v_mfma_f32_16x16x32_bf16 v[4:7], v[176:179], v[168:171], v[4:7]
	v_mfma_f32_16x16x32_bf16 v[0:3], v[184:187], v[168:171], v[0:3]
	v_mfma_f32_16x16x32_bf16 v[48:51], v[180:183], v[148:151], v[48:51]
	v_mfma_f32_16x16x32_bf16 v[40:43], v[188:191], v[148:151], v[40:43]
	v_mfma_f32_16x16x32_bf16 v[32:35], v[180:183], v[156:159], v[32:35]
	v_mfma_f32_16x16x32_bf16 v[24:27], v[188:191], v[156:159], v[24:27]
	v_mfma_f32_16x16x32_bf16 v[16:19], v[180:183], v[164:167], v[16:19]
	v_mfma_f32_16x16x32_bf16 v[8:11], v[188:191], v[164:167], v[8:11]
	v_mfma_f32_16x16x32_bf16 v[4:7], v[180:183], v[172:175], v[4:7]
	v_mfma_f32_16x16x32_bf16 v[0:3], v[188:191], v[172:175], v[0:3]
	s_add_i32 s40, s40, 2
	s_add_u32 s14, s14, 0x100
	s_addc_u32 s15, s15, 0
	s_add_u32 s38, s38, 0x100
	s_addc_u32 s39, s39, 0
	s_cmp_gt_u32 s40, 29
	s_barrier
	s_cbranch_scc0 .LBB0_200
	v_lshl_add_u32 v228, s4, 8, v237
	v_or_b32_e32 v226, 16, v228
	s_mov_b64 s[4:5], -1
	s_cmp_lt_i32 s36, 16
	v_ashrrev_i32_e32 v229, 31, v228
	v_lshlrev_b32_e32 v192, 1, v212
	v_ashrrev_i32_e32 v227, 31, v226
	v_or_b32_e32 v224, 32, v228
	v_or_b32_e32 v222, 48, v228
	s_cbranch_scc0 .LBB0_203
	s_and_b32 s7, s36, 7
	s_cmp_gt_i32 s36, 7
	s_cselect_b64 vcc, -1, 0
	s_and_b64 s[4:5], vcc, exec
	s_mov_b32 s4, 0x15000000
	s_cselect_b32 s4, s4, 0xd000000
	s_add_u32 s4, s50, s4
	s_addc_u32 s5, s51, 0
	s_lshl_b32 s9, s7, 9
	s_add_u32 s4, s4, s9
	v_cvt_f32_ubyte0_e32 v128, s7
	s_addc_u32 s5, s5, 0
	v_sub_f32_e32 v128, 0xc0a00000, v128
	s_mov_b32 s7, 0xc2fc0000
	v_lshl_add_u64 v[230:231], s[4:5], 0, v[192:193]
	v_cmp_gt_f32_e64 s[4:5], s7, v128
	v_ashrrev_i32_e32 v225, 31, v224
	s_nop 0
	v_cndmask_b32_e64 v129, 0, v234, s[4:5]
	v_add_f32_e32 v128, v128, v129
	v_exp_f32_e32 v128, v128
	s_and_b64 s[4:5], s[4:5], exec
	s_cselect_b32 s4, 0xffffffc0, 0
	v_mov_b32_e32 v129, v193
	v_ldexp_f32 v128, v128, s4
	v_sub_f32_e32 v128, 1.0, v128
	v_log_f32_e32 v241, v128
	v_lshlrev_b32_e32 v128, 9, v228
	v_and_b32_e32 v128, 0x1f9e00, v128
	v_lshl_add_u64 v[130:131], v[214:215], 0, v[128:129]
	v_lshl_add_u64 v[132:133], v[216:217], 0, v[128:129]
	global_load_dwordx4 v[180:183], v[130:131], off offset:16
	global_load_dwordx4 v[188:191], v[130:131], off
	global_load_dwordx4 v[176:179], v[132:133], off offset:16
	global_load_dwordx4 v[184:187], v[132:133], off
	v_or_b32_e32 v130, 0x2000, v128
	v_mov_b32_e32 v131, v193
	v_lshl_add_u64 v[132:133], v[214:215], 0, v[130:131]
	v_lshl_add_u64 v[130:131], v[216:217], 0, v[130:131]
	global_load_dwordx4 v[164:167], v[132:133], off offset:16
	global_load_dwordx4 v[172:175], v[132:133], off
	global_load_dwordx4 v[160:163], v[130:131], off offset:16
	global_load_dwordx4 v[168:171], v[130:131], off
	v_mul_f32_e64 v196, v241, -v239
	v_cmp_gt_f32_e64 s[4:5], s7, v196
	v_or_b32_e32 v130, 0x4000, v128
	v_mov_b32_e32 v131, v193
	v_cndmask_b32_e64 v196, 0, v234, s[4:5]
	v_fma_f32 v196, v241, -v239, v196
	v_exp_f32_e32 v196, v196
	v_cndmask_b32_e64 v197, 0, v235, s[4:5]
	v_lshl_add_u64 v[132:133], v[214:215], 0, v[130:131]
	v_lshl_add_u64 v[130:131], v[216:217], 0, v[130:131]
	v_ldexp_f32 v196, v196, v197
	v_mul_f32_e32 v196, 0x3d800000, v196
	v_cndmask_b32_e32 v242, 1.0, v196, vcc
	v_mov_b32_e32 v196, v124
	v_mov_b32_e32 v197, v112
	global_load_dwordx4 v[148:151], v[132:133], off offset:16
	global_load_dwordx4 v[156:159], v[132:133], off
	global_load_dwordx4 v[144:147], v[130:131], off offset:16
	global_load_dwordx4 v[152:155], v[130:131], off
	v_or_b32_e32 v128, 0x6000, v128
	v_lshl_add_u64 v[130:131], v[214:215], 0, v[128:129]
	v_lshl_add_u64 v[136:137], v[216:217], 0, v[128:129]
	global_load_dwordx4 v[132:135], v[130:131], off offset:16
	global_load_dwordx4 v[140:143], v[130:131], off
	s_nop 0
	global_load_dwordx4 v[128:131], v[136:137], off offset:16
	s_nop 0
	global_load_dwordx4 v[136:139], v[136:137], off
	s_movk_i32 s4, 0x5f
	s_waitcnt vmcnt(0)
	v_mov_b32_e32 v198, v188
	v_mov_b32_e32 v199, v184
	v_pk_mul_f32 v[196:197], v[196:197], v[198:199]
	s_nop 0
	v_sub_f32_e32 v184, v196, v197
	v_mov_b32_e32 v196, v112
	v_mov_b32_e32 v197, v124
	v_pk_mul_f32 v[196:197], v[196:197], v[198:199]
	v_mul_f32_e32 v223, v242, v184
	v_add_f32_e32 v184, v196, v197
	v_mul_f32_e32 v198, v242, v184
	v_mov_b32_e32 v196, v125
	v_mov_b32_e32 v197, v113
	v_mov_b32_e32 v184, v189
	v_pk_mul_f32 v[188:189], v[196:197], v[184:185]
	s_nop 0
	v_sub_f32_e32 v188, v188, v189
	v_mul_f32_e32 v196, v242, v188
	v_mov_b32_e32 v188, v113
	v_mov_b32_e32 v189, v125
	v_pk_mul_f32 v[184:185], v[188:189], v[184:185]
	v_mov_b32_e32 v188, v190
	v_add_f32_e32 v184, v184, v185
	v_mul_f32_e32 v197, v242, v184
	v_mov_b32_e32 v184, v126
	v_mov_b32_e32 v185, v114
	v_mov_b32_e32 v189, v186
	v_pk_mul_f32 v[184:185], v[184:185], v[188:189]
	v_mov_b32_e32 v186, v191
	v_sub_f32_e32 v184, v184, v185
	v_mul_f32_e32 v190, v242, v184
	v_mov_b32_e32 v184, v114
	v_mov_b32_e32 v185, v126
	v_pk_mul_f32 v[184:185], v[184:185], v[188:189]
	s_nop 0
	v_add_f32_e32 v184, v184, v185
	v_mul_f32_e32 v188, v242, v184
	v_mov_b32_e32 v184, v127
	v_mov_b32_e32 v185, v115
	v_pk_mul_f32 v[184:185], v[184:185], v[186:187]
	s_nop 0
	v_sub_f32_e32 v184, v184, v185
	v_mul_f32_e32 v189, v242, v184
	v_mov_b32_e32 v184, v115
	v_mov_b32_e32 v185, v127
	v_pk_mul_f32 v[184:185], v[184:185], v[186:187]
	v_mov_b32_e32 v186, v180
	v_add_f32_e32 v184, v184, v185
	v_mul_f32_e32 v191, v242, v184
	v_mov_b32_e32 v184, v120
	v_mov_b32_e32 v185, v104
	v_mov_b32_e32 v187, v176
	v_pk_mul_f32 v[184:185], v[184:185], v[186:187]
	s_nop 0
	v_sub_f32_e32 v176, v184, v185
	v_mov_b32_e32 v184, v104
	v_mov_b32_e32 v185, v120
	v_pk_mul_f32 v[184:185], v[184:185], v[186:187]
	v_mul_f32_e32 v199, v242, v176
	v_add_f32_e32 v176, v184, v185
	v_mul_f32_e32 v186, v242, v176
	v_mov_b32_e32 v184, v121
	v_mov_b32_e32 v185, v105
	v_mov_b32_e32 v176, v181
	v_pk_mul_f32 v[180:181], v[184:185], v[176:177]
	s_nop 0
	v_sub_f32_e32 v180, v180, v181
	v_mul_f32_e32 v184, v242, v180
	v_mov_b32_e32 v180, v105
	v_mov_b32_e32 v181, v121
	v_pk_mul_f32 v[176:177], v[180:181], v[176:177]
	v_mov_b32_e32 v180, v182
	v_add_f32_e32 v176, v176, v177
	v_mul_f32_e32 v185, v242, v176
	v_mov_b32_e32 v176, v122
	v_mov_b32_e32 v177, v106
	v_mov_b32_e32 v181, v178
	v_pk_mul_f32 v[176:177], v[176:177], v[180:181]
	v_mov_b32_e32 v178, v183
	v_sub_f32_e32 v176, v176, v177
	v_mul_f32_e32 v182, v242, v176
	v_mov_b32_e32 v176, v106
	v_mov_b32_e32 v177, v122
	v_pk_mul_f32 v[176:177], v[176:177], v[180:181]
	s_nop 0
	v_add_f32_e32 v176, v176, v177
	v_mul_f32_e32 v187, v242, v176
	v_mov_b32_e32 v176, v123
	v_mov_b32_e32 v177, v107
	v_pk_mul_f32 v[176:177], v[176:177], v[178:179]
	s_nop 0
	v_sub_f32_e32 v176, v176, v177
	v_mul_f32_e32 v181, v242, v176
	v_mov_b32_e32 v176, v107
	v_mov_b32_e32 v177, v123
	v_pk_mul_f32 v[176:177], v[176:177], v[178:179]
	v_cvt_pk_bf16_f32 v178, v223, v196
	v_cvt_pk_bf16_f32 v179, v190, v189
	v_cvt_pk_bf16_f32 v180, v199, v184
	v_cvt_pk_bf16_f32 v181, v182, v181
	v_cvt_pk_bf16_f32 v182, v198, v197
	s_nop 0
	v_add_f32_e32 v176, v176, v177
	v_mul_f32_e32 v176, v242, v176
	v_cvt_pk_bf16_f32 v183, v188, v191
	v_cvt_pk_bf16_f32 v184, v186, v185
	v_cvt_pk_bf16_f32 v185, v187, v176
	v_lshlrev_b64 v[176:177], 12, v[228:229]
	v_lshl_add_u64 v[176:177], v[230:231], 0, v[176:177]
	global_store_dwordx4 v[176:177], v[178:181], off
	global_store_dwordx4 v[176:177], v[182:185], off offset:256
	v_ashrrev_i32_e32 v223, 31, v222
	v_bitop3_b32 v178, v228, s4, 16 bitop3:0xc8
	v_add_u32_e32 v178, 1, v178
	v_cvt_f32_ubyte0_e32 v178, v178
	v_mul_f32_e64 v179, v241, -v178
	v_cmp_gt_f32_e64 s[4:5], s7, v179
	v_mov_b32_e32 v181, v168
	v_mov_b32_e32 v190, v60
	v_cndmask_b32_e64 v180, 0, v234, s[4:5]
	v_fma_f32 v178, v241, -v178, v180
	v_exp_f32_e32 v178, v178
	v_cndmask_b32_e64 v179, 0, v235, s[4:5]
	v_mov_b32_e32 v180, v172
	s_movk_i32 s4, 0x6f
	v_ldexp_f32 v178, v178, v179
	v_mul_f32_e32 v178, 0x3d800000, v178
	v_cndmask_b32_e32 v182, 1.0, v178, vcc
	v_mov_b32_e32 v178, v116
	v_mov_b32_e32 v179, v96
	v_pk_mul_f32 v[178:179], v[178:179], v[180:181]
	v_mov_b32_e32 v191, v48
	v_sub_f32_e32 v168, v178, v179
	v_mov_b32_e32 v178, v96
	v_mov_b32_e32 v179, v116
	v_pk_mul_f32 v[178:179], v[178:179], v[180:181]
	v_mul_f32_e32 v183, v182, v168
	v_add_f32_e32 v168, v178, v179
	v_mul_f32_e32 v180, v182, v168
	v_mov_b32_e32 v178, v117
	v_mov_b32_e32 v179, v97
	v_mov_b32_e32 v168, v173
	v_pk_mul_f32 v[172:173], v[178:179], v[168:169]
	s_nop 0
	v_sub_f32_e32 v172, v172, v173
	v_mul_f32_e32 v178, v182, v172
	v_mov_b32_e32 v172, v97
	v_mov_b32_e32 v173, v117
	v_pk_mul_f32 v[168:169], v[172:173], v[168:169]
	v_mov_b32_e32 v172, v174
	v_add_f32_e32 v168, v168, v169
	v_mul_f32_e32 v179, v182, v168
	v_mov_b32_e32 v168, v118
	v_mov_b32_e32 v169, v98
	v_mov_b32_e32 v173, v170
	v_pk_mul_f32 v[168:169], v[168:169], v[172:173]
	v_mov_b32_e32 v170, v175
	v_sub_f32_e32 v168, v168, v169
	v_mul_f32_e32 v174, v182, v168
	v_mov_b32_e32 v168, v98
	v_mov_b32_e32 v169, v118
	v_pk_mul_f32 v[168:169], v[168:169], v[172:173]
	s_nop 0
	v_add_f32_e32 v168, v168, v169
	v_mul_f32_e32 v172, v182, v168
	v_mov_b32_e32 v168, v119
	v_mov_b32_e32 v169, v99
	v_pk_mul_f32 v[168:169], v[168:169], v[170:171]
	s_nop 0
	v_sub_f32_e32 v168, v168, v169
	v_mul_f32_e32 v173, v182, v168
	v_mov_b32_e32 v168, v99
	v_mov_b32_e32 v169, v119
	v_pk_mul_f32 v[168:169], v[168:169], v[170:171]
	v_mov_b32_e32 v170, v164
	v_add_f32_e32 v168, v168, v169
	v_mul_f32_e32 v175, v182, v168
	v_mov_b32_e32 v168, v108
	v_mov_b32_e32 v169, v88
	v_mov_b32_e32 v171, v160
	v_pk_mul_f32 v[168:169], v[168:169], v[170:171]
	s_nop 0
	v_sub_f32_e32 v160, v168, v169
	v_mov_b32_e32 v168, v88
	v_mov_b32_e32 v169, v108
	v_pk_mul_f32 v[168:169], v[168:169], v[170:171]
	v_mul_f32_e32 v181, v182, v160
	v_add_f32_e32 v160, v168, v169
	v_mul_f32_e32 v170, v182, v160
	v_mov_b32_e32 v168, v109
	v_mov_b32_e32 v169, v89
	v_mov_b32_e32 v160, v165
	v_pk_mul_f32 v[164:165], v[168:169], v[160:161]
	s_nop 0
	v_sub_f32_e32 v164, v164, v165
	v_mul_f32_e32 v168, v182, v164
	v_mov_b32_e32 v164, v89
	v_mov_b32_e32 v165, v109
	v_pk_mul_f32 v[160:161], v[164:165], v[160:161]
	v_mov_b32_e32 v164, v166
	v_add_f32_e32 v160, v160, v161
	v_mul_f32_e32 v169, v182, v160
	v_mov_b32_e32 v160, v110
	v_mov_b32_e32 v161, v90
	v_mov_b32_e32 v165, v162
	v_pk_mul_f32 v[160:161], v[160:161], v[164:165]
	v_mov_b32_e32 v162, v167
	v_sub_f32_e32 v160, v160, v161
	v_mul_f32_e32 v166, v182, v160
	v_mov_b32_e32 v160, v90
	v_mov_b32_e32 v161, v110
	v_pk_mul_f32 v[160:161], v[160:161], v[164:165]
	s_nop 0
	v_add_f32_e32 v160, v160, v161
	v_mul_f32_e32 v171, v182, v160
	v_mov_b32_e32 v160, v111
	v_mov_b32_e32 v161, v91
	v_pk_mul_f32 v[160:161], v[160:161], v[162:163]
	s_nop 0
	v_sub_f32_e32 v160, v160, v161
	v_mul_f32_e32 v164, v182, v160
	v_mov_b32_e32 v160, v91
	v_mov_b32_e32 v161, v111
	v_pk_mul_f32 v[160:161], v[160:161], v[162:163]
	s_nop 0
	v_add_f32_e32 v160, v160, v161
	v_mul_f32_e32 v167, v182, v160
	v_cvt_pk_bf16_f32 v160, v183, v178
	v_cvt_pk_bf16_f32 v161, v174, v173
	v_cvt_pk_bf16_f32 v162, v181, v168
	v_cvt_pk_bf16_f32 v163, v166, v164
	v_cvt_pk_bf16_f32 v164, v180, v179
	v_cvt_pk_bf16_f32 v165, v172, v175
	v_cvt_pk_bf16_f32 v166, v170, v169
	v_lshlrev_b64 v[168:169], 12, v[226:227]
	v_lshl_add_u64 v[168:169], v[230:231], 0, v[168:169]
	v_cvt_pk_bf16_f32 v167, v171, v167
	global_store_dwordx4 v[168:169], v[160:163], off
	global_store_dwordx4 v[168:169], v[164:167], off offset:256
	s_nop 0
	v_bitop3_b32 v160, v228, s4, 32 bitop3:0xc8
	v_add_u32_e32 v160, 1, v160
	v_cvt_f32_ubyte0_e32 v160, v160
	v_mul_f32_e64 v161, v241, -v160
	v_cmp_gt_f32_e64 s[4:5], s7, v161
	v_mov_b32_e32 v163, v152
	s_nop 0
	v_cndmask_b32_e64 v162, 0, v234, s[4:5]
	v_fma_f32 v160, v241, -v160, v162
	v_exp_f32_e32 v160, v160
	v_cndmask_b32_e64 v161, 0, v235, s[4:5]
	v_mov_b32_e32 v162, v156
	s_movk_i32 s4, 0x7f
	v_ldexp_f32 v160, v160, v161
	v_mul_f32_e32 v160, 0x3d800000, v160
	v_cndmask_b32_e32 v164, 1.0, v160, vcc
	v_mov_b32_e32 v160, v100
	v_mov_b32_e32 v161, v80
	v_pk_mul_f32 v[160:161], v[160:161], v[162:163]
	s_nop 0
	v_sub_f32_e32 v152, v160, v161
	v_mov_b32_e32 v160, v80
	v_mov_b32_e32 v161, v100
	v_pk_mul_f32 v[160:161], v[160:161], v[162:163]
	v_mul_f32_e32 v165, v164, v152
	v_add_f32_e32 v152, v160, v161
	v_mul_f32_e32 v162, v164, v152
	v_mov_b32_e32 v160, v101
	v_mov_b32_e32 v161, v81
	v_mov_b32_e32 v152, v157
	v_pk_mul_f32 v[156:157], v[160:161], v[152:153]
	s_nop 0
	v_sub_f32_e32 v156, v156, v157
	v_mul_f32_e32 v160, v164, v156
	v_mov_b32_e32 v156, v81
	v_mov_b32_e32 v157, v101
	v_pk_mul_f32 v[152:153], v[156:157], v[152:153]
	v_mov_b32_e32 v156, v158
	v_add_f32_e32 v152, v152, v153
	v_mul_f32_e32 v161, v164, v152
	v_mov_b32_e32 v152, v102
	v_mov_b32_e32 v153, v82
	v_mov_b32_e32 v157, v154
	v_pk_mul_f32 v[152:153], v[152:153], v[156:157]
	v_mov_b32_e32 v154, v159
	v_sub_f32_e32 v152, v152, v153
	v_mul_f32_e32 v158, v164, v152
	v_mov_b32_e32 v152, v82
	v_mov_b32_e32 v153, v102
	v_pk_mul_f32 v[152:153], v[152:153], v[156:157]
	s_nop 0
	v_add_f32_e32 v152, v152, v153
	v_mul_f32_e32 v156, v164, v152
	v_mov_b32_e32 v152, v103
	v_mov_b32_e32 v153, v83
	v_pk_mul_f32 v[152:153], v[152:153], v[154:155]
	s_nop 0
	v_sub_f32_e32 v152, v152, v153
	v_mul_f32_e32 v157, v164, v152
	v_mov_b32_e32 v152, v83
	v_mov_b32_e32 v153, v103
	v_pk_mul_f32 v[152:153], v[152:153], v[154:155]
	v_mov_b32_e32 v154, v148
	v_add_f32_e32 v152, v152, v153
	v_mul_f32_e32 v159, v164, v152
	v_mov_b32_e32 v152, v92
	v_mov_b32_e32 v153, v72
	v_mov_b32_e32 v155, v144
	v_pk_mul_f32 v[152:153], v[152:153], v[154:155]
	s_nop 0
	v_sub_f32_e32 v144, v152, v153
	v_mov_b32_e32 v152, v72
	v_mov_b32_e32 v153, v92
	v_pk_mul_f32 v[152:153], v[152:153], v[154:155]
	v_mul_f32_e32 v163, v164, v144
	v_add_f32_e32 v144, v152, v153
	v_mul_f32_e32 v154, v164, v144
	v_mov_b32_e32 v152, v93
	v_mov_b32_e32 v153, v73
	v_mov_b32_e32 v144, v149
	v_pk_mul_f32 v[148:149], v[152:153], v[144:145]
	s_nop 0
	v_sub_f32_e32 v148, v148, v149
	v_mul_f32_e32 v152, v164, v148
	v_mov_b32_e32 v148, v73
	v_mov_b32_e32 v149, v93
	v_pk_mul_f32 v[144:145], v[148:149], v[144:145]
	v_mov_b32_e32 v148, v150
	v_add_f32_e32 v144, v144, v145
	v_mul_f32_e32 v153, v164, v144
	v_mov_b32_e32 v144, v94
	v_mov_b32_e32 v145, v74
	v_mov_b32_e32 v149, v146
	v_pk_mul_f32 v[144:145], v[144:145], v[148:149]
	v_mov_b32_e32 v146, v151
	v_sub_f32_e32 v144, v144, v145
	v_mul_f32_e32 v150, v164, v144
	v_mov_b32_e32 v144, v74
	v_mov_b32_e32 v145, v94
	v_pk_mul_f32 v[144:145], v[144:145], v[148:149]
	s_nop 0
	v_add_f32_e32 v144, v144, v145
	v_mul_f32_e32 v155, v164, v144
	v_mov_b32_e32 v144, v95
	v_mov_b32_e32 v145, v75
	v_pk_mul_f32 v[144:145], v[144:145], v[146:147]
	s_nop 0
	v_sub_f32_e32 v144, v144, v145
	v_mul_f32_e32 v148, v164, v144
	v_mov_b32_e32 v144, v75
	v_mov_b32_e32 v145, v95
	v_pk_mul_f32 v[144:145], v[144:145], v[146:147]
	s_nop 0
	v_add_f32_e32 v144, v144, v145
	v_mul_f32_e32 v151, v164, v144
	v_cvt_pk_bf16_f32 v144, v165, v160
	v_cvt_pk_bf16_f32 v145, v158, v157
	v_cvt_pk_bf16_f32 v146, v163, v152
	v_cvt_pk_bf16_f32 v147, v150, v148
	v_cvt_pk_bf16_f32 v148, v162, v161
	v_cvt_pk_bf16_f32 v149, v156, v159
	v_cvt_pk_bf16_f32 v150, v154, v153
	v_lshlrev_b64 v[152:153], 12, v[224:225]
	v_lshl_add_u64 v[152:153], v[230:231], 0, v[152:153]
	v_cvt_pk_bf16_f32 v151, v155, v151
	global_store_dwordx4 v[152:153], v[144:147], off
	global_store_dwordx4 v[152:153], v[148:151], off offset:256
	s_nop 0
	v_bitop3_b32 v144, v228, s4, 48 bitop3:0xc8
	v_add_u32_e32 v144, 1, v144
	v_cvt_f32_ubyte0_e32 v144, v144
	v_mul_f32_e64 v145, v241, -v144
	v_cmp_gt_f32_e64 s[4:5], s7, v145
	v_mov_b32_e32 v147, v136
	s_nop 0
	v_cndmask_b32_e64 v146, 0, v234, s[4:5]
	v_fma_f32 v144, v241, -v144, v146
	v_exp_f32_e32 v144, v144
	v_cndmask_b32_e64 v145, 0, v235, s[4:5]
	v_mov_b32_e32 v146, v140
	s_mov_b64 s[4:5], 0x80000
	v_ldexp_f32 v144, v144, v145
	v_mul_f32_e32 v144, 0x3d800000, v144
	v_cndmask_b32_e32 v148, 1.0, v144, vcc
	v_mov_b32_e32 v144, v84
	v_mov_b32_e32 v145, v68
	v_pk_mul_f32 v[144:145], v[144:145], v[146:147]
	s_nop 0
	v_sub_f32_e32 v136, v144, v145
	v_mov_b32_e32 v144, v68
	v_mov_b32_e32 v145, v84
	v_pk_mul_f32 v[144:145], v[144:145], v[146:147]
	v_mul_f32_e32 v149, v148, v136
	v_add_f32_e32 v136, v144, v145
	v_mul_f32_e32 v146, v148, v136
	v_mov_b32_e32 v144, v85
	v_mov_b32_e32 v145, v69
	v_mov_b32_e32 v136, v141
	v_pk_mul_f32 v[140:141], v[144:145], v[136:137]
	s_nop 0
	v_sub_f32_e32 v140, v140, v141
	v_mul_f32_e32 v144, v148, v140
	v_mov_b32_e32 v140, v69
	v_mov_b32_e32 v141, v85
	v_pk_mul_f32 v[136:137], v[140:141], v[136:137]
	v_mov_b32_e32 v140, v142
	v_add_f32_e32 v136, v136, v137
	v_mul_f32_e32 v145, v148, v136
	v_mov_b32_e32 v136, v86
	v_mov_b32_e32 v137, v70
	v_mov_b32_e32 v141, v138
	v_pk_mul_f32 v[136:137], v[136:137], v[140:141]
	v_mov_b32_e32 v138, v143
	v_sub_f32_e32 v136, v136, v137
	v_mul_f32_e32 v142, v148, v136
	v_mov_b32_e32 v136, v70
	v_mov_b32_e32 v137, v86
	v_pk_mul_f32 v[136:137], v[136:137], v[140:141]
	s_nop 0
	v_add_f32_e32 v136, v136, v137
	v_mul_f32_e32 v140, v148, v136
	v_mov_b32_e32 v136, v87
	v_mov_b32_e32 v137, v71
	v_pk_mul_f32 v[136:137], v[136:137], v[138:139]
	s_nop 0
	v_sub_f32_e32 v136, v136, v137
	v_mul_f32_e32 v141, v148, v136
	v_mov_b32_e32 v136, v71
	v_mov_b32_e32 v137, v87
	v_pk_mul_f32 v[136:137], v[136:137], v[138:139]
	v_mov_b32_e32 v138, v132
	v_add_f32_e32 v136, v136, v137
	v_mul_f32_e32 v143, v148, v136
	v_mov_b32_e32 v136, v76
	v_mov_b32_e32 v137, v64
	v_mov_b32_e32 v139, v128
	v_pk_mul_f32 v[136:137], v[136:137], v[138:139]
	s_nop 0
	v_sub_f32_e32 v128, v136, v137
	v_mov_b32_e32 v136, v64
	v_mov_b32_e32 v137, v76
	v_pk_mul_f32 v[136:137], v[136:137], v[138:139]
	v_mul_f32_e32 v147, v148, v128
	v_add_f32_e32 v128, v136, v137
	v_mul_f32_e32 v138, v148, v128
	v_mov_b32_e32 v136, v77
	v_mov_b32_e32 v137, v65
	v_mov_b32_e32 v128, v133
	v_pk_mul_f32 v[132:133], v[136:137], v[128:129]
	s_nop 0
	v_sub_f32_e32 v132, v132, v133
	v_mul_f32_e32 v136, v148, v132
	v_mov_b32_e32 v132, v65
	v_mov_b32_e32 v133, v77
	v_pk_mul_f32 v[128:129], v[132:133], v[128:129]
	v_mov_b32_e32 v132, v134
	v_add_f32_e32 v128, v128, v129
	v_mul_f32_e32 v137, v148, v128
	v_mov_b32_e32 v128, v78
	v_mov_b32_e32 v129, v66
	v_mov_b32_e32 v133, v130
	v_pk_mul_f32 v[128:129], v[128:129], v[132:133]
	v_mov_b32_e32 v130, v135
	v_sub_f32_e32 v128, v128, v129
	v_mul_f32_e32 v134, v148, v128
	v_mov_b32_e32 v128, v66
	v_mov_b32_e32 v129, v78
	v_pk_mul_f32 v[128:129], v[128:129], v[132:133]
	s_nop 0
	v_add_f32_e32 v128, v128, v129
	v_mul_f32_e32 v139, v148, v128
	v_mov_b32_e32 v128, v79
	v_mov_b32_e32 v129, v67
	v_pk_mul_f32 v[128:129], v[128:129], v[130:131]
	s_nop 0
	v_sub_f32_e32 v128, v128, v129
	v_mul_f32_e32 v132, v148, v128
	v_mov_b32_e32 v128, v67
	v_mov_b32_e32 v129, v79
	v_pk_mul_f32 v[128:129], v[128:129], v[130:131]
	s_nop 0
	v_add_f32_e32 v128, v128, v129
	v_mul_f32_e32 v135, v148, v128
	v_cvt_pk_bf16_f32 v128, v149, v144
	v_cvt_pk_bf16_f32 v129, v142, v141
	v_cvt_pk_bf16_f32 v130, v147, v136
	v_cvt_pk_bf16_f32 v131, v134, v132
	v_cvt_pk_bf16_f32 v132, v146, v145
	v_cvt_pk_bf16_f32 v133, v140, v143
	v_cvt_pk_bf16_f32 v134, v138, v137
	v_lshlrev_b64 v[136:137], 12, v[222:223]
	v_lshl_add_u64 v[136:137], v[230:231], 0, v[136:137]
	v_cvt_pk_bf16_f32 v135, v139, v135
	global_store_dwordx4 v[136:137], v[128:131], off
	global_store_dwordx4 v[136:137], v[132:135], off offset:256
	s_nop 0
	v_mov_b32_e32 v128, 0x4000
	v_lshl_add_u32 v128, v228, 7, v128
	v_and_b32_e32 v128, 0x7e780, v128
	v_lshlrev_b32_e32 v128, 2, v128
	v_mov_b32_e32 v129, v193
	v_lshl_add_u64 v[130:131], v[214:215], 0, v[128:129]
	v_lshl_add_u64 v[132:133], v[216:217], 0, v[128:129]
	global_load_dwordx4 v[168:171], v[130:131], off offset:16
	global_load_dwordx4 v[172:175], v[130:131], off
	global_load_dwordx4 v[178:181], v[132:133], off offset:16
	global_load_dwordx4 v[182:185], v[132:133], off
	v_or_b32_e32 v130, 0x2000, v128
	v_mov_b32_e32 v131, v193
	v_lshl_add_u64 v[132:133], v[214:215], 0, v[130:131]
	v_lshl_add_u64 v[130:131], v[216:217], 0, v[130:131]
	global_load_dwordx4 v[164:167], v[132:133], off offset:16
	global_load_dwordx4 v[186:189], v[132:133], off
	global_load_dwordx4 v[160:163], v[130:131], off offset:16
	global_load_dwordx4 v[196:199], v[130:131], off
	v_or_b32_e32 v130, 0x4000, v128
	v_mov_b32_e32 v131, v193
	v_lshl_add_u64 v[132:133], v[214:215], 0, v[130:131]
	v_lshl_add_u64 v[130:131], v[216:217], 0, v[130:131]
	global_load_dwordx4 v[148:151], v[132:133], off offset:16
	global_load_dwordx4 v[156:159], v[132:133], off
	global_load_dwordx4 v[144:147], v[130:131], off offset:16
	global_load_dwordx4 v[152:155], v[130:131], off
	v_or_b32_e32 v128, 0x6000, v128
	v_lshl_add_u64 v[130:131], v[214:215], 0, v[128:129]
	v_lshl_add_u64 v[136:137], v[216:217], 0, v[128:129]
	global_load_dwordx4 v[132:135], v[130:131], off offset:16
	global_load_dwordx4 v[140:143], v[130:131], off
	s_nop 0
	global_load_dwordx4 v[128:131], v[136:137], off offset:16
	s_nop 0
	global_load_dwordx4 v[136:139], v[136:137], off
	s_waitcnt vmcnt(0)
	v_mov_b32_e32 v244, v172
	v_mov_b32_e32 v245, v182
	v_pk_mul_f32 v[190:191], v[190:191], v[244:245]
	v_mov_b32_e32 v182, v173
	v_sub_f32_e32 v172, v190, v191
	v_mov_b32_e32 v190, v48
	v_mov_b32_e32 v191, v60
	v_pk_mul_f32 v[190:191], v[190:191], v[244:245]
	v_mul_f32_e32 v223, v242, v172
	v_add_f32_e32 v172, v190, v191
	v_mov_b32_e32 v190, v61
	v_mov_b32_e32 v191, v49
	v_mul_f32_e32 v225, v242, v172
	v_pk_mul_f32 v[172:173], v[190:191], v[182:183]
	s_nop 0
	v_sub_f32_e32 v172, v172, v173
	v_mul_f32_e32 v190, v242, v172
	v_mov_b32_e32 v172, v49
	v_mov_b32_e32 v173, v61
	v_pk_mul_f32 v[172:173], v[172:173], v[182:183]
	v_mov_b32_e32 v182, v174
	v_add_f32_e32 v172, v172, v173
	v_mul_f32_e32 v191, v242, v172
	v_mov_b32_e32 v172, v62
	v_mov_b32_e32 v173, v50
	v_mov_b32_e32 v183, v184
	v_pk_mul_f32 v[172:173], v[172:173], v[182:183]
	v_mov_b32_e32 v184, v175
	v_sub_f32_e32 v172, v172, v173
	v_mul_f32_e32 v243, v242, v172
	v_mov_b32_e32 v172, v50
	v_mov_b32_e32 v173, v62
	v_pk_mul_f32 v[172:173], v[172:173], v[182:183]
	v_mov_b32_e32 v174, v168
	v_add_f32_e32 v172, v172, v173
	v_mul_f32_e32 v182, v242, v172
	v_mov_b32_e32 v172, v63
	v_mov_b32_e32 v173, v51
	v_pk_mul_f32 v[172:173], v[172:173], v[184:185]
	v_mov_b32_e32 v175, v178
	v_sub_f32_e32 v172, v172, v173
	v_mul_f32_e32 v183, v242, v172
	v_mov_b32_e32 v172, v51
	v_mov_b32_e32 v173, v63
	v_pk_mul_f32 v[172:173], v[172:173], v[184:185]
	v_mov_b32_e32 v178, v169
	v_add_f32_e32 v172, v172, v173
	v_mul_f32_e32 v184, v242, v172
	v_mov_b32_e32 v172, v56
	v_mov_b32_e32 v173, v40
	v_pk_mul_f32 v[172:173], v[172:173], v[174:175]
	s_nop 0
	v_sub_f32_e32 v168, v172, v173
	v_mov_b32_e32 v172, v40
	v_mov_b32_e32 v173, v56
	v_pk_mul_f32 v[172:173], v[172:173], v[174:175]
	v_mul_f32_e32 v185, v242, v168
	v_add_f32_e32 v168, v172, v173
	v_mov_b32_e32 v172, v57
	v_mov_b32_e32 v173, v41
	v_mul_f32_e32 v174, v242, v168
	v_pk_mul_f32 v[168:169], v[172:173], v[178:179]
	v_mov_b32_e32 v172, v170
	v_sub_f32_e32 v168, v168, v169
	v_mul_f32_e32 v175, v242, v168
	v_mov_b32_e32 v168, v41
	v_mov_b32_e32 v169, v57
	v_pk_mul_f32 v[168:169], v[168:169], v[178:179]
	v_mov_b32_e32 v173, v180
	v_add_f32_e32 v168, v168, v169
	v_mul_f32_e32 v178, v242, v168
	v_mov_b32_e32 v168, v58
	v_mov_b32_e32 v169, v42
	v_pk_mul_f32 v[168:169], v[168:169], v[172:173]
	v_mov_b32_e32 v180, v171
	v_sub_f32_e32 v168, v168, v169
	v_mul_f32_e32 v179, v242, v168
	v_mov_b32_e32 v168, v42
	v_mov_b32_e32 v169, v58
	v_pk_mul_f32 v[168:169], v[168:169], v[172:173]
	s_nop 0
	v_add_f32_e32 v168, v168, v169
	v_mul_f32_e32 v244, v242, v168
	v_mov_b32_e32 v168, v59
	v_mov_b32_e32 v169, v43
	v_pk_mul_f32 v[168:169], v[168:169], v[180:181]
	s_nop 0
	v_sub_f32_e32 v168, v168, v169
	v_mul_f32_e32 v171, v242, v168
	v_mov_b32_e32 v168, v43
	v_mov_b32_e32 v169, v59
	v_pk_mul_f32 v[168:169], v[168:169], v[180:181]
	s_nop 0
	v_add_f32_e32 v168, v168, v169
	v_mul_f32_e32 v180, v242, v168
	v_cvt_pk_bf16_f32 v168, v223, v190
	v_cvt_pk_bf16_f32 v169, v243, v183
	v_cvt_pk_bf16_f32 v170, v185, v175
	v_cvt_pk_bf16_f32 v171, v179, v171
	v_cvt_pk_bf16_f32 v172, v225, v191
	v_cvt_pk_bf16_f32 v173, v182, v184
	v_cvt_pk_bf16_f32 v174, v174, v178
	v_lshl_add_u64 v[178:179], v[176:177], 0, s[4:5]
	s_mov_b32 s4, 0x80000
	v_add_co_u32_e64 v176, s[4:5], s4, v176
	v_cvt_pk_bf16_f32 v175, v244, v180
	s_nop 1
	v_addc_co_u32_e64 v177, s[4:5], 0, v177, s[4:5]
	global_store_dwordx4 v[176:177], v[168:171], off
	global_store_dwordx4 v[178:179], v[172:175], off offset:256
	s_nop 0
	v_add_u32_e32 v168, 0x90, v228
	v_and_b32_e32 v169, 0x5f, v168
	v_add_u32_e32 v169, 1, v169
	v_cvt_f32_ubyte0_e32 v169, v169
	v_mul_f32_e64 v170, v241, -v169
	v_cmp_gt_f32_e64 s[4:5], s7, v170
	v_mov_b32_e32 v171, v32
	v_mov_b32_e32 v172, v186
	v_cndmask_b32_e64 v170, 0, v234, s[4:5]
	v_fma_f32 v169, v241, -v169, v170
	v_exp_f32_e32 v169, v169
	v_cndmask_b32_e64 v170, 0, v235, s[4:5]
	v_mov_b32_e32 v173, v196
	v_mov_b32_e32 v196, v187
	v_ldexp_f32 v169, v169, v170
	v_mov_b32_e32 v170, v52
	v_mul_f32_e32 v169, 0x3d800000, v169
	v_pk_mul_f32 v[170:171], v[170:171], v[172:173]
	v_cndmask_b32_e32 v169, 1.0, v169, vcc
	v_sub_f32_e32 v170, v170, v171
	v_mul_f32_e32 v174, v169, v170
	v_mov_b32_e32 v170, v32
	v_mov_b32_e32 v171, v52
	v_pk_mul_f32 v[170:171], v[170:171], v[172:173]
	v_mov_b32_e32 v172, v188
	v_add_f32_e32 v170, v170, v171
	v_mul_f32_e32 v175, v169, v170
	v_mov_b32_e32 v170, v53
	v_mov_b32_e32 v171, v33
	v_pk_mul_f32 v[170:171], v[170:171], v[196:197]
	v_mov_b32_e32 v173, v198
	v_sub_f32_e32 v170, v170, v171
	v_mul_f32_e32 v176, v169, v170
	v_mov_b32_e32 v170, v33
	v_mov_b32_e32 v171, v53
	v_pk_mul_f32 v[170:171], v[170:171], v[196:197]
	v_mov_b32_e32 v198, v189
	v_add_f32_e32 v170, v170, v171
	v_mul_f32_e32 v177, v169, v170
	v_mov_b32_e32 v170, v54
	v_mov_b32_e32 v171, v34
	v_pk_mul_f32 v[170:171], v[170:171], v[172:173]
	s_nop 0
	v_sub_f32_e32 v170, v170, v171
	v_mul_f32_e32 v178, v169, v170
	v_mov_b32_e32 v170, v34
	v_mov_b32_e32 v171, v54
	v_pk_mul_f32 v[170:171], v[170:171], v[172:173]
	v_mov_b32_e32 v172, v164
	v_add_f32_e32 v170, v170, v171
	v_mul_f32_e32 v179, v169, v170
	v_mov_b32_e32 v170, v55
	v_mov_b32_e32 v171, v35
	v_pk_mul_f32 v[170:171], v[170:171], v[198:199]
	v_mov_b32_e32 v173, v160
	v_sub_f32_e32 v170, v170, v171
	v_mul_f32_e32 v180, v169, v170
	v_mov_b32_e32 v170, v35
	v_mov_b32_e32 v171, v55
	v_pk_mul_f32 v[170:171], v[170:171], v[198:199]
	s_nop 0
	v_add_f32_e32 v170, v170, v171
	v_mul_f32_e32 v181, v169, v170
	v_mov_b32_e32 v170, v44
	v_mov_b32_e32 v171, v24
	v_pk_mul_f32 v[170:171], v[170:171], v[172:173]
	s_nop 0
	v_sub_f32_e32 v160, v170, v171
	v_mov_b32_e32 v170, v24
	v_mov_b32_e32 v171, v44
	v_pk_mul_f32 v[170:171], v[170:171], v[172:173]
	v_mul_f32_e32 v182, v169, v160
	v_add_f32_e32 v160, v170, v171
	v_mul_f32_e32 v172, v169, v160
	v_mov_b32_e32 v170, v45
	v_mov_b32_e32 v171, v25
	v_mov_b32_e32 v160, v165
	v_pk_mul_f32 v[164:165], v[170:171], v[160:161]
	s_nop 0
	v_sub_f32_e32 v164, v164, v165
	v_mul_f32_e32 v170, v169, v164
	v_mov_b32_e32 v164, v25
	v_mov_b32_e32 v165, v45
	v_pk_mul_f32 v[160:161], v[164:165], v[160:161]
	v_mov_b32_e32 v164, v166
	v_add_f32_e32 v160, v160, v161
	v_mul_f32_e32 v171, v169, v160
	v_mov_b32_e32 v160, v46
	v_mov_b32_e32 v161, v26
	v_mov_b32_e32 v165, v162
	v_pk_mul_f32 v[160:161], v[160:161], v[164:165]
	v_mov_b32_e32 v162, v167
	v_sub_f32_e32 v160, v160, v161
	v_mul_f32_e32 v166, v169, v160
	v_mov_b32_e32 v160, v26
	v_mov_b32_e32 v161, v46
	v_pk_mul_f32 v[160:161], v[160:161], v[164:165]
	s_nop 0
	v_add_f32_e32 v160, v160, v161
	v_mul_f32_e32 v173, v169, v160
	v_mov_b32_e32 v160, v47
	v_mov_b32_e32 v161, v27
	v_pk_mul_f32 v[160:161], v[160:161], v[162:163]
	s_nop 0
	v_sub_f32_e32 v160, v160, v161
	v_mul_f32_e32 v164, v169, v160
	v_mov_b32_e32 v160, v27
	v_mov_b32_e32 v161, v47
	v_pk_mul_f32 v[160:161], v[160:161], v[162:163]
	s_nop 0
	v_add_f32_e32 v160, v160, v161
	v_mul_f32_e32 v167, v169, v160
	v_ashrrev_i32_e32 v169, 31, v168
	v_lshlrev_b64 v[168:169], 12, v[168:169]
	v_cvt_pk_bf16_f32 v160, v174, v176
	v_cvt_pk_bf16_f32 v161, v178, v180
	v_cvt_pk_bf16_f32 v162, v182, v170
	v_cvt_pk_bf16_f32 v163, v166, v164
	v_lshl_add_u64 v[168:169], v[230:231], 0, v[168:169]
	v_cvt_pk_bf16_f32 v164, v175, v177
	v_cvt_pk_bf16_f32 v165, v179, v181
	v_cvt_pk_bf16_f32 v166, v172, v171
	v_cvt_pk_bf16_f32 v167, v173, v167
	global_store_dwordx4 v[168:169], v[160:163], off
	global_store_dwordx4 v[168:169], v[164:167], off offset:256
	s_nop 0
	v_add_u32_e32 v160, 0xa0, v228
	v_and_b32_e32 v161, 0x6f, v160
	v_add_u32_e32 v161, 1, v161
	v_cvt_f32_ubyte0_e32 v161, v161
	v_mul_f32_e64 v162, v241, -v161
	v_cmp_gt_f32_e64 s[4:5], s7, v162
	v_mov_b32_e32 v163, v16
	v_mov_b32_e32 v164, v156
	v_cndmask_b32_e64 v162, 0, v234, s[4:5]
	v_fma_f32 v161, v241, -v161, v162
	v_exp_f32_e32 v161, v161
	v_cndmask_b32_e64 v162, 0, v235, s[4:5]
	v_mov_b32_e32 v165, v152
	v_ldexp_f32 v161, v161, v162
	v_mov_b32_e32 v162, v36
	v_pk_mul_f32 v[162:163], v[162:163], v[164:165]
	v_mul_f32_e32 v161, 0x3d800000, v161
	v_sub_f32_e32 v152, v162, v163
	v_mov_b32_e32 v162, v16
	v_mov_b32_e32 v163, v36
	v_cndmask_b32_e32 v161, 1.0, v161, vcc
	v_pk_mul_f32 v[162:163], v[162:163], v[164:165]
	v_mul_f32_e32 v166, v161, v152
	v_add_f32_e32 v152, v162, v163
	v_mul_f32_e32 v164, v161, v152
	v_mov_b32_e32 v162, v37
	v_mov_b32_e32 v163, v17
	v_mov_b32_e32 v152, v157
	v_pk_mul_f32 v[156:157], v[162:163], v[152:153]
	s_nop 0
	v_sub_f32_e32 v156, v156, v157
	v_mul_f32_e32 v162, v161, v156
	v_mov_b32_e32 v156, v17
	v_mov_b32_e32 v157, v37
	v_pk_mul_f32 v[152:153], v[156:157], v[152:153]
	v_mov_b32_e32 v156, v158
	v_add_f32_e32 v152, v152, v153
	v_mul_f32_e32 v163, v161, v152
	v_mov_b32_e32 v152, v38
	v_mov_b32_e32 v153, v18
	v_mov_b32_e32 v157, v154
	v_pk_mul_f32 v[152:153], v[152:153], v[156:157]
	v_mov_b32_e32 v154, v159
	v_sub_f32_e32 v152, v152, v153
	v_mul_f32_e32 v158, v161, v152
	v_mov_b32_e32 v152, v18
	v_mov_b32_e32 v153, v38
	v_pk_mul_f32 v[152:153], v[152:153], v[156:157]
	s_nop 0
	v_add_f32_e32 v152, v152, v153
	v_mul_f32_e32 v156, v161, v152
	v_mov_b32_e32 v152, v39
	v_mov_b32_e32 v153, v19
	v_pk_mul_f32 v[152:153], v[152:153], v[154:155]
	s_nop 0
	v_sub_f32_e32 v152, v152, v153
	v_mul_f32_e32 v157, v161, v152
	v_mov_b32_e32 v152, v19
	v_mov_b32_e32 v153, v39
	v_pk_mul_f32 v[152:153], v[152:153], v[154:155]
	v_mov_b32_e32 v154, v148
	v_add_f32_e32 v152, v152, v153
	v_mul_f32_e32 v159, v161, v152
	v_mov_b32_e32 v152, v28
	v_mov_b32_e32 v153, v8
	v_mov_b32_e32 v155, v144
	v_pk_mul_f32 v[152:153], v[152:153], v[154:155]
	s_nop 0
	v_sub_f32_e32 v144, v152, v153
	v_mov_b32_e32 v152, v8
	v_mov_b32_e32 v153, v28
	v_pk_mul_f32 v[152:153], v[152:153], v[154:155]
	v_mul_f32_e32 v165, v161, v144
	v_add_f32_e32 v144, v152, v153
	v_mul_f32_e32 v154, v161, v144
	v_mov_b32_e32 v152, v29
	v_mov_b32_e32 v153, v9
	v_mov_b32_e32 v144, v149
	v_pk_mul_f32 v[148:149], v[152:153], v[144:145]
	s_nop 0
	v_sub_f32_e32 v148, v148, v149
	v_mul_f32_e32 v152, v161, v148
	v_mov_b32_e32 v148, v9
	v_mov_b32_e32 v149, v29
	v_pk_mul_f32 v[144:145], v[148:149], v[144:145]
	v_mov_b32_e32 v148, v150
	v_add_f32_e32 v144, v144, v145
	v_mul_f32_e32 v153, v161, v144
	v_mov_b32_e32 v144, v30
	v_mov_b32_e32 v145, v10
	v_mov_b32_e32 v149, v146
	v_pk_mul_f32 v[144:145], v[144:145], v[148:149]
	v_mov_b32_e32 v146, v151
	v_sub_f32_e32 v144, v144, v145
	v_mul_f32_e32 v150, v161, v144
	v_mov_b32_e32 v144, v10
	v_mov_b32_e32 v145, v30
	v_pk_mul_f32 v[144:145], v[144:145], v[148:149]
	s_nop 0
	v_add_f32_e32 v144, v144, v145
	v_mul_f32_e32 v155, v161, v144
	v_mov_b32_e32 v144, v31
	v_mov_b32_e32 v145, v11
	v_pk_mul_f32 v[144:145], v[144:145], v[146:147]
	s_nop 0
	v_sub_f32_e32 v144, v144, v145
	v_mul_f32_e32 v148, v161, v144
	v_mov_b32_e32 v144, v11
	v_mov_b32_e32 v145, v31
	v_pk_mul_f32 v[144:145], v[144:145], v[146:147]
	s_nop 0
	v_add_f32_e32 v144, v144, v145
	v_mul_f32_e32 v151, v161, v144
	v_ashrrev_i32_e32 v161, 31, v160
	v_cvt_pk_bf16_f32 v144, v166, v162
	v_cvt_pk_bf16_f32 v145, v158, v157
	v_cvt_pk_bf16_f32 v146, v165, v152
	v_cvt_pk_bf16_f32 v147, v150, v148
	v_cvt_pk_bf16_f32 v148, v164, v163
	v_cvt_pk_bf16_f32 v149, v156, v159
	v_cvt_pk_bf16_f32 v150, v154, v153
	v_lshlrev_b64 v[152:153], 12, v[160:161]
	v_lshl_add_u64 v[152:153], v[230:231], 0, v[152:153]
	v_cvt_pk_bf16_f32 v151, v155, v151
	global_store_dwordx4 v[152:153], v[144:147], off
	global_store_dwordx4 v[152:153], v[148:151], off offset:256
	s_nop 0
	v_add_u32_e32 v144, 0xb0, v228
	v_and_b32_e32 v145, 0x7f, v144
	v_add_u32_e32 v145, 1, v145
	v_cvt_f32_ubyte0_e32 v145, v145
	v_mul_f32_e64 v146, v241, -v145
	v_cmp_gt_f32_e64 s[4:5], s7, v146
	v_mov_b32_e32 v147, v4
	v_mov_b32_e32 v148, v140
	v_cndmask_b32_e64 v146, 0, v234, s[4:5]
	v_fma_f32 v145, v241, -v145, v146
	v_exp_f32_e32 v145, v145
	v_cndmask_b32_e64 v146, 0, v235, s[4:5]
	v_mov_b32_e32 v149, v136
	s_mov_b64 s[4:5], 0
	v_ldexp_f32 v145, v145, v146
	v_mov_b32_e32 v146, v20
	v_pk_mul_f32 v[146:147], v[146:147], v[148:149]
	v_mul_f32_e32 v145, 0x3d800000, v145
	v_sub_f32_e32 v136, v146, v147
	v_mov_b32_e32 v146, v4
	v_mov_b32_e32 v147, v20
	v_cndmask_b32_e32 v145, 1.0, v145, vcc
	v_pk_mul_f32 v[146:147], v[146:147], v[148:149]
	v_mul_f32_e32 v150, v145, v136
	v_add_f32_e32 v136, v146, v147
	v_mul_f32_e32 v148, v145, v136
	v_mov_b32_e32 v146, v21
	v_mov_b32_e32 v147, v5
	v_mov_b32_e32 v136, v141
	v_pk_mul_f32 v[140:141], v[146:147], v[136:137]
	s_nop 0
	v_sub_f32_e32 v140, v140, v141
	v_mul_f32_e32 v146, v145, v140
	v_mov_b32_e32 v140, v5
	v_mov_b32_e32 v141, v21
	v_pk_mul_f32 v[136:137], v[140:141], v[136:137]
	v_mov_b32_e32 v140, v142
	v_add_f32_e32 v136, v136, v137
	v_mul_f32_e32 v147, v145, v136
	v_mov_b32_e32 v136, v22
	v_mov_b32_e32 v137, v6
	v_mov_b32_e32 v141, v138
	v_pk_mul_f32 v[136:137], v[136:137], v[140:141]
	v_mov_b32_e32 v138, v143
	v_sub_f32_e32 v136, v136, v137
	v_mul_f32_e32 v142, v145, v136
	v_mov_b32_e32 v136, v6
	v_mov_b32_e32 v137, v22
	v_pk_mul_f32 v[136:137], v[136:137], v[140:141]
	s_nop 0
	v_add_f32_e32 v136, v136, v137
	v_mul_f32_e32 v140, v145, v136
	v_mov_b32_e32 v136, v23
	v_mov_b32_e32 v137, v7
	v_pk_mul_f32 v[136:137], v[136:137], v[138:139]
	s_nop 0
	v_sub_f32_e32 v136, v136, v137
	v_mul_f32_e32 v141, v145, v136
	v_mov_b32_e32 v136, v7
	v_mov_b32_e32 v137, v23
	v_pk_mul_f32 v[136:137], v[136:137], v[138:139]
	v_mov_b32_e32 v138, v132
	v_add_f32_e32 v136, v136, v137
	v_mul_f32_e32 v143, v145, v136
	v_mov_b32_e32 v136, v12
	v_mov_b32_e32 v137, v0
	v_mov_b32_e32 v139, v128
	v_pk_mul_f32 v[136:137], v[136:137], v[138:139]
	s_nop 0
	v_sub_f32_e32 v128, v136, v137
	v_mov_b32_e32 v136, v0
	v_mov_b32_e32 v137, v12
	v_pk_mul_f32 v[136:137], v[136:137], v[138:139]
	v_mul_f32_e32 v149, v145, v128
	v_add_f32_e32 v128, v136, v137
	v_mul_f32_e32 v138, v145, v128
	v_mov_b32_e32 v136, v13
	v_mov_b32_e32 v137, v1
	v_mov_b32_e32 v128, v133
	v_pk_mul_f32 v[132:133], v[136:137], v[128:129]
	s_nop 0
	v_sub_f32_e32 v132, v132, v133
	v_mul_f32_e32 v136, v145, v132
	v_mov_b32_e32 v132, v1
	v_mov_b32_e32 v133, v13
	v_pk_mul_f32 v[128:129], v[132:133], v[128:129]
	v_mov_b32_e32 v132, v134
	v_add_f32_e32 v128, v128, v129
	v_mul_f32_e32 v139, v145, v128
	v_mov_b32_e32 v128, v14
	v_mov_b32_e32 v129, v2
	v_mov_b32_e32 v133, v130
	v_pk_mul_f32 v[128:129], v[128:129], v[132:133]
	v_mov_b32_e32 v130, v135
	v_sub_f32_e32 v128, v128, v129
	v_mul_f32_e32 v137, v145, v128
	v_mov_b32_e32 v128, v2
	v_mov_b32_e32 v129, v14
	v_pk_mul_f32 v[128:129], v[128:129], v[132:133]
	v_cvt_pk_bf16_f32 v134, v150, v146
	v_cvt_pk_bf16_f32 v135, v142, v141
	v_cvt_pk_bf16_f32 v136, v149, v136
	s_nop 0
	v_add_f32_e32 v128, v128, v129
	v_mul_f32_e32 v132, v145, v128
	v_mov_b32_e32 v128, v15
	v_mov_b32_e32 v129, v3
	v_pk_mul_f32 v[128:129], v[128:129], v[130:131]
	s_nop 0
	v_sub_f32_e32 v128, v128, v129
	v_mul_f32_e32 v133, v145, v128
	v_mov_b32_e32 v128, v3
	v_mov_b32_e32 v129, v15
	v_pk_mul_f32 v[128:129], v[128:129], v[130:131]
	v_cvt_pk_bf16_f32 v137, v137, v133
	s_nop 0
	v_add_f32_e32 v128, v128, v129
	v_mul_f32_e32 v131, v145, v128
	v_ashrrev_i32_e32 v145, 31, v144
	v_cvt_pk_bf16_f32 v128, v148, v147
	v_cvt_pk_bf16_f32 v129, v140, v143
	v_cvt_pk_bf16_f32 v130, v138, v139
	v_cvt_pk_bf16_f32 v131, v132, v131
	v_lshlrev_b64 v[132:133], 12, v[144:145]
	v_lshl_add_u64 v[132:133], v[230:231], 0, v[132:133]
	global_store_dwordx4 v[132:133], v[134:137], off

.LBB0_216:
	v_mov_b64_e32 v[0:1], 0x1600
	s_ashr_i32 s7, s6, 31
	v_cmp_lt_i64_e32 vcc, s[8:9], v[0:1]
	s_lshl_b64 s[8:9], s[6:7], 20
	s_add_u32 s8, s22, s8
	s_addc_u32 s9, s23, s9
	s_and_b64 s[10:11], vcc, exec
	s_cselect_b32 s7, s9, s15
	s_cselect_b32 s36, s8, s14
	s_ashr_i32 s5, s4, 31
	s_lshl_b64 s[10:11], s[4:5], 20
	s_add_u32 s10, s24, s10
	s_addc_u32 s11, s25, s11
	s_and_b64 s[18:19], vcc, exec
	s_cselect_b32 s5, s11, s17
	s_cselect_b32 s37, s10, s16
	s_add_u32 s14, s14, 0x80080
	s_addc_u32 s15, s15, 0
	s_add_u32 s38, s16, 0x100
	v_mov_b32_e32 v0, 0
	s_addc_u32 s39, s17, 0
	s_mov_b32 s40, -2
	v_mov_b32_e32 v1, v0
	v_mov_b32_e32 v2, v0
	v_mov_b32_e32 v3, v0
	v_mov_b32_e32 v8, v0
	v_mov_b32_e32 v9, v0
	v_mov_b32_e32 v10, v0
	v_mov_b32_e32 v11, v0
	v_mov_b32_e32 v16, v0
	v_mov_b32_e32 v17, v0
	v_mov_b32_e32 v18, v0
	v_mov_b32_e32 v19, v0
	v_mov_b32_e32 v24, v0
	v_mov_b32_e32 v25, v0
	v_mov_b32_e32 v26, v0
	v_mov_b32_e32 v27, v0
	v_mov_b32_e32 v32, v0
	v_mov_b32_e32 v33, v0
	v_mov_b32_e32 v34, v0
	v_mov_b32_e32 v35, v0
	v_mov_b32_e32 v40, v0
	v_mov_b32_e32 v41, v0
	v_mov_b32_e32 v42, v0
	v_mov_b32_e32 v43, v0
	v_mov_b32_e32 v48, v0
	v_mov_b32_e32 v49, v0
	v_mov_b32_e32 v50, v0
	v_mov_b32_e32 v51, v0
	v_mov_b32_e32 v56, v0
	v_mov_b32_e32 v57, v0
	v_mov_b32_e32 v58, v0
	v_mov_b32_e32 v59, v0
	v_mov_b32_e32 v4, v0
	v_mov_b32_e32 v5, v0
	v_mov_b32_e32 v6, v0
	v_mov_b32_e32 v7, v0
	v_mov_b32_e32 v12, v0
	v_mov_b32_e32 v13, v0
	v_mov_b32_e32 v14, v0
	v_mov_b32_e32 v15, v0
	v_mov_b32_e32 v20, v0
	v_mov_b32_e32 v21, v0
	v_mov_b32_e32 v22, v0
	v_mov_b32_e32 v23, v0
	v_mov_b32_e32 v28, v0
	v_mov_b32_e32 v29, v0
	v_mov_b32_e32 v30, v0
	v_mov_b32_e32 v31, v0
	v_mov_b32_e32 v36, v0
	v_mov_b32_e32 v37, v0
	v_mov_b32_e32 v38, v0
	v_mov_b32_e32 v39, v0
	v_mov_b32_e32 v44, v0
	v_mov_b32_e32 v45, v0
	v_mov_b32_e32 v46, v0
	v_mov_b32_e32 v47, v0
	v_mov_b32_e32 v52, v0
	v_mov_b32_e32 v53, v0
	v_mov_b32_e32 v54, v0
	v_mov_b32_e32 v55, v0
	v_mov_b32_e32 v60, v0
	v_mov_b32_e32 v61, v0
	v_mov_b32_e32 v62, v0
	v_mov_b32_e32 v63, v0
	v_mov_b32_e32 v64, v0
	v_mov_b32_e32 v65, v0
	v_mov_b32_e32 v66, v0
	v_mov_b32_e32 v67, v0
	v_mov_b32_e32 v72, v0
	v_mov_b32_e32 v73, v0
	v_mov_b32_e32 v74, v0
	v_mov_b32_e32 v75, v0
	v_mov_b32_e32 v80, v0
	v_mov_b32_e32 v81, v0
	v_mov_b32_e32 v82, v0
	v_mov_b32_e32 v83, v0
	v_mov_b32_e32 v88, v0
	v_mov_b32_e32 v89, v0
	v_mov_b32_e32 v90, v0
	v_mov_b32_e32 v91, v0
	v_mov_b32_e32 v96, v0
	v_mov_b32_e32 v97, v0
	v_mov_b32_e32 v98, v0
	v_mov_b32_e32 v99, v0
	v_mov_b32_e32 v104, v0
	v_mov_b32_e32 v105, v0
	v_mov_b32_e32 v106, v0
	v_mov_b32_e32 v107, v0
	v_mov_b32_e32 v112, v0
	v_mov_b32_e32 v113, v0
	v_mov_b32_e32 v114, v0
	v_mov_b32_e32 v115, v0
	v_mov_b32_e32 v120, v0
	v_mov_b32_e32 v121, v0
	v_mov_b32_e32 v122, v0
	v_mov_b32_e32 v123, v0
	v_mov_b32_e32 v68, v0
	v_mov_b32_e32 v69, v0
	v_mov_b32_e32 v70, v0
	v_mov_b32_e32 v71, v0
	v_mov_b32_e32 v76, v0
	v_mov_b32_e32 v77, v0
	v_mov_b32_e32 v78, v0
	v_mov_b32_e32 v79, v0
	v_mov_b32_e32 v84, v0
	v_mov_b32_e32 v85, v0
	v_mov_b32_e32 v86, v0
	v_mov_b32_e32 v87, v0
	v_mov_b32_e32 v92, v0
	v_mov_b32_e32 v93, v0
	v_mov_b32_e32 v94, v0
	v_mov_b32_e32 v95, v0
	v_mov_b32_e32 v100, v0
	v_mov_b32_e32 v101, v0
	v_mov_b32_e32 v102, v0
	v_mov_b32_e32 v103, v0
	v_mov_b32_e32 v108, v0
	v_mov_b32_e32 v109, v0
	v_mov_b32_e32 v110, v0
	v_mov_b32_e32 v111, v0
	v_mov_b32_e32 v116, v0
	v_mov_b32_e32 v117, v0
	v_mov_b32_e32 v118, v0
	v_mov_b32_e32 v119, v0
	v_mov_b32_e32 v124, v0
	v_mov_b32_e32 v125, v0
	v_mov_b32_e32 v126, v0
	v_mov_b32_e32 v127, v0
	s_mov_b64 s[48:49], 0x80
	v_add_u32_e32 v220, 0x10000, v141
.LBB0_217:
	s_add_u32 s16, s14, 0xfff80080
	s_addc_u32 s17, s15, -1
	s_add_i32 s41, 0, 0x10000
	ds_read_b128 v[144:147], v220 offset:0
	ds_read_b128 v[148:151], v220 offset:1024
	ds_read_b128 v[152:155], v220 offset:2048
	ds_read_b128 v[156:159], v220 offset:3072
	s_cmp_eq_u32 s40, 28
	s_cselect_b32 s19, s7, s17
	s_cselect_b32 s18, s36, s16
	s_cselect_b32 s17, s5, s39
	s_cselect_b32 s16, s37, s38
	s_add_i32 m0, s13, 0xc000
	ds_read_b128 v[160:163], v143
	ds_read_b128 v[164:167], v143 offset:1024
	ds_read_b128 v[168:171], v143 offset:2048
	ds_read_b128 v[172:175], v143 offset:3072
	ds_read_b128 v[176:179], v143 offset:4096
	ds_read_b128 v[180:183], v143 offset:5120
	ds_read_b128 v[184:187], v143 offset:6144
	ds_read_b128 v[188:191], v143 offset:7168
	global_load_lds_dwordx4 v134, s[14:15]
	s_add_i32 m0, s13, 0xe000
	s_nop 0
	global_load_lds_dwordx4 v136, s[14:15]
	s_waitcnt lgkmcnt(8)
	s_barrier
	s_waitcnt lgkmcnt(0)
	v_mfma_f32_16x16x32_bf16 v[124:127], v[144:147], v[160:163], v[124:127]
	v_mfma_f32_16x16x32_bf16 v[116:119], v[152:155], v[160:163], v[116:119]
	v_mfma_f32_16x16x32_bf16 v[108:111], v[144:147], v[168:171], v[108:111]
	v_mfma_f32_16x16x32_bf16 v[100:103], v[152:155], v[168:171], v[100:103]
	v_mfma_f32_16x16x32_bf16 v[92:95], v[144:147], v[176:179], v[92:95]
	v_mfma_f32_16x16x32_bf16 v[84:87], v[152:155], v[176:179], v[84:87]
	v_mfma_f32_16x16x32_bf16 v[76:79], v[144:147], v[184:187], v[76:79]
	v_mfma_f32_16x16x32_bf16 v[68:71], v[152:155], v[184:187], v[68:71]
	v_mfma_f32_16x16x32_bf16 v[124:127], v[148:151], v[164:167], v[124:127]
	v_mfma_f32_16x16x32_bf16 v[116:119], v[156:159], v[164:167], v[116:119]
	v_mfma_f32_16x16x32_bf16 v[108:111], v[148:151], v[172:175], v[108:111]
	v_mfma_f32_16x16x32_bf16 v[100:103], v[156:159], v[172:175], v[100:103]
	v_mfma_f32_16x16x32_bf16 v[92:95], v[148:151], v[180:183], v[92:95]
	v_mfma_f32_16x16x32_bf16 v[84:87], v[156:159], v[180:183], v[84:87]
	v_mfma_f32_16x16x32_bf16 v[76:79], v[148:151], v[188:191], v[76:79]
	v_mfma_f32_16x16x32_bf16 v[68:71], v[156:159], v[188:191], v[68:71]
	s_barrier
	s_add_i32 s44, 0, 0x14000
	s_add_i32 s41, s41, s26
	ds_read_b128 v[196:199], v220 offset:16384
	ds_read_b128 v[204:207], v220 offset:17408
	ds_read_b128 v[208:211], v220 offset:18432
	ds_read_b128 v[214:217], v220 offset:19456
	s_mov_b32 m0, s41
	s_nop 0
	global_load_lds_dwordx4 v192, s[16:17]
	s_add_i32 m0, s41, 0x2000
	s_nop 0
	global_load_lds_dwordx4 v128, s[16:17]
	s_barrier
	s_waitcnt lgkmcnt(0)
	v_mfma_f32_16x16x32_bf16 v[120:123], v[196:199], v[160:163], v[120:123]
	v_mfma_f32_16x16x32_bf16 v[112:115], v[208:211], v[160:163], v[112:115]
	v_mfma_f32_16x16x32_bf16 v[104:107], v[196:199], v[168:171], v[104:107]
	v_mfma_f32_16x16x32_bf16 v[96:99], v[208:211], v[168:171], v[96:99]
	v_mfma_f32_16x16x32_bf16 v[88:91], v[196:199], v[176:179], v[88:91]
	v_mfma_f32_16x16x32_bf16 v[80:83], v[208:211], v[176:179], v[80:83]
	v_mfma_f32_16x16x32_bf16 v[72:75], v[196:199], v[184:187], v[72:75]
	v_mfma_f32_16x16x32_bf16 v[64:67], v[208:211], v[184:187], v[64:67]
	v_mfma_f32_16x16x32_bf16 v[120:123], v[204:207], v[164:167], v[120:123]
	v_mfma_f32_16x16x32_bf16 v[112:115], v[214:217], v[164:167], v[112:115]
	v_mfma_f32_16x16x32_bf16 v[104:107], v[204:207], v[172:175], v[104:107]
	v_mfma_f32_16x16x32_bf16 v[96:99], v[214:217], v[172:175], v[96:99]
	v_mfma_f32_16x16x32_bf16 v[88:91], v[204:207], v[180:183], v[88:91]
	v_mfma_f32_16x16x32_bf16 v[80:83], v[214:217], v[180:183], v[80:83]
	v_mfma_f32_16x16x32_bf16 v[72:75], v[204:207], v[188:191], v[72:75]
	v_mfma_f32_16x16x32_bf16 v[64:67], v[214:217], v[188:191], v[64:67]
	s_mov_b32 m0, s13
	s_add_u32 s48, s18, 0x80
	s_addc_u32 s49, s19, 0
	s_barrier
	ds_read_b128 v[160:163], v143 offset:16384
	ds_read_b128 v[164:167], v143 offset:17408
	ds_read_b128 v[168:171], v143 offset:18432
	ds_read_b128 v[172:175], v143 offset:19456
	ds_read_b128 v[176:179], v143 offset:20480
	ds_read_b128 v[180:183], v143 offset:21504
	ds_read_b128 v[184:187], v143 offset:22528
	ds_read_b128 v[188:191], v143 offset:23552
	global_load_lds_dwordx4 v132, s[18:19]
	s_mov_b32 m0, s28
	s_nop 0
	global_load_lds_dwordx4 v130, s[18:19]
	s_barrier
	s_waitcnt lgkmcnt(0)
	v_mfma_f32_16x16x32_bf16 v[60:63], v[144:147], v[160:163], v[60:63]
	v_mfma_f32_16x16x32_bf16 v[52:55], v[152:155], v[160:163], v[52:55]
	v_mfma_f32_16x16x32_bf16 v[44:47], v[144:147], v[168:171], v[44:47]
	v_mfma_f32_16x16x32_bf16 v[36:39], v[152:155], v[168:171], v[36:39]
	v_mfma_f32_16x16x32_bf16 v[28:31], v[144:147], v[176:179], v[28:31]
	v_mfma_f32_16x16x32_bf16 v[20:23], v[152:155], v[176:179], v[20:23]
	v_mfma_f32_16x16x32_bf16 v[12:15], v[144:147], v[184:187], v[12:15]
	v_mfma_f32_16x16x32_bf16 v[4:7], v[152:155], v[184:187], v[4:7]
	v_mfma_f32_16x16x32_bf16 v[60:63], v[148:151], v[164:167], v[60:63]
	v_mfma_f32_16x16x32_bf16 v[52:55], v[156:159], v[164:167], v[52:55]
	v_mfma_f32_16x16x32_bf16 v[44:47], v[148:151], v[172:175], v[44:47]
	v_mfma_f32_16x16x32_bf16 v[36:39], v[156:159], v[172:175], v[36:39]
	v_mfma_f32_16x16x32_bf16 v[28:31], v[148:151], v[180:183], v[28:31]
	v_mfma_f32_16x16x32_bf16 v[20:23], v[156:159], v[180:183], v[20:23]
	v_mfma_f32_16x16x32_bf16 v[12:15], v[148:151], v[188:191], v[12:15]
	v_mfma_f32_16x16x32_bf16 v[4:7], v[156:159], v[188:191], v[4:7]
	s_barrier
	s_add_u32 s42, s16, 0x80000
	s_addc_u32 s43, s17, 0
	s_add_i32 s41, s44, s26
	s_mov_b32 m0, s41
	s_nop 0
	global_load_lds_dwordx4 v192, s[42:43]
	s_add_i32 m0, s41, 0x2000
	s_nop 0
	global_load_lds_dwordx4 v128, s[42:43]
	s_waitcnt vmcnt(6)
	s_barrier
	v_mfma_f32_16x16x32_bf16 v[56:59], v[196:199], v[160:163], v[56:59]
	v_mfma_f32_16x16x32_bf16 v[48:51], v[208:211], v[160:163], v[48:51]
	v_mfma_f32_16x16x32_bf16 v[40:43], v[196:199], v[168:171], v[40:43]
	v_mfma_f32_16x16x32_bf16 v[32:35], v[208:211], v[168:171], v[32:35]
	v_mfma_f32_16x16x32_bf16 v[24:27], v[196:199], v[176:179], v[24:27]
	v_mfma_f32_16x16x32_bf16 v[16:19], v[208:211], v[176:179], v[16:19]
	v_mfma_f32_16x16x32_bf16 v[8:11], v[196:199], v[184:187], v[8:11]
	v_mfma_f32_16x16x32_bf16 v[0:3], v[208:211], v[184:187], v[0:3]
	v_mfma_f32_16x16x32_bf16 v[56:59], v[204:207], v[164:167], v[56:59]
	v_mfma_f32_16x16x32_bf16 v[48:51], v[214:217], v[164:167], v[48:51]
	v_mfma_f32_16x16x32_bf16 v[40:43], v[204:207], v[172:175], v[40:43]
	v_mfma_f32_16x16x32_bf16 v[32:35], v[214:217], v[172:175], v[32:35]
	v_mfma_f32_16x16x32_bf16 v[24:27], v[204:207], v[180:183], v[24:27]
	v_mfma_f32_16x16x32_bf16 v[16:19], v[214:217], v[180:183], v[16:19]
	v_mfma_f32_16x16x32_bf16 v[8:11], v[204:207], v[188:191], v[8:11]
	v_mfma_f32_16x16x32_bf16 v[0:3], v[214:217], v[188:191], v[0:3]
	s_add_i32 s41, 0, 0x18000
	s_barrier
	ds_read_b128 v[144:147], v220 offset:32768
	ds_read_b128 v[148:151], v220 offset:33792
	ds_read_b128 v[152:155], v220 offset:34816
	ds_read_b128 v[156:159], v220 offset:35840
	s_add_u32 s18, s18, 0x80000
	s_addc_u32 s19, s19, 0
	s_mov_b32 m0, s29
	ds_read_b128 v[160:163], v143 offset:32768
	ds_read_b128 v[164:167], v143 offset:33792
	ds_read_b128 v[168:171], v143 offset:34816
	ds_read_b128 v[172:175], v143 offset:35840
	ds_read_b128 v[176:179], v143 offset:36864
	ds_read_b128 v[180:183], v143 offset:37888
	ds_read_b128 v[184:187], v143 offset:38912
	ds_read_b128 v[188:191], v143 offset:39936
	global_load_lds_dwordx4 v132, s[18:19]
	s_mov_b32 m0, s30
	s_nop 0
	global_load_lds_dwordx4 v130, s[18:19]
	s_waitcnt lgkmcnt(8)
	s_barrier
	s_waitcnt lgkmcnt(0)
	v_mfma_f32_16x16x32_bf16 v[124:127], v[144:147], v[160:163], v[124:127]
	v_mfma_f32_16x16x32_bf16 v[116:119], v[152:155], v[160:163], v[116:119]
	v_mfma_f32_16x16x32_bf16 v[108:111], v[144:147], v[168:171], v[108:111]
	v_mfma_f32_16x16x32_bf16 v[100:103], v[152:155], v[168:171], v[100:103]
	v_mfma_f32_16x16x32_bf16 v[92:95], v[144:147], v[176:179], v[92:95]
	v_mfma_f32_16x16x32_bf16 v[84:87], v[152:155], v[176:179], v[84:87]
	v_mfma_f32_16x16x32_bf16 v[76:79], v[144:147], v[184:187], v[76:79]
	v_mfma_f32_16x16x32_bf16 v[68:71], v[152:155], v[184:187], v[68:71]
	v_mfma_f32_16x16x32_bf16 v[124:127], v[148:151], v[164:167], v[124:127]
	v_mfma_f32_16x16x32_bf16 v[116:119], v[156:159], v[164:167], v[116:119]
	v_mfma_f32_16x16x32_bf16 v[108:111], v[148:151], v[172:175], v[108:111]
	v_mfma_f32_16x16x32_bf16 v[100:103], v[156:159], v[172:175], v[100:103]
	v_mfma_f32_16x16x32_bf16 v[92:95], v[148:151], v[180:183], v[92:95]
	v_mfma_f32_16x16x32_bf16 v[84:87], v[156:159], v[180:183], v[84:87]
	v_mfma_f32_16x16x32_bf16 v[76:79], v[148:151], v[188:191], v[76:79]
	v_mfma_f32_16x16x32_bf16 v[68:71], v[156:159], v[188:191], v[68:71]
	s_barrier
	s_add_i32 s18, 0, 0x1c000
	s_add_i32 s19, s41, s26
	s_add_i32 m0, s19, 0xffffff80
	ds_read_b128 v[196:199], v220 offset:49152
	ds_read_b128 v[204:207], v220 offset:50176
	ds_read_b128 v[208:211], v220 offset:51200
	ds_read_b128 v[214:217], v220 offset:52224
	global_load_lds_dwordx4 v192, s[16:17] offset:128
	s_add_i32 m0, s19, 0x1f80
	s_nop 0
	global_load_lds_dwordx4 v128, s[16:17] offset:128
	s_barrier
	s_waitcnt lgkmcnt(0)
	v_mfma_f32_16x16x32_bf16 v[120:123], v[196:199], v[160:163], v[120:123]
	v_mfma_f32_16x16x32_bf16 v[112:115], v[208:211], v[160:163], v[112:115]
	v_mfma_f32_16x16x32_bf16 v[104:107], v[196:199], v[168:171], v[104:107]
	v_mfma_f32_16x16x32_bf16 v[96:99], v[208:211], v[168:171], v[96:99]
	v_mfma_f32_16x16x32_bf16 v[88:91], v[196:199], v[176:179], v[88:91]
	v_mfma_f32_16x16x32_bf16 v[80:83], v[208:211], v[176:179], v[80:83]
	v_mfma_f32_16x16x32_bf16 v[72:75], v[196:199], v[184:187], v[72:75]
	v_mfma_f32_16x16x32_bf16 v[64:67], v[208:211], v[184:187], v[64:67]
	v_mfma_f32_16x16x32_bf16 v[120:123], v[204:207], v[164:167], v[120:123]
	v_mfma_f32_16x16x32_bf16 v[112:115], v[214:217], v[164:167], v[112:115]
	v_mfma_f32_16x16x32_bf16 v[104:107], v[204:207], v[172:175], v[104:107]
	v_mfma_f32_16x16x32_bf16 v[96:99], v[214:217], v[172:175], v[96:99]
	v_mfma_f32_16x16x32_bf16 v[88:91], v[204:207], v[180:183], v[88:91]
	v_mfma_f32_16x16x32_bf16 v[80:83], v[214:217], v[180:183], v[80:83]
	v_mfma_f32_16x16x32_bf16 v[72:75], v[204:207], v[188:191], v[72:75]
	v_mfma_f32_16x16x32_bf16 v[64:67], v[214:217], v[188:191], v[64:67]
	s_mov_b32 m0, s33
	s_barrier
	ds_read_b128 v[160:163], v143 offset:49152
	ds_read_b128 v[164:167], v143 offset:50176
	ds_read_b128 v[168:171], v143 offset:51200
	ds_read_b128 v[172:175], v143 offset:52224
	ds_read_b128 v[176:179], v143 offset:53248
	ds_read_b128 v[180:183], v143 offset:54272
	ds_read_b128 v[184:187], v143 offset:55296
	ds_read_b128 v[188:191], v143 offset:56320
	global_load_lds_dwordx4 v132, s[48:49]
	s_mov_b32 m0, s34
	s_nop 0
	global_load_lds_dwordx4 v130, s[48:49]
	s_barrier
	s_waitcnt lgkmcnt(0)
	v_mfma_f32_16x16x32_bf16 v[60:63], v[144:147], v[160:163], v[60:63]
	v_mfma_f32_16x16x32_bf16 v[52:55], v[152:155], v[160:163], v[52:55]
	v_mfma_f32_16x16x32_bf16 v[44:47], v[144:147], v[168:171], v[44:47]
	v_mfma_f32_16x16x32_bf16 v[36:39], v[152:155], v[168:171], v[36:39]
	v_mfma_f32_16x16x32_bf16 v[28:31], v[144:147], v[176:179], v[28:31]
	v_mfma_f32_16x16x32_bf16 v[20:23], v[152:155], v[176:179], v[20:23]
	v_mfma_f32_16x16x32_bf16 v[12:15], v[144:147], v[184:187], v[12:15]
	v_mfma_f32_16x16x32_bf16 v[4:7], v[152:155], v[184:187], v[4:7]
	v_mfma_f32_16x16x32_bf16 v[60:63], v[148:151], v[164:167], v[60:63]
	v_mfma_f32_16x16x32_bf16 v[52:55], v[156:159], v[164:167], v[52:55]
	v_mfma_f32_16x16x32_bf16 v[44:47], v[148:151], v[172:175], v[44:47]
	v_mfma_f32_16x16x32_bf16 v[36:39], v[156:159], v[172:175], v[36:39]
	v_mfma_f32_16x16x32_bf16 v[28:31], v[148:151], v[180:183], v[28:31]
	v_mfma_f32_16x16x32_bf16 v[20:23], v[156:159], v[180:183], v[20:23]
	v_mfma_f32_16x16x32_bf16 v[12:15], v[148:151], v[188:191], v[12:15]
	v_mfma_f32_16x16x32_bf16 v[4:7], v[156:159], v[188:191], v[4:7]
	s_barrier
	s_add_u32 s16, s16, 0x80080
	s_addc_u32 s17, s17, 0
	s_add_i32 s18, s18, s26
	s_mov_b32 m0, s18
	s_nop 0
	global_load_lds_dwordx4 v192, s[16:17]
	s_add_i32 m0, s18, 0x2000
	s_nop 0
	global_load_lds_dwordx4 v128, s[16:17]
	s_waitcnt vmcnt(6)
	s_barrier
	v_mfma_f32_16x16x32_bf16 v[56:59], v[196:199], v[160:163], v[56:59]
	v_mfma_f32_16x16x32_bf16 v[48:51], v[208:211], v[160:163], v[48:51]
	v_mfma_f32_16x16x32_bf16 v[40:43], v[196:199], v[168:171], v[40:43]
	v_mfma_f32_16x16x32_bf16 v[32:35], v[208:211], v[168:171], v[32:35]
	v_mfma_f32_16x16x32_bf16 v[24:27], v[196:199], v[176:179], v[24:27]
	v_mfma_f32_16x16x32_bf16 v[16:19], v[208:211], v[176:179], v[16:19]
	v_mfma_f32_16x16x32_bf16 v[8:11], v[196:199], v[184:187], v[8:11]
	v_mfma_f32_16x16x32_bf16 v[0:3], v[208:211], v[184:187], v[0:3]
	v_mfma_f32_16x16x32_bf16 v[56:59], v[204:207], v[164:167], v[56:59]
	v_mfma_f32_16x16x32_bf16 v[48:51], v[214:217], v[164:167], v[48:51]
	v_mfma_f32_16x16x32_bf16 v[40:43], v[204:207], v[172:175], v[40:43]
	v_mfma_f32_16x16x32_bf16 v[32:35], v[214:217], v[172:175], v[32:35]
	v_mfma_f32_16x16x32_bf16 v[24:27], v[204:207], v[180:183], v[24:27]
	v_mfma_f32_16x16x32_bf16 v[16:19], v[214:217], v[180:183], v[16:19]
	v_mfma_f32_16x16x32_bf16 v[8:11], v[204:207], v[188:191], v[8:11]
	v_mfma_f32_16x16x32_bf16 v[0:3], v[214:217], v[188:191], v[0:3]
	s_add_i32 s40, s40, 2
	s_add_u32 s14, s14, 0x100
	s_addc_u32 s15, s15, 0
	s_add_u32 s38, s38, 0x100
	s_addc_u32 s39, s39, 0
	s_cmp_gt_u32 s40, 29
	s_barrier
	s_cbranch_scc0 .LBB0_217
	v_mul_f32_e32 v145, 0xbfb8aa3b, v124
	v_exp_f32_e32 v145, v145
	v_lshl_or_b32 v146, s35, 7, v142
	v_lshl_add_u32 v144, s12, 8, v140
	v_ashrrev_i32_e32 v147, 31, v146
	v_add_f32_e32 v145, 1.0, v145
	v_rcp_f32_e32 v145, v145
	v_mov_b64_e32 v[138:139], s[2:3]
	s_movk_i32 s5, 0x2c00
	v_mad_i64_i32 v[148:149], s[14:15], v144, s5, v[138:139]
	v_mul_f32_e32 v124, v124, v145
	v_mul_f32_e32 v120, v124, v120
	v_mul_f32_e32 v124, 0xbfb8aa3b, v125
	v_exp_f32_e32 v124, v124
	s_and_b64 vcc, exec, s[0:1]
	s_mov_b32 s35, s4
	s_mov_b32 s12, s6
	v_add_f32_e32 v124, 1.0, v124
	v_rcp_f32_e32 v124, v124
	s_mov_b64 s[16:17], s[10:11]
	v_mul_f32_e32 v124, v125, v124
	v_mul_f32_e32 v121, v124, v121
	v_mul_f32_e32 v124, 0xbfb8aa3b, v126
	v_exp_f32_e32 v124, v124
	s_nop 0
	v_add_f32_e32 v124, 1.0, v124
	v_rcp_f32_e32 v124, v124
	s_nop 0
	v_mul_f32_e32 v124, v126, v124
	v_mul_f32_e32 v122, v124, v122
	v_mul_f32_e32 v124, 0xbfb8aa3b, v127
	v_exp_f32_e32 v124, v124
	s_nop 0
	v_add_f32_e32 v124, 1.0, v124
	v_rcp_f32_e32 v124, v124
	s_nop 0
	v_mul_f32_e32 v124, v127, v124
	v_mul_f32_e32 v123, v124, v123
	v_mul_f32_e32 v124, 0xbfb8aa3b, v116
	v_exp_f32_e32 v124, v124
	s_nop 0
	v_add_f32_e32 v124, 1.0, v124
	v_rcp_f32_e32 v124, v124
	s_nop 0
	v_mul_f32_e32 v116, v116, v124
	v_mul_f32_e32 v116, v116, v112
	v_mul_f32_e32 v112, 0xbfb8aa3b, v117
	v_exp_f32_e32 v112, v112
	s_nop 0
	v_add_f32_e32 v112, 1.0, v112
	v_rcp_f32_e32 v112, v112
	s_nop 0
	v_mul_f32_e32 v112, v117, v112
	v_mul_f32_e32 v117, v112, v113
	v_mul_f32_e32 v112, 0xbfb8aa3b, v118
	v_exp_f32_e32 v112, v112
	s_nop 0
	v_add_f32_e32 v112, 1.0, v112
	v_rcp_f32_e32 v112, v112
	s_nop 0
	v_mul_f32_e32 v112, v118, v112
	v_mul_f32_e32 v124, v112, v114
	v_mul_f32_e32 v112, 0xbfb8aa3b, v119
	v_exp_f32_e32 v112, v112
	v_cvt_pk_bf16_f32 v114, v120, v121
	s_nop 0
	v_add_f32_e32 v112, 1.0, v112
	v_rcp_f32_e32 v112, v112
	s_nop 0
	v_mul_f32_e32 v112, v119, v112
	v_mul_f32_e32 v125, v112, v115
	v_lshlrev_b64 v[112:113], 1, v[146:147]
	v_lshl_add_u64 v[118:119], v[148:149], 0, v[112:113]
	v_cvt_pk_bf16_f32 v115, v122, v123
	v_cvt_pk_bf16_f32 v116, v116, v117
	v_cvt_pk_bf16_f32 v117, v124, v125
	global_store_dwordx4 v[118:119], v[114:117], off
	s_nop 1
	v_mul_f32_e32 v116, 0xbfb8aa3b, v108
	v_exp_f32_e32 v116, v116
	v_or_b32_e32 v114, 16, v144
	v_mad_i64_i32 v[114:115], s[14:15], v114, s5, v[138:139]
	v_add_f32_e32 v116, 1.0, v116
	v_rcp_f32_e32 v116, v116
	s_nop 0
	v_mul_f32_e32 v108, v108, v116
	v_mul_f32_e32 v104, v108, v104
	v_mul_f32_e32 v108, 0xbfb8aa3b, v109
	v_exp_f32_e32 v108, v108
	s_nop 0
	v_add_f32_e32 v108, 1.0, v108
	v_rcp_f32_e32 v108, v108
	s_nop 0
	v_mul_f32_e32 v108, v109, v108
	v_mul_f32_e32 v105, v108, v105
	v_mul_f32_e32 v108, 0xbfb8aa3b, v110
	v_exp_f32_e32 v108, v108
	s_nop 0
	v_add_f32_e32 v108, 1.0, v108
	v_rcp_f32_e32 v108, v108
	s_nop 0
	v_mul_f32_e32 v108, v110, v108
	v_mul_f32_e32 v106, v108, v106
	v_mul_f32_e32 v108, 0xbfb8aa3b, v111
	v_exp_f32_e32 v108, v108
	s_nop 0
	v_add_f32_e32 v108, 1.0, v108
	v_rcp_f32_e32 v108, v108
	s_nop 0
	v_mul_f32_e32 v108, v111, v108
	v_mul_f32_e32 v107, v108, v107
	v_mul_f32_e32 v108, 0xbfb8aa3b, v100
	v_exp_f32_e32 v108, v108
	s_nop 0
	v_add_f32_e32 v108, 1.0, v108
	v_rcp_f32_e32 v108, v108
	s_nop 0
	v_mul_f32_e32 v100, v100, v108
	v_mul_f32_e32 v108, v100, v96
	v_mul_f32_e32 v96, 0xbfb8aa3b, v101
	v_exp_f32_e32 v96, v96
	s_nop 0
	v_add_f32_e32 v96, 1.0, v96
	v_rcp_f32_e32 v96, v96
	s_nop 0
	v_mul_f32_e32 v96, v101, v96
	v_mul_f32_e32 v109, v96, v97
	v_mul_f32_e32 v96, 0xbfb8aa3b, v102
	v_exp_f32_e32 v96, v96
	v_lshl_add_u64 v[100:101], v[114:115], 0, v[112:113]
	v_add_f32_e32 v96, 1.0, v96
	v_rcp_f32_e32 v96, v96
	s_nop 0
	v_mul_f32_e32 v96, v102, v96
	v_mul_f32_e32 v102, v96, v98
	v_mul_f32_e32 v96, 0xbfb8aa3b, v103
	v_exp_f32_e32 v96, v96
	s_nop 0
	v_add_f32_e32 v96, 1.0, v96
	v_rcp_f32_e32 v96, v96
	s_nop 0
	v_mul_f32_e32 v96, v103, v96
	v_mul_f32_e32 v99, v96, v99
	v_cvt_pk_bf16_f32 v96, v104, v105
	v_cvt_pk_bf16_f32 v97, v106, v107
	v_cvt_pk_bf16_f32 v98, v108, v109
	v_cvt_pk_bf16_f32 v99, v102, v99
	global_store_dwordx4 v[100:101], v[96:99], off
	s_nop 1
	v_mul_f32_e32 v98, 0xbfb8aa3b, v92
	v_exp_f32_e32 v98, v98
	v_or_b32_e32 v96, 32, v144
	v_mad_i64_i32 v[96:97], s[14:15], v96, s5, v[138:139]
	v_add_f32_e32 v98, 1.0, v98
	v_rcp_f32_e32 v98, v98
	s_nop 0
	v_mul_f32_e32 v92, v92, v98
	v_mul_f32_e32 v88, v92, v88
	v_mul_f32_e32 v92, 0xbfb8aa3b, v93
	v_exp_f32_e32 v92, v92
	s_nop 0
	v_add_f32_e32 v92, 1.0, v92
	v_rcp_f32_e32 v92, v92
	s_nop 0
	v_mul_f32_e32 v92, v93, v92
	v_mul_f32_e32 v89, v92, v89
	v_mul_f32_e32 v92, 0xbfb8aa3b, v94
	v_exp_f32_e32 v92, v92
	s_nop 0
	v_add_f32_e32 v92, 1.0, v92
	v_rcp_f32_e32 v92, v92
	s_nop 0
	v_mul_f32_e32 v92, v94, v92
	v_mul_f32_e32 v90, v92, v90
	v_mul_f32_e32 v92, 0xbfb8aa3b, v95
	v_exp_f32_e32 v92, v92
	s_nop 0
	v_add_f32_e32 v92, 1.0, v92
	v_rcp_f32_e32 v92, v92
	s_nop 0
	v_mul_f32_e32 v92, v95, v92
	v_mul_f32_e32 v91, v92, v91
	v_mul_f32_e32 v92, 0xbfb8aa3b, v84
	v_exp_f32_e32 v92, v92
	s_nop 0
	v_add_f32_e32 v92, 1.0, v92
	v_rcp_f32_e32 v92, v92
	s_nop 0
	v_mul_f32_e32 v84, v84, v92
	v_mul_f32_e32 v92, v84, v80
	v_mul_f32_e32 v80, 0xbfb8aa3b, v85
	v_exp_f32_e32 v80, v80
	s_nop 0
	v_add_f32_e32 v80, 1.0, v80
	v_rcp_f32_e32 v80, v80
	s_nop 0
	v_mul_f32_e32 v80, v85, v80
	v_mul_f32_e32 v93, v80, v81
	v_mul_f32_e32 v80, 0xbfb8aa3b, v86
	v_exp_f32_e32 v80, v80
	v_lshl_add_u64 v[84:85], v[96:97], 0, v[112:113]
	v_add_f32_e32 v80, 1.0, v80
	v_rcp_f32_e32 v80, v80
	s_nop 0
	v_mul_f32_e32 v80, v86, v80
	v_mul_f32_e32 v86, v80, v82
	v_mul_f32_e32 v80, 0xbfb8aa3b, v87
	v_exp_f32_e32 v80, v80
	s_nop 0
	v_add_f32_e32 v80, 1.0, v80
	v_rcp_f32_e32 v80, v80
	s_nop 0
	v_mul_f32_e32 v80, v87, v80
	v_mul_f32_e32 v83, v80, v83
	v_cvt_pk_bf16_f32 v80, v88, v89
	v_cvt_pk_bf16_f32 v81, v90, v91
	v_cvt_pk_bf16_f32 v82, v92, v93
	v_cvt_pk_bf16_f32 v83, v86, v83
	global_store_dwordx4 v[84:85], v[80:83], off
	s_nop 1
	v_mul_f32_e32 v82, 0xbfb8aa3b, v76
	v_exp_f32_e32 v82, v82
	v_or_b32_e32 v80, 48, v144
	v_mad_i64_i32 v[80:81], s[14:15], v80, s5, v[138:139]
	v_add_f32_e32 v82, 1.0, v82
	v_rcp_f32_e32 v82, v82
	s_nop 0
	v_mul_f32_e32 v76, v76, v82
	v_mul_f32_e32 v72, v76, v72
	v_mul_f32_e32 v76, 0xbfb8aa3b, v77
	v_exp_f32_e32 v76, v76
	s_nop 0
	v_add_f32_e32 v76, 1.0, v76
	v_rcp_f32_e32 v76, v76
	s_nop 0
	v_mul_f32_e32 v76, v77, v76
	v_mul_f32_e32 v73, v76, v73
	v_mul_f32_e32 v76, 0xbfb8aa3b, v78
	v_exp_f32_e32 v76, v76
	s_nop 0
	v_add_f32_e32 v76, 1.0, v76
	v_rcp_f32_e32 v76, v76
	s_nop 0
	v_mul_f32_e32 v76, v78, v76
	v_mul_f32_e32 v74, v76, v74
	v_mul_f32_e32 v76, 0xbfb8aa3b, v79
	v_exp_f32_e32 v76, v76
	s_nop 0
	v_add_f32_e32 v76, 1.0, v76
	v_rcp_f32_e32 v76, v76
	s_nop 0
	v_mul_f32_e32 v76, v79, v76
	v_mul_f32_e32 v75, v76, v75
	v_mul_f32_e32 v76, 0xbfb8aa3b, v68
	v_exp_f32_e32 v76, v76
	s_nop 0
	v_add_f32_e32 v76, 1.0, v76
	v_rcp_f32_e32 v76, v76
	s_nop 0
	v_mul_f32_e32 v68, v68, v76
	v_mul_f32_e32 v76, v68, v64
	v_mul_f32_e32 v64, 0xbfb8aa3b, v69
	v_exp_f32_e32 v64, v64
	s_nop 0
	v_add_f32_e32 v64, 1.0, v64
	v_rcp_f32_e32 v64, v64
	s_nop 0
	v_mul_f32_e32 v64, v69, v64
	v_mul_f32_e32 v77, v64, v65
	v_mul_f32_e32 v64, 0xbfb8aa3b, v70
	v_exp_f32_e32 v64, v64
	v_lshl_add_u64 v[68:69], v[80:81], 0, v[112:113]
	v_add_f32_e32 v64, 1.0, v64
	v_rcp_f32_e32 v64, v64
	s_nop 0
	v_mul_f32_e32 v64, v70, v64
	v_mul_f32_e32 v70, v64, v66
	v_mul_f32_e32 v64, 0xbfb8aa3b, v71
	v_exp_f32_e32 v64, v64
	s_nop 0
	v_add_f32_e32 v64, 1.0, v64
	v_rcp_f32_e32 v64, v64
	s_nop 0
	v_mul_f32_e32 v64, v71, v64
	v_mul_f32_e32 v67, v64, v67
	v_cvt_pk_bf16_f32 v64, v72, v73
	v_cvt_pk_bf16_f32 v65, v74, v75
	v_cvt_pk_bf16_f32 v66, v76, v77
	v_cvt_pk_bf16_f32 v67, v70, v67
	global_store_dwordx4 v[68:69], v[64:67], off
	s_nop 1
	v_mul_f32_e32 v66, 0xbfb8aa3b, v60
	v_exp_f32_e32 v66, v66
	v_add_u32_e32 v64, 0x80, v144
	v_mad_i64_i32 v[64:65], s[14:15], v64, s5, v[138:139]
	v_add_f32_e32 v66, 1.0, v66
	v_rcp_f32_e32 v66, v66
	s_nop 0
	v_mul_f32_e32 v60, v60, v66
	v_mul_f32_e32 v56, v60, v56
	v_mul_f32_e32 v60, 0xbfb8aa3b, v61
	v_exp_f32_e32 v60, v60
	s_nop 0
	v_add_f32_e32 v60, 1.0, v60
	v_rcp_f32_e32 v60, v60
	s_nop 0
	v_mul_f32_e32 v60, v61, v60
	v_mul_f32_e32 v57, v60, v57
	v_mul_f32_e32 v60, 0xbfb8aa3b, v62
	v_exp_f32_e32 v60, v60
	s_nop 0
	v_add_f32_e32 v60, 1.0, v60
	v_rcp_f32_e32 v60, v60
	s_nop 0
	v_mul_f32_e32 v60, v62, v60
	v_mul_f32_e32 v58, v60, v58
	v_mul_f32_e32 v60, 0xbfb8aa3b, v63
	v_exp_f32_e32 v60, v60
	s_nop 0
	v_add_f32_e32 v60, 1.0, v60
	v_rcp_f32_e32 v60, v60
	s_nop 0
	v_mul_f32_e32 v60, v63, v60
	v_mul_f32_e32 v59, v60, v59
	v_mul_f32_e32 v60, 0xbfb8aa3b, v52
	v_exp_f32_e32 v60, v60
	s_nop 0
	v_add_f32_e32 v60, 1.0, v60
	v_rcp_f32_e32 v60, v60
	s_nop 0
	v_mul_f32_e32 v52, v52, v60
	v_mul_f32_e32 v60, v52, v48
	v_mul_f32_e32 v48, 0xbfb8aa3b, v53
	v_exp_f32_e32 v48, v48
	s_nop 0
	v_add_f32_e32 v48, 1.0, v48
	v_rcp_f32_e32 v48, v48
	s_nop 0
	v_mul_f32_e32 v48, v53, v48
	v_mul_f32_e32 v61, v48, v49
	v_mul_f32_e32 v48, 0xbfb8aa3b, v54
	v_exp_f32_e32 v48, v48
	v_lshl_add_u64 v[52:53], v[64:65], 0, v[112:113]
	v_add_f32_e32 v48, 1.0, v48
	v_rcp_f32_e32 v48, v48
	s_nop 0
	v_mul_f32_e32 v48, v54, v48
	v_mul_f32_e32 v54, v48, v50
	v_mul_f32_e32 v48, 0xbfb8aa3b, v55
	v_exp_f32_e32 v48, v48
	s_nop 0
	v_add_f32_e32 v48, 1.0, v48
	v_rcp_f32_e32 v48, v48
	s_nop 0
	v_mul_f32_e32 v48, v55, v48
	v_mul_f32_e32 v51, v48, v51
	v_cvt_pk_bf16_f32 v48, v56, v57
	v_cvt_pk_bf16_f32 v49, v58, v59
	v_cvt_pk_bf16_f32 v50, v60, v61
	v_cvt_pk_bf16_f32 v51, v54, v51
	global_store_dwordx4 v[52:53], v[48:51], off
	s_nop 1
	v_mul_f32_e32 v50, 0xbfb8aa3b, v44
	v_exp_f32_e32 v50, v50
	v_add_u32_e32 v48, 0x90, v144
	v_mad_i64_i32 v[48:49], s[14:15], v48, s5, v[138:139]
	v_add_f32_e32 v50, 1.0, v50
	v_rcp_f32_e32 v50, v50
	s_nop 0
	v_mul_f32_e32 v44, v44, v50
	v_mul_f32_e32 v40, v44, v40
	v_mul_f32_e32 v44, 0xbfb8aa3b, v45
	v_exp_f32_e32 v44, v44
	s_nop 0
	v_add_f32_e32 v44, 1.0, v44
	v_rcp_f32_e32 v44, v44
	s_nop 0
	v_mul_f32_e32 v44, v45, v44
	v_mul_f32_e32 v41, v44, v41
	v_mul_f32_e32 v44, 0xbfb8aa3b, v46
	v_exp_f32_e32 v44, v44
	s_nop 0
	v_add_f32_e32 v44, 1.0, v44
	v_rcp_f32_e32 v44, v44
	s_nop 0
	v_mul_f32_e32 v44, v46, v44
	v_mul_f32_e32 v42, v44, v42
	v_mul_f32_e32 v44, 0xbfb8aa3b, v47
	v_exp_f32_e32 v44, v44
	s_nop 0
	v_add_f32_e32 v44, 1.0, v44
	v_rcp_f32_e32 v44, v44
	s_nop 0
	v_mul_f32_e32 v44, v47, v44
	v_mul_f32_e32 v43, v44, v43
	v_mul_f32_e32 v44, 0xbfb8aa3b, v36
	v_exp_f32_e32 v44, v44
	s_nop 0
	v_add_f32_e32 v44, 1.0, v44
	v_rcp_f32_e32 v44, v44
	s_nop 0
	v_mul_f32_e32 v36, v36, v44
	v_mul_f32_e32 v44, v36, v32
	v_mul_f32_e32 v32, 0xbfb8aa3b, v37
	v_exp_f32_e32 v32, v32
	s_nop 0
	v_add_f32_e32 v32, 1.0, v32
	v_rcp_f32_e32 v32, v32
	s_nop 0
	v_mul_f32_e32 v32, v37, v32
	v_mul_f32_e32 v45, v32, v33
	v_mul_f32_e32 v32, 0xbfb8aa3b, v38
	v_exp_f32_e32 v32, v32
	v_lshl_add_u64 v[36:37], v[48:49], 0, v[112:113]
	v_add_f32_e32 v32, 1.0, v32
	v_rcp_f32_e32 v32, v32
	s_nop 0
	v_mul_f32_e32 v32, v38, v32
	v_mul_f32_e32 v38, v32, v34
	v_mul_f32_e32 v32, 0xbfb8aa3b, v39
	v_exp_f32_e32 v32, v32
	s_nop 0
	v_add_f32_e32 v32, 1.0, v32
	v_rcp_f32_e32 v32, v32
	s_nop 0
	v_mul_f32_e32 v32, v39, v32
	v_mul_f32_e32 v35, v32, v35
	v_cvt_pk_bf16_f32 v32, v40, v41
	v_cvt_pk_bf16_f32 v33, v42, v43
	v_cvt_pk_bf16_f32 v34, v44, v45
	v_cvt_pk_bf16_f32 v35, v38, v35
	global_store_dwordx4 v[36:37], v[32:35], off
	s_nop 1
	v_mul_f32_e32 v34, 0xbfb8aa3b, v28
	v_exp_f32_e32 v34, v34
	v_add_u32_e32 v32, 0xa0, v144
	v_mad_i64_i32 v[32:33], s[14:15], v32, s5, v[138:139]
	v_add_f32_e32 v34, 1.0, v34
	v_rcp_f32_e32 v34, v34
	s_nop 0
	v_mul_f32_e32 v28, v28, v34
	v_mul_f32_e32 v24, v28, v24
	v_mul_f32_e32 v28, 0xbfb8aa3b, v29
	v_exp_f32_e32 v28, v28
	s_nop 0
	v_add_f32_e32 v28, 1.0, v28
	v_rcp_f32_e32 v28, v28
	s_nop 0
	v_mul_f32_e32 v28, v29, v28
	v_mul_f32_e32 v25, v28, v25
	v_mul_f32_e32 v28, 0xbfb8aa3b, v30
	v_exp_f32_e32 v28, v28
	s_nop 0
	v_add_f32_e32 v28, 1.0, v28
	v_rcp_f32_e32 v28, v28
	s_nop 0
	v_mul_f32_e32 v28, v30, v28
	v_mul_f32_e32 v26, v28, v26
	v_mul_f32_e32 v28, 0xbfb8aa3b, v31
	v_exp_f32_e32 v28, v28
	s_nop 0
	v_add_f32_e32 v28, 1.0, v28
	v_rcp_f32_e32 v28, v28
	s_nop 0
	v_mul_f32_e32 v28, v31, v28
	v_mul_f32_e32 v27, v28, v27
	v_mul_f32_e32 v28, 0xbfb8aa3b, v20
	v_exp_f32_e32 v28, v28
	s_nop 0
	v_add_f32_e32 v28, 1.0, v28
	v_rcp_f32_e32 v28, v28
	s_nop 0
	v_mul_f32_e32 v20, v20, v28
	v_mul_f32_e32 v28, v20, v16
	v_mul_f32_e32 v16, 0xbfb8aa3b, v21
	v_exp_f32_e32 v16, v16
	s_nop 0
	v_add_f32_e32 v16, 1.0, v16
	v_rcp_f32_e32 v16, v16
	s_nop 0
	v_mul_f32_e32 v16, v21, v16
	v_mul_f32_e32 v29, v16, v17
	v_mul_f32_e32 v16, 0xbfb8aa3b, v22
	v_exp_f32_e32 v16, v16
	v_lshl_add_u64 v[20:21], v[32:33], 0, v[112:113]
	v_add_f32_e32 v16, 1.0, v16
	v_rcp_f32_e32 v16, v16
	s_nop 0
	v_mul_f32_e32 v16, v22, v16
	v_mul_f32_e32 v22, v16, v18
	v_mul_f32_e32 v16, 0xbfb8aa3b, v23
	v_exp_f32_e32 v16, v16
	s_nop 0
	v_add_f32_e32 v16, 1.0, v16
	v_rcp_f32_e32 v16, v16
	s_nop 0
	v_mul_f32_e32 v16, v23, v16
	v_mul_f32_e32 v19, v16, v19
	v_cvt_pk_bf16_f32 v16, v24, v25
	v_cvt_pk_bf16_f32 v17, v26, v27
	v_cvt_pk_bf16_f32 v18, v28, v29
	v_cvt_pk_bf16_f32 v19, v22, v19
	global_store_dwordx4 v[20:21], v[16:19], off
	s_nop 1
	v_mul_f32_e32 v18, 0xbfb8aa3b, v12
	v_exp_f32_e32 v18, v18
	v_add_u32_e32 v16, 0xb0, v144
	v_mad_i64_i32 v[16:17], s[14:15], v16, s5, v[138:139]
	v_add_f32_e32 v18, 1.0, v18
	v_rcp_f32_e32 v18, v18
	s_mov_b64 s[14:15], s[8:9]
	v_mul_f32_e32 v12, v12, v18
	v_mul_f32_e32 v8, v12, v8
	v_mul_f32_e32 v12, 0xbfb8aa3b, v13
	v_exp_f32_e32 v12, v12
	s_nop 0
	v_add_f32_e32 v12, 1.0, v12
	v_rcp_f32_e32 v12, v12
	s_nop 0
	v_mul_f32_e32 v12, v13, v12
	v_mul_f32_e32 v9, v12, v9
	v_mul_f32_e32 v12, 0xbfb8aa3b, v14
	v_exp_f32_e32 v12, v12
	s_nop 0
	v_add_f32_e32 v12, 1.0, v12
	v_rcp_f32_e32 v12, v12
	s_nop 0
	v_mul_f32_e32 v12, v14, v12
	v_mul_f32_e32 v10, v12, v10
	v_mul_f32_e32 v12, 0xbfb8aa3b, v15
	v_exp_f32_e32 v12, v12
	s_nop 0
	v_add_f32_e32 v12, 1.0, v12
	v_rcp_f32_e32 v12, v12
	s_nop 0
	v_mul_f32_e32 v12, v15, v12
	v_mul_f32_e32 v11, v12, v11
	v_mul_f32_e32 v12, 0xbfb8aa3b, v4
	v_exp_f32_e32 v12, v12
	s_nop 0
	v_add_f32_e32 v12, 1.0, v12
	v_rcp_f32_e32 v12, v12
	s_nop 0
	v_mul_f32_e32 v4, v4, v12
	v_mul_f32_e32 v12, v4, v0
	v_mul_f32_e32 v0, 0xbfb8aa3b, v5
	v_exp_f32_e32 v0, v0
	s_nop 0
	v_add_f32_e32 v0, 1.0, v0
	v_rcp_f32_e32 v0, v0
	s_nop 0
	v_mul_f32_e32 v0, v5, v0
	v_mul_f32_e32 v13, v0, v1
	v_mul_f32_e32 v0, 0xbfb8aa3b, v6
	v_exp_f32_e32 v0, v0
	v_lshl_add_u64 v[4:5], v[16:17], 0, v[112:113]
	v_add_f32_e32 v0, 1.0, v0
	v_rcp_f32_e32 v0, v0
	s_nop 0
	v_mul_f32_e32 v0, v6, v0
	v_mul_f32_e32 v6, v0, v2
	v_mul_f32_e32 v0, 0xbfb8aa3b, v7
	v_exp_f32_e32 v0, v0
	s_nop 0
	v_add_f32_e32 v0, 1.0, v0
	v_rcp_f32_e32 v0, v0
	s_nop 0
	v_mul_f32_e32 v0, v7, v0
	v_mul_f32_e32 v3, v0, v3
	v_cvt_pk_bf16_f32 v0, v8, v9
	v_cvt_pk_bf16_f32 v1, v10, v11
	v_cvt_pk_bf16_f32 v2, v12, v13
	v_cvt_pk_bf16_f32 v3, v6, v3
	global_store_dwordx4 v[4:5], v[0:3], off
	s_cbranch_vccz .LBB0_214
	s_waitcnt vmcnt(0)
	v_readlane_b32 s34, v254, 18
	s_cmpk_gt_u32 s21, 0xff
	v_readlane_b32 s35, v254, 19
	v_readlane_b32 s31, v254, 20
	s_cbranch_scc1 .LBB0_221
	s_barrier

.LBB0_246:
	s_add_i32 s44, s12, 2
	s_add_u32 s14, s10, 0x80
	s_addc_u32 s13, s11, 0
	s_add_i32 s45, 0, 0x10000
	v_add_u32_e32 v132, s45, v191
	ds_read_b128 v[120:123], v132
	ds_read_b128 v[124:127], v132 offset:1024
	ds_read_b128 v[128:131], v132 offset:2048
	ds_read_b128 v[132:135], v132 offset:3072
	s_cmp_eq_u32 s36, s12
	s_cselect_b32 s12, s4, s14
	s_cselect_b32 s13, s5, s13
	s_cselect_b32 s15, s7, s43
	s_cselect_b32 s14, s6, s42
	s_add_i32 m0, s26, 0xc000
	ds_read_b128 v[144:147], v205
	ds_read_b128 v[148:151], v205 offset:1024
	ds_read_b128 v[152:155], v205 offset:2048
	ds_read_b128 v[156:159], v205 offset:3072
	ds_read_b128 v[160:163], v205 offset:4096
	ds_read_b128 v[164:167], v205 offset:5120
	ds_read_b128 v[178:181], v205 offset:6144
	ds_read_b128 v[182:185], v205 offset:7168
	global_load_lds_dwordx4 v174, s[10:11]
	s_add_i32 m0, s26, 0xe000
	s_nop 0
	global_load_lds_dwordx4 v176, s[10:11]
	s_waitcnt lgkmcnt(8)
	s_barrier
	s_waitcnt lgkmcnt(0)
	v_mfma_f32_16x16x32_bf16 v[140:143], v[120:123], v[144:147], v[140:143]
	v_mfma_f32_16x16x32_bf16 v[136:139], v[128:131], v[144:147], v[136:139]
	v_mfma_f32_16x16x32_bf16 v[108:111], v[120:123], v[152:155], v[108:111]
	v_mfma_f32_16x16x32_bf16 v[104:107], v[128:131], v[152:155], v[104:107]
	v_mfma_f32_16x16x32_bf16 v[92:95], v[120:123], v[160:163], v[92:95]
	v_mfma_f32_16x16x32_bf16 v[88:91], v[128:131], v[160:163], v[88:91]
	v_mfma_f32_16x16x32_bf16 v[76:79], v[120:123], v[178:181], v[76:79]
	v_mfma_f32_16x16x32_bf16 v[72:75], v[128:131], v[178:181], v[72:75]
	v_mfma_f32_16x16x32_bf16 v[140:143], v[124:127], v[148:151], v[140:143]
	v_mfma_f32_16x16x32_bf16 v[136:139], v[132:135], v[148:151], v[136:139]
	v_mfma_f32_16x16x32_bf16 v[108:111], v[124:127], v[156:159], v[108:111]
	v_mfma_f32_16x16x32_bf16 v[104:107], v[132:135], v[156:159], v[104:107]
	v_mfma_f32_16x16x32_bf16 v[92:95], v[124:127], v[164:167], v[92:95]
	v_mfma_f32_16x16x32_bf16 v[88:91], v[132:135], v[164:167], v[88:91]
	v_mfma_f32_16x16x32_bf16 v[76:79], v[124:127], v[182:185], v[76:79]
	v_mfma_f32_16x16x32_bf16 v[72:75], v[132:135], v[182:185], v[72:75]
	s_barrier
	s_add_i32 s46, 0, 0x14000
	v_add_u32_e32 v210, s46, v191
	s_add_i32 s45, s45, s25
	ds_read_b128 v[186:189], v210
	ds_read_b128 v[196:199], v210 offset:1024
	ds_read_b128 v[206:209], v210 offset:2048
	ds_read_b128 v[214:217], v210 offset:3072
	v_lshl_add_u64 v[210:211], s[14:15], 0, v[192:193]
	s_mov_b32 m0, s45
	v_lshl_add_u64 v[218:219], s[14:15], 0, v[172:173]
	global_load_lds_dwordx4 v192, s[14:15]
	s_add_i32 m0, s45, 0x2000
	s_nop 0
	global_load_lds_dwordx4 v172, s[14:15]
	s_barrier
	s_waitcnt lgkmcnt(0)
	v_mfma_f32_16x16x32_bf16 v[116:119], v[186:189], v[144:147], v[116:119]
	v_mfma_f32_16x16x32_bf16 v[112:115], v[206:209], v[144:147], v[112:115]
	v_mfma_f32_16x16x32_bf16 v[100:103], v[186:189], v[152:155], v[100:103]
	v_mfma_f32_16x16x32_bf16 v[96:99], v[206:209], v[152:155], v[96:99]
	v_mfma_f32_16x16x32_bf16 v[84:87], v[186:189], v[160:163], v[84:87]
	v_mfma_f32_16x16x32_bf16 v[80:83], v[206:209], v[160:163], v[80:83]
	v_mfma_f32_16x16x32_bf16 v[68:71], v[186:189], v[178:181], v[68:71]
	v_mfma_f32_16x16x32_bf16 v[64:67], v[206:209], v[178:181], v[64:67]
	v_mfma_f32_16x16x32_bf16 v[116:119], v[196:199], v[148:151], v[116:119]
	v_mfma_f32_16x16x32_bf16 v[112:115], v[214:217], v[148:151], v[112:115]
	v_mfma_f32_16x16x32_bf16 v[100:103], v[196:199], v[156:159], v[100:103]
	v_mfma_f32_16x16x32_bf16 v[96:99], v[214:217], v[156:159], v[96:99]
	v_mfma_f32_16x16x32_bf16 v[84:87], v[196:199], v[164:167], v[84:87]
	v_mfma_f32_16x16x32_bf16 v[80:83], v[214:217], v[164:167], v[80:83]
	v_mfma_f32_16x16x32_bf16 v[68:71], v[196:199], v[182:185], v[68:71]
	v_mfma_f32_16x16x32_bf16 v[64:67], v[214:217], v[182:185], v[64:67]
	s_mov_b32 m0, s26
	v_lshl_add_u64 v[220:221], s[12:13], 0, v[168:169]
	s_barrier
	ds_read_b128 v[144:147], v205 offset:16384
	ds_read_b128 v[148:151], v205 offset:17408
	ds_read_b128 v[152:155], v205 offset:18432
	ds_read_b128 v[156:159], v205 offset:19456
	ds_read_b128 v[160:163], v205 offset:20480
	ds_read_b128 v[164:167], v205 offset:21504
	ds_read_b128 v[178:181], v205 offset:22528
	ds_read_b128 v[182:185], v205 offset:23552
	global_load_lds_dwordx4 v168, s[12:13]
	v_lshl_add_u64 v[222:223], s[12:13], 0, v[170:171]
	s_mov_b32 m0, s27
	s_nop 0
	global_load_lds_dwordx4 v170, s[12:13]
	s_barrier
	s_waitcnt lgkmcnt(0)
	v_mfma_f32_16x16x32_bf16 v[60:63], v[120:123], v[144:147], v[60:63]
	v_mfma_f32_16x16x32_bf16 v[56:59], v[128:131], v[144:147], v[56:59]
	v_mfma_f32_16x16x32_bf16 v[44:47], v[120:123], v[152:155], v[44:47]
	v_mfma_f32_16x16x32_bf16 v[40:43], v[128:131], v[152:155], v[40:43]
	v_mfma_f32_16x16x32_bf16 v[28:31], v[120:123], v[160:163], v[28:31]
	v_mfma_f32_16x16x32_bf16 v[24:27], v[128:131], v[160:163], v[24:27]
	v_mfma_f32_16x16x32_bf16 v[12:15], v[120:123], v[178:181], v[12:15]
	v_mfma_f32_16x16x32_bf16 v[8:11], v[128:131], v[178:181], v[8:11]
	v_mfma_f32_16x16x32_bf16 v[60:63], v[124:127], v[148:151], v[60:63]
	v_mfma_f32_16x16x32_bf16 v[56:59], v[132:135], v[148:151], v[56:59]
	v_mfma_f32_16x16x32_bf16 v[44:47], v[124:127], v[156:159], v[44:47]
	v_mfma_f32_16x16x32_bf16 v[40:43], v[132:135], v[156:159], v[40:43]
	v_mfma_f32_16x16x32_bf16 v[28:31], v[124:127], v[164:167], v[28:31]
	v_mfma_f32_16x16x32_bf16 v[24:27], v[132:135], v[164:167], v[24:27]
	v_mfma_f32_16x16x32_bf16 v[12:15], v[124:127], v[182:185], v[12:15]
	v_mfma_f32_16x16x32_bf16 v[8:11], v[132:135], v[182:185], v[8:11]
	s_barrier
	s_add_u32 s14, s14, s52
	s_addc_u32 s15, s15, 0
	s_add_i32 s45, s46, s25
	v_lshl_add_u64 v[224:225], s[14:15], 0, v[192:193]
	s_mov_b32 m0, s45
	v_lshl_add_u64 v[226:227], s[14:15], 0, v[172:173]
	global_load_lds_dwordx4 v192, s[14:15]
	s_add_i32 m0, s45, 0x2000
	s_nop 0
	global_load_lds_dwordx4 v172, s[14:15]
	s_waitcnt vmcnt(6)
	s_barrier
	v_mfma_f32_16x16x32_bf16 v[52:55], v[186:189], v[144:147], v[52:55]
	v_mfma_f32_16x16x32_bf16 v[48:51], v[206:209], v[144:147], v[48:51]
	v_mfma_f32_16x16x32_bf16 v[36:39], v[186:189], v[152:155], v[36:39]
	v_mfma_f32_16x16x32_bf16 v[32:35], v[206:209], v[152:155], v[32:35]
	v_mfma_f32_16x16x32_bf16 v[20:23], v[186:189], v[160:163], v[20:23]
	v_mfma_f32_16x16x32_bf16 v[16:19], v[206:209], v[160:163], v[16:19]
	v_mfma_f32_16x16x32_bf16 v[4:7], v[186:189], v[178:181], v[4:7]
	v_mfma_f32_16x16x32_bf16 v[0:3], v[206:209], v[178:181], v[0:3]
	v_mfma_f32_16x16x32_bf16 v[52:55], v[196:199], v[148:151], v[52:55]
	v_mfma_f32_16x16x32_bf16 v[48:51], v[214:217], v[148:151], v[48:51]
	v_mfma_f32_16x16x32_bf16 v[36:39], v[196:199], v[156:159], v[36:39]
	v_mfma_f32_16x16x32_bf16 v[32:35], v[214:217], v[156:159], v[32:35]
	v_mfma_f32_16x16x32_bf16 v[20:23], v[196:199], v[164:167], v[20:23]
	v_mfma_f32_16x16x32_bf16 v[16:19], v[214:217], v[164:167], v[16:19]
	v_mfma_f32_16x16x32_bf16 v[4:7], v[196:199], v[182:185], v[4:7]
	v_mfma_f32_16x16x32_bf16 v[0:3], v[214:217], v[182:185], v[0:3]
	s_add_i32 s14, 0, 0x18000
	v_add_u32_e32 v132, s14, v191
	s_barrier
	ds_read_b128 v[120:123], v132
	ds_read_b128 v[124:127], v132 offset:1024
	ds_read_b128 v[128:131], v132 offset:2048
	ds_read_b128 v[132:135], v132 offset:3072
	s_add_u32 s12, s12, s52
	s_addc_u32 s13, s13, 0
	s_mov_b32 m0, s28
	ds_read_b128 v[144:147], v205 offset:32768
	ds_read_b128 v[148:151], v205 offset:33792
	ds_read_b128 v[152:155], v205 offset:34816
	ds_read_b128 v[156:159], v205 offset:35840
	ds_read_b128 v[160:163], v205 offset:36864
	ds_read_b128 v[164:167], v205 offset:37888
	ds_read_b128 v[178:181], v205 offset:38912
	ds_read_b128 v[182:185], v205 offset:39936
	global_load_lds_dwordx4 v168, s[12:13]
	s_mov_b32 m0, s29
	s_nop 0
	global_load_lds_dwordx4 v170, s[12:13]
	s_waitcnt lgkmcnt(8)
	s_barrier
	s_waitcnt lgkmcnt(0)
	v_mfma_f32_16x16x32_bf16 v[140:143], v[120:123], v[144:147], v[140:143]
	v_mfma_f32_16x16x32_bf16 v[136:139], v[128:131], v[144:147], v[136:139]
	v_mfma_f32_16x16x32_bf16 v[108:111], v[120:123], v[152:155], v[108:111]
	v_mfma_f32_16x16x32_bf16 v[104:107], v[128:131], v[152:155], v[104:107]
	v_mfma_f32_16x16x32_bf16 v[92:95], v[120:123], v[160:163], v[92:95]
	v_mfma_f32_16x16x32_bf16 v[88:91], v[128:131], v[160:163], v[88:91]
	v_mfma_f32_16x16x32_bf16 v[76:79], v[120:123], v[178:181], v[76:79]
	v_mfma_f32_16x16x32_bf16 v[72:75], v[128:131], v[178:181], v[72:75]
	v_mfma_f32_16x16x32_bf16 v[140:143], v[124:127], v[148:151], v[140:143]
	v_mfma_f32_16x16x32_bf16 v[136:139], v[132:135], v[148:151], v[136:139]
	v_mfma_f32_16x16x32_bf16 v[108:111], v[124:127], v[156:159], v[108:111]
	v_mfma_f32_16x16x32_bf16 v[104:107], v[132:135], v[156:159], v[104:107]
	v_mfma_f32_16x16x32_bf16 v[92:95], v[124:127], v[164:167], v[92:95]
	v_mfma_f32_16x16x32_bf16 v[88:91], v[132:135], v[164:167], v[88:91]
	v_mfma_f32_16x16x32_bf16 v[76:79], v[124:127], v[182:185], v[76:79]
	v_mfma_f32_16x16x32_bf16 v[72:75], v[132:135], v[182:185], v[72:75]
	s_barrier
	s_add_i32 s12, 0, 0x1c000
	s_add_i32 s13, s14, s25
	v_add_u32_e32 v212, s12, v191
	v_lshl_add_u64 v[210:211], v[210:211], 0, s[48:49]
	s_mov_b32 m0, s13
	ds_read_b128 v[186:189], v212
	ds_read_b128 v[196:199], v212 offset:1024
	ds_read_b128 v[206:209], v212 offset:2048
	ds_read_b128 v[214:217], v212 offset:3072
	global_load_lds_dwordx4 v[210:211], off
	v_lshl_add_u64 v[210:211], v[218:219], 0, s[48:49]
	s_add_i32 m0, s13, 0x2000
	s_nop 0
	global_load_lds_dwordx4 v[210:211], off
	s_barrier
	s_waitcnt lgkmcnt(0)
	v_mfma_f32_16x16x32_bf16 v[116:119], v[186:189], v[144:147], v[116:119]
	v_mfma_f32_16x16x32_bf16 v[112:115], v[206:209], v[144:147], v[112:115]
	v_mfma_f32_16x16x32_bf16 v[100:103], v[186:189], v[152:155], v[100:103]
	v_mfma_f32_16x16x32_bf16 v[96:99], v[206:209], v[152:155], v[96:99]
	v_mfma_f32_16x16x32_bf16 v[84:87], v[186:189], v[160:163], v[84:87]
	v_mfma_f32_16x16x32_bf16 v[80:83], v[206:209], v[160:163], v[80:83]
	v_mfma_f32_16x16x32_bf16 v[68:71], v[186:189], v[178:181], v[68:71]
	v_mfma_f32_16x16x32_bf16 v[64:67], v[206:209], v[178:181], v[64:67]
	v_mfma_f32_16x16x32_bf16 v[116:119], v[196:199], v[148:151], v[116:119]
	v_mfma_f32_16x16x32_bf16 v[112:115], v[214:217], v[148:151], v[112:115]
	v_mfma_f32_16x16x32_bf16 v[100:103], v[196:199], v[156:159], v[100:103]
	v_mfma_f32_16x16x32_bf16 v[96:99], v[214:217], v[156:159], v[96:99]
	v_mfma_f32_16x16x32_bf16 v[84:87], v[196:199], v[164:167], v[84:87]
	v_mfma_f32_16x16x32_bf16 v[80:83], v[214:217], v[164:167], v[80:83]
	v_mfma_f32_16x16x32_bf16 v[68:71], v[196:199], v[182:185], v[68:71]
	v_mfma_f32_16x16x32_bf16 v[64:67], v[214:217], v[182:185], v[64:67]
	s_mov_b32 m0, s34
	v_lshl_add_u64 v[210:211], v[220:221], 0, s[48:49]
	s_barrier
	ds_read_b128 v[144:147], v205 offset:49152
	ds_read_b128 v[148:151], v205 offset:50176
	ds_read_b128 v[152:155], v205 offset:51200
	ds_read_b128 v[156:159], v205 offset:52224
	ds_read_b128 v[160:163], v205 offset:53248
	ds_read_b128 v[164:167], v205 offset:54272
	ds_read_b128 v[178:181], v205 offset:55296
	ds_read_b128 v[182:185], v205 offset:56320
	global_load_lds_dwordx4 v[210:211], off
	v_lshl_add_u64 v[210:211], v[222:223], 0, s[48:49]
	s_mov_b32 m0, s35
	s_nop 0
	global_load_lds_dwordx4 v[210:211], off
	s_barrier
	s_waitcnt lgkmcnt(0)
	v_mfma_f32_16x16x32_bf16 v[60:63], v[120:123], v[144:147], v[60:63]
	v_mfma_f32_16x16x32_bf16 v[56:59], v[128:131], v[144:147], v[56:59]
	v_mfma_f32_16x16x32_bf16 v[44:47], v[120:123], v[152:155], v[44:47]
	v_mfma_f32_16x16x32_bf16 v[40:43], v[128:131], v[152:155], v[40:43]
	v_mfma_f32_16x16x32_bf16 v[28:31], v[120:123], v[160:163], v[28:31]
	v_mfma_f32_16x16x32_bf16 v[24:27], v[128:131], v[160:163], v[24:27]
	v_mfma_f32_16x16x32_bf16 v[12:15], v[120:123], v[178:181], v[12:15]
	v_mfma_f32_16x16x32_bf16 v[8:11], v[128:131], v[178:181], v[8:11]
	v_mfma_f32_16x16x32_bf16 v[60:63], v[124:127], v[148:151], v[60:63]
	v_mfma_f32_16x16x32_bf16 v[56:59], v[132:135], v[148:151], v[56:59]
	v_mfma_f32_16x16x32_bf16 v[44:47], v[124:127], v[156:159], v[44:47]
	v_mfma_f32_16x16x32_bf16 v[40:43], v[132:135], v[156:159], v[40:43]
	v_mfma_f32_16x16x32_bf16 v[28:31], v[124:127], v[164:167], v[28:31]
	v_mfma_f32_16x16x32_bf16 v[24:27], v[132:135], v[164:167], v[24:27]
	v_mfma_f32_16x16x32_bf16 v[12:15], v[124:127], v[182:185], v[12:15]
	v_mfma_f32_16x16x32_bf16 v[8:11], v[132:135], v[182:185], v[8:11]
	s_barrier
	s_add_i32 s12, s12, s25
	v_lshl_add_u64 v[120:121], v[224:225], 0, s[48:49]
	s_mov_b32 m0, s12
	s_nop 0
	global_load_lds_dwordx4 v[120:121], off
	v_lshl_add_u64 v[120:121], v[226:227], 0, s[48:49]
	s_add_i32 m0, s12, 0x2000
	s_nop 0
	global_load_lds_dwordx4 v[120:121], off
	s_waitcnt vmcnt(6)
	s_barrier
	v_mfma_f32_16x16x32_bf16 v[52:55], v[186:189], v[144:147], v[52:55]
	v_mfma_f32_16x16x32_bf16 v[48:51], v[206:209], v[144:147], v[48:51]
	v_mfma_f32_16x16x32_bf16 v[36:39], v[186:189], v[152:155], v[36:39]
	v_mfma_f32_16x16x32_bf16 v[32:35], v[206:209], v[152:155], v[32:35]
	v_mfma_f32_16x16x32_bf16 v[20:23], v[186:189], v[160:163], v[20:23]
	v_mfma_f32_16x16x32_bf16 v[16:19], v[206:209], v[160:163], v[16:19]
	v_mfma_f32_16x16x32_bf16 v[4:7], v[186:189], v[178:181], v[4:7]
	v_mfma_f32_16x16x32_bf16 v[0:3], v[206:209], v[178:181], v[0:3]
	v_mfma_f32_16x16x32_bf16 v[52:55], v[196:199], v[148:151], v[52:55]
	v_mfma_f32_16x16x32_bf16 v[48:51], v[214:217], v[148:151], v[48:51]
	v_mfma_f32_16x16x32_bf16 v[36:39], v[196:199], v[156:159], v[36:39]
	v_mfma_f32_16x16x32_bf16 v[32:35], v[214:217], v[156:159], v[32:35]
	v_mfma_f32_16x16x32_bf16 v[20:23], v[196:199], v[164:167], v[20:23]
	v_mfma_f32_16x16x32_bf16 v[16:19], v[214:217], v[164:167], v[16:19]
	v_mfma_f32_16x16x32_bf16 v[4:7], v[196:199], v[182:185], v[4:7]
	v_mfma_f32_16x16x32_bf16 v[0:3], v[214:217], v[182:185], v[0:3]
	s_add_u32 s10, s10, 0x100
	s_addc_u32 s11, s11, 0
	s_add_u32 s42, s42, 0x100
	s_addc_u32 s43, s43, 0
	s_cmp_ge_u32 s44, s33
	s_mov_b32 s12, s44
	s_barrier
	s_cbranch_scc0 .LBB0_246
	v_lshl_or_b32 v144, s41, 8, v204
	s_ashr_i32 s10, s40, 4
	s_mul_hi_i32 s11, s10, 0xc000
	s_mul_i32 s10, s10, 0xc000
	v_ashrrev_i32_e32 v145, 31, v144
	v_lshl_add_u32 v146, s40, 8, v190
	s_add_u32 s10, s30, s10
	v_lshlrev_b64 v[178:179], 1, v[144:145]
	v_ashrrev_i32_e32 v147, 31, v146
	s_addc_u32 s11, s31, s11
	v_lshl_add_u64 v[180:181], s[2:3], 0, v[178:179]
	v_lshlrev_b64 v[182:183], 12, v[146:147]
	v_lshl_add_u64 v[124:125], v[144:145], 2, s[10:11]
	v_lshl_add_u64 v[144:145], v[180:181], 0, v[182:183]
	global_load_dwordx4 v[128:131], v[124:125], off offset:16
	global_load_dwordx4 v[132:135], v[124:125], off
	global_load_dwordx4 v[120:123], v[124:125], off offset:528
	s_nop 0
	global_load_dwordx4 v[124:127], v[124:125], off offset:512
	s_nop 0
	global_load_dwordx4 v[196:199], v[144:145], off
	global_load_dwordx4 v[206:209], v[144:145], off offset:256
	v_or_b32_e32 v144, 16, v146
	v_ashrrev_i32_e32 v145, 31, v144
	v_lshlrev_b64 v[188:189], 12, v[144:145]
	v_lshl_add_u64 v[144:145], v[180:181], 0, v[188:189]
	global_load_dwordx4 v[164:167], v[144:145], off
	global_load_dwordx4 v[160:163], v[144:145], off offset:256
	v_or_b32_e32 v144, 32, v146
	v_ashrrev_i32_e32 v145, 31, v144
	v_lshlrev_b64 v[186:187], 12, v[144:145]
	v_lshl_add_u64 v[144:145], v[180:181], 0, v[186:187]
	global_load_dwordx4 v[156:159], v[144:145], off
	global_load_dwordx4 v[152:155], v[144:145], off offset:256
	v_or_b32_e32 v144, 48, v146
	v_ashrrev_i32_e32 v145, 31, v144
	v_lshlrev_b64 v[184:185], 12, v[144:145]
	v_lshl_add_u64 v[144:145], v[180:181], 0, v[184:185]
	global_load_dwordx4 v[148:151], v[144:145], off
	s_nop 0
	global_load_dwordx4 v[144:147], v[144:145], off offset:256
	s_mov_b64 s[10:11], 0x80000
	s_and_b64 vcc, exec, s[0:1]
	s_mov_b32 s41, s38
	s_mov_b32 s40, s39
	s_mov_b64 s[12:13], s[6:7]
	v_readlane_b32 s14, v254, 21
	s_movk_i32 s15, 0x2000
	s_waitcnt vmcnt(0)
	v_lshlrev_b32_e32 v210, 16, v196
	v_and_b32_e32 v211, 0xffff0000, v196
	v_lshlrev_b32_e32 v196, 16, v197
	v_and_b32_e32 v197, 0xffff0000, v197
	v_lshlrev_b32_e32 v214, 16, v198
	v_and_b32_e32 v215, 0xffff0000, v198
	v_lshlrev_b32_e32 v198, 16, v199
	v_and_b32_e32 v199, 0xffff0000, v199
	v_pk_fma_f32 v[140:141], v[140:141], v[132:133], v[210:211]
	v_pk_fma_f32 v[142:143], v[142:143], v[134:135], v[196:197]
	v_pk_fma_f32 v[196:197], v[138:139], v[130:131], v[198:199]
	v_pk_fma_f32 v[138:139], v[136:137], v[128:129], v[214:215]
	v_cvt_pk_bf16_f32 v136, v140, v141
	v_lshl_add_u64 v[140:141], s[8:9], 0, v[182:183]
	v_cvt_pk_bf16_f32 v137, v142, v143
	v_cvt_pk_bf16_f32 v138, v138, v139
	v_cvt_pk_bf16_f32 v139, v196, v197
	v_lshl_add_u64 v[140:141], v[140:141], 0, v[178:179]
	global_store_dwordx4 v[140:141], v[136:139], off
	v_lshlrev_b32_e32 v142, 16, v208
	v_and_b32_e32 v143, 0xffff0000, v208
	v_lshlrev_b32_e32 v136, 16, v206
	v_and_b32_e32 v137, 0xffff0000, v206
	v_lshlrev_b32_e32 v138, 16, v207
	v_and_b32_e32 v139, 0xffff0000, v207
	v_lshlrev_b32_e32 v196, 16, v209
	v_and_b32_e32 v197, 0xffff0000, v209
	v_pk_fma_f32 v[118:119], v[118:119], v[126:127], v[138:139]
	v_pk_fma_f32 v[116:117], v[116:117], v[124:125], v[136:137]
	v_pk_fma_f32 v[136:137], v[114:115], v[122:123], v[196:197]
	v_pk_fma_f32 v[114:115], v[112:113], v[120:121], v[142:143]
	v_cvt_pk_bf16_f32 v112, v116, v117
	v_cvt_pk_bf16_f32 v113, v118, v119
	v_lshlrev_b32_e32 v116, 16, v166
	v_cvt_pk_bf16_f32 v114, v114, v115
	v_cvt_pk_bf16_f32 v115, v136, v137
	global_store_dwordx4 v[140:141], v[112:115], off offset:256
	v_and_b32_e32 v117, 0xffff0000, v166
	v_lshlrev_b32_e32 v118, 16, v167
	v_lshlrev_b32_e32 v112, 16, v164
	v_and_b32_e32 v113, 0xffff0000, v164
	v_and_b32_e32 v119, 0xffff0000, v167
	v_pk_fma_f32 v[108:109], v[108:109], v[132:133], v[112:113]
	v_lshlrev_b32_e32 v114, 16, v165
	v_and_b32_e32 v115, 0xffff0000, v165
	v_pk_fma_f32 v[112:113], v[106:107], v[130:131], v[118:119]
	v_pk_fma_f32 v[106:107], v[104:105], v[128:129], v[116:117]
	v_cvt_pk_bf16_f32 v104, v108, v109
	v_lshl_add_u64 v[108:109], s[8:9], 0, v[188:189]
	v_pk_fma_f32 v[110:111], v[110:111], v[134:135], v[114:115]
	v_lshl_add_u64 v[108:109], v[108:109], 0, v[178:179]
	v_cvt_pk_bf16_f32 v105, v110, v111
	v_cvt_pk_bf16_f32 v106, v106, v107
	v_cvt_pk_bf16_f32 v107, v112, v113
	global_store_dwordx4 v[108:109], v[104:107], off
	v_lshlrev_b32_e32 v110, 16, v162
	v_and_b32_e32 v111, 0xffff0000, v162
	v_lshlrev_b32_e32 v104, 16, v160
	v_and_b32_e32 v105, 0xffff0000, v160
	v_lshlrev_b32_e32 v106, 16, v161
	v_and_b32_e32 v107, 0xffff0000, v161
	v_lshlrev_b32_e32 v112, 16, v163
	v_and_b32_e32 v113, 0xffff0000, v163
	v_pk_fma_f32 v[102:103], v[102:103], v[126:127], v[106:107]
	v_pk_fma_f32 v[100:101], v[100:101], v[124:125], v[104:105]
	v_pk_fma_f32 v[104:105], v[98:99], v[122:123], v[112:113]
	v_pk_fma_f32 v[98:99], v[96:97], v[120:121], v[110:111]
	v_cvt_pk_bf16_f32 v96, v100, v101
	v_cvt_pk_bf16_f32 v97, v102, v103
	v_lshlrev_b32_e32 v100, 16, v158
	v_cvt_pk_bf16_f32 v98, v98, v99
	v_cvt_pk_bf16_f32 v99, v104, v105
	global_store_dwordx4 v[108:109], v[96:99], off offset:256
	v_and_b32_e32 v101, 0xffff0000, v158
	v_lshlrev_b32_e32 v102, 16, v159
	v_lshlrev_b32_e32 v96, 16, v156
	v_and_b32_e32 v97, 0xffff0000, v156
	v_and_b32_e32 v103, 0xffff0000, v159
	v_pk_fma_f32 v[92:93], v[92:93], v[132:133], v[96:97]
	v_lshlrev_b32_e32 v98, 16, v157
	v_and_b32_e32 v99, 0xffff0000, v157
	v_pk_fma_f32 v[96:97], v[90:91], v[130:131], v[102:103]
	v_pk_fma_f32 v[90:91], v[88:89], v[128:129], v[100:101]
	v_cvt_pk_bf16_f32 v88, v92, v93
	v_lshl_add_u64 v[92:93], s[8:9], 0, v[186:187]
	v_pk_fma_f32 v[94:95], v[94:95], v[134:135], v[98:99]
	v_lshl_add_u64 v[92:93], v[92:93], 0, v[178:179]
	v_cvt_pk_bf16_f32 v89, v94, v95
	v_cvt_pk_bf16_f32 v90, v90, v91
	v_cvt_pk_bf16_f32 v91, v96, v97
	global_store_dwordx4 v[92:93], v[88:91], off
	v_lshlrev_b32_e32 v94, 16, v154
	v_and_b32_e32 v95, 0xffff0000, v154
	v_lshlrev_b32_e32 v88, 16, v152
	v_and_b32_e32 v89, 0xffff0000, v152
	v_lshlrev_b32_e32 v90, 16, v153
	v_and_b32_e32 v91, 0xffff0000, v153
	v_lshlrev_b32_e32 v96, 16, v155
	v_and_b32_e32 v97, 0xffff0000, v155
	v_pk_fma_f32 v[86:87], v[86:87], v[126:127], v[90:91]
	v_pk_fma_f32 v[84:85], v[84:85], v[124:125], v[88:89]
	v_pk_fma_f32 v[88:89], v[82:83], v[122:123], v[96:97]
	v_pk_fma_f32 v[82:83], v[80:81], v[120:121], v[94:95]
	v_cvt_pk_bf16_f32 v80, v84, v85
	v_cvt_pk_bf16_f32 v81, v86, v87
	v_lshlrev_b32_e32 v84, 16, v150
	v_cvt_pk_bf16_f32 v82, v82, v83
	v_cvt_pk_bf16_f32 v83, v88, v89
	global_store_dwordx4 v[92:93], v[80:83], off offset:256
	v_and_b32_e32 v85, 0xffff0000, v150
	v_lshlrev_b32_e32 v86, 16, v151
	v_lshlrev_b32_e32 v80, 16, v148
	v_and_b32_e32 v81, 0xffff0000, v148
	v_and_b32_e32 v87, 0xffff0000, v151
	v_pk_fma_f32 v[76:77], v[76:77], v[132:133], v[80:81]
	v_lshlrev_b32_e32 v82, 16, v149
	v_and_b32_e32 v83, 0xffff0000, v149
	v_pk_fma_f32 v[80:81], v[74:75], v[130:131], v[86:87]
	v_pk_fma_f32 v[74:75], v[72:73], v[128:129], v[84:85]
	v_cvt_pk_bf16_f32 v72, v76, v77
	v_lshl_add_u64 v[76:77], s[8:9], 0, v[184:185]
	v_pk_fma_f32 v[78:79], v[78:79], v[134:135], v[82:83]
	v_lshl_add_u64 v[76:77], v[76:77], 0, v[178:179]
	v_cvt_pk_bf16_f32 v73, v78, v79
	v_cvt_pk_bf16_f32 v74, v74, v75
	v_cvt_pk_bf16_f32 v75, v80, v81
	global_store_dwordx4 v[76:77], v[72:75], off
	v_lshlrev_b32_e32 v78, 16, v146
	v_and_b32_e32 v79, 0xffff0000, v146
	v_lshlrev_b32_e32 v72, 16, v144
	v_and_b32_e32 v73, 0xffff0000, v144
	v_lshlrev_b32_e32 v74, 16, v145
	v_and_b32_e32 v75, 0xffff0000, v145
	v_lshlrev_b32_e32 v80, 16, v147
	v_and_b32_e32 v81, 0xffff0000, v147
	v_pk_fma_f32 v[70:71], v[70:71], v[126:127], v[74:75]
	v_pk_fma_f32 v[68:69], v[68:69], v[124:125], v[72:73]
	v_pk_fma_f32 v[72:73], v[66:67], v[122:123], v[80:81]
	v_pk_fma_f32 v[66:67], v[64:65], v[120:121], v[78:79]
	v_cvt_pk_bf16_f32 v64, v68, v69
	v_cvt_pk_bf16_f32 v65, v70, v71
	v_lshl_add_u64 v[98:99], v[182:183], 0, s[10:11]
	v_cvt_pk_bf16_f32 v66, v66, v67
	v_cvt_pk_bf16_f32 v67, v72, v73
	global_store_dwordx4 v[76:77], v[64:67], off offset:256
	s_mov_b64 s[10:11], 0x90000
	v_lshl_add_u64 v[100:101], v[182:183], 0, s[10:11]
	v_lshl_add_u64 v[64:65], v[180:181], 0, v[98:99]
	global_load_dwordx4 v[74:77], v[64:65], off
	global_load_dwordx4 v[78:81], v[64:65], off offset:256
	v_lshl_add_u64 v[64:65], v[180:181], 0, v[100:101]
	global_load_dwordx4 v[82:85], v[64:65], off
	global_load_dwordx4 v[86:89], v[64:65], off offset:256
	s_mov_b64 s[10:11], 0xa0000
	v_lshl_add_u64 v[102:103], v[182:183], 0, s[10:11]
	v_lshl_add_u64 v[64:65], v[180:181], 0, v[102:103]
	global_load_dwordx4 v[90:93], v[64:65], off
	global_load_dwordx4 v[94:97], v[64:65], off offset:256
	s_mov_b64 s[10:11], 0xb0000
	v_lshl_add_u64 v[72:73], v[182:183], 0, s[10:11]
	v_lshl_add_u64 v[64:65], v[180:181], 0, v[72:73]
	global_load_dwordx4 v[68:71], v[64:65], off
	s_nop 0
	global_load_dwordx4 v[64:67], v[64:65], off offset:256
	s_mov_b64 s[10:11], s[4:5]
	s_waitcnt vmcnt(0)
	v_lshlrev_b32_e32 v104, 16, v74
	v_and_b32_e32 v105, 0xffff0000, v74
	v_lshlrev_b32_e32 v74, 16, v75
	v_and_b32_e32 v75, 0xffff0000, v75
	v_lshlrev_b32_e32 v106, 16, v76
	v_and_b32_e32 v107, 0xffff0000, v76
	v_lshlrev_b32_e32 v76, 16, v77
	v_and_b32_e32 v77, 0xffff0000, v77
	v_pk_fma_f32 v[60:61], v[60:61], v[132:133], v[104:105]
	v_pk_fma_f32 v[62:63], v[62:63], v[134:135], v[74:75]
	v_pk_fma_f32 v[74:75], v[58:59], v[130:131], v[76:77]
	v_pk_fma_f32 v[58:59], v[56:57], v[128:129], v[106:107]
	v_cvt_pk_bf16_f32 v56, v60, v61
	v_lshl_add_u64 v[60:61], s[8:9], 0, v[98:99]
	v_cvt_pk_bf16_f32 v57, v62, v63
	v_cvt_pk_bf16_f32 v58, v58, v59
	v_cvt_pk_bf16_f32 v59, v74, v75
	v_lshl_add_u64 v[60:61], v[60:61], 0, v[178:179]
	global_store_dwordx4 v[60:61], v[56:59], off
	v_lshlrev_b32_e32 v62, 16, v80
	v_and_b32_e32 v63, 0xffff0000, v80
	v_lshlrev_b32_e32 v56, 16, v78
	v_and_b32_e32 v57, 0xffff0000, v78
	v_lshlrev_b32_e32 v58, 16, v79
	v_and_b32_e32 v59, 0xffff0000, v79
	v_lshlrev_b32_e32 v74, 16, v81
	v_and_b32_e32 v75, 0xffff0000, v81
	v_pk_fma_f32 v[54:55], v[54:55], v[126:127], v[58:59]
	v_pk_fma_f32 v[52:53], v[52:53], v[124:125], v[56:57]
	v_pk_fma_f32 v[56:57], v[50:51], v[122:123], v[74:75]
	v_pk_fma_f32 v[50:51], v[48:49], v[120:121], v[62:63]
	v_cvt_pk_bf16_f32 v48, v52, v53
	v_cvt_pk_bf16_f32 v49, v54, v55
	v_lshlrev_b32_e32 v52, 16, v84
	v_cvt_pk_bf16_f32 v50, v50, v51
	v_cvt_pk_bf16_f32 v51, v56, v57
	global_store_dwordx4 v[60:61], v[48:51], off offset:256
	v_and_b32_e32 v53, 0xffff0000, v84
	v_lshlrev_b32_e32 v54, 16, v85
	v_lshlrev_b32_e32 v48, 16, v82
	v_and_b32_e32 v49, 0xffff0000, v82
	v_and_b32_e32 v55, 0xffff0000, v85
	v_pk_fma_f32 v[44:45], v[44:45], v[132:133], v[48:49]
	v_lshlrev_b32_e32 v50, 16, v83
	v_and_b32_e32 v51, 0xffff0000, v83
	v_pk_fma_f32 v[48:49], v[42:43], v[130:131], v[54:55]
	v_pk_fma_f32 v[42:43], v[40:41], v[128:129], v[52:53]
	v_cvt_pk_bf16_f32 v40, v44, v45
	v_lshl_add_u64 v[44:45], s[8:9], 0, v[100:101]
	v_pk_fma_f32 v[46:47], v[46:47], v[134:135], v[50:51]
	v_lshl_add_u64 v[44:45], v[44:45], 0, v[178:179]
	v_cvt_pk_bf16_f32 v41, v46, v47
	v_cvt_pk_bf16_f32 v42, v42, v43
	v_cvt_pk_bf16_f32 v43, v48, v49
	global_store_dwordx4 v[44:45], v[40:43], off
	v_lshlrev_b32_e32 v46, 16, v88
	v_and_b32_e32 v47, 0xffff0000, v88
	v_lshlrev_b32_e32 v40, 16, v86
	v_and_b32_e32 v41, 0xffff0000, v86
	v_lshlrev_b32_e32 v42, 16, v87
	v_and_b32_e32 v43, 0xffff0000, v87
	v_lshlrev_b32_e32 v48, 16, v89
	v_and_b32_e32 v49, 0xffff0000, v89
	v_pk_fma_f32 v[38:39], v[38:39], v[126:127], v[42:43]
	v_pk_fma_f32 v[36:37], v[36:37], v[124:125], v[40:41]
	v_pk_fma_f32 v[40:41], v[34:35], v[122:123], v[48:49]
	v_pk_fma_f32 v[34:35], v[32:33], v[120:121], v[46:47]
	v_cvt_pk_bf16_f32 v32, v36, v37
	v_cvt_pk_bf16_f32 v33, v38, v39
	v_lshlrev_b32_e32 v36, 16, v92
	v_cvt_pk_bf16_f32 v34, v34, v35
	v_cvt_pk_bf16_f32 v35, v40, v41
	global_store_dwordx4 v[44:45], v[32:35], off offset:256
	v_and_b32_e32 v37, 0xffff0000, v92
	v_lshlrev_b32_e32 v38, 16, v93
	v_lshlrev_b32_e32 v32, 16, v90
	v_and_b32_e32 v33, 0xffff0000, v90
	v_and_b32_e32 v39, 0xffff0000, v93
	v_pk_fma_f32 v[28:29], v[28:29], v[132:133], v[32:33]
	v_lshlrev_b32_e32 v34, 16, v91
	v_and_b32_e32 v35, 0xffff0000, v91
	v_pk_fma_f32 v[32:33], v[26:27], v[130:131], v[38:39]
	v_pk_fma_f32 v[26:27], v[24:25], v[128:129], v[36:37]
	v_cvt_pk_bf16_f32 v24, v28, v29
	v_lshl_add_u64 v[28:29], s[8:9], 0, v[102:103]
	v_pk_fma_f32 v[30:31], v[30:31], v[134:135], v[34:35]
	v_lshl_add_u64 v[28:29], v[28:29], 0, v[178:179]
	v_cvt_pk_bf16_f32 v25, v30, v31
	v_cvt_pk_bf16_f32 v26, v26, v27
	v_cvt_pk_bf16_f32 v27, v32, v33
	global_store_dwordx4 v[28:29], v[24:27], off
	v_lshlrev_b32_e32 v30, 16, v96
	v_and_b32_e32 v31, 0xffff0000, v96
	v_lshlrev_b32_e32 v24, 16, v94
	v_and_b32_e32 v25, 0xffff0000, v94
	v_lshlrev_b32_e32 v26, 16, v95
	v_and_b32_e32 v27, 0xffff0000, v95
	v_lshlrev_b32_e32 v32, 16, v97
	v_and_b32_e32 v33, 0xffff0000, v97
	v_pk_fma_f32 v[22:23], v[22:23], v[126:127], v[26:27]
	v_pk_fma_f32 v[20:21], v[20:21], v[124:125], v[24:25]
	v_pk_fma_f32 v[24:25], v[18:19], v[122:123], v[32:33]
	v_pk_fma_f32 v[18:19], v[16:17], v[120:121], v[30:31]
	v_cvt_pk_bf16_f32 v16, v20, v21
	v_cvt_pk_bf16_f32 v17, v22, v23
	v_lshlrev_b32_e32 v20, 16, v70
	v_cvt_pk_bf16_f32 v18, v18, v19
	v_cvt_pk_bf16_f32 v19, v24, v25
	global_store_dwordx4 v[28:29], v[16:19], off offset:256
	v_and_b32_e32 v21, 0xffff0000, v70
	v_lshlrev_b32_e32 v22, 16, v71
	v_lshlrev_b32_e32 v16, 16, v68
	v_and_b32_e32 v17, 0xffff0000, v68
	v_and_b32_e32 v23, 0xffff0000, v71
	v_pk_fma_f32 v[12:13], v[12:13], v[132:133], v[16:17]
	v_lshlrev_b32_e32 v18, 16, v69
	v_and_b32_e32 v19, 0xffff0000, v69
	v_pk_fma_f32 v[16:17], v[10:11], v[130:131], v[22:23]
	v_pk_fma_f32 v[10:11], v[8:9], v[128:129], v[20:21]
	v_cvt_pk_bf16_f32 v8, v12, v13
	v_lshl_add_u64 v[12:13], s[8:9], 0, v[72:73]
	v_pk_fma_f32 v[14:15], v[14:15], v[134:135], v[18:19]
	v_lshl_add_u64 v[12:13], v[12:13], 0, v[178:179]
	v_cvt_pk_bf16_f32 v9, v14, v15
	v_cvt_pk_bf16_f32 v10, v10, v11
	v_cvt_pk_bf16_f32 v11, v16, v17
	global_store_dwordx4 v[12:13], v[8:11], off
	v_lshlrev_b32_e32 v14, 16, v66
	v_and_b32_e32 v15, 0xffff0000, v66
	v_lshlrev_b32_e32 v8, 16, v64
	v_and_b32_e32 v9, 0xffff0000, v64
	v_lshlrev_b32_e32 v16, 16, v67
	v_and_b32_e32 v17, 0xffff0000, v67
	v_lshlrev_b32_e32 v10, 16, v65
	v_and_b32_e32 v11, 0xffff0000, v65
	v_pk_fma_f32 v[4:5], v[4:5], v[124:125], v[8:9]
	v_pk_fma_f32 v[8:9], v[2:3], v[122:123], v[16:17]
	v_pk_fma_f32 v[2:3], v[0:1], v[120:121], v[14:15]
	v_pk_fma_f32 v[6:7], v[6:7], v[126:127], v[10:11]
	v_cvt_pk_bf16_f32 v0, v4, v5
	s_nop 0
	v_cvt_pk_bf16_f32 v1, v6, v7
	v_cvt_pk_bf16_f32 v2, v2, v3
	v_cvt_pk_bf16_f32 v3, v8, v9
	global_store_dwordx4 v[12:13], v[0:3], off offset:256
	s_cbranch_vccz .LBB0_235
	s_waitcnt vmcnt(0)
	s_cmpk_gt_u32 s16, 0xff
	s_cbranch_scc1 .LBB0_250
	s_barrier

.LBB0_271:
	s_add_u32 s39, s10, 0x100
	v_mov_b32_e32 v0, 0
	s_addc_u32 s40, s11, 0
	s_mov_b32 s41, -2
	v_mov_b32_e32 v1, v0
	v_mov_b32_e32 v2, v0
	v_mov_b32_e32 v3, v0
	v_mov_b32_e32 v4, v0
	v_mov_b32_e32 v5, v0
	v_mov_b32_e32 v6, v0
	v_mov_b32_e32 v7, v0
	v_mov_b32_e32 v12, v0
	v_mov_b32_e32 v13, v0
	v_mov_b32_e32 v14, v0
	v_mov_b32_e32 v15, v0
	v_mov_b32_e32 v20, v0
	v_mov_b32_e32 v21, v0
	v_mov_b32_e32 v22, v0
	v_mov_b32_e32 v23, v0
	v_mov_b32_e32 v28, v0
	v_mov_b32_e32 v29, v0
	v_mov_b32_e32 v30, v0
	v_mov_b32_e32 v31, v0
	v_mov_b32_e32 v36, v0
	v_mov_b32_e32 v37, v0
	v_mov_b32_e32 v38, v0
	v_mov_b32_e32 v39, v0
	v_mov_b32_e32 v44, v0
	v_mov_b32_e32 v45, v0
	v_mov_b32_e32 v46, v0
	v_mov_b32_e32 v47, v0
	v_mov_b32_e32 v52, v0
	v_mov_b32_e32 v53, v0
	v_mov_b32_e32 v54, v0
	v_mov_b32_e32 v55, v0
	v_mov_b32_e32 v8, v0
	v_mov_b32_e32 v9, v0
	v_mov_b32_e32 v10, v0
	v_mov_b32_e32 v11, v0
	v_mov_b32_e32 v16, v0
	v_mov_b32_e32 v17, v0
	v_mov_b32_e32 v18, v0
	v_mov_b32_e32 v19, v0
	v_mov_b32_e32 v24, v0
	v_mov_b32_e32 v25, v0
	v_mov_b32_e32 v26, v0
	v_mov_b32_e32 v27, v0
	v_mov_b32_e32 v32, v0
	v_mov_b32_e32 v33, v0
	v_mov_b32_e32 v34, v0
	v_mov_b32_e32 v35, v0
	v_mov_b32_e32 v40, v0
	v_mov_b32_e32 v41, v0
	v_mov_b32_e32 v42, v0
	v_mov_b32_e32 v43, v0
	v_mov_b32_e32 v48, v0
	v_mov_b32_e32 v49, v0
	v_mov_b32_e32 v50, v0
	v_mov_b32_e32 v51, v0
	v_mov_b32_e32 v56, v0
	v_mov_b32_e32 v57, v0
	v_mov_b32_e32 v58, v0
	v_mov_b32_e32 v59, v0
	v_mov_b32_e32 v60, v0
	v_mov_b32_e32 v61, v0
	v_mov_b32_e32 v62, v0
	v_mov_b32_e32 v63, v0
	v_mov_b32_e32 v64, v0
	v_mov_b32_e32 v65, v0
	v_mov_b32_e32 v66, v0
	v_mov_b32_e32 v67, v0
	v_mov_b32_e32 v68, v0
	v_mov_b32_e32 v69, v0
	v_mov_b32_e32 v70, v0
	v_mov_b32_e32 v71, v0
	v_mov_b32_e32 v76, v0
	v_mov_b32_e32 v77, v0
	v_mov_b32_e32 v78, v0
	v_mov_b32_e32 v79, v0
	v_mov_b32_e32 v84, v0
	v_mov_b32_e32 v85, v0
	v_mov_b32_e32 v86, v0
	v_mov_b32_e32 v87, v0
	v_mov_b32_e32 v92, v0
	v_mov_b32_e32 v93, v0
	v_mov_b32_e32 v94, v0
	v_mov_b32_e32 v95, v0
	v_mov_b32_e32 v100, v0
	v_mov_b32_e32 v101, v0
	v_mov_b32_e32 v102, v0
	v_mov_b32_e32 v103, v0
	v_mov_b32_e32 v124, v0
	v_mov_b32_e32 v125, v0
	v_mov_b32_e32 v126, v0
	v_mov_b32_e32 v127, v0
	v_mov_b32_e32 v128, v0
	v_mov_b32_e32 v129, v0
	v_mov_b32_e32 v130, v0
	v_mov_b32_e32 v131, v0
	v_mov_b32_e32 v72, v0
	v_mov_b32_e32 v73, v0
	v_mov_b32_e32 v74, v0
	v_mov_b32_e32 v75, v0
	v_mov_b32_e32 v80, v0
	v_mov_b32_e32 v81, v0
	v_mov_b32_e32 v82, v0
	v_mov_b32_e32 v83, v0
	v_mov_b32_e32 v88, v0
	v_mov_b32_e32 v89, v0
	v_mov_b32_e32 v90, v0
	v_mov_b32_e32 v91, v0
	v_mov_b32_e32 v96, v0
	v_mov_b32_e32 v97, v0
	v_mov_b32_e32 v98, v0
	v_mov_b32_e32 v99, v0
	v_mov_b32_e32 v104, v0
	v_mov_b32_e32 v105, v0
	v_mov_b32_e32 v106, v0
	v_mov_b32_e32 v107, v0
	v_mov_b32_e32 v132, v0
	v_mov_b32_e32 v133, v0
	v_mov_b32_e32 v134, v0
	v_mov_b32_e32 v135, v0
	v_mov_b32_e32 v136, v0
	v_mov_b32_e32 v137, v0
	v_mov_b32_e32 v138, v0
	v_mov_b32_e32 v139, v0
	v_mov_b32_e32 v140, v0
	v_mov_b32_e32 v141, v0
	v_mov_b32_e32 v142, v0
	v_mov_b32_e32 v143, v0
	s_mov_b64 s[44:45], 0x80
	v_add_u32_e32 v220, 0x10000, v187
.LBB0_272:
	s_add_u32 s10, s8, 0x100
	s_addc_u32 s11, s9, 0
	s_add_i32 s42, 0, 0x10000
	ds_read_b128 v[108:111], v220 offset:0
	ds_read_b128 v[112:115], v220 offset:1024
	ds_read_b128 v[116:119], v220 offset:2048
	ds_read_b128 v[120:123], v220 offset:3072
	s_cmpk_eq_i32 s41, 0x54
	s_cselect_b32 s15, s5, s11
	s_cselect_b32 s14, s4, s10
	s_cselect_b32 s13, s7, s40
	s_cselect_b32 s12, s6, s39
	s_add_i32 m0, s25, 0xc000
	ds_read_b128 v[144:147], v189
	ds_read_b128 v[148:151], v189 offset:1024
	ds_read_b128 v[152:155], v189 offset:2048
	ds_read_b128 v[156:159], v189 offset:3072
	ds_read_b128 v[160:163], v189 offset:4096
	ds_read_b128 v[174:177], v189 offset:5120
	ds_read_b128 v[178:181], v189 offset:6144
	ds_read_b128 v[182:185], v189 offset:7168
	global_load_lds_dwordx4 v170, s[8:9]
	s_add_i32 m0, s25, 0xe000
	s_nop 0
	global_load_lds_dwordx4 v172, s[8:9]
	s_waitcnt lgkmcnt(8)
	s_barrier
	s_waitcnt lgkmcnt(0)
	v_mfma_f32_16x16x32_bf16 v[140:143], v[108:111], v[144:147], v[140:143]
	v_mfma_f32_16x16x32_bf16 v[136:139], v[116:119], v[144:147], v[136:139]
	v_mfma_f32_16x16x32_bf16 v[132:135], v[108:111], v[152:155], v[132:135]
	v_mfma_f32_16x16x32_bf16 v[104:107], v[116:119], v[152:155], v[104:107]
	v_mfma_f32_16x16x32_bf16 v[96:99], v[108:111], v[160:163], v[96:99]
	v_mfma_f32_16x16x32_bf16 v[88:91], v[116:119], v[160:163], v[88:91]
	v_mfma_f32_16x16x32_bf16 v[80:83], v[108:111], v[178:181], v[80:83]
	v_mfma_f32_16x16x32_bf16 v[72:75], v[116:119], v[178:181], v[72:75]
	v_mfma_f32_16x16x32_bf16 v[140:143], v[112:115], v[148:151], v[140:143]
	v_mfma_f32_16x16x32_bf16 v[136:139], v[120:123], v[148:151], v[136:139]
	v_mfma_f32_16x16x32_bf16 v[132:135], v[112:115], v[156:159], v[132:135]
	v_mfma_f32_16x16x32_bf16 v[104:107], v[120:123], v[156:159], v[104:107]
	v_mfma_f32_16x16x32_bf16 v[96:99], v[112:115], v[174:177], v[96:99]
	v_mfma_f32_16x16x32_bf16 v[88:91], v[120:123], v[174:177], v[88:91]
	v_mfma_f32_16x16x32_bf16 v[80:83], v[112:115], v[182:185], v[80:83]
	v_mfma_f32_16x16x32_bf16 v[72:75], v[120:123], v[182:185], v[72:75]
	s_barrier
	s_add_i32 s43, 0, 0x14000
	s_add_i32 s8, s42, s19
	ds_read_b128 v[196:199], v220 offset:16384
	ds_read_b128 v[204:207], v220 offset:17408
	ds_read_b128 v[208:211], v220 offset:18432
	ds_read_b128 v[214:217], v220 offset:19456
	s_mov_b32 m0, s8
	s_nop 0
	global_load_lds_dwordx4 v192, s[12:13]
	s_add_i32 m0, s8, 0x2000
	s_nop 0
	global_load_lds_dwordx4 v168, s[12:13]
	s_barrier
	s_waitcnt lgkmcnt(0)
	v_mfma_f32_16x16x32_bf16 v[128:131], v[196:199], v[144:147], v[128:131]
	v_mfma_f32_16x16x32_bf16 v[124:127], v[208:211], v[144:147], v[124:127]
	v_mfma_f32_16x16x32_bf16 v[100:103], v[196:199], v[152:155], v[100:103]
	v_mfma_f32_16x16x32_bf16 v[92:95], v[208:211], v[152:155], v[92:95]
	v_mfma_f32_16x16x32_bf16 v[84:87], v[196:199], v[160:163], v[84:87]
	v_mfma_f32_16x16x32_bf16 v[76:79], v[208:211], v[160:163], v[76:79]
	v_mfma_f32_16x16x32_bf16 v[68:71], v[196:199], v[178:181], v[68:71]
	v_mfma_f32_16x16x32_bf16 v[64:67], v[208:211], v[178:181], v[64:67]
	v_mfma_f32_16x16x32_bf16 v[128:131], v[204:207], v[148:151], v[128:131]
	v_mfma_f32_16x16x32_bf16 v[124:127], v[214:217], v[148:151], v[124:127]
	v_mfma_f32_16x16x32_bf16 v[100:103], v[204:207], v[156:159], v[100:103]
	v_mfma_f32_16x16x32_bf16 v[92:95], v[214:217], v[156:159], v[92:95]
	v_mfma_f32_16x16x32_bf16 v[84:87], v[204:207], v[174:177], v[84:87]
	v_mfma_f32_16x16x32_bf16 v[76:79], v[214:217], v[174:177], v[76:79]
	v_mfma_f32_16x16x32_bf16 v[68:71], v[204:207], v[182:185], v[68:71]
	v_mfma_f32_16x16x32_bf16 v[64:67], v[214:217], v[182:185], v[64:67]
	s_mov_b32 m0, s25
	s_add_u32 s44, s14, 0x80
	s_addc_u32 s45, s15, 0
	s_barrier
	ds_read_b128 v[144:147], v189 offset:16384
	ds_read_b128 v[148:151], v189 offset:17408
	ds_read_b128 v[152:155], v189 offset:18432
	ds_read_b128 v[156:159], v189 offset:19456
	ds_read_b128 v[160:163], v189 offset:20480
	ds_read_b128 v[174:177], v189 offset:21504
	ds_read_b128 v[178:181], v189 offset:22528
	ds_read_b128 v[182:185], v189 offset:23552
	global_load_lds_dwordx4 v164, s[14:15]
	s_mov_b32 m0, s26
	s_nop 0
	global_load_lds_dwordx4 v166, s[14:15]
	s_barrier
	s_waitcnt lgkmcnt(0)
	v_mfma_f32_16x16x32_bf16 v[60:63], v[108:111], v[144:147], v[60:63]
	v_mfma_f32_16x16x32_bf16 v[56:59], v[116:119], v[144:147], v[56:59]
	v_mfma_f32_16x16x32_bf16 v[48:51], v[108:111], v[152:155], v[48:51]
	v_mfma_f32_16x16x32_bf16 v[40:43], v[116:119], v[152:155], v[40:43]
	v_mfma_f32_16x16x32_bf16 v[32:35], v[108:111], v[160:163], v[32:35]
	v_mfma_f32_16x16x32_bf16 v[24:27], v[116:119], v[160:163], v[24:27]
	v_mfma_f32_16x16x32_bf16 v[16:19], v[108:111], v[178:181], v[16:19]
	v_mfma_f32_16x16x32_bf16 v[8:11], v[116:119], v[178:181], v[8:11]
	v_mfma_f32_16x16x32_bf16 v[60:63], v[112:115], v[148:151], v[60:63]
	v_mfma_f32_16x16x32_bf16 v[56:59], v[120:123], v[148:151], v[56:59]
	v_mfma_f32_16x16x32_bf16 v[48:51], v[112:115], v[156:159], v[48:51]
	v_mfma_f32_16x16x32_bf16 v[40:43], v[120:123], v[156:159], v[40:43]
	v_mfma_f32_16x16x32_bf16 v[32:35], v[112:115], v[174:177], v[32:35]
	v_mfma_f32_16x16x32_bf16 v[24:27], v[120:123], v[174:177], v[24:27]
	v_mfma_f32_16x16x32_bf16 v[16:19], v[112:115], v[182:185], v[16:19]
	v_mfma_f32_16x16x32_bf16 v[8:11], v[120:123], v[182:185], v[8:11]
	s_barrier
	s_add_u32 s8, s12, 0x160000
	s_addc_u32 s9, s13, 0
	s_add_i32 s42, s43, s19
	s_mov_b32 m0, s42
	s_nop 0
	global_load_lds_dwordx4 v192, s[8:9]
	s_add_i32 m0, s42, 0x2000
	s_nop 0
	global_load_lds_dwordx4 v168, s[8:9]
	s_waitcnt vmcnt(6)
	s_barrier
	v_mfma_f32_16x16x32_bf16 v[52:55], v[196:199], v[144:147], v[52:55]
	v_mfma_f32_16x16x32_bf16 v[44:47], v[208:211], v[144:147], v[44:47]
	v_mfma_f32_16x16x32_bf16 v[36:39], v[196:199], v[152:155], v[36:39]
	v_mfma_f32_16x16x32_bf16 v[28:31], v[208:211], v[152:155], v[28:31]
	v_mfma_f32_16x16x32_bf16 v[20:23], v[196:199], v[160:163], v[20:23]
	v_mfma_f32_16x16x32_bf16 v[12:15], v[208:211], v[160:163], v[12:15]
	v_mfma_f32_16x16x32_bf16 v[4:7], v[196:199], v[178:181], v[4:7]
	v_mfma_f32_16x16x32_bf16 v[0:3], v[208:211], v[178:181], v[0:3]
	v_mfma_f32_16x16x32_bf16 v[52:55], v[204:207], v[148:151], v[52:55]
	v_mfma_f32_16x16x32_bf16 v[44:47], v[214:217], v[148:151], v[44:47]
	v_mfma_f32_16x16x32_bf16 v[36:39], v[204:207], v[156:159], v[36:39]
	v_mfma_f32_16x16x32_bf16 v[28:31], v[214:217], v[156:159], v[28:31]
	v_mfma_f32_16x16x32_bf16 v[20:23], v[204:207], v[174:177], v[20:23]
	v_mfma_f32_16x16x32_bf16 v[12:15], v[214:217], v[174:177], v[12:15]
	v_mfma_f32_16x16x32_bf16 v[4:7], v[204:207], v[182:185], v[4:7]
	v_mfma_f32_16x16x32_bf16 v[0:3], v[214:217], v[182:185], v[0:3]
	s_add_i32 s42, 0, 0x18000
	s_barrier
	ds_read_b128 v[108:111], v220 offset:32768
	ds_read_b128 v[112:115], v220 offset:33792
	ds_read_b128 v[116:119], v220 offset:34816
	ds_read_b128 v[120:123], v220 offset:35840
	s_add_u32 s8, s14, 0x160000
	s_addc_u32 s9, s15, 0
	s_mov_b32 m0, s27
	ds_read_b128 v[144:147], v189 offset:32768
	ds_read_b128 v[148:151], v189 offset:33792
	ds_read_b128 v[152:155], v189 offset:34816
	ds_read_b128 v[156:159], v189 offset:35840
	ds_read_b128 v[160:163], v189 offset:36864
	ds_read_b128 v[174:177], v189 offset:37888
	ds_read_b128 v[178:181], v189 offset:38912
	ds_read_b128 v[182:185], v189 offset:39936
	global_load_lds_dwordx4 v164, s[8:9]
	s_mov_b32 m0, s28
	s_nop 0
	global_load_lds_dwordx4 v166, s[8:9]
	s_waitcnt lgkmcnt(8)
	s_barrier
	s_waitcnt lgkmcnt(0)
	v_mfma_f32_16x16x32_bf16 v[140:143], v[108:111], v[144:147], v[140:143]
	v_mfma_f32_16x16x32_bf16 v[136:139], v[116:119], v[144:147], v[136:139]
	v_mfma_f32_16x16x32_bf16 v[132:135], v[108:111], v[152:155], v[132:135]
	v_mfma_f32_16x16x32_bf16 v[104:107], v[116:119], v[152:155], v[104:107]
	v_mfma_f32_16x16x32_bf16 v[96:99], v[108:111], v[160:163], v[96:99]
	v_mfma_f32_16x16x32_bf16 v[88:91], v[116:119], v[160:163], v[88:91]
	v_mfma_f32_16x16x32_bf16 v[80:83], v[108:111], v[178:181], v[80:83]
	v_mfma_f32_16x16x32_bf16 v[72:75], v[116:119], v[178:181], v[72:75]
	v_mfma_f32_16x16x32_bf16 v[140:143], v[112:115], v[148:151], v[140:143]
	v_mfma_f32_16x16x32_bf16 v[136:139], v[120:123], v[148:151], v[136:139]
	v_mfma_f32_16x16x32_bf16 v[132:135], v[112:115], v[156:159], v[132:135]
	v_mfma_f32_16x16x32_bf16 v[104:107], v[120:123], v[156:159], v[104:107]
	v_mfma_f32_16x16x32_bf16 v[96:99], v[112:115], v[174:177], v[96:99]
	v_mfma_f32_16x16x32_bf16 v[88:91], v[120:123], v[174:177], v[88:91]
	v_mfma_f32_16x16x32_bf16 v[80:83], v[112:115], v[182:185], v[80:83]
	v_mfma_f32_16x16x32_bf16 v[72:75], v[120:123], v[182:185], v[72:75]
	s_barrier
	s_add_i32 s14, 0, 0x1c000
	s_add_i32 s8, s42, s19
	s_add_i32 m0, s8, 0xffffff80
	ds_read_b128 v[196:199], v220 offset:49152
	ds_read_b128 v[204:207], v220 offset:50176
	ds_read_b128 v[208:211], v220 offset:51200
	ds_read_b128 v[214:217], v220 offset:52224
	global_load_lds_dwordx4 v192, s[12:13] offset:128
	s_add_i32 m0, s8, 0x1f80
	s_nop 0
	global_load_lds_dwordx4 v168, s[12:13] offset:128
	s_barrier
	s_waitcnt lgkmcnt(0)
	v_mfma_f32_16x16x32_bf16 v[128:131], v[196:199], v[144:147], v[128:131]
	v_mfma_f32_16x16x32_bf16 v[124:127], v[208:211], v[144:147], v[124:127]
	v_mfma_f32_16x16x32_bf16 v[100:103], v[196:199], v[152:155], v[100:103]
	v_mfma_f32_16x16x32_bf16 v[92:95], v[208:211], v[152:155], v[92:95]
	v_mfma_f32_16x16x32_bf16 v[84:87], v[196:199], v[160:163], v[84:87]
	v_mfma_f32_16x16x32_bf16 v[76:79], v[208:211], v[160:163], v[76:79]
	v_mfma_f32_16x16x32_bf16 v[68:71], v[196:199], v[178:181], v[68:71]
	v_mfma_f32_16x16x32_bf16 v[64:67], v[208:211], v[178:181], v[64:67]
	v_mfma_f32_16x16x32_bf16 v[128:131], v[204:207], v[148:151], v[128:131]
	v_mfma_f32_16x16x32_bf16 v[124:127], v[214:217], v[148:151], v[124:127]
	v_mfma_f32_16x16x32_bf16 v[100:103], v[204:207], v[156:159], v[100:103]
	v_mfma_f32_16x16x32_bf16 v[92:95], v[214:217], v[156:159], v[92:95]
	v_mfma_f32_16x16x32_bf16 v[84:87], v[204:207], v[174:177], v[84:87]
	v_mfma_f32_16x16x32_bf16 v[76:79], v[214:217], v[174:177], v[76:79]
	v_mfma_f32_16x16x32_bf16 v[68:71], v[204:207], v[182:185], v[68:71]
	v_mfma_f32_16x16x32_bf16 v[64:67], v[214:217], v[182:185], v[64:67]
	s_mov_b32 m0, s31
	s_barrier
	ds_read_b128 v[144:147], v189 offset:49152
	ds_read_b128 v[148:151], v189 offset:50176
	ds_read_b128 v[152:155], v189 offset:51200
	ds_read_b128 v[156:159], v189 offset:52224
	ds_read_b128 v[160:163], v189 offset:53248
	ds_read_b128 v[174:177], v189 offset:54272
	ds_read_b128 v[178:181], v189 offset:55296
	ds_read_b128 v[182:185], v189 offset:56320
	global_load_lds_dwordx4 v164, s[44:45]
	s_mov_b32 m0, s33
	s_nop 0
	global_load_lds_dwordx4 v166, s[44:45]
	s_barrier
	s_waitcnt lgkmcnt(0)
	v_mfma_f32_16x16x32_bf16 v[60:63], v[108:111], v[144:147], v[60:63]
	v_mfma_f32_16x16x32_bf16 v[56:59], v[116:119], v[144:147], v[56:59]
	v_mfma_f32_16x16x32_bf16 v[48:51], v[108:111], v[152:155], v[48:51]
	v_mfma_f32_16x16x32_bf16 v[40:43], v[116:119], v[152:155], v[40:43]
	v_mfma_f32_16x16x32_bf16 v[32:35], v[108:111], v[160:163], v[32:35]
	v_mfma_f32_16x16x32_bf16 v[24:27], v[116:119], v[160:163], v[24:27]
	v_mfma_f32_16x16x32_bf16 v[16:19], v[108:111], v[178:181], v[16:19]
	v_mfma_f32_16x16x32_bf16 v[8:11], v[116:119], v[178:181], v[8:11]
	v_mfma_f32_16x16x32_bf16 v[60:63], v[112:115], v[148:151], v[60:63]
	v_mfma_f32_16x16x32_bf16 v[56:59], v[120:123], v[148:151], v[56:59]
	v_mfma_f32_16x16x32_bf16 v[48:51], v[112:115], v[156:159], v[48:51]
	v_mfma_f32_16x16x32_bf16 v[40:43], v[120:123], v[156:159], v[40:43]
	v_mfma_f32_16x16x32_bf16 v[32:35], v[112:115], v[174:177], v[32:35]
	v_mfma_f32_16x16x32_bf16 v[24:27], v[120:123], v[174:177], v[24:27]
	v_mfma_f32_16x16x32_bf16 v[16:19], v[112:115], v[182:185], v[16:19]
	v_mfma_f32_16x16x32_bf16 v[8:11], v[120:123], v[182:185], v[8:11]
	s_barrier
	s_add_u32 s8, s12, 0x160080
	s_addc_u32 s9, s13, 0
	s_add_i32 s12, s14, s19
	s_mov_b32 m0, s12
	s_nop 0
	global_load_lds_dwordx4 v192, s[8:9]
	s_add_i32 m0, s12, 0x2000
	s_nop 0
	global_load_lds_dwordx4 v168, s[8:9]
	s_waitcnt vmcnt(6)
	s_barrier
	v_mfma_f32_16x16x32_bf16 v[52:55], v[196:199], v[144:147], v[52:55]
	v_mfma_f32_16x16x32_bf16 v[44:47], v[208:211], v[144:147], v[44:47]
	v_mfma_f32_16x16x32_bf16 v[36:39], v[196:199], v[152:155], v[36:39]
	v_mfma_f32_16x16x32_bf16 v[28:31], v[208:211], v[152:155], v[28:31]
	v_mfma_f32_16x16x32_bf16 v[20:23], v[196:199], v[160:163], v[20:23]
	v_mfma_f32_16x16x32_bf16 v[12:15], v[208:211], v[160:163], v[12:15]
	v_mfma_f32_16x16x32_bf16 v[4:7], v[196:199], v[178:181], v[4:7]
	v_mfma_f32_16x16x32_bf16 v[0:3], v[208:211], v[178:181], v[0:3]
	v_mfma_f32_16x16x32_bf16 v[52:55], v[204:207], v[148:151], v[52:55]
	v_mfma_f32_16x16x32_bf16 v[44:47], v[214:217], v[148:151], v[44:47]
	v_mfma_f32_16x16x32_bf16 v[36:39], v[204:207], v[156:159], v[36:39]
	v_mfma_f32_16x16x32_bf16 v[28:31], v[214:217], v[156:159], v[28:31]
	v_mfma_f32_16x16x32_bf16 v[20:23], v[204:207], v[174:177], v[20:23]
	v_mfma_f32_16x16x32_bf16 v[12:15], v[214:217], v[174:177], v[12:15]
	v_mfma_f32_16x16x32_bf16 v[4:7], v[204:207], v[182:185], v[4:7]
	v_mfma_f32_16x16x32_bf16 v[0:3], v[214:217], v[182:185], v[0:3]
	s_add_i32 s41, s41, 2
	s_add_u32 s39, s39, 0x100
	s_addc_u32 s40, s40, 0
	s_cmpk_gt_u32 s41, 0x55
	s_mov_b64 s[8:9], s[10:11]
	s_barrier
	s_cbranch_scc0 .LBB0_272
	s_ashr_i32 s8, s37, 4
	v_lshl_or_b32 v144, s38, 8, v188
	s_mul_hi_i32 s9, s8, 0xc000
	s_mul_i32 s8, s8, 0xc000
	v_lshl_add_u32 v178, s37, 8, v186
	s_add_u32 s8, s29, s8
	v_ashrrev_i32_e32 v145, 31, v144
	v_ashrrev_i32_e32 v179, 31, v178
	s_addc_u32 s9, s30, s9
	v_lshlrev_b64 v[174:175], 2, v[144:145]
	v_lshl_add_u64 v[176:177], v[144:145], 1, s[2:3]
	v_lshlrev_b64 v[144:145], 12, v[178:179]
	v_lshl_add_u64 v[112:113], s[8:9], 0, v[174:175]
	v_lshl_add_u64 v[144:145], v[176:177], 0, v[144:145]
	global_load_dwordx4 v[116:119], v[112:113], off offset:16
	global_load_dwordx4 v[120:123], v[112:113], off
	global_load_dwordx4 v[108:111], v[112:113], off offset:528
	s_nop 0
	global_load_dwordx4 v[112:115], v[112:113], off offset:512
	s_nop 0
	global_load_dwordx4 v[196:199], v[144:145], off
	global_load_dwordx4 v[204:207], v[144:145], off offset:256
	v_or_b32_e32 v184, 16, v178
	v_ashrrev_i32_e32 v185, 31, v184
	v_lshlrev_b64 v[144:145], 12, v[184:185]
	v_lshl_add_u64 v[144:145], v[176:177], 0, v[144:145]
	global_load_dwordx4 v[208:211], v[144:145], off
	global_load_dwordx4 v[160:163], v[144:145], off offset:256
	v_or_b32_e32 v182, 32, v178
	v_ashrrev_i32_e32 v183, 31, v182
	v_lshlrev_b64 v[144:145], 12, v[182:183]
	v_lshl_add_u64 v[144:145], v[176:177], 0, v[144:145]
	global_load_dwordx4 v[156:159], v[144:145], off
	global_load_dwordx4 v[152:155], v[144:145], off offset:256
	v_or_b32_e32 v180, 48, v178
	v_ashrrev_i32_e32 v181, 31, v180
	v_lshlrev_b64 v[144:145], 12, v[180:181]
	v_lshl_add_u64 v[144:145], v[176:177], 0, v[144:145]
	global_load_dwordx4 v[148:151], v[144:145], off
	s_nop 0
	global_load_dwordx4 v[144:147], v[144:145], off offset:256
	v_readlane_b32 s52, v254, 39
	v_readlane_b32 s66, v254, 53
	v_readlane_b32 s67, v254, 54
	s_and_b64 vcc, exec, s[0:1]
	s_mov_b32 s38, s35
	s_mov_b32 s37, s36
	s_mov_b64 s[10:11], s[6:7]
	s_mov_b64 s[8:9], s[4:5]
	v_readlane_b32 s14, v254, 21
	s_movk_i32 s15, 0x2000
	v_readlane_b32 s53, v254, 40
	v_readlane_b32 s54, v254, 41
	v_readlane_b32 s55, v254, 42
	v_readlane_b32 s56, v254, 43
	v_readlane_b32 s57, v254, 44
	v_readlane_b32 s58, v254, 45
	v_readlane_b32 s59, v254, 46
	v_readlane_b32 s60, v254, 47
	v_readlane_b32 s61, v254, 48
	v_readlane_b32 s62, v254, 49
	v_readlane_b32 s63, v254, 50
	v_readlane_b32 s64, v254, 51
	v_readlane_b32 s65, v254, 52
	s_waitcnt vmcnt(0)
	v_lshlrev_b32_e32 v190, 16, v196
	v_and_b32_e32 v191, 0xffff0000, v196
	v_pk_fma_f32 v[140:141], v[140:141], v[120:121], v[190:191]
	v_lshlrev_b64 v[190:191], 13, v[178:179]
	v_lshlrev_b32_e32 v196, 16, v197
	v_and_b32_e32 v197, 0xffff0000, v197
	v_lshl_add_u64 v[190:191], s[66:67], 0, v[190:191]
	v_pk_fma_f32 v[142:143], v[142:143], v[122:123], v[196:197]
	v_lshl_add_u64 v[190:191], v[190:191], 0, v[174:175]
	global_store_dwordx4 v[190:191], v[140:143], off
	v_lshlrev_b32_e32 v214, 16, v198
	v_and_b32_e32 v215, 0xffff0000, v198
	v_lshlrev_b32_e32 v140, 16, v206
	v_and_b32_e32 v141, 0xffff0000, v206
	v_lshlrev_b32_e32 v142, 16, v207
	v_and_b32_e32 v143, 0xffff0000, v207
	v_pk_fma_f32 v[126:127], v[126:127], v[110:111], v[142:143]
	v_pk_fma_f32 v[124:125], v[124:125], v[108:109], v[140:141]
	global_store_dwordx4 v[190:191], v[124:127], off offset:528
	v_lshlrev_b32_e32 v198, 16, v199
	v_and_b32_e32 v199, 0xffff0000, v199
	v_lshlrev_b32_e32 v124, 16, v208
	v_and_b32_e32 v125, 0xffff0000, v208
	v_pk_fma_f32 v[124:125], v[132:133], v[120:121], v[124:125]
	v_lshlrev_b64 v[132:133], 13, v[184:185]
	v_lshlrev_b32_e32 v126, 16, v209
	v_and_b32_e32 v127, 0xffff0000, v209
	v_lshl_add_u64 v[132:133], s[66:67], 0, v[132:133]
	v_pk_fma_f32 v[126:127], v[134:135], v[122:123], v[126:127]
	v_lshl_add_u64 v[132:133], v[132:133], 0, v[174:175]
	v_pk_fma_f32 v[138:139], v[138:139], v[118:119], v[198:199]
	v_pk_fma_f32 v[136:137], v[136:137], v[116:117], v[214:215]
	global_store_dwordx4 v[132:133], v[124:127], off
	global_store_dwordx4 v[190:191], v[136:139], off offset:16
	s_nop 0
	v_lshlrev_b32_e32 v124, 16, v162
	v_and_b32_e32 v125, 0xffff0000, v162
	v_lshlrev_b32_e32 v126, 16, v163
	v_and_b32_e32 v127, 0xffff0000, v163
	v_lshlrev_b32_e32 v136, 16, v204
	v_and_b32_e32 v137, 0xffff0000, v204
	v_lshlrev_b32_e32 v138, 16, v205
	v_and_b32_e32 v139, 0xffff0000, v205
	v_pk_fma_f32 v[94:95], v[94:95], v[110:111], v[126:127]
	v_pk_fma_f32 v[92:93], v[92:93], v[108:109], v[124:125]
	v_pk_fma_f32 v[130:131], v[130:131], v[114:115], v[138:139]
	v_pk_fma_f32 v[128:129], v[128:129], v[112:113], v[136:137]
	global_store_dwordx4 v[132:133], v[92:95], off offset:528
	global_store_dwordx4 v[190:191], v[128:131], off offset:512
	s_nop 0
	v_lshlrev_b32_e32 v92, 16, v156
	v_and_b32_e32 v93, 0xffff0000, v156
	v_lshlrev_b32_e32 v128, 16, v210
	v_and_b32_e32 v129, 0xffff0000, v210
	v_lshlrev_b32_e32 v130, 16, v211
	v_and_b32_e32 v131, 0xffff0000, v211
	v_pk_fma_f32 v[92:93], v[96:97], v[120:121], v[92:93]
	v_lshlrev_b64 v[96:97], 13, v[182:183]
	v_pk_fma_f32 v[106:107], v[106:107], v[118:119], v[130:131]
	v_pk_fma_f32 v[104:105], v[104:105], v[116:117], v[128:129]
	v_lshlrev_b32_e32 v94, 16, v157
	v_and_b32_e32 v95, 0xffff0000, v157
	v_lshl_add_u64 v[96:97], s[66:67], 0, v[96:97]
	global_store_dwordx4 v[132:133], v[104:107], off offset:16
	v_pk_fma_f32 v[94:95], v[98:99], v[122:123], v[94:95]
	v_lshl_add_u64 v[96:97], v[96:97], 0, v[174:175]
	v_lshlrev_b32_e32 v104, 16, v160
	v_and_b32_e32 v105, 0xffff0000, v160
	v_lshlrev_b32_e32 v106, 16, v161
	v_and_b32_e32 v107, 0xffff0000, v161
	v_pk_fma_f32 v[102:103], v[102:103], v[114:115], v[106:107]
	v_pk_fma_f32 v[100:101], v[100:101], v[112:113], v[104:105]
	global_store_dwordx4 v[96:97], v[92:95], off
	global_store_dwordx4 v[132:133], v[100:103], off offset:512
	v_add_u32_e32 v98, 0x90, v178
	v_lshlrev_b32_e32 v92, 16, v154
	v_and_b32_e32 v93, 0xffff0000, v154
	v_lshlrev_b32_e32 v94, 16, v155
	v_and_b32_e32 v95, 0xffff0000, v155
	v_lshlrev_b32_e32 v100, 16, v158
	v_and_b32_e32 v101, 0xffff0000, v158
	v_lshlrev_b32_e32 v102, 16, v159
	v_and_b32_e32 v103, 0xffff0000, v159
	v_pk_fma_f32 v[78:79], v[78:79], v[110:111], v[94:95]
	v_pk_fma_f32 v[76:77], v[76:77], v[108:109], v[92:93]
	v_pk_fma_f32 v[90:91], v[90:91], v[118:119], v[102:103]
	v_pk_fma_f32 v[88:89], v[88:89], v[116:117], v[100:101]
	global_store_dwordx4 v[96:97], v[76:79], off offset:528
	global_store_dwordx4 v[96:97], v[88:91], off offset:16
	v_ashrrev_i32_e32 v99, 31, v98
	v_lshlrev_b32_e32 v76, 16, v148
	v_and_b32_e32 v77, 0xffff0000, v148
	v_lshlrev_b32_e32 v88, 16, v152
	v_and_b32_e32 v89, 0xffff0000, v152
	v_lshlrev_b32_e32 v90, 16, v153
	v_and_b32_e32 v91, 0xffff0000, v153
	v_pk_fma_f32 v[76:77], v[80:81], v[120:121], v[76:77]
	v_lshlrev_b64 v[80:81], 13, v[180:181]
	v_pk_fma_f32 v[86:87], v[86:87], v[114:115], v[90:91]
	v_pk_fma_f32 v[84:85], v[84:85], v[112:113], v[88:89]
	v_lshlrev_b32_e32 v78, 16, v149
	v_and_b32_e32 v79, 0xffff0000, v149
	v_lshl_add_u64 v[80:81], s[66:67], 0, v[80:81]
	global_store_dwordx4 v[96:97], v[84:87], off offset:512
	v_pk_fma_f32 v[78:79], v[82:83], v[122:123], v[78:79]
	v_lshl_add_u64 v[80:81], v[80:81], 0, v[174:175]
	v_lshlrev_b32_e32 v84, 16, v150
	v_and_b32_e32 v85, 0xffff0000, v150
	v_lshlrev_b32_e32 v86, 16, v151
	v_and_b32_e32 v87, 0xffff0000, v151
	global_store_dwordx4 v[80:81], v[76:79], off
	v_pk_fma_f32 v[74:75], v[74:75], v[118:119], v[86:87]
	v_pk_fma_f32 v[72:73], v[72:73], v[116:117], v[84:85]
	v_lshlrev_b32_e32 v76, 16, v146
	v_and_b32_e32 v77, 0xffff0000, v146
	v_lshlrev_b32_e32 v78, 16, v147
	v_and_b32_e32 v79, 0xffff0000, v147
	v_add_u32_e32 v96, 0x80, v178
	global_store_dwordx4 v[80:81], v[72:75], off offset:16
	v_pk_fma_f32 v[66:67], v[66:67], v[110:111], v[78:79]
	v_pk_fma_f32 v[64:65], v[64:65], v[108:109], v[76:77]
	v_lshlrev_b32_e32 v72, 16, v144
	v_and_b32_e32 v73, 0xffff0000, v144
	v_lshlrev_b32_e32 v74, 16, v145
	v_and_b32_e32 v75, 0xffff0000, v145
	v_ashrrev_i32_e32 v97, 31, v96
	v_pk_fma_f32 v[70:71], v[70:71], v[114:115], v[74:75]
	v_pk_fma_f32 v[68:69], v[68:69], v[112:113], v[72:73]
	global_store_dwordx4 v[80:81], v[64:67], off offset:528
	global_store_dwordx4 v[80:81], v[68:71], off offset:512
	v_add_u32_e32 v100, 0xa0, v178
	v_lshlrev_b64 v[64:65], 12, v[96:97]
	v_lshl_add_u64 v[64:65], v[176:177], 0, v[64:65]
	global_load_dwordx4 v[68:71], v[64:65], off
	global_load_dwordx4 v[72:75], v[64:65], off offset:256
	v_lshlrev_b64 v[64:65], 12, v[98:99]
	v_lshl_add_u64 v[64:65], v[176:177], 0, v[64:65]
	global_load_dwordx4 v[76:79], v[64:65], off
	global_load_dwordx4 v[80:83], v[64:65], off offset:256
	v_ashrrev_i32_e32 v101, 31, v100
	v_lshlrev_b64 v[64:65], 12, v[100:101]
	v_lshl_add_u64 v[64:65], v[176:177], 0, v[64:65]
	global_load_dwordx4 v[84:87], v[64:65], off
	global_load_dwordx4 v[88:91], v[64:65], off offset:256
	v_add_u32_e32 v102, 0xb0, v178
	v_ashrrev_i32_e32 v103, 31, v102
	v_lshlrev_b64 v[64:65], 12, v[102:103]
	v_lshl_add_u64 v[64:65], v[176:177], 0, v[64:65]
	global_load_dwordx4 v[92:95], v[64:65], off
	s_nop 0
	global_load_dwordx4 v[64:67], v[64:65], off offset:256
	s_waitcnt vmcnt(0)
	v_lshlrev_b32_e32 v104, 16, v68
	v_and_b32_e32 v105, 0xffff0000, v68
	v_lshlrev_b32_e32 v68, 16, v69
	v_and_b32_e32 v69, 0xffff0000, v69
	v_pk_fma_f32 v[62:63], v[62:63], v[122:123], v[68:69]
	v_lshlrev_b64 v[68:69], 13, v[96:97]
	v_lshl_add_u64 v[68:69], s[66:67], 0, v[68:69]
	v_pk_fma_f32 v[60:61], v[60:61], v[120:121], v[104:105]
	v_lshl_add_u64 v[68:69], v[68:69], 0, v[174:175]
	global_store_dwordx4 v[68:69], v[60:63], off
	v_lshlrev_b32_e32 v106, 16, v70
	v_and_b32_e32 v107, 0xffff0000, v70
	v_lshlrev_b32_e32 v60, 16, v74
	v_and_b32_e32 v61, 0xffff0000, v74
	v_lshlrev_b32_e32 v62, 16, v75
	v_and_b32_e32 v63, 0xffff0000, v75
	v_pk_fma_f32 v[46:47], v[46:47], v[110:111], v[62:63]
	v_pk_fma_f32 v[44:45], v[44:45], v[108:109], v[60:61]
	global_store_dwordx4 v[68:69], v[44:47], off offset:528
	v_lshlrev_b32_e32 v70, 16, v71
	v_and_b32_e32 v71, 0xffff0000, v71
	v_lshlrev_b32_e32 v44, 16, v76
	v_and_b32_e32 v45, 0xffff0000, v76
	v_pk_fma_f32 v[44:45], v[48:49], v[120:121], v[44:45]
	v_lshlrev_b64 v[48:49], 13, v[98:99]
	v_lshlrev_b32_e32 v46, 16, v77
	v_and_b32_e32 v47, 0xffff0000, v77
	v_lshl_add_u64 v[48:49], s[66:67], 0, v[48:49]
	v_pk_fma_f32 v[58:59], v[58:59], v[118:119], v[70:71]
	v_pk_fma_f32 v[56:57], v[56:57], v[116:117], v[106:107]
	v_pk_fma_f32 v[46:47], v[50:51], v[122:123], v[46:47]
	v_lshl_add_u64 v[48:49], v[48:49], 0, v[174:175]
	global_store_dwordx4 v[68:69], v[56:59], off offset:16
	global_store_dwordx4 v[48:49], v[44:47], off
	s_nop 0
	v_lshlrev_b32_e32 v56, 16, v72
	v_and_b32_e32 v57, 0xffff0000, v72
	v_lshlrev_b32_e32 v58, 16, v73
	v_and_b32_e32 v59, 0xffff0000, v73
	v_lshlrev_b32_e32 v44, 16, v82
	v_and_b32_e32 v45, 0xffff0000, v82
	v_lshlrev_b32_e32 v46, 16, v83
	v_and_b32_e32 v47, 0xffff0000, v83
	v_pk_fma_f32 v[54:55], v[54:55], v[114:115], v[58:59]
	v_pk_fma_f32 v[52:53], v[52:53], v[112:113], v[56:57]
	v_pk_fma_f32 v[30:31], v[30:31], v[110:111], v[46:47]
	v_pk_fma_f32 v[28:29], v[28:29], v[108:109], v[44:45]
	global_store_dwordx4 v[68:69], v[52:55], off offset:512
	global_store_dwordx4 v[48:49], v[28:31], off offset:528
	s_nop 0
	v_lshlrev_b32_e32 v52, 16, v78
	v_and_b32_e32 v53, 0xffff0000, v78
	v_lshlrev_b32_e32 v54, 16, v79
	v_and_b32_e32 v55, 0xffff0000, v79
	v_lshlrev_b32_e32 v28, 16, v84
	v_and_b32_e32 v29, 0xffff0000, v84
	v_pk_fma_f32 v[42:43], v[42:43], v[118:119], v[54:55]
	v_pk_fma_f32 v[40:41], v[40:41], v[116:117], v[52:53]
	v_pk_fma_f32 v[28:29], v[32:33], v[120:121], v[28:29]
	v_lshlrev_b64 v[32:33], 13, v[100:101]
	global_store_dwordx4 v[48:49], v[40:43], off offset:16
	v_lshlrev_b32_e32 v30, 16, v85
	v_and_b32_e32 v31, 0xffff0000, v85
	v_lshlrev_b32_e32 v40, 16, v80
	v_and_b32_e32 v41, 0xffff0000, v80
	v_lshlrev_b32_e32 v42, 16, v81
	v_and_b32_e32 v43, 0xffff0000, v81
	v_lshl_add_u64 v[32:33], s[66:67], 0, v[32:33]
	v_pk_fma_f32 v[38:39], v[38:39], v[114:115], v[42:43]
	v_pk_fma_f32 v[36:37], v[36:37], v[112:113], v[40:41]
	v_pk_fma_f32 v[30:31], v[34:35], v[122:123], v[30:31]
	v_lshl_add_u64 v[32:33], v[32:33], 0, v[174:175]
	global_store_dwordx4 v[48:49], v[36:39], off offset:512
	global_store_dwordx4 v[32:33], v[28:31], off
	s_nop 0
	v_lshlrev_b32_e32 v36, 16, v86
	v_and_b32_e32 v37, 0xffff0000, v86
	v_lshlrev_b32_e32 v38, 16, v87
	v_and_b32_e32 v39, 0xffff0000, v87
	v_lshlrev_b32_e32 v28, 16, v90
	v_and_b32_e32 v29, 0xffff0000, v90
	v_lshlrev_b32_e32 v30, 16, v91
	v_and_b32_e32 v31, 0xffff0000, v91
	v_pk_fma_f32 v[26:27], v[26:27], v[118:119], v[38:39]
	v_pk_fma_f32 v[24:25], v[24:25], v[116:117], v[36:37]
	v_pk_fma_f32 v[14:15], v[14:15], v[110:111], v[30:31]
	v_pk_fma_f32 v[12:13], v[12:13], v[108:109], v[28:29]
	global_store_dwordx4 v[32:33], v[24:27], off offset:16
	global_store_dwordx4 v[32:33], v[12:15], off offset:528
	s_nop 0
	v_lshlrev_b32_e32 v24, 16, v88
	v_and_b32_e32 v25, 0xffff0000, v88
	v_lshlrev_b32_e32 v26, 16, v89
	v_and_b32_e32 v27, 0xffff0000, v89
	v_lshlrev_b32_e32 v12, 16, v92
	v_and_b32_e32 v13, 0xffff0000, v92
	v_pk_fma_f32 v[22:23], v[22:23], v[114:115], v[26:27]
	v_pk_fma_f32 v[20:21], v[20:21], v[112:113], v[24:25]
	v_pk_fma_f32 v[12:13], v[16:17], v[120:121], v[12:13]
	v_lshlrev_b64 v[16:17], 13, v[102:103]
	global_store_dwordx4 v[32:33], v[20:23], off offset:512
	v_lshlrev_b32_e32 v14, 16, v93
	v_and_b32_e32 v15, 0xffff0000, v93
	v_lshlrev_b32_e32 v20, 16, v94
	v_and_b32_e32 v21, 0xffff0000, v94
	v_lshlrev_b32_e32 v22, 16, v95
	v_and_b32_e32 v23, 0xffff0000, v95
	v_lshl_add_u64 v[16:17], s[66:67], 0, v[16:17]
	v_pk_fma_f32 v[14:15], v[18:19], v[122:123], v[14:15]
	v_lshl_add_u64 v[16:17], v[16:17], 0, v[174:175]
	v_pk_fma_f32 v[10:11], v[10:11], v[118:119], v[22:23]
	v_pk_fma_f32 v[8:9], v[8:9], v[116:117], v[20:21]
	global_store_dwordx4 v[16:17], v[12:15], off
	global_store_dwordx4 v[16:17], v[8:11], off offset:16
	s_nop 0
	v_lshlrev_b32_e32 v12, 16, v66
	v_lshlrev_b32_e32 v8, 16, v64
	v_and_b32_e32 v9, 0xffff0000, v64
	v_lshlrev_b32_e32 v10, 16, v65
	v_and_b32_e32 v11, 0xffff0000, v65
	v_and_b32_e32 v13, 0xffff0000, v66
	v_lshlrev_b32_e32 v14, 16, v67
	v_and_b32_e32 v15, 0xffff0000, v67
	v_pk_fma_f32 v[6:7], v[6:7], v[114:115], v[10:11]
	v_pk_fma_f32 v[4:5], v[4:5], v[112:113], v[8:9]
	v_pk_fma_f32 v[2:3], v[2:3], v[110:111], v[14:15]
	v_pk_fma_f32 v[0:1], v[0:1], v[108:109], v[12:13]
	global_store_dwordx4 v[16:17], v[4:7], off offset:512
	global_store_dwordx4 v[16:17], v[0:3], off offset:528
	s_cbranch_vccz .LBB0_261
	s_waitcnt vmcnt(0)
	s_cmpk_gt_u32 s16, 0xff
	s_cbranch_scc1 .LBB0_276
	s_barrier

.LBB0_293:
	v_mov_b64_e32 v[0:1], 0x400
	s_ashr_i32 s7, s6, 31
	v_cmp_lt_i64_e32 vcc, s[8:9], v[0:1]
	s_lshl_b64 s[8:9], s[6:7], 20
	s_add_u32 s8, s20, s8
	s_addc_u32 s9, s21, s9
	s_and_b64 s[10:11], vcc, exec
	s_cselect_b32 s7, s9, s15
	s_cselect_b32 s38, s8, s14
	s_ashr_i32 s5, s4, 31
	s_lshl_b64 s[10:11], s[4:5], 20
	s_add_u32 s10, s22, s10
	s_addc_u32 s11, s23, s11
	s_and_b64 s[18:19], vcc, exec
	s_cselect_b32 s5, s11, s17
	s_cselect_b32 s39, s10, s16
	s_add_u32 s14, s14, 0x80080
	s_addc_u32 s15, s15, 0
	s_add_u32 s40, s16, 0x100
	v_mov_b32_e32 v0, 0
	s_addc_u32 s41, s17, 0
	s_mov_b32 s42, -2
	v_mov_b32_e32 v1, v0
	v_mov_b32_e32 v2, v0
	v_mov_b32_e32 v3, v0
	v_mov_b32_e32 v4, v0
	v_mov_b32_e32 v5, v0
	v_mov_b32_e32 v6, v0
	v_mov_b32_e32 v7, v0
	v_mov_b32_e32 v8, v0
	v_mov_b32_e32 v9, v0
	v_mov_b32_e32 v10, v0
	v_mov_b32_e32 v11, v0
	v_mov_b32_e32 v12, v0
	v_mov_b32_e32 v13, v0
	v_mov_b32_e32 v14, v0
	v_mov_b32_e32 v15, v0
	v_mov_b32_e32 v32, v0
	v_mov_b32_e32 v33, v0
	v_mov_b32_e32 v34, v0
	v_mov_b32_e32 v35, v0
	v_mov_b32_e32 v36, v0
	v_mov_b32_e32 v37, v0
	v_mov_b32_e32 v38, v0
	v_mov_b32_e32 v39, v0
	v_mov_b32_e32 v40, v0
	v_mov_b32_e32 v41, v0
	v_mov_b32_e32 v42, v0
	v_mov_b32_e32 v43, v0
	v_mov_b32_e32 v44, v0
	v_mov_b32_e32 v45, v0
	v_mov_b32_e32 v46, v0
	v_mov_b32_e32 v47, v0
	v_mov_b32_e32 v16, v0
	v_mov_b32_e32 v17, v0
	v_mov_b32_e32 v18, v0
	v_mov_b32_e32 v19, v0
	v_mov_b32_e32 v20, v0
	v_mov_b32_e32 v21, v0
	v_mov_b32_e32 v22, v0
	v_mov_b32_e32 v23, v0
	v_mov_b32_e32 v24, v0
	v_mov_b32_e32 v25, v0
	v_mov_b32_e32 v26, v0
	v_mov_b32_e32 v27, v0
	v_mov_b32_e32 v28, v0
	v_mov_b32_e32 v29, v0
	v_mov_b32_e32 v30, v0
	v_mov_b32_e32 v31, v0
	v_mov_b32_e32 v48, v0
	v_mov_b32_e32 v49, v0
	v_mov_b32_e32 v50, v0
	v_mov_b32_e32 v51, v0
	v_mov_b32_e32 v52, v0
	v_mov_b32_e32 v53, v0
	v_mov_b32_e32 v54, v0
	v_mov_b32_e32 v55, v0
	v_mov_b32_e32 v56, v0
	v_mov_b32_e32 v57, v0
	v_mov_b32_e32 v58, v0
	v_mov_b32_e32 v59, v0
	v_mov_b32_e32 v60, v0
	v_mov_b32_e32 v61, v0
	v_mov_b32_e32 v62, v0
	v_mov_b32_e32 v63, v0
	v_mov_b32_e32 v80, v0
	v_mov_b32_e32 v81, v0
	v_mov_b32_e32 v82, v0
	v_mov_b32_e32 v83, v0
	v_mov_b32_e32 v84, v0
	v_mov_b32_e32 v85, v0
	v_mov_b32_e32 v86, v0
	v_mov_b32_e32 v87, v0
	v_mov_b32_e32 v88, v0
	v_mov_b32_e32 v89, v0
	v_mov_b32_e32 v90, v0
	v_mov_b32_e32 v91, v0
	v_mov_b32_e32 v92, v0
	v_mov_b32_e32 v93, v0
	v_mov_b32_e32 v94, v0
	v_mov_b32_e32 v95, v0
	v_mov_b32_e32 v112, v0
	v_mov_b32_e32 v113, v0
	v_mov_b32_e32 v114, v0
	v_mov_b32_e32 v115, v0
	v_mov_b32_e32 v116, v0
	v_mov_b32_e32 v117, v0
	v_mov_b32_e32 v118, v0
	v_mov_b32_e32 v119, v0
	v_mov_b32_e32 v120, v0
	v_mov_b32_e32 v121, v0
	v_mov_b32_e32 v122, v0
	v_mov_b32_e32 v123, v0
	v_mov_b32_e32 v124, v0
	v_mov_b32_e32 v125, v0
	v_mov_b32_e32 v126, v0
	v_mov_b32_e32 v127, v0
	v_mov_b32_e32 v96, v0
	v_mov_b32_e32 v97, v0
	v_mov_b32_e32 v98, v0
	v_mov_b32_e32 v99, v0
	v_mov_b32_e32 v100, v0
	v_mov_b32_e32 v101, v0
	v_mov_b32_e32 v102, v0
	v_mov_b32_e32 v103, v0
	v_mov_b32_e32 v104, v0
	v_mov_b32_e32 v105, v0
	v_mov_b32_e32 v106, v0
	v_mov_b32_e32 v107, v0
	v_mov_b32_e32 v108, v0
	v_mov_b32_e32 v109, v0
	v_mov_b32_e32 v110, v0
	v_mov_b32_e32 v111, v0
	v_mov_b32_e32 v128, v0
	v_mov_b32_e32 v129, v0
	v_mov_b32_e32 v130, v0
	v_mov_b32_e32 v131, v0
	v_mov_b32_e32 v132, v0
	v_mov_b32_e32 v133, v0
	v_mov_b32_e32 v134, v0
	v_mov_b32_e32 v135, v0
	v_mov_b32_e32 v136, v0
	v_mov_b32_e32 v137, v0
	v_mov_b32_e32 v138, v0
	v_mov_b32_e32 v139, v0
	v_mov_b32_e32 v140, v0
	v_mov_b32_e32 v141, v0
	v_mov_b32_e32 v142, v0
	v_mov_b32_e32 v143, v0
	s_mov_b64 s[48:49], 0x80
	v_add_u32_e32 v220, 0x10000, v159
.LBB0_294:
	s_add_u32 s16, s14, 0xfff80080
	s_addc_u32 s17, s15, -1
	s_add_i32 s43, 0, 0x10000
	ds_read_b128 v[64:67], v220 offset:0
	ds_read_b128 v[68:71], v220 offset:1024
	ds_read_b128 v[72:75], v220 offset:2048
	ds_read_b128 v[76:79], v220 offset:3072
	s_cmp_eq_u32 s42, 28
	s_cselect_b32 s19, s7, s17
	s_cselect_b32 s18, s38, s16
	s_cselect_b32 s17, s5, s41
	s_cselect_b32 s16, s39, s40
	s_add_i32 m0, s13, 0xc000
	ds_read_b128 v[154:157], v161
	ds_read_b128 v[162:165], v161 offset:1024
	ds_read_b128 v[166:169], v161 offset:2048
	ds_read_b128 v[170:173], v161 offset:3072
	ds_read_b128 v[174:177], v161 offset:4096
	ds_read_b128 v[178:181], v161 offset:5120
	ds_read_b128 v[182:185], v161 offset:6144
	ds_read_b128 v[186:189], v161 offset:7168
	global_load_lds_dwordx4 v150, s[14:15]
	s_add_i32 m0, s13, 0xe000
	s_nop 0
	global_load_lds_dwordx4 v152, s[14:15]
	s_waitcnt lgkmcnt(8)
	s_barrier
	s_waitcnt lgkmcnt(0)
	v_mfma_f32_16x16x32_bf16 v[140:143], v[64:67], v[154:157], v[140:143]
	v_mfma_f32_16x16x32_bf16 v[136:139], v[72:75], v[154:157], v[136:139]
	v_mfma_f32_16x16x32_bf16 v[132:135], v[64:67], v[166:169], v[132:135]
	v_mfma_f32_16x16x32_bf16 v[128:131], v[72:75], v[166:169], v[128:131]
	v_mfma_f32_16x16x32_bf16 v[108:111], v[64:67], v[174:177], v[108:111]
	v_mfma_f32_16x16x32_bf16 v[104:107], v[72:75], v[174:177], v[104:107]
	v_mfma_f32_16x16x32_bf16 v[100:103], v[64:67], v[182:185], v[100:103]
	v_mfma_f32_16x16x32_bf16 v[96:99], v[72:75], v[182:185], v[96:99]
	v_mfma_f32_16x16x32_bf16 v[140:143], v[68:71], v[162:165], v[140:143]
	v_mfma_f32_16x16x32_bf16 v[136:139], v[76:79], v[162:165], v[136:139]
	v_mfma_f32_16x16x32_bf16 v[132:135], v[68:71], v[170:173], v[132:135]
	v_mfma_f32_16x16x32_bf16 v[128:131], v[76:79], v[170:173], v[128:131]
	v_mfma_f32_16x16x32_bf16 v[108:111], v[68:71], v[178:181], v[108:111]
	v_mfma_f32_16x16x32_bf16 v[104:107], v[76:79], v[178:181], v[104:107]
	v_mfma_f32_16x16x32_bf16 v[100:103], v[68:71], v[186:189], v[100:103]
	v_mfma_f32_16x16x32_bf16 v[96:99], v[76:79], v[186:189], v[96:99]
	s_barrier
	s_add_i32 s46, 0, 0x14000
	s_add_i32 s43, s43, s27
	ds_read_b128 v[196:199], v220 offset:16384
	ds_read_b128 v[204:207], v220 offset:17408
	ds_read_b128 v[208:211], v220 offset:18432
	ds_read_b128 v[214:217], v220 offset:19456
	s_mov_b32 m0, s43
	s_nop 0
	global_load_lds_dwordx4 v192, s[16:17]
	s_add_i32 m0, s43, 0x2000
	s_nop 0
	global_load_lds_dwordx4 v148, s[16:17]
	s_barrier
	s_waitcnt lgkmcnt(0)
	v_mfma_f32_16x16x32_bf16 v[124:127], v[196:199], v[154:157], v[124:127]
	v_mfma_f32_16x16x32_bf16 v[120:123], v[208:211], v[154:157], v[120:123]
	v_mfma_f32_16x16x32_bf16 v[116:119], v[196:199], v[166:169], v[116:119]
	v_mfma_f32_16x16x32_bf16 v[112:115], v[208:211], v[166:169], v[112:115]
	v_mfma_f32_16x16x32_bf16 v[92:95], v[196:199], v[174:177], v[92:95]
	v_mfma_f32_16x16x32_bf16 v[88:91], v[208:211], v[174:177], v[88:91]
	v_mfma_f32_16x16x32_bf16 v[84:87], v[196:199], v[182:185], v[84:87]
	v_mfma_f32_16x16x32_bf16 v[80:83], v[208:211], v[182:185], v[80:83]
	v_mfma_f32_16x16x32_bf16 v[124:127], v[204:207], v[162:165], v[124:127]
	v_mfma_f32_16x16x32_bf16 v[120:123], v[214:217], v[162:165], v[120:123]
	v_mfma_f32_16x16x32_bf16 v[116:119], v[204:207], v[170:173], v[116:119]
	v_mfma_f32_16x16x32_bf16 v[112:115], v[214:217], v[170:173], v[112:115]
	v_mfma_f32_16x16x32_bf16 v[92:95], v[204:207], v[178:181], v[92:95]
	v_mfma_f32_16x16x32_bf16 v[88:91], v[214:217], v[178:181], v[88:91]
	v_mfma_f32_16x16x32_bf16 v[84:87], v[204:207], v[186:189], v[84:87]
	v_mfma_f32_16x16x32_bf16 v[80:83], v[214:217], v[186:189], v[80:83]
	s_mov_b32 m0, s13
	s_add_u32 s48, s18, 0x80
	s_addc_u32 s49, s19, 0
	s_barrier
	ds_read_b128 v[154:157], v161 offset:16384
	ds_read_b128 v[162:165], v161 offset:17408
	ds_read_b128 v[166:169], v161 offset:18432
	ds_read_b128 v[170:173], v161 offset:19456
	ds_read_b128 v[174:177], v161 offset:20480
	ds_read_b128 v[178:181], v161 offset:21504
	ds_read_b128 v[182:185], v161 offset:22528
	ds_read_b128 v[186:189], v161 offset:23552
	global_load_lds_dwordx4 v144, s[18:19]
	s_mov_b32 m0, s28
	s_nop 0
	global_load_lds_dwordx4 v146, s[18:19]
	s_barrier
	s_waitcnt lgkmcnt(0)
	v_mfma_f32_16x16x32_bf16 v[60:63], v[64:67], v[154:157], v[60:63]
	v_mfma_f32_16x16x32_bf16 v[56:59], v[72:75], v[154:157], v[56:59]
	v_mfma_f32_16x16x32_bf16 v[52:55], v[64:67], v[166:169], v[52:55]
	v_mfma_f32_16x16x32_bf16 v[48:51], v[72:75], v[166:169], v[48:51]
	v_mfma_f32_16x16x32_bf16 v[28:31], v[64:67], v[174:177], v[28:31]
	v_mfma_f32_16x16x32_bf16 v[24:27], v[72:75], v[174:177], v[24:27]
	v_mfma_f32_16x16x32_bf16 v[20:23], v[64:67], v[182:185], v[20:23]
	v_mfma_f32_16x16x32_bf16 v[16:19], v[72:75], v[182:185], v[16:19]
	v_mfma_f32_16x16x32_bf16 v[60:63], v[68:71], v[162:165], v[60:63]
	v_mfma_f32_16x16x32_bf16 v[56:59], v[76:79], v[162:165], v[56:59]
	v_mfma_f32_16x16x32_bf16 v[52:55], v[68:71], v[170:173], v[52:55]
	v_mfma_f32_16x16x32_bf16 v[48:51], v[76:79], v[170:173], v[48:51]
	v_mfma_f32_16x16x32_bf16 v[28:31], v[68:71], v[178:181], v[28:31]
	v_mfma_f32_16x16x32_bf16 v[24:27], v[76:79], v[178:181], v[24:27]
	v_mfma_f32_16x16x32_bf16 v[20:23], v[68:71], v[186:189], v[20:23]
	v_mfma_f32_16x16x32_bf16 v[16:19], v[76:79], v[186:189], v[16:19]
	s_barrier
	s_add_u32 s44, s16, 0x80000
	s_addc_u32 s45, s17, 0
	s_add_i32 s43, s46, s27
	s_mov_b32 m0, s43
	s_nop 0
	global_load_lds_dwordx4 v192, s[44:45]
	s_add_i32 m0, s43, 0x2000
	s_nop 0
	global_load_lds_dwordx4 v148, s[44:45]
	s_waitcnt vmcnt(6)
	s_barrier
	v_mfma_f32_16x16x32_bf16 v[44:47], v[196:199], v[154:157], v[44:47]
	v_mfma_f32_16x16x32_bf16 v[40:43], v[208:211], v[154:157], v[40:43]
	v_mfma_f32_16x16x32_bf16 v[36:39], v[196:199], v[166:169], v[36:39]
	v_mfma_f32_16x16x32_bf16 v[32:35], v[208:211], v[166:169], v[32:35]
	v_mfma_f32_16x16x32_bf16 v[12:15], v[196:199], v[174:177], v[12:15]
	v_mfma_f32_16x16x32_bf16 v[8:11], v[208:211], v[174:177], v[8:11]
	v_mfma_f32_16x16x32_bf16 v[4:7], v[196:199], v[182:185], v[4:7]
	v_mfma_f32_16x16x32_bf16 v[0:3], v[208:211], v[182:185], v[0:3]
	v_mfma_f32_16x16x32_bf16 v[44:47], v[204:207], v[162:165], v[44:47]
	v_mfma_f32_16x16x32_bf16 v[40:43], v[214:217], v[162:165], v[40:43]
	v_mfma_f32_16x16x32_bf16 v[36:39], v[204:207], v[170:173], v[36:39]
	v_mfma_f32_16x16x32_bf16 v[32:35], v[214:217], v[170:173], v[32:35]
	v_mfma_f32_16x16x32_bf16 v[12:15], v[204:207], v[178:181], v[12:15]
	v_mfma_f32_16x16x32_bf16 v[8:11], v[214:217], v[178:181], v[8:11]
	v_mfma_f32_16x16x32_bf16 v[4:7], v[204:207], v[186:189], v[4:7]
	v_mfma_f32_16x16x32_bf16 v[0:3], v[214:217], v[186:189], v[0:3]
	s_add_i32 s43, 0, 0x18000
	s_barrier
	ds_read_b128 v[64:67], v220 offset:32768
	ds_read_b128 v[68:71], v220 offset:33792
	ds_read_b128 v[72:75], v220 offset:34816
	ds_read_b128 v[76:79], v220 offset:35840
	s_add_u32 s18, s18, 0x80000
	s_addc_u32 s19, s19, 0
	s_mov_b32 m0, s29
	ds_read_b128 v[154:157], v161 offset:32768
	ds_read_b128 v[162:165], v161 offset:33792
	ds_read_b128 v[166:169], v161 offset:34816
	ds_read_b128 v[170:173], v161 offset:35840
	ds_read_b128 v[174:177], v161 offset:36864
	ds_read_b128 v[178:181], v161 offset:37888
	ds_read_b128 v[182:185], v161 offset:38912
	ds_read_b128 v[186:189], v161 offset:39936
	global_load_lds_dwordx4 v144, s[18:19]
	s_mov_b32 m0, s30
	s_nop 0
	global_load_lds_dwordx4 v146, s[18:19]
	s_waitcnt lgkmcnt(8)
	s_barrier
	s_waitcnt lgkmcnt(0)
	v_mfma_f32_16x16x32_bf16 v[140:143], v[64:67], v[154:157], v[140:143]
	v_mfma_f32_16x16x32_bf16 v[136:139], v[72:75], v[154:157], v[136:139]
	v_mfma_f32_16x16x32_bf16 v[132:135], v[64:67], v[166:169], v[132:135]
	v_mfma_f32_16x16x32_bf16 v[128:131], v[72:75], v[166:169], v[128:131]
	v_mfma_f32_16x16x32_bf16 v[108:111], v[64:67], v[174:177], v[108:111]
	v_mfma_f32_16x16x32_bf16 v[104:107], v[72:75], v[174:177], v[104:107]
	v_mfma_f32_16x16x32_bf16 v[100:103], v[64:67], v[182:185], v[100:103]
	v_mfma_f32_16x16x32_bf16 v[96:99], v[72:75], v[182:185], v[96:99]
	v_mfma_f32_16x16x32_bf16 v[140:143], v[68:71], v[162:165], v[140:143]
	v_mfma_f32_16x16x32_bf16 v[136:139], v[76:79], v[162:165], v[136:139]
	v_mfma_f32_16x16x32_bf16 v[132:135], v[68:71], v[170:173], v[132:135]
	v_mfma_f32_16x16x32_bf16 v[128:131], v[76:79], v[170:173], v[128:131]
	v_mfma_f32_16x16x32_bf16 v[108:111], v[68:71], v[178:181], v[108:111]
	v_mfma_f32_16x16x32_bf16 v[104:107], v[76:79], v[178:181], v[104:107]
	v_mfma_f32_16x16x32_bf16 v[100:103], v[68:71], v[186:189], v[100:103]
	v_mfma_f32_16x16x32_bf16 v[96:99], v[76:79], v[186:189], v[96:99]
	s_barrier
	s_add_i32 s18, 0, 0x1c000
	s_add_i32 s19, s43, s27
	s_add_i32 m0, s19, 0xffffff80
	ds_read_b128 v[196:199], v220 offset:49152
	ds_read_b128 v[204:207], v220 offset:50176
	ds_read_b128 v[208:211], v220 offset:51200
	ds_read_b128 v[214:217], v220 offset:52224
	global_load_lds_dwordx4 v192, s[16:17] offset:128
	s_add_i32 m0, s19, 0x1f80
	s_nop 0
	global_load_lds_dwordx4 v148, s[16:17] offset:128
	s_barrier
	s_waitcnt lgkmcnt(0)
	v_mfma_f32_16x16x32_bf16 v[124:127], v[196:199], v[154:157], v[124:127]
	v_mfma_f32_16x16x32_bf16 v[120:123], v[208:211], v[154:157], v[120:123]
	v_mfma_f32_16x16x32_bf16 v[116:119], v[196:199], v[166:169], v[116:119]
	v_mfma_f32_16x16x32_bf16 v[112:115], v[208:211], v[166:169], v[112:115]
	v_mfma_f32_16x16x32_bf16 v[92:95], v[196:199], v[174:177], v[92:95]
	v_mfma_f32_16x16x32_bf16 v[88:91], v[208:211], v[174:177], v[88:91]
	v_mfma_f32_16x16x32_bf16 v[84:87], v[196:199], v[182:185], v[84:87]
	v_mfma_f32_16x16x32_bf16 v[80:83], v[208:211], v[182:185], v[80:83]
	v_mfma_f32_16x16x32_bf16 v[124:127], v[204:207], v[162:165], v[124:127]
	v_mfma_f32_16x16x32_bf16 v[120:123], v[214:217], v[162:165], v[120:123]
	v_mfma_f32_16x16x32_bf16 v[116:119], v[204:207], v[170:173], v[116:119]
	v_mfma_f32_16x16x32_bf16 v[112:115], v[214:217], v[170:173], v[112:115]
	v_mfma_f32_16x16x32_bf16 v[92:95], v[204:207], v[178:181], v[92:95]
	v_mfma_f32_16x16x32_bf16 v[88:91], v[214:217], v[178:181], v[88:91]
	v_mfma_f32_16x16x32_bf16 v[84:87], v[204:207], v[186:189], v[84:87]
	v_mfma_f32_16x16x32_bf16 v[80:83], v[214:217], v[186:189], v[80:83]
	s_mov_b32 m0, s34
	s_barrier
	ds_read_b128 v[154:157], v161 offset:49152
	ds_read_b128 v[162:165], v161 offset:50176
	ds_read_b128 v[166:169], v161 offset:51200
	ds_read_b128 v[170:173], v161 offset:52224
	ds_read_b128 v[174:177], v161 offset:53248
	ds_read_b128 v[178:181], v161 offset:54272
	ds_read_b128 v[182:185], v161 offset:55296
	ds_read_b128 v[186:189], v161 offset:56320
	global_load_lds_dwordx4 v144, s[48:49]
	s_mov_b32 m0, s35
	s_nop 0
	global_load_lds_dwordx4 v146, s[48:49]
	s_barrier
	s_waitcnt lgkmcnt(0)
	v_mfma_f32_16x16x32_bf16 v[60:63], v[64:67], v[154:157], v[60:63]
	v_mfma_f32_16x16x32_bf16 v[56:59], v[72:75], v[154:157], v[56:59]
	v_mfma_f32_16x16x32_bf16 v[52:55], v[64:67], v[166:169], v[52:55]
	v_mfma_f32_16x16x32_bf16 v[48:51], v[72:75], v[166:169], v[48:51]
	v_mfma_f32_16x16x32_bf16 v[28:31], v[64:67], v[174:177], v[28:31]
	v_mfma_f32_16x16x32_bf16 v[24:27], v[72:75], v[174:177], v[24:27]
	v_mfma_f32_16x16x32_bf16 v[20:23], v[64:67], v[182:185], v[20:23]
	v_mfma_f32_16x16x32_bf16 v[16:19], v[72:75], v[182:185], v[16:19]
	v_mfma_f32_16x16x32_bf16 v[60:63], v[68:71], v[162:165], v[60:63]
	v_mfma_f32_16x16x32_bf16 v[56:59], v[76:79], v[162:165], v[56:59]
	v_mfma_f32_16x16x32_bf16 v[52:55], v[68:71], v[170:173], v[52:55]
	v_mfma_f32_16x16x32_bf16 v[48:51], v[76:79], v[170:173], v[48:51]
	v_mfma_f32_16x16x32_bf16 v[28:31], v[68:71], v[178:181], v[28:31]
	v_mfma_f32_16x16x32_bf16 v[24:27], v[76:79], v[178:181], v[24:27]
	v_mfma_f32_16x16x32_bf16 v[20:23], v[68:71], v[186:189], v[20:23]
	v_mfma_f32_16x16x32_bf16 v[16:19], v[76:79], v[186:189], v[16:19]
	s_barrier
	s_add_u32 s16, s16, 0x80080
	s_addc_u32 s17, s17, 0
	s_add_i32 s18, s18, s27
	s_mov_b32 m0, s18
	s_nop 0
	global_load_lds_dwordx4 v192, s[16:17]
	s_add_i32 m0, s18, 0x2000
	s_nop 0
	global_load_lds_dwordx4 v148, s[16:17]
	s_waitcnt vmcnt(6)
	s_barrier
	v_mfma_f32_16x16x32_bf16 v[44:47], v[196:199], v[154:157], v[44:47]
	v_mfma_f32_16x16x32_bf16 v[40:43], v[208:211], v[154:157], v[40:43]
	v_mfma_f32_16x16x32_bf16 v[36:39], v[196:199], v[166:169], v[36:39]
	v_mfma_f32_16x16x32_bf16 v[32:35], v[208:211], v[166:169], v[32:35]
	v_mfma_f32_16x16x32_bf16 v[12:15], v[196:199], v[174:177], v[12:15]
	v_mfma_f32_16x16x32_bf16 v[8:11], v[208:211], v[174:177], v[8:11]
	v_mfma_f32_16x16x32_bf16 v[4:7], v[196:199], v[182:185], v[4:7]
	v_mfma_f32_16x16x32_bf16 v[0:3], v[208:211], v[182:185], v[0:3]
	v_mfma_f32_16x16x32_bf16 v[44:47], v[204:207], v[162:165], v[44:47]
	v_mfma_f32_16x16x32_bf16 v[40:43], v[214:217], v[162:165], v[40:43]
	v_mfma_f32_16x16x32_bf16 v[36:39], v[204:207], v[170:173], v[36:39]
	v_mfma_f32_16x16x32_bf16 v[32:35], v[214:217], v[170:173], v[32:35]
	v_mfma_f32_16x16x32_bf16 v[12:15], v[204:207], v[178:181], v[12:15]
	v_mfma_f32_16x16x32_bf16 v[8:11], v[214:217], v[178:181], v[8:11]
	v_mfma_f32_16x16x32_bf16 v[4:7], v[204:207], v[186:189], v[4:7]
	v_mfma_f32_16x16x32_bf16 v[0:3], v[214:217], v[186:189], v[0:3]
	s_add_i32 s42, s42, 2
	s_add_u32 s14, s14, 0x100
	s_addc_u32 s15, s15, 0
	s_add_u32 s40, s40, 0x100
	s_addc_u32 s41, s41, 0
	s_cmp_gt_u32 s42, 29
	s_barrier
	s_cbranch_scc0 .LBB0_294
	s_ashr_i32 s5, s12, 4
	v_lshl_or_b32 v190, s37, 8, v160
	s_mul_hi_i32 s7, s5, 0xc000
	s_mul_i32 s5, s5, 0xc000
	s_add_u32 s14, s31, s5
	v_ashrrev_i32_e32 v191, 31, v190
	v_lshl_add_u32 v154, s12, 8, v158
	v_readlane_b32 s52, v254, 23
	s_addc_u32 s15, s33, s7
	v_lshlrev_b64 v[156:157], 2, v[190:191]
	v_readlane_b32 s53, v254, 24
	v_ashrrev_i32_e32 v155, 31, v154
	v_lshl_add_u64 v[68:69], s[14:15], 0, v[156:157]
	v_lshl_add_u64 v[156:157], s[52:53], 0, v[156:157]
	v_lshlrev_b64 v[162:163], 13, v[154:155]
	v_lshl_add_u64 v[174:175], v[156:157], 0, v[162:163]
	global_load_dwordx4 v[72:75], v[68:69], off offset:16
	global_load_dwordx4 v[76:79], v[68:69], off
	global_load_dwordx4 v[64:67], v[68:69], off offset:528
	s_nop 0
	global_load_dwordx4 v[68:71], v[68:69], off offset:512
	s_nop 0
	global_load_dwordx4 v[162:165], v[174:175], off offset:16
	global_load_dwordx4 v[166:169], v[174:175], off
	global_load_dwordx4 v[170:173], v[174:175], off offset:528
	s_nop 0
	global_load_dwordx4 v[174:177], v[174:175], off offset:512
	v_or_b32_e32 v204, 16, v154
	v_ashrrev_i32_e32 v205, 31, v204
	v_lshlrev_b64 v[178:179], 13, v[204:205]
	v_lshl_add_u64 v[196:197], v[156:157], 0, v[178:179]
	global_load_dwordx4 v[178:181], v[196:197], off offset:16
	global_load_dwordx4 v[182:185], v[196:197], off
	global_load_dwordx4 v[186:189], v[196:197], off offset:528
	s_nop 0
	global_load_dwordx4 v[196:199], v[196:197], off offset:512
	v_lshlrev_b64 v[206:207], 12, v[154:155]
	s_and_b64 vcc, exec, s[0:1]
	s_mov_b32 s37, s4
	s_mov_b32 s12, s6
	s_mov_b64 s[16:17], s[10:11]
	s_mov_b64 s[14:15], s[8:9]
	s_mov_b32 s11, 0xc000
	v_readlane_b32 s54, v254, 25
	v_readlane_b32 s55, v254, 26
	v_readlane_b32 s56, v254, 27
	v_readlane_b32 s57, v254, 28
	v_readlane_b32 s58, v254, 29
	v_readlane_b32 s59, v254, 30
	v_readlane_b32 s60, v254, 31
	v_readlane_b32 s61, v254, 32
	v_readlane_b32 s62, v254, 33
	v_readlane_b32 s63, v254, 34
	v_readlane_b32 s64, v254, 35
	v_readlane_b32 s65, v254, 36
	v_readlane_b32 s66, v254, 37
	v_readlane_b32 s67, v254, 38
	s_waitcnt vmcnt(0)
	v_pk_fma_f32 v[136:137], v[136:137], v[72:73], v[162:163]
	v_pk_fma_f32 v[142:143], v[142:143], v[78:79], v[168:169]
	v_pk_fma_f32 v[140:141], v[140:141], v[76:77], v[166:167]
	v_pk_fma_f32 v[164:165], v[138:139], v[74:75], v[164:165]
	v_cvt_pk_bf16_f32 v138, v140, v141
	v_cvt_pk_bf16_f32 v139, v142, v143
	v_cvt_pk_bf16_f32 v140, v136, v137
	v_lshl_add_u64 v[142:143], s[2:3], 0, v[206:207]
	v_lshlrev_b64 v[136:137], 1, v[190:191]
	v_lshl_add_u64 v[142:143], v[142:143], 0, v[136:137]
	v_pk_fma_f32 v[124:125], v[124:125], v[68:69], v[174:175]
	v_cvt_pk_bf16_f32 v141, v164, v165
	global_store_dwordx4 v[142:143], v[138:141], off
	v_pk_fma_f32 v[126:127], v[126:127], v[70:71], v[176:177]
	v_pk_fma_f32 v[128:129], v[128:129], v[72:73], v[178:179]
	v_pk_fma_f32 v[138:139], v[122:123], v[66:67], v[172:173]
	v_pk_fma_f32 v[122:123], v[120:121], v[64:65], v[170:171]
	v_cvt_pk_bf16_f32 v120, v124, v125
	v_cvt_pk_bf16_f32 v121, v126, v127
	v_lshlrev_b64 v[124:125], 12, v[204:205]
	v_cvt_pk_bf16_f32 v122, v122, v123
	v_cvt_pk_bf16_f32 v123, v138, v139
	global_store_dwordx4 v[142:143], v[120:123], off offset:256
	v_lshl_add_u64 v[124:125], s[2:3], 0, v[124:125]
	v_lshl_add_u64 v[124:125], v[124:125], 0, v[136:137]
	v_pk_fma_f32 v[120:121], v[132:133], v[76:77], v[182:183]
	v_pk_fma_f32 v[122:123], v[134:135], v[78:79], v[184:185]
	v_cvt_pk_bf16_f32 v120, v120, v121
	v_or_b32_e32 v142, 32, v154
	v_cvt_pk_bf16_f32 v121, v122, v123
	v_pk_fma_f32 v[126:127], v[130:131], v[74:75], v[180:181]
	v_cvt_pk_bf16_f32 v122, v128, v129
	v_pk_fma_f32 v[118:119], v[118:119], v[70:71], v[198:199]
	v_cvt_pk_bf16_f32 v123, v126, v127
	global_store_dwordx4 v[124:125], v[120:123], off
	v_pk_fma_f32 v[116:117], v[116:117], v[68:69], v[196:197]
	v_ashrrev_i32_e32 v143, 31, v142
	v_pk_fma_f32 v[120:121], v[114:115], v[66:67], v[188:189]
	v_pk_fma_f32 v[114:115], v[112:113], v[64:65], v[186:187]
	v_cvt_pk_bf16_f32 v112, v116, v117
	v_cvt_pk_bf16_f32 v113, v118, v119
	v_or_b32_e32 v166, 48, v154
	v_cvt_pk_bf16_f32 v114, v114, v115
	v_cvt_pk_bf16_f32 v115, v120, v121
	global_store_dwordx4 v[124:125], v[112:115], off offset:256
	v_ashrrev_i32_e32 v167, 31, v166
	v_lshlrev_b64 v[128:129], 13, v[166:167]
	v_lshlrev_b64 v[112:113], 13, v[142:143]
	v_lshl_add_u64 v[124:125], v[156:157], 0, v[112:113]
	global_load_dwordx4 v[112:115], v[124:125], off offset:16
	global_load_dwordx4 v[116:119], v[124:125], off
	global_load_dwordx4 v[120:123], v[124:125], off offset:528
	s_nop 0
	global_load_dwordx4 v[124:127], v[124:125], off offset:512
	v_lshl_add_u64 v[162:163], v[156:157], 0, v[128:129]
	global_load_dwordx4 v[128:131], v[162:163], off offset:16
	global_load_dwordx4 v[132:135], v[162:163], off
	global_load_dwordx4 v[138:141], v[162:163], off offset:528
	s_nop 0
	global_load_dwordx4 v[162:165], v[162:163], off offset:512
	v_lshlrev_b64 v[142:143], 12, v[142:143]
	s_waitcnt vmcnt(0)
	v_pk_fma_f32 v[114:115], v[106:107], v[74:75], v[114:115]
	v_pk_fma_f32 v[108:109], v[108:109], v[76:77], v[116:117]
	v_pk_fma_f32 v[106:107], v[104:105], v[72:73], v[112:113]
	v_cvt_pk_bf16_f32 v104, v108, v109
	v_lshl_add_u64 v[108:109], s[2:3], 0, v[142:143]
	v_pk_fma_f32 v[110:111], v[110:111], v[78:79], v[118:119]
	v_lshl_add_u64 v[108:109], v[108:109], 0, v[136:137]
	v_cvt_pk_bf16_f32 v105, v110, v111
	v_pk_fma_f32 v[92:93], v[92:93], v[68:69], v[124:125]
	v_cvt_pk_bf16_f32 v106, v106, v107
	v_cvt_pk_bf16_f32 v107, v114, v115
	global_store_dwordx4 v[108:109], v[104:107], off
	v_pk_fma_f32 v[94:95], v[94:95], v[70:71], v[126:127]
	v_add_u32_e32 v112, 0x80, v154
	v_pk_fma_f32 v[104:105], v[90:91], v[66:67], v[122:123]
	v_pk_fma_f32 v[90:91], v[88:89], v[64:65], v[120:121]
	v_cvt_pk_bf16_f32 v88, v92, v93
	v_cvt_pk_bf16_f32 v89, v94, v95
	v_lshlrev_b64 v[92:93], 12, v[166:167]
	v_cvt_pk_bf16_f32 v90, v90, v91
	v_cvt_pk_bf16_f32 v91, v104, v105
	global_store_dwordx4 v[108:109], v[88:91], off offset:256
	v_lshl_add_u64 v[92:93], s[2:3], 0, v[92:93]
	v_lshl_add_u64 v[92:93], v[92:93], 0, v[136:137]
	v_pk_fma_f32 v[88:89], v[100:101], v[76:77], v[132:133]
	v_pk_fma_f32 v[90:91], v[102:103], v[78:79], v[134:135]
	v_cvt_pk_bf16_f32 v88, v88, v89
	v_pk_fma_f32 v[94:95], v[98:99], v[74:75], v[130:131]
	v_cvt_pk_bf16_f32 v89, v90, v91
	v_pk_fma_f32 v[96:97], v[96:97], v[72:73], v[128:129]
	v_pk_fma_f32 v[86:87], v[86:87], v[70:71], v[164:165]
	v_cvt_pk_bf16_f32 v90, v96, v97
	v_cvt_pk_bf16_f32 v91, v94, v95
	global_store_dwordx4 v[92:93], v[88:91], off
	v_pk_fma_f32 v[84:85], v[84:85], v[68:69], v[162:163]
	v_ashrrev_i32_e32 v113, 31, v112
	v_pk_fma_f32 v[88:89], v[82:83], v[66:67], v[140:141]
	v_pk_fma_f32 v[82:83], v[80:81], v[64:65], v[138:139]
	v_cvt_pk_bf16_f32 v80, v84, v85
	v_cvt_pk_bf16_f32 v81, v86, v87
	v_add_u32_e32 v114, 0x90, v154
	v_cvt_pk_bf16_f32 v82, v82, v83
	v_cvt_pk_bf16_f32 v83, v88, v89
	global_store_dwordx4 v[92:93], v[80:83], off offset:256
	v_ashrrev_i32_e32 v115, 31, v114
	v_lshlrev_b64 v[96:97], 13, v[114:115]
	v_lshlrev_b64 v[80:81], 13, v[112:113]
	v_lshl_add_u64 v[92:93], v[156:157], 0, v[80:81]
	global_load_dwordx4 v[80:83], v[92:93], off offset:16
	global_load_dwordx4 v[84:87], v[92:93], off
	global_load_dwordx4 v[88:91], v[92:93], off offset:528
	s_nop 0
	global_load_dwordx4 v[92:95], v[92:93], off offset:512
	v_lshl_add_u64 v[108:109], v[156:157], 0, v[96:97]
	global_load_dwordx4 v[96:99], v[108:109], off offset:16
	global_load_dwordx4 v[100:103], v[108:109], off
	global_load_dwordx4 v[104:107], v[108:109], off offset:528
	s_nop 0
	global_load_dwordx4 v[108:111], v[108:109], off offset:512
	v_lshlrev_b64 v[112:113], 12, v[112:113]
	s_waitcnt vmcnt(0)
	v_pk_fma_f32 v[82:83], v[58:59], v[74:75], v[82:83]
	v_pk_fma_f32 v[60:61], v[60:61], v[76:77], v[84:85]
	v_pk_fma_f32 v[58:59], v[56:57], v[72:73], v[80:81]
	v_cvt_pk_bf16_f32 v56, v60, v61
	v_lshl_add_u64 v[60:61], s[2:3], 0, v[112:113]
	v_pk_fma_f32 v[62:63], v[62:63], v[78:79], v[86:87]
	v_lshl_add_u64 v[60:61], v[60:61], 0, v[136:137]
	v_cvt_pk_bf16_f32 v57, v62, v63
	v_pk_fma_f32 v[44:45], v[44:45], v[68:69], v[92:93]
	v_cvt_pk_bf16_f32 v58, v58, v59
	v_cvt_pk_bf16_f32 v59, v82, v83
	global_store_dwordx4 v[60:61], v[56:59], off
	v_pk_fma_f32 v[46:47], v[46:47], v[70:71], v[94:95]
	v_add_u32_e32 v80, 0xa0, v154
	v_pk_fma_f32 v[56:57], v[42:43], v[66:67], v[90:91]
	v_pk_fma_f32 v[42:43], v[40:41], v[64:65], v[88:89]
	v_cvt_pk_bf16_f32 v40, v44, v45
	v_cvt_pk_bf16_f32 v41, v46, v47
	v_lshlrev_b64 v[44:45], 12, v[114:115]
	v_cvt_pk_bf16_f32 v42, v42, v43
	v_cvt_pk_bf16_f32 v43, v56, v57
	global_store_dwordx4 v[60:61], v[40:43], off offset:256
	v_lshl_add_u64 v[44:45], s[2:3], 0, v[44:45]
	v_lshl_add_u64 v[44:45], v[44:45], 0, v[136:137]
	v_pk_fma_f32 v[40:41], v[52:53], v[76:77], v[100:101]
	v_pk_fma_f32 v[42:43], v[54:55], v[78:79], v[102:103]
	v_cvt_pk_bf16_f32 v40, v40, v41
	v_pk_fma_f32 v[46:47], v[50:51], v[74:75], v[98:99]
	v_cvt_pk_bf16_f32 v41, v42, v43
	v_pk_fma_f32 v[48:49], v[48:49], v[72:73], v[96:97]
	v_pk_fma_f32 v[38:39], v[38:39], v[70:71], v[110:111]
	v_cvt_pk_bf16_f32 v42, v48, v49
	v_cvt_pk_bf16_f32 v43, v46, v47
	global_store_dwordx4 v[44:45], v[40:43], off
	v_pk_fma_f32 v[36:37], v[36:37], v[68:69], v[108:109]
	v_ashrrev_i32_e32 v81, 31, v80
	v_pk_fma_f32 v[40:41], v[34:35], v[66:67], v[106:107]
	v_pk_fma_f32 v[34:35], v[32:33], v[64:65], v[104:105]
	v_cvt_pk_bf16_f32 v32, v36, v37
	v_cvt_pk_bf16_f32 v33, v38, v39
	v_add_u32_e32 v82, 0xb0, v154
	v_cvt_pk_bf16_f32 v34, v34, v35
	v_cvt_pk_bf16_f32 v35, v40, v41
	global_store_dwordx4 v[44:45], v[32:35], off offset:256
	v_ashrrev_i32_e32 v83, 31, v82
	v_lshlrev_b64 v[48:49], 13, v[82:83]
	v_lshlrev_b64 v[32:33], 13, v[80:81]
	v_lshl_add_u64 v[44:45], v[156:157], 0, v[32:33]
	global_load_dwordx4 v[32:35], v[44:45], off offset:16
	global_load_dwordx4 v[36:39], v[44:45], off
	global_load_dwordx4 v[40:43], v[44:45], off offset:528
	s_nop 0
	global_load_dwordx4 v[44:47], v[44:45], off offset:512
	v_lshl_add_u64 v[60:61], v[156:157], 0, v[48:49]
	global_load_dwordx4 v[48:51], v[60:61], off offset:16
	global_load_dwordx4 v[52:55], v[60:61], off
	global_load_dwordx4 v[56:59], v[60:61], off offset:528
	s_nop 0
	global_load_dwordx4 v[60:63], v[60:61], off offset:512
	v_lshlrev_b64 v[80:81], 12, v[80:81]
	s_waitcnt vmcnt(0)
	v_pk_fma_f32 v[34:35], v[26:27], v[74:75], v[34:35]
	v_pk_fma_f32 v[28:29], v[28:29], v[76:77], v[36:37]
	v_pk_fma_f32 v[26:27], v[24:25], v[72:73], v[32:33]
	v_cvt_pk_bf16_f32 v24, v28, v29
	v_lshl_add_u64 v[28:29], s[2:3], 0, v[80:81]
	v_pk_fma_f32 v[30:31], v[30:31], v[78:79], v[38:39]
	v_lshl_add_u64 v[28:29], v[28:29], 0, v[136:137]
	v_cvt_pk_bf16_f32 v25, v30, v31
	v_pk_fma_f32 v[12:13], v[12:13], v[68:69], v[44:45]
	v_cvt_pk_bf16_f32 v26, v26, v27
	v_cvt_pk_bf16_f32 v27, v34, v35
	global_store_dwordx4 v[28:29], v[24:27], off
	v_pk_fma_f32 v[14:15], v[14:15], v[70:71], v[46:47]
	v_pk_fma_f32 v[16:17], v[16:17], v[72:73], v[48:49]
	v_pk_fma_f32 v[24:25], v[10:11], v[66:67], v[42:43]
	v_pk_fma_f32 v[10:11], v[8:9], v[64:65], v[40:41]
	v_cvt_pk_bf16_f32 v8, v12, v13
	v_cvt_pk_bf16_f32 v9, v14, v15
	v_lshlrev_b64 v[12:13], 12, v[82:83]
	v_cvt_pk_bf16_f32 v10, v10, v11
	v_cvt_pk_bf16_f32 v11, v24, v25
	global_store_dwordx4 v[28:29], v[8:11], off offset:256
	v_lshl_add_u64 v[12:13], s[2:3], 0, v[12:13]
	v_lshl_add_u64 v[12:13], v[12:13], 0, v[136:137]
	v_pk_fma_f32 v[8:9], v[20:21], v[76:77], v[52:53]
	v_pk_fma_f32 v[10:11], v[22:23], v[78:79], v[54:55]
	v_cvt_pk_bf16_f32 v8, v8, v9
	v_pk_fma_f32 v[14:15], v[18:19], v[74:75], v[50:51]
	v_cvt_pk_bf16_f32 v9, v10, v11
	v_cvt_pk_bf16_f32 v10, v16, v17
	v_pk_fma_f32 v[6:7], v[6:7], v[70:71], v[62:63]
	v_cvt_pk_bf16_f32 v11, v14, v15
	global_store_dwordx4 v[12:13], v[8:11], off
	v_pk_fma_f32 v[4:5], v[4:5], v[68:69], v[60:61]
	s_nop 0
	v_pk_fma_f32 v[8:9], v[2:3], v[66:67], v[58:59]
	v_pk_fma_f32 v[2:3], v[0:1], v[64:65], v[56:57]
	v_cvt_pk_bf16_f32 v0, v4, v5
	v_cvt_pk_bf16_f32 v1, v6, v7
	s_nop 0
	v_cvt_pk_bf16_f32 v2, v2, v3
	v_cvt_pk_bf16_f32 v3, v8, v9
	global_store_dwordx4 v[12:13], v[0:3], off offset:256
	s_cbranch_vccz .LBB0_287
	s_waitcnt vmcnt(0)
	s_cmpk_gt_u32 s25, 0xff
	s_cbranch_scc1 .LBB0_298
	s_barrier

.LBB0_414:
	s_ashr_i32 s9, s8, 31
	v_cmp_lt_i64_e32 vcc, s[10:11], v[202:203]
	s_lshl_b64 s[10:11], s[8:9], 20
	s_add_u32 s10, s24, s10
	s_addc_u32 s11, s25, s11
	s_and_b64 s[12:13], vcc, exec
	s_cselect_b32 s9, s11, s17
	s_cselect_b32 s38, s10, s16
	s_ashr_i32 s7, s6, 31
	s_lshl_b64 s[12:13], s[6:7], 20
	s_add_u32 s12, s26, s12
	s_addc_u32 s13, s27, s13
	s_and_b64 s[20:21], vcc, exec
	s_cselect_b32 s7, s13, s19
	s_cselect_b32 s39, s12, s18
	s_add_u32 s16, s16, 0x80080
	s_addc_u32 s17, s17, 0
	s_add_u32 s40, s18, 0x100
	v_mov_b32_e32 v0, 0
	s_addc_u32 s41, s19, 0
	s_mov_b32 s42, -2
	v_mov_b32_e32 v1, v0
	v_mov_b32_e32 v2, v0
	v_mov_b32_e32 v3, v0
	v_mov_b32_e32 v4, v0
	v_mov_b32_e32 v5, v0
	v_mov_b32_e32 v6, v0
	v_mov_b32_e32 v7, v0
	v_mov_b32_e32 v8, v0
	v_mov_b32_e32 v9, v0
	v_mov_b32_e32 v10, v0
	v_mov_b32_e32 v11, v0
	v_mov_b32_e32 v16, v0
	v_mov_b32_e32 v17, v0
	v_mov_b32_e32 v18, v0
	v_mov_b32_e32 v19, v0
	v_mov_b32_e32 v24, v0
	v_mov_b32_e32 v25, v0
	v_mov_b32_e32 v26, v0
	v_mov_b32_e32 v27, v0
	v_mov_b32_e32 v32, v0
	v_mov_b32_e32 v33, v0
	v_mov_b32_e32 v34, v0
	v_mov_b32_e32 v35, v0
	v_mov_b32_e32 v40, v0
	v_mov_b32_e32 v41, v0
	v_mov_b32_e32 v42, v0
	v_mov_b32_e32 v43, v0
	v_mov_b32_e32 v48, v0
	v_mov_b32_e32 v49, v0
	v_mov_b32_e32 v50, v0
	v_mov_b32_e32 v51, v0
	v_mov_b32_e32 v12, v0
	v_mov_b32_e32 v13, v0
	v_mov_b32_e32 v14, v0
	v_mov_b32_e32 v15, v0
	v_mov_b32_e32 v20, v0
	v_mov_b32_e32 v21, v0
	v_mov_b32_e32 v22, v0
	v_mov_b32_e32 v23, v0
	v_mov_b32_e32 v28, v0
	v_mov_b32_e32 v29, v0
	v_mov_b32_e32 v30, v0
	v_mov_b32_e32 v31, v0
	v_mov_b32_e32 v36, v0
	v_mov_b32_e32 v37, v0
	v_mov_b32_e32 v38, v0
	v_mov_b32_e32 v39, v0
	v_mov_b32_e32 v44, v0
	v_mov_b32_e32 v45, v0
	v_mov_b32_e32 v46, v0
	v_mov_b32_e32 v47, v0
	v_mov_b32_e32 v52, v0
	v_mov_b32_e32 v53, v0
	v_mov_b32_e32 v54, v0
	v_mov_b32_e32 v55, v0
	v_mov_b32_e32 v56, v0
	v_mov_b32_e32 v57, v0
	v_mov_b32_e32 v58, v0
	v_mov_b32_e32 v59, v0
	v_mov_b32_e32 v60, v0
	v_mov_b32_e32 v61, v0
	v_mov_b32_e32 v62, v0
	v_mov_b32_e32 v63, v0
	v_mov_b32_e32 v64, v0
	v_mov_b32_e32 v65, v0
	v_mov_b32_e32 v66, v0
	v_mov_b32_e32 v67, v0
	v_mov_b32_e32 v68, v0
	v_mov_b32_e32 v69, v0
	v_mov_b32_e32 v70, v0
	v_mov_b32_e32 v71, v0
	v_mov_b32_e32 v72, v0
	v_mov_b32_e32 v73, v0
	v_mov_b32_e32 v74, v0
	v_mov_b32_e32 v75, v0
	v_mov_b32_e32 v80, v0
	v_mov_b32_e32 v81, v0
	v_mov_b32_e32 v82, v0
	v_mov_b32_e32 v83, v0
	v_mov_b32_e32 v88, v0
	v_mov_b32_e32 v89, v0
	v_mov_b32_e32 v90, v0
	v_mov_b32_e32 v91, v0
	v_mov_b32_e32 v96, v0
	v_mov_b32_e32 v97, v0
	v_mov_b32_e32 v98, v0
	v_mov_b32_e32 v99, v0
	v_mov_b32_e32 v104, v0
	v_mov_b32_e32 v105, v0
	v_mov_b32_e32 v106, v0
	v_mov_b32_e32 v107, v0
	v_mov_b32_e32 v112, v0
	v_mov_b32_e32 v113, v0
	v_mov_b32_e32 v114, v0
	v_mov_b32_e32 v115, v0
	v_mov_b32_e32 v76, v0
	v_mov_b32_e32 v77, v0
	v_mov_b32_e32 v78, v0
	v_mov_b32_e32 v79, v0
	v_mov_b32_e32 v84, v0
	v_mov_b32_e32 v85, v0
	v_mov_b32_e32 v86, v0
	v_mov_b32_e32 v87, v0
	v_mov_b32_e32 v92, v0
	v_mov_b32_e32 v93, v0
	v_mov_b32_e32 v94, v0
	v_mov_b32_e32 v95, v0
	v_mov_b32_e32 v100, v0
	v_mov_b32_e32 v101, v0
	v_mov_b32_e32 v102, v0
	v_mov_b32_e32 v103, v0
	v_mov_b32_e32 v108, v0
	v_mov_b32_e32 v109, v0
	v_mov_b32_e32 v110, v0
	v_mov_b32_e32 v111, v0
	v_mov_b32_e32 v116, v0
	v_mov_b32_e32 v117, v0
	v_mov_b32_e32 v118, v0
	v_mov_b32_e32 v119, v0
	v_mov_b32_e32 v120, v0
	v_mov_b32_e32 v121, v0
	v_mov_b32_e32 v122, v0
	v_mov_b32_e32 v123, v0
	v_mov_b32_e32 v124, v0
	v_mov_b32_e32 v125, v0
	v_mov_b32_e32 v126, v0
	v_mov_b32_e32 v127, v0
	s_mov_b64 s[48:49], 0x80
	v_add_u32_e32 v196, 0x10000, v143
.LBB0_415:
	s_add_u32 s18, s16, 0xfff80080
	s_addc_u32 s19, s17, -1
	s_add_i32 s43, 0, 0x10000
	ds_read_b128 v[146:149], v196 offset:0
	ds_read_b128 v[150:153], v196 offset:1024
	ds_read_b128 v[154:157], v196 offset:2048
	ds_read_b128 v[158:161], v196 offset:3072
	s_cmp_eq_u32 s42, 28
	s_cselect_b32 s21, s9, s19
	s_cselect_b32 s20, s38, s18
	s_cselect_b32 s19, s7, s41
	s_cselect_b32 s18, s39, s40
	s_add_i32 m0, s30, 0xc000
	ds_read_b128 v[162:165], v145
	ds_read_b128 v[166:169], v145 offset:1024
	ds_read_b128 v[170:173], v145 offset:2048
	ds_read_b128 v[174:177], v145 offset:3072
	ds_read_b128 v[178:181], v145 offset:4096
	ds_read_b128 v[182:185], v145 offset:5120
	ds_read_b128 v[186:189], v145 offset:6144
	ds_read_b128 v[204:207], v145 offset:7168
	global_load_lds_dwordx4 v136, s[16:17]
	s_add_i32 m0, s30, 0xe000
	s_nop 0
	global_load_lds_dwordx4 v138, s[16:17]
	s_waitcnt lgkmcnt(8)
	s_barrier
	s_waitcnt lgkmcnt(0)
	v_mfma_f32_16x16x32_bf16 v[124:127], v[146:149], v[162:165], v[124:127]
	v_mfma_f32_16x16x32_bf16 v[120:123], v[154:157], v[162:165], v[120:123]
	v_mfma_f32_16x16x32_bf16 v[116:119], v[146:149], v[170:173], v[116:119]
	v_mfma_f32_16x16x32_bf16 v[108:111], v[154:157], v[170:173], v[108:111]
	v_mfma_f32_16x16x32_bf16 v[100:103], v[146:149], v[178:181], v[100:103]
	v_mfma_f32_16x16x32_bf16 v[92:95], v[154:157], v[178:181], v[92:95]
	v_mfma_f32_16x16x32_bf16 v[84:87], v[146:149], v[186:189], v[84:87]
	v_mfma_f32_16x16x32_bf16 v[76:79], v[154:157], v[186:189], v[76:79]
	v_mfma_f32_16x16x32_bf16 v[124:127], v[150:153], v[166:169], v[124:127]
	v_mfma_f32_16x16x32_bf16 v[120:123], v[158:161], v[166:169], v[120:123]
	v_mfma_f32_16x16x32_bf16 v[116:119], v[150:153], v[174:177], v[116:119]
	v_mfma_f32_16x16x32_bf16 v[108:111], v[158:161], v[174:177], v[108:111]
	v_mfma_f32_16x16x32_bf16 v[100:103], v[150:153], v[182:185], v[100:103]
	v_mfma_f32_16x16x32_bf16 v[92:95], v[158:161], v[182:185], v[92:95]
	v_mfma_f32_16x16x32_bf16 v[84:87], v[150:153], v[204:207], v[84:87]
	v_mfma_f32_16x16x32_bf16 v[76:79], v[158:161], v[204:207], v[76:79]
	s_barrier
	s_add_i32 s46, 0, 0x14000
	s_add_i32 s43, s43, s28
	ds_read_b128 v[208:211], v196 offset:16384
	ds_read_b128 v[214:217], v196 offset:17408
	ds_read_b128 v[218:221], v196 offset:18432
	ds_read_b128 v[222:225], v196 offset:19456
	s_mov_b32 m0, s43
	s_nop 0
	global_load_lds_dwordx4 v192, s[18:19]
	s_add_i32 m0, s43, 0x2000
	s_nop 0
	global_load_lds_dwordx4 v128, s[18:19]
	s_barrier
	s_waitcnt lgkmcnt(0)
	v_mfma_f32_16x16x32_bf16 v[112:115], v[208:211], v[162:165], v[112:115]
	v_mfma_f32_16x16x32_bf16 v[104:107], v[218:221], v[162:165], v[104:107]
	v_mfma_f32_16x16x32_bf16 v[96:99], v[208:211], v[170:173], v[96:99]
	v_mfma_f32_16x16x32_bf16 v[88:91], v[218:221], v[170:173], v[88:91]
	v_mfma_f32_16x16x32_bf16 v[80:83], v[208:211], v[178:181], v[80:83]
	v_mfma_f32_16x16x32_bf16 v[72:75], v[218:221], v[178:181], v[72:75]
	v_mfma_f32_16x16x32_bf16 v[68:71], v[208:211], v[186:189], v[68:71]
	v_mfma_f32_16x16x32_bf16 v[64:67], v[218:221], v[186:189], v[64:67]
	v_mfma_f32_16x16x32_bf16 v[112:115], v[214:217], v[166:169], v[112:115]
	v_mfma_f32_16x16x32_bf16 v[104:107], v[222:225], v[166:169], v[104:107]
	v_mfma_f32_16x16x32_bf16 v[96:99], v[214:217], v[174:177], v[96:99]
	v_mfma_f32_16x16x32_bf16 v[88:91], v[222:225], v[174:177], v[88:91]
	v_mfma_f32_16x16x32_bf16 v[80:83], v[214:217], v[182:185], v[80:83]
	v_mfma_f32_16x16x32_bf16 v[72:75], v[222:225], v[182:185], v[72:75]
	v_mfma_f32_16x16x32_bf16 v[68:71], v[214:217], v[204:207], v[68:71]
	v_mfma_f32_16x16x32_bf16 v[64:67], v[222:225], v[204:207], v[64:67]
	s_mov_b32 m0, s30
	s_add_u32 s48, s20, 0x80
	s_addc_u32 s49, s21, 0
	s_barrier
	ds_read_b128 v[162:165], v145 offset:16384
	ds_read_b128 v[166:169], v145 offset:17408
	ds_read_b128 v[170:173], v145 offset:18432
	ds_read_b128 v[174:177], v145 offset:19456
	ds_read_b128 v[178:181], v145 offset:20480
	ds_read_b128 v[182:185], v145 offset:21504
	ds_read_b128 v[186:189], v145 offset:22528
	ds_read_b128 v[204:207], v145 offset:23552
	global_load_lds_dwordx4 v132, s[20:21]
	s_mov_b32 m0, s31
	s_nop 0
	global_load_lds_dwordx4 v130, s[20:21]
	s_barrier
	s_waitcnt lgkmcnt(0)
	v_mfma_f32_16x16x32_bf16 v[60:63], v[146:149], v[162:165], v[60:63]
	v_mfma_f32_16x16x32_bf16 v[56:59], v[154:157], v[162:165], v[56:59]
	v_mfma_f32_16x16x32_bf16 v[52:55], v[146:149], v[170:173], v[52:55]
	v_mfma_f32_16x16x32_bf16 v[44:47], v[154:157], v[170:173], v[44:47]
	v_mfma_f32_16x16x32_bf16 v[36:39], v[146:149], v[178:181], v[36:39]
	v_mfma_f32_16x16x32_bf16 v[28:31], v[154:157], v[178:181], v[28:31]
	v_mfma_f32_16x16x32_bf16 v[20:23], v[146:149], v[186:189], v[20:23]
	v_mfma_f32_16x16x32_bf16 v[12:15], v[154:157], v[186:189], v[12:15]
	v_mfma_f32_16x16x32_bf16 v[60:63], v[150:153], v[166:169], v[60:63]
	v_mfma_f32_16x16x32_bf16 v[56:59], v[158:161], v[166:169], v[56:59]
	v_mfma_f32_16x16x32_bf16 v[52:55], v[150:153], v[174:177], v[52:55]
	v_mfma_f32_16x16x32_bf16 v[44:47], v[158:161], v[174:177], v[44:47]
	v_mfma_f32_16x16x32_bf16 v[36:39], v[150:153], v[182:185], v[36:39]
	v_mfma_f32_16x16x32_bf16 v[28:31], v[158:161], v[182:185], v[28:31]
	v_mfma_f32_16x16x32_bf16 v[20:23], v[150:153], v[204:207], v[20:23]
	v_mfma_f32_16x16x32_bf16 v[12:15], v[158:161], v[204:207], v[12:15]
	s_barrier
	s_add_u32 s44, s18, 0x80000
	s_addc_u32 s45, s19, 0
	s_add_i32 s43, s46, s28
	s_mov_b32 m0, s43
	s_nop 0
	global_load_lds_dwordx4 v192, s[44:45]
	s_add_i32 m0, s43, 0x2000
	s_nop 0
	global_load_lds_dwordx4 v128, s[44:45]
	s_waitcnt vmcnt(6)
	s_barrier
	v_mfma_f32_16x16x32_bf16 v[48:51], v[208:211], v[162:165], v[48:51]
	v_mfma_f32_16x16x32_bf16 v[40:43], v[218:221], v[162:165], v[40:43]
	v_mfma_f32_16x16x32_bf16 v[32:35], v[208:211], v[170:173], v[32:35]
	v_mfma_f32_16x16x32_bf16 v[24:27], v[218:221], v[170:173], v[24:27]
	v_mfma_f32_16x16x32_bf16 v[16:19], v[208:211], v[178:181], v[16:19]
	v_mfma_f32_16x16x32_bf16 v[8:11], v[218:221], v[178:181], v[8:11]
	v_mfma_f32_16x16x32_bf16 v[4:7], v[208:211], v[186:189], v[4:7]
	v_mfma_f32_16x16x32_bf16 v[0:3], v[218:221], v[186:189], v[0:3]
	v_mfma_f32_16x16x32_bf16 v[48:51], v[214:217], v[166:169], v[48:51]
	v_mfma_f32_16x16x32_bf16 v[40:43], v[222:225], v[166:169], v[40:43]
	v_mfma_f32_16x16x32_bf16 v[32:35], v[214:217], v[174:177], v[32:35]
	v_mfma_f32_16x16x32_bf16 v[24:27], v[222:225], v[174:177], v[24:27]
	v_mfma_f32_16x16x32_bf16 v[16:19], v[214:217], v[182:185], v[16:19]
	v_mfma_f32_16x16x32_bf16 v[8:11], v[222:225], v[182:185], v[8:11]
	v_mfma_f32_16x16x32_bf16 v[4:7], v[214:217], v[204:207], v[4:7]
	v_mfma_f32_16x16x32_bf16 v[0:3], v[222:225], v[204:207], v[0:3]
	s_add_i32 s43, 0, 0x18000
	s_barrier
	ds_read_b128 v[146:149], v196 offset:32768
	ds_read_b128 v[150:153], v196 offset:33792
	ds_read_b128 v[154:157], v196 offset:34816
	ds_read_b128 v[158:161], v196 offset:35840
	s_add_u32 s20, s20, 0x80000
	s_addc_u32 s21, s21, 0
	s_mov_b32 m0, s33
	ds_read_b128 v[162:165], v145 offset:32768
	ds_read_b128 v[166:169], v145 offset:33792
	ds_read_b128 v[170:173], v145 offset:34816
	ds_read_b128 v[174:177], v145 offset:35840
	ds_read_b128 v[178:181], v145 offset:36864
	ds_read_b128 v[182:185], v145 offset:37888
	ds_read_b128 v[186:189], v145 offset:38912
	ds_read_b128 v[204:207], v145 offset:39936
	global_load_lds_dwordx4 v132, s[20:21]
	s_mov_b32 m0, s34
	s_nop 0
	global_load_lds_dwordx4 v130, s[20:21]
	s_waitcnt lgkmcnt(8)
	s_barrier
	s_waitcnt lgkmcnt(0)
	v_mfma_f32_16x16x32_bf16 v[124:127], v[146:149], v[162:165], v[124:127]
	v_mfma_f32_16x16x32_bf16 v[120:123], v[154:157], v[162:165], v[120:123]
	v_mfma_f32_16x16x32_bf16 v[116:119], v[146:149], v[170:173], v[116:119]
	v_mfma_f32_16x16x32_bf16 v[108:111], v[154:157], v[170:173], v[108:111]
	v_mfma_f32_16x16x32_bf16 v[100:103], v[146:149], v[178:181], v[100:103]
	v_mfma_f32_16x16x32_bf16 v[92:95], v[154:157], v[178:181], v[92:95]
	v_mfma_f32_16x16x32_bf16 v[84:87], v[146:149], v[186:189], v[84:87]
	v_mfma_f32_16x16x32_bf16 v[76:79], v[154:157], v[186:189], v[76:79]
	v_mfma_f32_16x16x32_bf16 v[124:127], v[150:153], v[166:169], v[124:127]
	v_mfma_f32_16x16x32_bf16 v[120:123], v[158:161], v[166:169], v[120:123]
	v_mfma_f32_16x16x32_bf16 v[116:119], v[150:153], v[174:177], v[116:119]
	v_mfma_f32_16x16x32_bf16 v[108:111], v[158:161], v[174:177], v[108:111]
	v_mfma_f32_16x16x32_bf16 v[100:103], v[150:153], v[182:185], v[100:103]
	v_mfma_f32_16x16x32_bf16 v[92:95], v[158:161], v[182:185], v[92:95]
	v_mfma_f32_16x16x32_bf16 v[84:87], v[150:153], v[204:207], v[84:87]
	v_mfma_f32_16x16x32_bf16 v[76:79], v[158:161], v[204:207], v[76:79]
	s_barrier
	s_add_i32 s20, 0, 0x1c000
	s_add_i32 s21, s43, s28
	s_add_i32 m0, s21, 0xffffff80
	ds_read_b128 v[208:211], v196 offset:49152
	ds_read_b128 v[214:217], v196 offset:50176
	ds_read_b128 v[218:221], v196 offset:51200
	ds_read_b128 v[222:225], v196 offset:52224
	global_load_lds_dwordx4 v192, s[18:19] offset:128
	s_add_i32 m0, s21, 0x1f80
	s_nop 0
	global_load_lds_dwordx4 v128, s[18:19] offset:128
	s_barrier
	s_waitcnt lgkmcnt(0)
	v_mfma_f32_16x16x32_bf16 v[112:115], v[208:211], v[162:165], v[112:115]
	v_mfma_f32_16x16x32_bf16 v[104:107], v[218:221], v[162:165], v[104:107]
	v_mfma_f32_16x16x32_bf16 v[96:99], v[208:211], v[170:173], v[96:99]
	v_mfma_f32_16x16x32_bf16 v[88:91], v[218:221], v[170:173], v[88:91]
	v_mfma_f32_16x16x32_bf16 v[80:83], v[208:211], v[178:181], v[80:83]
	v_mfma_f32_16x16x32_bf16 v[72:75], v[218:221], v[178:181], v[72:75]
	v_mfma_f32_16x16x32_bf16 v[68:71], v[208:211], v[186:189], v[68:71]
	v_mfma_f32_16x16x32_bf16 v[64:67], v[218:221], v[186:189], v[64:67]
	v_mfma_f32_16x16x32_bf16 v[112:115], v[214:217], v[166:169], v[112:115]
	v_mfma_f32_16x16x32_bf16 v[104:107], v[222:225], v[166:169], v[104:107]
	v_mfma_f32_16x16x32_bf16 v[96:99], v[214:217], v[174:177], v[96:99]
	v_mfma_f32_16x16x32_bf16 v[88:91], v[222:225], v[174:177], v[88:91]
	v_mfma_f32_16x16x32_bf16 v[80:83], v[214:217], v[182:185], v[80:83]
	v_mfma_f32_16x16x32_bf16 v[72:75], v[222:225], v[182:185], v[72:75]
	v_mfma_f32_16x16x32_bf16 v[68:71], v[214:217], v[204:207], v[68:71]
	v_mfma_f32_16x16x32_bf16 v[64:67], v[222:225], v[204:207], v[64:67]
	s_mov_b32 m0, s35
	s_barrier
	ds_read_b128 v[162:165], v145 offset:49152
	ds_read_b128 v[166:169], v145 offset:50176
	ds_read_b128 v[170:173], v145 offset:51200
	ds_read_b128 v[174:177], v145 offset:52224
	ds_read_b128 v[178:181], v145 offset:53248
	ds_read_b128 v[182:185], v145 offset:54272
	ds_read_b128 v[186:189], v145 offset:55296
	ds_read_b128 v[204:207], v145 offset:56320
	global_load_lds_dwordx4 v132, s[48:49]
	s_mov_b32 m0, s36
	s_nop 0
	global_load_lds_dwordx4 v130, s[48:49]
	s_barrier
	s_waitcnt lgkmcnt(0)
	v_mfma_f32_16x16x32_bf16 v[60:63], v[146:149], v[162:165], v[60:63]
	v_mfma_f32_16x16x32_bf16 v[56:59], v[154:157], v[162:165], v[56:59]
	v_mfma_f32_16x16x32_bf16 v[52:55], v[146:149], v[170:173], v[52:55]
	v_mfma_f32_16x16x32_bf16 v[44:47], v[154:157], v[170:173], v[44:47]
	v_mfma_f32_16x16x32_bf16 v[36:39], v[146:149], v[178:181], v[36:39]
	v_mfma_f32_16x16x32_bf16 v[28:31], v[154:157], v[178:181], v[28:31]
	v_mfma_f32_16x16x32_bf16 v[20:23], v[146:149], v[186:189], v[20:23]
	v_mfma_f32_16x16x32_bf16 v[12:15], v[154:157], v[186:189], v[12:15]
	v_mfma_f32_16x16x32_bf16 v[60:63], v[150:153], v[166:169], v[60:63]
	v_mfma_f32_16x16x32_bf16 v[56:59], v[158:161], v[166:169], v[56:59]
	v_mfma_f32_16x16x32_bf16 v[52:55], v[150:153], v[174:177], v[52:55]
	v_mfma_f32_16x16x32_bf16 v[44:47], v[158:161], v[174:177], v[44:47]
	v_mfma_f32_16x16x32_bf16 v[36:39], v[150:153], v[182:185], v[36:39]
	v_mfma_f32_16x16x32_bf16 v[28:31], v[158:161], v[182:185], v[28:31]
	v_mfma_f32_16x16x32_bf16 v[20:23], v[150:153], v[204:207], v[20:23]
	v_mfma_f32_16x16x32_bf16 v[12:15], v[158:161], v[204:207], v[12:15]
	s_barrier
	s_add_u32 s18, s18, 0x80080
	s_addc_u32 s19, s19, 0
	s_add_i32 s20, s20, s28
	s_mov_b32 m0, s20
	s_nop 0
	global_load_lds_dwordx4 v192, s[18:19]
	s_add_i32 m0, s20, 0x2000
	s_nop 0
	global_load_lds_dwordx4 v128, s[18:19]
	s_waitcnt vmcnt(6)
	s_barrier
	v_mfma_f32_16x16x32_bf16 v[48:51], v[208:211], v[162:165], v[48:51]
	v_mfma_f32_16x16x32_bf16 v[40:43], v[218:221], v[162:165], v[40:43]
	v_mfma_f32_16x16x32_bf16 v[32:35], v[208:211], v[170:173], v[32:35]
	v_mfma_f32_16x16x32_bf16 v[24:27], v[218:221], v[170:173], v[24:27]
	v_mfma_f32_16x16x32_bf16 v[16:19], v[208:211], v[178:181], v[16:19]
	v_mfma_f32_16x16x32_bf16 v[8:11], v[218:221], v[178:181], v[8:11]
	v_mfma_f32_16x16x32_bf16 v[4:7], v[208:211], v[186:189], v[4:7]
	v_mfma_f32_16x16x32_bf16 v[0:3], v[218:221], v[186:189], v[0:3]
	v_mfma_f32_16x16x32_bf16 v[48:51], v[214:217], v[166:169], v[48:51]
	v_mfma_f32_16x16x32_bf16 v[40:43], v[222:225], v[166:169], v[40:43]
	v_mfma_f32_16x16x32_bf16 v[32:35], v[214:217], v[174:177], v[32:35]
	v_mfma_f32_16x16x32_bf16 v[24:27], v[222:225], v[174:177], v[24:27]
	v_mfma_f32_16x16x32_bf16 v[16:19], v[214:217], v[182:185], v[16:19]
	v_mfma_f32_16x16x32_bf16 v[8:11], v[222:225], v[182:185], v[8:11]
	v_mfma_f32_16x16x32_bf16 v[4:7], v[214:217], v[204:207], v[4:7]
	v_mfma_f32_16x16x32_bf16 v[0:3], v[222:225], v[204:207], v[0:3]
	s_add_i32 s42, s42, 2
	s_add_u32 s16, s16, 0x100
	s_addc_u32 s17, s17, 0
	s_add_u32 s40, s40, 0x100
	s_addc_u32 s41, s41, 0
	s_cmp_gt_u32 s42, 29
	s_barrier
	s_cbranch_scc0 .LBB0_415
	s_mul_hi_i32 s9, s15, 0x2aaaaaab
	v_lshl_add_u32 v153, s14, 8, v142
	s_lshr_b32 s14, s9, 31
	s_lshr_b32 s9, s9, 2
	s_add_i32 s9, s9, s14
	s_lshl_b32 s7, s15, 8
	s_mul_i32 s16, s9, 0x1800
	v_readlane_b32 s40, v254, 14
	v_readlane_b32 s41, v254, 15
	s_sub_i32 s40, s7, s16
	s_mov_b64 s[20:21], s[40:41]
	v_readlane_b32 s42, v254, 16
	v_readlane_b32 s43, v254, 17
	v_writelane_b32 v254, s20, 14
	s_mov_b64 s[14:15], -1
	s_cmpk_gt_i32 s40, 0xfff
	v_writelane_b32 v254, s21, 15
	v_writelane_b32 v254, s22, 16
	v_writelane_b32 v254, s23, 17
	v_or_b32_e32 v152, 16, v153
	v_or_b32_e32 v151, 32, v153
	v_or_b32_e32 v150, 48, v153
	v_add_u32_e32 v149, 0x80, v153
	v_add_u32_e32 v148, 0x90, v153
	v_add_u32_e32 v147, 0xa0, v153
	v_add_u32_e32 v146, 0xb0, v153
	s_cbranch_scc0 .LBB0_418
	v_mov_b32_e32 v156, v193
	v_mov_b32_e32 v157, v193
	s_ashr_i32 s17, s16, 31
	v_mov_b64_e32 v[140:141], s[2:3]
	s_mov_b32 s9, 0x9000
	v_cvt_pk_fp8_f32 v156, v124, v125
	v_cvt_pk_fp8_f32 v157, v120, v121
	s_lshl_b64 s[14:15], s[16:17], 1
	v_mad_i64_i32 v[154:155], s[16:17], v153, s9, v[140:141]
	s_add_u32 s14, s14, 0x2000
	v_readlane_b32 s16, v254, 14
	s_addc_u32 s15, s15, 0
	v_readlane_b32 s17, v254, 15
	v_lshl_add_u64 v[154:155], v[154:155], 0, s[14:15]
	s_mov_b64 s[20:21], s[16:17]
	v_cvt_pk_fp8_f32 v156, v126, v127 op_sel:[0,0,1]
	v_cvt_pk_fp8_f32 v157, v122, v123 op_sel:[0,0,1]
	v_lshl_add_u64 v[154:155], v[154:155], 0, s[20:21]
	v_lshl_add_u64 v[154:155], v[154:155], 0, s[4:5]
	v_lshl_add_u64 v[154:155], v[154:155], 0, v[134:135]
	global_store_dwordx2 v[154:155], v[156:157], off offset:-4096
	v_mov_b32_e32 v156, v193
	v_mov_b32_e32 v157, v193
	v_cvt_pk_fp8_f32 v156, v112, v113
	v_cvt_pk_fp8_f32 v157, v104, v105
	v_readlane_b32 s18, v254, 16
	v_readlane_b32 s19, v254, 17
	v_cvt_pk_fp8_f32 v156, v114, v115 op_sel:[0,0,1]
	v_cvt_pk_fp8_f32 v157, v106, v107 op_sel:[0,0,1]
	global_store_dwordx2 v[154:155], v[156:157], off offset:-3968
	v_mov_b32_e32 v156, v193
	v_mov_b32_e32 v157, v193
	v_cvt_pk_fp8_f32 v156, v116, v117
	v_cvt_pk_fp8_f32 v157, v108, v109
	v_mad_i64_i32 v[154:155], s[16:17], v152, s9, v[140:141]
	v_lshl_add_u64 v[154:155], v[154:155], 0, s[14:15]
	v_cvt_pk_fp8_f32 v156, v118, v119 op_sel:[0,0,1]
	v_cvt_pk_fp8_f32 v157, v110, v111 op_sel:[0,0,1]
	v_lshl_add_u64 v[154:155], v[154:155], 0, s[20:21]
	v_lshl_add_u64 v[154:155], v[154:155], 0, s[4:5]
	v_lshl_add_u64 v[154:155], v[154:155], 0, v[134:135]
	global_store_dwordx2 v[154:155], v[156:157], off offset:-4096
	v_mov_b32_e32 v156, v193
	v_mov_b32_e32 v157, v193
	v_cvt_pk_fp8_f32 v156, v96, v97
	v_cvt_pk_fp8_f32 v157, v88, v89
	v_cvt_pk_fp8_f32 v156, v98, v99 op_sel:[0,0,1]
	v_cvt_pk_fp8_f32 v157, v90, v91 op_sel:[0,0,1]
	global_store_dwordx2 v[154:155], v[156:157], off offset:-3968
	v_mov_b32_e32 v156, v193
	v_mov_b32_e32 v157, v193
	v_cvt_pk_fp8_f32 v156, v100, v101
	v_cvt_pk_fp8_f32 v157, v92, v93
	v_mad_i64_i32 v[154:155], s[16:17], v151, s9, v[140:141]
	v_lshl_add_u64 v[154:155], v[154:155], 0, s[14:15]
	v_cvt_pk_fp8_f32 v156, v102, v103 op_sel:[0,0,1]
	v_cvt_pk_fp8_f32 v157, v94, v95 op_sel:[0,0,1]
	v_lshl_add_u64 v[154:155], v[154:155], 0, s[20:21]
	v_lshl_add_u64 v[154:155], v[154:155], 0, s[4:5]
	v_lshl_add_u64 v[154:155], v[154:155], 0, v[134:135]
	global_store_dwordx2 v[154:155], v[156:157], off offset:-4096
	v_mov_b32_e32 v156, v193
	v_mov_b32_e32 v157, v193
	v_cvt_pk_fp8_f32 v156, v80, v81
	v_cvt_pk_fp8_f32 v157, v72, v73
	v_cvt_pk_fp8_f32 v156, v82, v83 op_sel:[0,0,1]
	v_cvt_pk_fp8_f32 v157, v74, v75 op_sel:[0,0,1]
	global_store_dwordx2 v[154:155], v[156:157], off offset:-3968
	v_mov_b32_e32 v156, v193
	v_mov_b32_e32 v157, v193
	v_cvt_pk_fp8_f32 v156, v84, v85
	v_cvt_pk_fp8_f32 v157, v76, v77
	v_mad_i64_i32 v[154:155], s[16:17], v150, s9, v[140:141]
	v_lshl_add_u64 v[154:155], v[154:155], 0, s[14:15]
	v_cvt_pk_fp8_f32 v156, v86, v87 op_sel:[0,0,1]
	v_cvt_pk_fp8_f32 v157, v78, v79 op_sel:[0,0,1]
	v_lshl_add_u64 v[154:155], v[154:155], 0, s[20:21]
	v_lshl_add_u64 v[154:155], v[154:155], 0, s[4:5]
	v_lshl_add_u64 v[154:155], v[154:155], 0, v[134:135]
	global_store_dwordx2 v[154:155], v[156:157], off offset:-4096
	v_mov_b32_e32 v156, v193
	v_mov_b32_e32 v157, v193
	v_cvt_pk_fp8_f32 v156, v68, v69
	v_cvt_pk_fp8_f32 v157, v64, v65
	v_cvt_pk_fp8_f32 v156, v70, v71 op_sel:[0,0,1]
	v_cvt_pk_fp8_f32 v157, v66, v67 op_sel:[0,0,1]
	global_store_dwordx2 v[154:155], v[156:157], off offset:-3968
	v_mov_b32_e32 v156, v193
	v_mov_b32_e32 v157, v193
	v_cvt_pk_fp8_f32 v156, v60, v61
	v_cvt_pk_fp8_f32 v157, v56, v57
	v_mad_i64_i32 v[154:155], s[16:17], v149, s9, v[140:141]
	v_lshl_add_u64 v[154:155], v[154:155], 0, s[14:15]
	v_cvt_pk_fp8_f32 v156, v62, v63 op_sel:[0,0,1]
	v_cvt_pk_fp8_f32 v157, v58, v59 op_sel:[0,0,1]
	v_lshl_add_u64 v[154:155], v[154:155], 0, s[20:21]
	v_lshl_add_u64 v[154:155], v[154:155], 0, s[4:5]
	v_lshl_add_u64 v[154:155], v[154:155], 0, v[134:135]
	global_store_dwordx2 v[154:155], v[156:157], off offset:-4096
	v_mov_b32_e32 v156, v193
	v_mov_b32_e32 v157, v193
	v_cvt_pk_fp8_f32 v156, v48, v49
	v_cvt_pk_fp8_f32 v157, v40, v41
	v_cvt_pk_fp8_f32 v156, v50, v51 op_sel:[0,0,1]
	v_cvt_pk_fp8_f32 v157, v42, v43 op_sel:[0,0,1]
	global_store_dwordx2 v[154:155], v[156:157], off offset:-3968
	v_mov_b32_e32 v156, v193
	v_mov_b32_e32 v157, v193
	v_cvt_pk_fp8_f32 v156, v52, v53
	v_cvt_pk_fp8_f32 v157, v44, v45
	v_mad_i64_i32 v[154:155], s[16:17], v148, s9, v[140:141]
	v_lshl_add_u64 v[154:155], v[154:155], 0, s[14:15]
	v_cvt_pk_fp8_f32 v156, v54, v55 op_sel:[0,0,1]
	v_cvt_pk_fp8_f32 v157, v46, v47 op_sel:[0,0,1]
	v_lshl_add_u64 v[154:155], v[154:155], 0, s[20:21]
	v_lshl_add_u64 v[154:155], v[154:155], 0, s[4:5]
	v_lshl_add_u64 v[154:155], v[154:155], 0, v[134:135]
	global_store_dwordx2 v[154:155], v[156:157], off offset:-4096
	v_mov_b32_e32 v156, v193
	v_mov_b32_e32 v157, v193
	v_cvt_pk_fp8_f32 v156, v32, v33
	v_cvt_pk_fp8_f32 v157, v24, v25
	v_cvt_pk_fp8_f32 v156, v34, v35 op_sel:[0,0,1]
	v_cvt_pk_fp8_f32 v157, v26, v27 op_sel:[0,0,1]
	global_store_dwordx2 v[154:155], v[156:157], off offset:-3968
	v_mov_b32_e32 v156, v193
	v_mov_b32_e32 v157, v193
	v_cvt_pk_fp8_f32 v156, v36, v37
	v_cvt_pk_fp8_f32 v157, v28, v29
	v_mad_i64_i32 v[154:155], s[16:17], v147, s9, v[140:141]
	v_lshl_add_u64 v[154:155], v[154:155], 0, s[14:15]
	v_cvt_pk_fp8_f32 v156, v38, v39 op_sel:[0,0,1]
	v_cvt_pk_fp8_f32 v157, v30, v31 op_sel:[0,0,1]
	v_lshl_add_u64 v[154:155], v[154:155], 0, s[20:21]
	v_lshl_add_u64 v[154:155], v[154:155], 0, s[4:5]
	v_lshl_add_u64 v[154:155], v[154:155], 0, v[134:135]
	global_store_dwordx2 v[154:155], v[156:157], off offset:-4096
	v_mov_b32_e32 v156, v193
	v_mov_b32_e32 v157, v193
	v_cvt_pk_fp8_f32 v156, v16, v17
	v_cvt_pk_fp8_f32 v157, v8, v9
	v_mad_i64_i32 v[140:141], s[16:17], v146, s9, v[140:141]
	v_cvt_pk_fp8_f32 v156, v18, v19 op_sel:[0,0,1]
	v_cvt_pk_fp8_f32 v157, v10, v11 op_sel:[0,0,1]
	v_lshl_add_u64 v[140:141], v[140:141], 0, s[14:15]
	v_lshl_add_u64 v[140:141], v[140:141], 0, s[20:21]
	v_lshl_add_u64 v[140:141], v[140:141], 0, s[4:5]
	global_store_dwordx2 v[154:155], v[156:157], off offset:-3968
	v_mov_b32_e32 v154, v193
	v_mov_b32_e32 v155, v193
	v_cvt_pk_fp8_f32 v154, v20, v21
	v_cvt_pk_fp8_f32 v155, v12, v13
	v_lshl_add_u64 v[140:141], v[140:141], 0, v[134:135]
	s_mov_b64 s[14:15], 0
	v_cvt_pk_fp8_f32 v154, v22, v23 op_sel:[0,0,1]
	v_cvt_pk_fp8_f32 v155, v14, v15 op_sel:[0,0,1]
	global_store_dwordx2 v[140:141], v[154:155], off offset:-4096
	v_mov_b32_e32 v154, v193
	v_mov_b32_e32 v155, v193
	v_cvt_pk_fp8_f32 v154, v4, v5
	v_cvt_pk_fp8_f32 v155, v0, v1
	v_cvt_pk_fp8_f32 v154, v6, v7 op_sel:[0,0,1]
	v_cvt_pk_fp8_f32 v155, v2, v3 op_sel:[0,0,1]
	global_store_dwordx2 v[140:141], v[154:155], off offset:-3968
